# overflow guard made post-hoc: tile row-sum checked after the exps, recovery path recomputes S(t) from the still-resident K slot; drops the 17-op max tree per tile
# speedup vs baseline: 1.0350x; 1.0196x over previous
; __device__ __forceinline__ void attn_unit(LAS unsigned char* lds, const bf16_t* Z, bf16_t* A2, const float* tabg, int seq_base, int S, int h, int qb, float lam) {
;     const int tid = otid(), w = __builtin_amdgcn_readfirstlane(tid >> 6), lane = tid & 63, r32 = lane & 31, hi = lane >> 5, g4 = lane >> 4, i16 = lane & 15;
;     const int rg = w & 3, m = w >> 2;
;     LAS unsigned char* Kb = lds + OFF_K; LAS unsigned char* Vb = lds + OFF_V;
;     LAS float* scr = (LAS float*)(lds + OFF_SCR) + w * 64;
;     LAS float* tab = (LAS float*)(lds + OFF_TAB);
;     for (int i = tid; i < 449; i += 512) { int d = i - 224; d = d < -128 ? -128 : (d > 128 ? 128 : d); tab[i] = tabg[h * 257 + d + 128]; }
;     const int qlo = qb * 128 + rg * 32;
;     bf16x8 qf[4];
;     { const bf16_t* qrow = Z + (size_t)(seq_base + qlo + r32) * NZ + h * 128 + m * 64 + 8 * hi;
; #pragma unroll
;       for (int ds = 0; ds < 4; ++ds) qf[ds] = *(const bf16x8*)(qrow + 16 * ds); }
;     const char* kvbase = (const char*)(Z + (size_t)seq_base * NZ + h * 128);
;     unsigned koff[2], voff[2];
; #pragma unroll
;     for (int i = 0; i < 2; ++i) { const int row = (i * 8 + w) * 4 + (lane >> 4), cp = lane & 15;
;         koff[i] = (unsigned)(row * NZ + 512 + ((cp ^ (row & 15)) << 3)) * 2u; voff[i] = (unsigned)(row * NZ + 1024 + ((cp ^ (4 * (row & 3))) << 3)) * 2u; }
;     const unsigned kb_u = (unsigned)(size_t)Kb + (unsigned)w * 1024u, vb_u = (unsigned)(size_t)Vb + (unsigned)w * 1024u;
;     ...
;     ATT_STAGE(0, 0); ATT_STAGE(1, 1);
;     asm volatile("s_waitcnt vmcnt(4) lgkmcnt(0)" ::: "memory"); __builtin_amdgcn_s_barrier(); asm volatile("" ::: "memory");
; #pragma unroll
;     for (int ds = 0; ds < 4; ++ds) asm volatile("" : "+v"(qf[ds]));
;     const float tabL = tab[0], tabR = tab[448];
;     f32x16 O[4];
; #pragma unroll
;     for (int d = 0; d < 4; ++d)
; #pragma unroll
;         for (int r = 0; r < 16; ++r) O[d][r] = 0.f;
;     float mu = 0.f; f32x2 ls2 = {0.f, 0.f};
;     f32x16 cblk; float coff_cur = __builtin_nanf("");
; #pragma unroll
;     for (int r = 0; r < 16; ++r) cblk[r] = 0.f;
;     const int NT = S >> 6;
;     const unsigned kfo = r32 * 256 + ((unsigned)((m * 8 + hi) ^ (r32 & 15)) << 4);
;     const unsigned vj = (i16 >> 2) & 3;
;     const unsigned vfo = (4 * hi + (i16 >> 2)) * 256 + (vj << 6) + 32 * (g4 & 1) + 8 * (i16 & 3);
;     int bc = 0, bn = 2;
.LBB0_292:
	s_or_b64 exec, exec, s[8:9]
	s_waitcnt lgkmcnt(0)
	s_add_u32 s8, s4, 0x7800000
	s_addc_u32 s9, s5, 0
	s_lshl_b32 s10, s26, 11
	s_and_b32 s11, s10, 0x2000
	s_and_b32 s10, s25, 32
	s_ashr_i32 s15, s27, 6
	s_or_b32 s10, s10, s23
	s_and_b32 s17, s15, 3
	s_lshl_b32 s14, s10, 7
	s_lshl_b32 s10, s17, 5
	s_or_b32 s34, s10, s14
	v_and_b32_e32 v148, 31, v68
	s_or_b32 s14, s34, s11
	v_or_b32_e32 v2, s14, v148
	s_ashr_i32 s16, s27, 8
	v_lshlrev_b32_e32 v162, 12, v2
	v_lshl_add_u64 v[2:3], s[8:9], 0, v[162:163]
	s_lshl_b32 s48, s30, 8
	s_lshl_b32 s28, s16, 6
	v_bfe_u32 v159, v68, 5, 1
	v_lshl_add_u64 v[2:3], v[2:3], 0, s[48:49]
	s_ashr_i32 s29, s28, 31
	v_lshl_add_u64 v[2:3], s[28:29], 1, v[2:3]
	v_lshlrev_b32_e32 v162, 4, v159
	v_lshl_add_u64 v[2:3], v[2:3], 0, v[162:163]
	global_load_dwordx4 v[116:119], v[2:3], off
	global_load_dwordx4 v[120:123], v[2:3], off offset:32
	global_load_dwordx4 v[124:127], v[2:3], off offset:64
	global_load_dwordx4 v[128:131], v[2:3], off offset:96
	s_lshl_b32 s11, s11, 12
	s_add_u32 s8, s8, s11
	v_bfe_u32 v4, v68, 4, 2
	s_addc_u32 s9, s9, 0
	s_lshl_b32 s11, s15, 2
	v_or_b32_e32 v5, s11, v4
	v_lshlrev_b32_e32 v35, 5, v4
	v_bitop3_b32 v4, s11, v68, v4 bitop3:0x36
	v_lshlrev_b32_e32 v4, 3, v4
	v_and_b32_e32 v34, 15, v68
	v_lshlrev_b32_e32 v5, 11, v5
	v_and_b32_e32 v4, 0x78, v4
	v_lshlrev_b32_e32 v6, 3, v34
	v_or_b32_e32 v7, v4, v5
	v_lshl_or_b32 v149, v7, 1, v249
	v_bitop3_b32 v7, v5, v35, v6 bitop3:0xf6
	v_add_u32_e32 v5, 0x10000, v5
	v_or_b32_e32 v4, v4, v5
	s_add_u32 s8, s8, s48
	v_lshl_or_b32 v161, v4, 1, v249
	v_bitop3_b32 v4, v5, v35, v6 bitop3:0xf6
	s_addc_u32 s9, s9, 0
	s_lshl_b32 s29, s15, 10
	s_add_i32 s11, 0, 0xc000
	v_lshl_or_b32 v160, v7, 1, v250
	v_lshl_or_b32 v176, v4, 1, v250
	s_add_i32 s28, s29, 0
	s_add_i32 s29, s29, s11
	s_mov_b32 s15, m0
	s_mov_b32 m0, s28
	s_nop 0
	global_load_lds_dwordx4 v149, s[8:9]
	s_mov_b32 m0, s29
	s_nop 0
	global_load_lds_dwordx4 v160, s[8:9]
	s_add_u32 m0, s28, 0x2000
	s_nop 0
	global_load_lds_dwordx4 v161, s[8:9]
	s_add_u32 m0, s29, 0x2000
	s_nop 0
	global_load_lds_dwordx4 v176, s[8:9]
	s_mov_b32 m0, s15
	s_add_u32 s36, s8, 0x40000
	s_addc_u32 s37, s9, 0
	s_add_i32 s15, s28, 0x4000
	s_add_i32 s31, s29, 0x4000
	s_mov_b32 s33, m0
	s_mov_b32 m0, s15
	s_nop 0
	global_load_lds_dwordx4 v149, s[36:37]
	s_mov_b32 m0, s31
	s_nop 0
	global_load_lds_dwordx4 v160, s[36:37]
	s_add_u32 m0, s15, 0x2000
	s_nop 0
	global_load_lds_dwordx4 v161, s[36:37]
	s_add_u32 m0, s31, 0x2000
	s_nop 0
	global_load_lds_dwordx4 v176, s[36:37]
	s_mov_b32 m0, s33
	s_mov_b32 s32, m0
	s_mov_b32 s4, s8
	s_add_u32 s8, s8, 0x40000
	s_addc_u32 s9, s9, 0
	s_add_u32 s42, s8, 0x40000
	s_addc_u32 s43, s9, 0
	s_add_u32 m0, s28, 0x8000
	v_add_u32_e32 v172, 0x80000, v149
	global_load_lds_dwordx4 v149, s[42:43]
	s_add_u32 m0, s28, 0xa000
	v_add_u32_e32 v173, 0x80000, v161
	global_load_lds_dwordx4 v161, s[42:43]
	v_add_u32_e32 v174, 0x40000, v160
	v_add_u32_e32 v175, 0x40000, v176
	s_lshl_b32 s15, s30, 7
	s_and_b32 s37, s27, 0x3fffffc0
	s_lshl_b32 s37, s37, 2
	s_add_i32 s30, s37, 0x18000
	v_and_b32_e32 v183, 63, v68
	v_lshl_add_u32 v185, v159, 4, s30
	v_lshl_add_u32 v184, v148, 2, s30
	s_add_i32 s33, s34, 0x9f
	v_add_lshl_u32 v251, s34, v148, 2
	v_lshlrev_b32_e32 v252, 4, v159
	v_sub_u32_e32 v162, v252, v251
	s_add_i32 s34, s34, 0xffffff41
	s_ashr_i32 s11, s34, 6
	s_add_i32 s11, s11, 1
	s_lshl_b32 s11, s11, 6
	s_max_i32 s11, s11, 0
	s_add_i32 s31, s33, 63
	s_andn2_b32 s31, s31, 63
	s_sub_u32 s31, s31, 64
	s_lshr_b32 s10, s11, 6
	s_sub_i32 s10, s10, 2
	s_max_i32 s10, s10, 0
	s_lshl_b32 s37, s16, 3
	v_lshlrev_b32_e32 v19, 8, v148
	v_bitop3_b32 v251, s37, v34, v159 bitop3:0x36
	v_lshlrev_b32_e32 v252, 2, v159
	v_lshrrev_b32_e32 v253, 2, v34
	v_lshlrev_b32_e32 v254, 3, v68
	v_lshl_add_u32 v19, v251, 4, v19
	v_or_b32_e32 v252, v252, v253
	v_and_b32_e32 v254, 24, v254
	v_and_b32_e32 v251, 32, v35
	v_lshlrev_b32_e32 v252, 8, v252
	v_lshl_or_b32 v253, v253, 6, v254
	v_xor_b32_e32 v180, 32, v19
	v_or3_b32 v179, v252, v251, v253
	v_xor_b32_e32 v181, 64, v19
	v_xor_b32_e32 v182, 0x60, v19
	v_add_u32_e32 v228, 0xc000, v179
	v_xor_b32_e32 v229, 0x40, v179
	v_add_u32_e32 v229, 0xc000, v229
	v_xor_b32_e32 v230, 0x80, v179
	v_add_u32_e32 v230, 0xc000, v230
	v_xor_b32_e32 v231, 0xc0, v179
	v_add_u32_e32 v231, 0xc000, v231
	v_add_u32_e32 v164, 0x1d000, v19
	v_add_u32_e32 v168, 0xd000, v228
	v_add_u32_e32 v165, 0x1d000, v180
	v_add_u32_e32 v169, 0xd000, v229
	v_add_u32_e32 v166, 0x1d000, v181
	v_add_u32_e32 v170, 0xd000, v230
	v_add_u32_e32 v167, 0x1d000, v182
	v_add_u32_e32 v171, 0xd000, v231
	v_mov_b64_e32 v[20:21], 0
	v_mov_b64_e32 v[22:23], 0
	v_mov_b64_e32 v[24:25], 0
	v_mov_b64_e32 v[26:27], 0
	v_mov_b64_e32 v[28:29], 0
	v_mov_b64_e32 v[30:31], 0
	v_mov_b64_e32 v[32:33], 0
	v_mov_b64_e32 v[34:35], 0
	v_mov_b64_e32 v[36:37], 0
	v_mov_b64_e32 v[38:39], 0
	v_mov_b64_e32 v[40:41], 0
	v_mov_b64_e32 v[42:43], 0
	v_mov_b64_e32 v[44:45], 0
	v_mov_b64_e32 v[46:47], 0
	v_mov_b64_e32 v[48:49], 0
	v_mov_b64_e32 v[50:51], 0
	v_mov_b64_e32 v[52:53], 0
	v_mov_b64_e32 v[54:55], 0
	v_mov_b64_e32 v[56:57], 0
	v_mov_b64_e32 v[58:59], 0
	v_mov_b64_e32 v[60:61], 0
	v_mov_b64_e32 v[62:63], 0
	v_mov_b64_e32 v[64:65], 0
	v_mov_b64_e32 v[66:67], 0
	v_mov_b64_e32 v[68:69], 0
	v_mov_b64_e32 v[70:71], 0
	v_mov_b64_e32 v[72:73], 0
	v_mov_b64_e32 v[74:75], 0
	v_mov_b64_e32 v[76:77], 0
	v_mov_b64_e32 v[78:79], 0
	v_mov_b64_e32 v[80:81], 0
	v_mov_b64_e32 v[82:83], 0
	v_mov_b64_e32 v[150:151], 0
	v_mov_b32_e32 v186, 0
	s_waitcnt vmcnt(6) lgkmcnt(0)
	s_barrier
; __device__ __forceinline__ void attn_unit(LAS unsigned char* lds, const bf16_t* Z, bf16_t* A2, const float* tabg, int seq_base, int S, int h, int qb, float lam) {
;     ...
;         bool near = true; float cc = 0.f;
;         if (kv0 - (qlo + 31) >= 128) { near = false; cc = tabR; } else if (qlo - (kv0 + 63) >= 128) { near = false; cc = tabL; }
;         { const float coff = cc - mu;
;           if (__any(!(coff == coff_cur))) { coff_cur = coff;
; #pragma unroll
;               for (int r = 0; r < 16; ++r) cblk[r] = coff;
;               asm volatile("" : "+v"(cblk)); } }
;         f32x16 p0, p1;
;         {
;             bf16x8 kf[8];
; #pragma unroll
;             for (int ds = 0; ds < 4; ++ds) { kf[2 * ds] = *(const LAS bf16x8*)(Kt + (kfo ^ (unsigned)(ds << 5))); kf[2 * ds + 1] = *(const LAS bf16x8*)(Kt + 32 * 256 + (kfo ^ (unsigned)(ds << 5))); }
;             __builtin_amdgcn_sched_barrier(0);
;             p0 = __builtin_amdgcn_mfma_f32_32x32x16_bf16(kf[0], qf[0], cblk, 0, 0, 0);
;             p1 = __builtin_amdgcn_mfma_f32_32x32x16_bf16(kf[1], qf[0], cblk, 0, 0, 0);
; #pragma unroll
;             for (int ds = 1; ds < 4; ++ds) {
;                 p0 = __builtin_amdgcn_mfma_f32_32x32x16_bf16(kf[2 * ds], qf[ds], p0, 0, 0, 0);
;                 p1 = __builtin_amdgcn_mfma_f32_32x32x16_bf16(kf[2 * ds + 1], qf[ds], p1, 0, 0, 0);
;             }
;         }
;     ...
;         const unsigned vbase = (unsigned)(size_t)Vt + vfo;
;         s16x4 va[8], vb[8];
;         VREADS1(va, 0);
;         if (near) {
;             const LAS float* tp = tab + (kv0 + 4 * hi - (qlo + r32) + 224);
; #pragma unroll
;             for (int r = 0; r < 16; ++r) { p0[r] += tp[(r & 3) + 8 * (r >> 2)]; p1[r] += tp[32 + (r & 3) + 8 * (r >> 2)]; }
;         }
;         float mx = max2f(max16f(p0), max16f(p1));
;         const bool first = (t == 0);
;         if (first || __any(mx > THR)) {
;             { auto rr = __builtin_amdgcn_permlane32_swap(__float_as_uint(mx), __float_as_uint(mx), false, false); mx = max2f(__uint_as_float(rr[0]), __uint_as_float(rr[1])); }
;             const float delta = first ? mx : fmaxf(mx, 0.f);
;             const float alpha = first ? 1.0f : __builtin_amdgcn_exp2f(-delta);
;             mu += delta; ls2 *= alpha;
;             if (!first) {
;                 asm volatile("" ::: "memory");
;                 scr[r32] = alpha;
	v_mov_b32_e32 v187, 0x18800
	ds_read_b32 v177, v187
	ds_read_b32 v178, v187 offset:1792
	ds_read_b128 v[132:135], v19
	ds_read_b128 v[136:139], v19 offset:8192
	ds_read_b128 v[140:143], v180
	ds_read_b128 v[144:147], v180 offset:8192
	ds_read_b128 v[220:223], v181
	ds_read_b128 v[224:227], v181 offset:8192
	ds_read_b128 v[232:235], v182
	ds_read_b128 v[236:239], v182 offset:8192
	s_waitcnt lgkmcnt(8)
	s_cmp_eq_u32 s11, 0
	s_cselect_b32 s37, 0, 1
	s_mov_b32 s35, s37
	v_mov_b32_e32 v251, 0
	s_cmp_eq_u32 s37, 1
	s_cselect_b64 vcc, -1, 0
	v_cndmask_b32_e32 v251, v251, v177, vcc
	s_cmp_eq_u32 s37, 2
	s_cselect_b64 vcc, -1, 0
	v_cndmask_b32_e32 v251, v251, v178, vcc
	v_sub_f32_e32 v2, v251, v186
	v_mov_b32_e32 v3, v2
	v_mov_b64_e32 v[4:5], v[2:3]
	v_mov_b64_e32 v[6:7], v[2:3]
	v_mov_b64_e32 v[8:9], v[2:3]
	v_mov_b64_e32 v[10:11], v[2:3]
	v_mov_b64_e32 v[12:13], v[2:3]
	v_mov_b64_e32 v[14:15], v[2:3]
	v_mov_b64_e32 v[16:17], v[2:3]
	s_nop 1
	s_waitcnt lgkmcnt(7)
	v_mfma_f32_32x32x16_bf16 v[84:99], v[132:135], v[116:119], v[2:17]
	s_waitcnt lgkmcnt(6)
	v_mfma_f32_32x32x16_bf16 v[100:115], v[136:139], v[116:119], v[2:17]
	s_waitcnt lgkmcnt(5)
	v_mfma_f32_32x32x16_bf16 v[84:99], v[140:143], v[120:123], v[84:99]
	s_waitcnt lgkmcnt(4)
	v_mfma_f32_32x32x16_bf16 v[100:115], v[144:147], v[120:123], v[100:115]
	s_waitcnt lgkmcnt(3)
	v_mfma_f32_32x32x16_bf16 v[84:99], v[220:223], v[124:127], v[84:99]
	s_waitcnt lgkmcnt(2)
	v_mfma_f32_32x32x16_bf16 v[100:115], v[224:227], v[124:127], v[100:115]
	s_waitcnt lgkmcnt(1)
	v_mfma_f32_32x32x16_bf16 v[84:99], v[232:235], v[128:131], v[84:99]
	s_waitcnt lgkmcnt(0)
	v_mfma_f32_32x32x16_bf16 v[100:115], v[236:239], v[128:131], v[100:115]
	s_nop 15
	s_nop 15
	s_mov_b32 s5, 0
	s_cmp_lg_u32 s11, 0
	s_cbranch_scc1 .LatA_p0_nonear
	s_lshl_b32 s38, s5, 2
	s_add_i32 s38, s38, 0x18b80
	v_add_u32_e32 v187, s38, v162
	ds_read2_b32 v[196:197], v187 offset0:0 offset1:1
	ds_read2_b32 v[198:199], v187 offset0:2 offset1:3
	ds_read2_b32 v[200:201], v187 offset0:8 offset1:9
	ds_read2_b32 v[202:203], v187 offset0:10 offset1:11
	ds_read2_b32 v[212:213], v187 offset0:16 offset1:17
	ds_read2_b32 v[214:215], v187 offset0:18 offset1:19
	ds_read2_b32 v[216:217], v187 offset0:24 offset1:25
	ds_read2_b32 v[218:219], v187 offset0:26 offset1:27
	s_waitcnt lgkmcnt(0)
	v_pk_add_f32 v[84:85], v[84:85], v[196:197]
	v_pk_add_f32 v[86:87], v[86:87], v[198:199]
	v_pk_add_f32 v[88:89], v[88:89], v[200:201]
	v_pk_add_f32 v[90:91], v[90:91], v[202:203]
	v_pk_add_f32 v[92:93], v[92:93], v[212:213]
	v_pk_add_f32 v[94:95], v[94:95], v[214:215]
	v_pk_add_f32 v[96:97], v[96:97], v[216:217]
	v_pk_add_f32 v[98:99], v[98:99], v[218:219]
	ds_read2_b32 v[196:197], v187 offset0:32 offset1:33
	ds_read2_b32 v[198:199], v187 offset0:34 offset1:35
	ds_read2_b32 v[200:201], v187 offset0:40 offset1:41
	ds_read2_b32 v[202:203], v187 offset0:42 offset1:43
	ds_read2_b32 v[212:213], v187 offset0:48 offset1:49
	ds_read2_b32 v[214:215], v187 offset0:50 offset1:51
	ds_read2_b32 v[216:217], v187 offset0:56 offset1:57
	ds_read2_b32 v[218:219], v187 offset0:58 offset1:59
	s_waitcnt lgkmcnt(0)
	v_pk_add_f32 v[100:101], v[100:101], v[196:197]
	v_pk_add_f32 v[102:103], v[102:103], v[198:199]
	v_pk_add_f32 v[104:105], v[104:105], v[200:201]
	v_pk_add_f32 v[106:107], v[106:107], v[202:203]
	v_pk_add_f32 v[108:109], v[108:109], v[212:213]
	v_pk_add_f32 v[110:111], v[110:111], v[214:215]
	v_pk_add_f32 v[112:113], v[112:113], v[216:217]
	v_pk_add_f32 v[114:115], v[114:115], v[218:219]
.LatA_p0_nonear:
	v_max3_f32 v251, v84, v85, v86
	v_max3_f32 v252, v87, v88, v89
	v_max3_f32 v251, v251, v90, v91
	v_max3_f32 v252, v252, v92, v93
	v_max3_f32 v251, v251, v94, v95
	v_max3_f32 v252, v252, v96, v97
	v_max3_f32 v251, v251, v98, v99
	v_max3_f32 v252, v252, v100, v101
	v_max3_f32 v251, v251, v102, v103
	v_max3_f32 v252, v252, v104, v105
	v_max3_f32 v251, v251, v106, v107
	v_max3_f32 v252, v252, v108, v109
	v_max3_f32 v251, v251, v110, v111
	v_max3_f32 v252, v252, v112, v113
	v_max3_f32 v251, v251, v114, v115
	v_max_f32_e32 v251, v251, v252
	v_mov_b32_e32 v252, v251
	s_nop 1
	v_permlane32_swap_b32_e32 v251, v252
	v_max_f32_e32 v186, v251, v252
	v_sub_f32_e32 v84, v84, v186
	v_sub_f32_e32 v85, v85, v186
	v_sub_f32_e32 v86, v86, v186
	v_sub_f32_e32 v87, v87, v186
	v_sub_f32_e32 v88, v88, v186
	v_sub_f32_e32 v89, v89, v186
	v_sub_f32_e32 v90, v90, v186
	v_sub_f32_e32 v91, v91, v186
	v_sub_f32_e32 v92, v92, v186
	v_sub_f32_e32 v93, v93, v186
	v_sub_f32_e32 v94, v94, v186
	v_sub_f32_e32 v95, v95, v186
	v_sub_f32_e32 v96, v96, v186
	v_sub_f32_e32 v97, v97, v186
	v_sub_f32_e32 v98, v98, v186
	v_sub_f32_e32 v99, v99, v186
	v_sub_f32_e32 v100, v100, v186
	v_sub_f32_e32 v101, v101, v186
	v_sub_f32_e32 v102, v102, v186
	v_sub_f32_e32 v103, v103, v186
	v_sub_f32_e32 v104, v104, v186
	v_sub_f32_e32 v105, v105, v186
	v_sub_f32_e32 v106, v106, v186
	v_sub_f32_e32 v107, v107, v186
	v_sub_f32_e32 v108, v108, v186
	v_sub_f32_e32 v109, v109, v186
	v_sub_f32_e32 v110, v110, v186
	v_sub_f32_e32 v111, v111, v186
	v_sub_f32_e32 v112, v112, v186
	v_sub_f32_e32 v113, v113, v186
	v_sub_f32_e32 v114, v114, v186
	v_sub_f32_e32 v115, v115, v186
	s_add_u32 s38, s5, 64
	s_cmp_lt_u32 s38, s11
	s_cselect_b32 s37, 1, 0
	s_cmp_gt_u32 s38, s31
	s_cselect_b32 s40, 2, 0
	s_or_b32 s37, s37, s40
	s_mov_b32 s35, s37
	v_mov_b32_e32 v251, 0
	s_cmp_eq_u32 s37, 1
	s_cselect_b64 vcc, -1, 0
	v_cndmask_b32_e32 v251, v251, v177, vcc
	s_cmp_eq_u32 s37, 2
	s_cselect_b64 vcc, -1, 0
	v_cndmask_b32_e32 v251, v251, v178, vcc
	v_sub_f32_e32 v2, v251, v186
	v_mov_b32_e32 v3, v2
	v_mov_b64_e32 v[4:5], v[2:3]
	v_mov_b64_e32 v[6:7], v[2:3]
	v_mov_b64_e32 v[8:9], v[2:3]
	v_mov_b64_e32 v[10:11], v[2:3]
	v_mov_b64_e32 v[12:13], v[2:3]
	v_mov_b64_e32 v[14:15], v[2:3]
	v_mov_b64_e32 v[16:17], v[2:3]
	s_waitcnt vmcnt(0)
	s_barrier
; #define LAS __attribute__((address_space(3)))
; __device__ __forceinline__ float max2f(float a, float b) { float r; asm("v_max_f32_e32 %0, %1, %2" : "=v"(r) : "v"(a), "v"(b)); return r; }
; #define LGKM0() do { __builtin_amdgcn_sched_barrier(0); asm volatile("s_waitcnt lgkmcnt(0)" ::: "memory"); __builtin_amdgcn_sched_barrier(0); } while (0)
; __device__ __forceinline__ void attn_unit(LAS unsigned char* lds, const bf16_t* Z, bf16_t* A2, const float* tabg, int seq_base, int S, int h, int qb, float lam) {
;     ...
;         if (first || __any(mx > THR)) {
;             { auto rr = __builtin_amdgcn_permlane32_swap(__float_as_uint(mx), __float_as_uint(mx), false, false); mx = max2f(__uint_as_float(rr[0]), __uint_as_float(rr[1])); }
;             const float delta = first ? mx : fmaxf(mx, 0.f);
;             const float alpha = first ? 1.0f : __builtin_amdgcn_exp2f(-delta);
;             mu += delta; ls2 *= alpha;
;             if (!first) {
;                 asm volatile("" ::: "memory");
;                 scr[r32] = alpha;
;                 asm volatile("s_waitcnt lgkmcnt(0)" ::: "memory");
; #pragma unroll
;                 for (int g = 0; g < 4; ++g) { const f32x4 a4 = *(const LAS f32x4*)(scr + 8 * g + 4 * hi);
; #pragma unroll
;                     for (int d = 0; d < 4; ++d) { O[d][4 * g + 0] *= a4[0]; O[d][4 * g + 1] *= a4[1]; O[d][4 * g + 2] *= a4[2]; O[d][4 * g + 3] *= a4[3]; } }
;                 asm volatile("s_waitcnt lgkmcnt(0)" ::: "memory");
;             }
; #pragma unroll
;             for (int r = 0; r < 16; ++r) { p0[r] -= delta; p1[r] -= delta; }
;             asm volatile("" : "+v"(p0), "+v"(p1));
;         }
; #pragma unroll
;         for (int r = 0; r < 16; ++r) { p0[r] = __builtin_amdgcn_exp2f(p0[r]); p1[r] = __builtin_amdgcn_exp2f(p1[r]); }
; #pragma unroll
;         for (int r = 0; r < 16; r += 2) { ls2 += (f32x2){p0[r], p0[r + 1]}; ls2 += (f32x2){p1[r], p1[r + 1]}; }
;         bf16x8 pa[4]; pa[0] = pack8(p0, 0); pa[1] = pack8(p0, 8); pa[2] = pack8(p1, 0); pa[3] = pack8(p1, 8);
;         LGKM0(); VREADS1(vb, 1); PV1(va, 0); LGKM0(); VREADS1(va, 2); PV1(vb, 1); LGKM0(); VREADS1(vb, 3); PV1(va, 2); LGKM0(); PV1(vb, 3);
;     ...
;         if (t + 2 < NT) asm volatile("s_waitcnt vmcnt(4) lgkmcnt(0)" ::: "memory"); else asm volatile("s_waitcnt vmcnt(0) lgkmcnt(0)" ::: "memory");
;         __builtin_amdgcn_s_barrier(); asm volatile("" ::: "memory");
	ds_read_b128 v[132:135], v19 offset:16384
	ds_read_b128 v[136:139], v19 offset:24576
	ds_read_b128 v[140:143], v180 offset:16384
	ds_read_b128 v[144:147], v180 offset:24576
	ds_read_b128 v[220:223], v181 offset:16384
	ds_read_b128 v[224:227], v181 offset:24576
	ds_read_b128 v[232:235], v182 offset:16384
	s_waitcnt lgkmcnt(6)
	s_add_u32 m0, s28, 0x1d000
	v_mfma_f32_32x32x16_bf16 v[188:203], v[132:135], v[116:119], v[2:17]
	global_load_lds_dwordx4 v172, s[8:9]
	ds_read_b128 v[236:239], v182 offset:24576
	v_exp_f32_e32 v84, v84
	v_exp_f32_e32 v85, v85
	v_exp_f32_e32 v86, v86
	v_exp_f32_e32 v87, v87
	v_exp_f32_e32 v88, v88
	v_pk_add_f32 v[252:253], v[84:85], v[86:87]
	v_exp_f32_e32 v89, v89
	s_waitcnt lgkmcnt(6)
	s_add_u32 m0, s29, 0x8000
	v_mfma_f32_32x32x16_bf16 v[204:219], v[136:139], v[116:119], v[2:17]
	global_load_lds_dwordx4 v174, s[8:9]
	ds_read_b64_tr_b16 v[132:133], v228 offset:0
	ds_read_b64_tr_b16 v[134:135], v228 offset:2048
	v_cvt_pk_bf16_f32 v84, v84, v85
	v_cvt_pk_bf16_f32 v85, v86, v87
	v_exp_f32_e32 v90, v90
	v_exp_f32_e32 v91, v91
	v_pk_add_f32 v[252:253], v[252:253], v[88:89]
	v_pk_add_f32 v[252:253], v[252:253], v[90:91]
	v_cvt_pk_bf16_f32 v86, v88, v89
	v_cvt_pk_bf16_f32 v87, v90, v91
	v_exp_f32_e32 v92, v92
	s_waitcnt lgkmcnt(7)
	s_add_u32 m0, s28, 0x1f000
	v_mfma_f32_32x32x16_bf16 v[188:203], v[140:143], v[120:123], v[188:203]
	global_load_lds_dwordx4 v173, s[8:9]
	ds_read_b64_tr_b16 v[136:137], v229 offset:0
	ds_read_b64_tr_b16 v[138:139], v229 offset:2048
	v_exp_f32_e32 v93, v93
	v_exp_f32_e32 v94, v94
	v_exp_f32_e32 v95, v95
	v_pk_add_f32 v[252:253], v[252:253], v[92:93]
	v_pk_add_f32 v[252:253], v[252:253], v[94:95]
	v_exp_f32_e32 v96, v96
	s_waitcnt lgkmcnt(8)
	s_add_u32 m0, s29, 0xa000
	v_mfma_f32_32x32x16_bf16 v[204:219], v[144:147], v[120:123], v[204:219]
	global_load_lds_dwordx4 v175, s[8:9]
	ds_read_b64_tr_b16 v[140:141], v230 offset:0
	ds_read_b64_tr_b16 v[142:143], v230 offset:2048
	v_exp_f32_e32 v97, v97
	v_cvt_pk_bf16_f32 v88, v92, v93
	v_cvt_pk_bf16_f32 v89, v94, v95
	v_exp_f32_e32 v98, v98
	v_exp_f32_e32 v99, v99
	v_pk_add_f32 v[252:253], v[252:253], v[96:97]
	v_pk_add_f32 v[252:253], v[252:253], v[98:99]
	v_cvt_pk_bf16_f32 v90, v96, v97
	v_cvt_pk_bf16_f32 v91, v98, v99
	s_waitcnt lgkmcnt(9)
	v_mfma_f32_32x32x16_bf16 v[188:203], v[220:223], v[124:127], v[188:203]
	ds_read_b64_tr_b16 v[144:145], v231 offset:0
	ds_read_b64_tr_b16 v[146:147], v231 offset:2048
	v_exp_f32_e32 v100, v100
	v_exp_f32_e32 v101, v101
	v_exp_f32_e32 v102, v102
	v_exp_f32_e32 v103, v103
	v_pk_add_f32 v[252:253], v[252:253], v[100:101]
	v_pk_add_f32 v[252:253], v[252:253], v[102:103]
	v_exp_f32_e32 v104, v104
	s_waitcnt lgkmcnt(10)
	v_mfma_f32_32x32x16_bf16 v[204:219], v[224:227], v[124:127], v[204:219]
	ds_read_b64_tr_b16 v[220:221], v228 offset:4096
	ds_read_b64_tr_b16 v[222:223], v228 offset:6144
	v_exp_f32_e32 v105, v105
	v_cvt_pk_bf16_f32 v100, v100, v101
	v_cvt_pk_bf16_f32 v101, v102, v103
	v_exp_f32_e32 v106, v106
	v_exp_f32_e32 v107, v107
	v_pk_add_f32 v[252:253], v[252:253], v[104:105]
	v_pk_add_f32 v[252:253], v[252:253], v[106:107]
	v_cvt_pk_bf16_f32 v102, v104, v105
	v_cvt_pk_bf16_f32 v103, v106, v107
	s_waitcnt lgkmcnt(11)
	v_mfma_f32_32x32x16_bf16 v[188:203], v[232:235], v[128:131], v[188:203]
	ds_read_b64_tr_b16 v[224:225], v229 offset:4096
	ds_read_b64_tr_b16 v[226:227], v229 offset:6144
	v_exp_f32_e32 v108, v108
	v_exp_f32_e32 v109, v109
	v_exp_f32_e32 v110, v110
	v_exp_f32_e32 v111, v111
	v_pk_add_f32 v[252:253], v[252:253], v[108:109]
	v_pk_add_f32 v[252:253], v[252:253], v[110:111]
	v_exp_f32_e32 v112, v112
	s_waitcnt lgkmcnt(12)
	v_mfma_f32_32x32x16_bf16 v[204:219], v[236:239], v[128:131], v[204:219]
	ds_read_b64_tr_b16 v[232:233], v230 offset:4096
	ds_read_b64_tr_b16 v[234:235], v230 offset:6144
	v_exp_f32_e32 v113, v113
	v_cvt_pk_bf16_f32 v104, v108, v109
	v_cvt_pk_bf16_f32 v105, v110, v111
	v_exp_f32_e32 v114, v114
	v_exp_f32_e32 v115, v115
	v_pk_add_f32 v[252:253], v[252:253], v[112:113]
	v_pk_add_f32 v[252:253], v[252:253], v[114:115]
	v_cvt_pk_bf16_f32 v106, v112, v113
	v_cvt_pk_bf16_f32 v107, v114, v115
	v_max_f32_e32 v251, v252, v253
	v_cmp_nge_f32_e32 vcc, 0x45800000, v251
	s_cbranch_vccnz .LatA_recs_h0
.LatA_recret_h0:
	v_pk_add_f32 v[150:151], v[150:151], v[252:253]
	s_add_u32 s8, s8, 0x40000
	s_addc_u32 s9, s9, 0
	s_waitcnt vmcnt(4)
	s_barrier
	s_sub_u32 s10, s10, 1
	s_cbranch_scc1 .LatA_evs_h1
; #define LAS __attribute__((address_space(3)))
; __device__ __forceinline__ float max2f(float a, float b) { float r; asm("v_max_f32_e32 %0, %1, %2" : "=v"(r) : "v"(a), "v"(b)); return r; }
; #define LGKM0() do { __builtin_amdgcn_sched_barrier(0); asm volatile("s_waitcnt lgkmcnt(0)" ::: "memory"); __builtin_amdgcn_sched_barrier(0); } while (0)
; __device__ __forceinline__ void attn_unit(LAS unsigned char* lds, const bf16_t* Z, bf16_t* A2, const float* tabg, int seq_base, int S, int h, int qb, float lam) {
;     ...
;         float mx = max2f(max16f(p0), max16f(p1));
;         const bool first = (t == 0);
;         if (first || __any(mx > THR)) {
;             { auto rr = __builtin_amdgcn_permlane32_swap(__float_as_uint(mx), __float_as_uint(mx), false, false); mx = max2f(__uint_as_float(rr[0]), __uint_as_float(rr[1])); }
;             const float delta = first ? mx : fmaxf(mx, 0.f);
;             const float alpha = first ? 1.0f : __builtin_amdgcn_exp2f(-delta);
;             mu += delta; ls2 *= alpha;
;             if (!first) {
;                 asm volatile("" ::: "memory");
;                 scr[r32] = alpha;
;                 asm volatile("s_waitcnt lgkmcnt(0)" ::: "memory");
; #pragma unroll
;                 for (int g = 0; g < 4; ++g) { const f32x4 a4 = *(const LAS f32x4*)(scr + 8 * g + 4 * hi);
; #pragma unroll
;                     for (int d = 0; d < 4; ++d) { O[d][4 * g + 0] *= a4[0]; O[d][4 * g + 1] *= a4[1]; O[d][4 * g + 2] *= a4[2]; O[d][4 * g + 3] *= a4[3]; } }
;                 asm volatile("s_waitcnt lgkmcnt(0)" ::: "memory");
;             }
; #pragma unroll
;             for (int r = 0; r < 16; ++r) { p0[r] -= delta; p1[r] -= delta; }
;             asm volatile("" : "+v"(p0), "+v"(p1));
;         }
; #pragma unroll
;         for (int r = 0; r < 16; ++r) { p0[r] = __builtin_amdgcn_exp2f(p0[r]); p1[r] = __builtin_amdgcn_exp2f(p1[r]); }
; #pragma unroll
;         for (int r = 0; r < 16; r += 2) { ls2 += (f32x2){p0[r], p0[r + 1]}; ls2 += (f32x2){p1[r], p1[r + 1]}; }
;         bf16x8 pa[4]; pa[0] = pack8(p0, 0); pa[1] = pack8(p0, 8); pa[2] = pack8(p1, 0); pa[3] = pack8(p1, 8);
;         LGKM0(); VREADS1(vb, 1); PV1(va, 0); LGKM0(); VREADS1(va, 2); PV1(vb, 1); LGKM0(); VREADS1(vb, 3); PV1(va, 2); LGKM0(); PV1(vb, 3);
.LatA_evret_h1:
	s_waitcnt lgkmcnt(12)
	v_mfma_f32_32x32x16_bf16 v[20:35], v[84:87], v[132:135], v[20:35]
	ds_read_b64_tr_b16 v[236:237], v231 offset:4096
	ds_read_b64_tr_b16 v[238:239], v231 offset:6144
	v_exp_f32_e32 v188, v188
	v_exp_f32_e32 v189, v189
	s_waitcnt lgkmcnt(12)
	v_mfma_f32_32x32x16_bf16 v[36:51], v[84:87], v[136:139], v[36:51]
	ds_read_b64_tr_b16 v[132:133], v228 offset:8192
	ds_read_b64_tr_b16 v[134:135], v228 offset:10240
	v_exp_f32_e32 v190, v190
	v_exp_f32_e32 v191, v191
	s_waitcnt lgkmcnt(12)
	v_mfma_f32_32x32x16_bf16 v[52:67], v[84:87], v[140:143], v[52:67]
	ds_read_b64_tr_b16 v[136:137], v229 offset:8192
	ds_read_b64_tr_b16 v[138:139], v229 offset:10240
	v_exp_f32_e32 v192, v192
	v_pk_add_f32 v[252:253], v[188:189], v[190:191]
	v_exp_f32_e32 v193, v193
	s_waitcnt lgkmcnt(12)
	s_mov_b32 m0, s28
	v_mfma_f32_32x32x16_bf16 v[68:83], v[84:87], v[144:147], v[68:83]
	global_load_lds_dwordx4 v172, s[8:9]
	ds_read_b64_tr_b16 v[140:141], v230 offset:8192
	ds_read_b64_tr_b16 v[142:143], v230 offset:10240
	v_cvt_pk_bf16_f32 v188, v188, v189
	v_cvt_pk_bf16_f32 v189, v190, v191
	v_exp_f32_e32 v194, v194
	s_waitcnt lgkmcnt(12)
	v_mfma_f32_32x32x16_bf16 v[20:35], v[88:91], v[220:223], v[20:35]
	ds_read_b64_tr_b16 v[144:145], v231 offset:8192
	ds_read_b64_tr_b16 v[146:147], v231 offset:10240
	v_exp_f32_e32 v195, v195
	v_pk_add_f32 v[252:253], v[252:253], v[192:193]
	s_waitcnt lgkmcnt(12)
	v_mfma_f32_32x32x16_bf16 v[36:51], v[88:91], v[224:227], v[36:51]
	ds_read_b64_tr_b16 v[220:221], v228 offset:12288
	ds_read_b64_tr_b16 v[222:223], v228 offset:14336
	v_pk_add_f32 v[252:253], v[252:253], v[194:195]
	v_cvt_pk_bf16_f32 v190, v192, v193
	v_cvt_pk_bf16_f32 v191, v194, v195
	v_exp_f32_e32 v196, v196
	s_waitcnt lgkmcnt(12)
	v_mfma_f32_32x32x16_bf16 v[52:67], v[88:91], v[232:235], v[52:67]
	ds_read_b64_tr_b16 v[224:225], v229 offset:12288
	ds_read_b64_tr_b16 v[226:227], v229 offset:14336
	v_exp_f32_e32 v197, v197
	v_exp_f32_e32 v198, v198
	s_waitcnt lgkmcnt(12)
	s_add_u32 m0, s29, 0xd000
	v_mfma_f32_32x32x16_bf16 v[68:83], v[88:91], v[236:239], v[68:83]
	global_load_lds_dwordx4 v174, s[8:9]
	ds_read_b64_tr_b16 v[232:233], v230 offset:12288
	ds_read_b64_tr_b16 v[234:235], v230 offset:14336
	v_exp_f32_e32 v199, v199
	v_pk_add_f32 v[252:253], v[252:253], v[196:197]
	s_waitcnt lgkmcnt(12)
	v_mfma_f32_32x32x16_bf16 v[20:35], v[100:103], v[132:135], v[20:35]
	ds_read_b64_tr_b16 v[236:237], v231 offset:12288
	ds_read_b64_tr_b16 v[238:239], v231 offset:14336
	v_pk_add_f32 v[252:253], v[252:253], v[198:199]
	v_exp_f32_e32 v200, v200
	s_waitcnt lgkmcnt(12)
	v_mfma_f32_32x32x16_bf16 v[36:51], v[100:103], v[136:139], v[36:51]
	ds_read_b128 v[132:135], v19 offset:32768
	v_exp_f32_e32 v201, v201
	v_cvt_pk_bf16_f32 v192, v196, v197
	v_cvt_pk_bf16_f32 v193, v198, v199
	v_exp_f32_e32 v202, v202
	s_waitcnt lgkmcnt(11)
	v_mfma_f32_32x32x16_bf16 v[52:67], v[100:103], v[140:143], v[52:67]
	ds_read_b128 v[136:139], v19 offset:40960
	v_exp_f32_e32 v203, v203
	v_pk_add_f32 v[252:253], v[252:253], v[200:201]
	s_waitcnt lgkmcnt(10)
	s_add_u32 m0, s28, 0x2000
	v_mfma_f32_32x32x16_bf16 v[68:83], v[100:103], v[144:147], v[68:83]
	global_load_lds_dwordx4 v173, s[8:9]
	ds_read_b128 v[140:143], v180 offset:32768
	v_pk_add_f32 v[252:253], v[252:253], v[202:203]
	v_cvt_pk_bf16_f32 v194, v200, v201
	v_cvt_pk_bf16_f32 v195, v202, v203
	s_waitcnt lgkmcnt(9)
	v_mfma_f32_32x32x16_bf16 v[20:35], v[104:107], v[220:223], v[20:35]
	ds_read_b128 v[144:147], v180 offset:40960
	v_exp_f32_e32 v204, v204
	v_exp_f32_e32 v205, v205
	v_exp_f32_e32 v206, v206
	s_waitcnt lgkmcnt(8)
	v_mfma_f32_32x32x16_bf16 v[36:51], v[104:107], v[224:227], v[36:51]
	ds_read_b128 v[220:223], v181 offset:32768
	v_exp_f32_e32 v207, v207
	v_pk_add_f32 v[252:253], v[252:253], v[204:205]
	s_waitcnt lgkmcnt(7)
	v_mfma_f32_32x32x16_bf16 v[52:67], v[104:107], v[232:235], v[52:67]
	ds_read_b128 v[224:227], v181 offset:40960
	v_pk_add_f32 v[252:253], v[252:253], v[206:207]
	v_exp_f32_e32 v208, v208
	s_waitcnt lgkmcnt(6)
	s_add_u32 m0, s29, 0xf000
	v_mfma_f32_32x32x16_bf16 v[68:83], v[104:107], v[236:239], v[68:83]
	global_load_lds_dwordx4 v175, s[8:9]
	ds_read_b128 v[232:235], v182 offset:32768
	v_exp_f32_e32 v209, v209
	v_cvt_pk_bf16_f32 v204, v204, v205
	v_cvt_pk_bf16_f32 v205, v206, v207
	s_waitcnt lgkmcnt(6)
	v_mfma_f32_32x32x16_bf16 v[84:99], v[132:135], v[116:119], v[2:17]
	ds_read_b128 v[236:239], v182 offset:40960
	v_exp_f32_e32 v210, v210
	v_exp_f32_e32 v211, v211
	v_pk_add_f32 v[252:253], v[252:253], v[208:209]
	s_waitcnt lgkmcnt(6)
	v_mfma_f32_32x32x16_bf16 v[100:115], v[136:139], v[116:119], v[2:17]
	ds_read_b64_tr_b16 v[132:133], v228 offset:16384
	ds_read_b64_tr_b16 v[134:135], v228 offset:18432
	v_pk_add_f32 v[252:253], v[252:253], v[210:211]
	v_cvt_pk_bf16_f32 v206, v208, v209
	v_cvt_pk_bf16_f32 v207, v210, v211
	s_waitcnt lgkmcnt(7)
	v_mfma_f32_32x32x16_bf16 v[84:99], v[140:143], v[120:123], v[84:99]
	ds_read_b64_tr_b16 v[136:137], v229 offset:16384
	ds_read_b64_tr_b16 v[138:139], v229 offset:18432
	v_exp_f32_e32 v212, v212
	v_exp_f32_e32 v213, v213
	s_waitcnt lgkmcnt(8)
	v_mfma_f32_32x32x16_bf16 v[100:115], v[144:147], v[120:123], v[100:115]
	ds_read_b64_tr_b16 v[140:141], v230 offset:16384
	ds_read_b64_tr_b16 v[142:143], v230 offset:18432
	v_exp_f32_e32 v214, v214
	v_exp_f32_e32 v215, v215
	v_pk_add_f32 v[252:253], v[252:253], v[212:213]
	s_waitcnt lgkmcnt(9)
	v_mfma_f32_32x32x16_bf16 v[84:99], v[220:223], v[124:127], v[84:99]
	ds_read_b64_tr_b16 v[144:145], v231 offset:16384
	ds_read_b64_tr_b16 v[146:147], v231 offset:18432
	v_pk_add_f32 v[252:253], v[252:253], v[214:215]
	v_exp_f32_e32 v216, v216
	s_waitcnt lgkmcnt(10)
	v_mfma_f32_32x32x16_bf16 v[100:115], v[224:227], v[124:127], v[100:115]
	ds_read_b64_tr_b16 v[220:221], v228 offset:20480
	ds_read_b64_tr_b16 v[222:223], v228 offset:22528
	v_exp_f32_e32 v217, v217
	v_cvt_pk_bf16_f32 v208, v212, v213
	v_cvt_pk_bf16_f32 v209, v214, v215
	s_waitcnt lgkmcnt(11)
	v_mfma_f32_32x32x16_bf16 v[84:99], v[232:235], v[128:131], v[84:99]
	ds_read_b64_tr_b16 v[224:225], v229 offset:20480
	ds_read_b64_tr_b16 v[226:227], v229 offset:22528
	v_exp_f32_e32 v218, v218
	v_exp_f32_e32 v219, v219
	s_waitcnt lgkmcnt(12)
	v_mfma_f32_32x32x16_bf16 v[100:115], v[236:239], v[128:131], v[100:115]
	ds_read_b64_tr_b16 v[232:233], v230 offset:20480
	ds_read_b64_tr_b16 v[234:235], v230 offset:22528
	v_pk_add_f32 v[252:253], v[252:253], v[216:217]
	v_pk_add_f32 v[252:253], v[252:253], v[218:219]
	v_cvt_pk_bf16_f32 v210, v216, v217
	v_cvt_pk_bf16_f32 v211, v218, v219
	v_max_f32_e32 v251, v252, v253
	v_cmp_nge_f32_e32 vcc, 0x45800000, v251
	s_cbranch_vccnz .LatA_recs_h1

; #define LAS __attribute__((address_space(3)))
; __device__ __forceinline__ float max2f(float a, float b) { float r; asm("v_max_f32_e32 %0, %1, %2" : "=v"(r) : "v"(a), "v"(b)); return r; }
; #define LGKM0() do { __builtin_amdgcn_sched_barrier(0); asm volatile("s_waitcnt lgkmcnt(0)" ::: "memory"); __builtin_amdgcn_sched_barrier(0); } while (0)
; __device__ __forceinline__ void attn_unit(LAS unsigned char* lds, const bf16_t* Z, bf16_t* A2, const float* tabg, int seq_base, int S, int h, int qb, float lam) {
;     ...
;         float mx = max2f(max16f(p0), max16f(p1));
;         const bool first = (t == 0);
;         if (first || __any(mx > THR)) {
;             { auto rr = __builtin_amdgcn_permlane32_swap(__float_as_uint(mx), __float_as_uint(mx), false, false); mx = max2f(__uint_as_float(rr[0]), __uint_as_float(rr[1])); }
;             const float delta = first ? mx : fmaxf(mx, 0.f);
;             const float alpha = first ? 1.0f : __builtin_amdgcn_exp2f(-delta);
;             mu += delta; ls2 *= alpha;
;             if (!first) {
;                 asm volatile("" ::: "memory");
;                 scr[r32] = alpha;
;                 asm volatile("s_waitcnt lgkmcnt(0)" ::: "memory");
; #pragma unroll
;                 for (int g = 0; g < 4; ++g) { const f32x4 a4 = *(const LAS f32x4*)(scr + 8 * g + 4 * hi);
; #pragma unroll
;                     for (int d = 0; d < 4; ++d) { O[d][4 * g + 0] *= a4[0]; O[d][4 * g + 1] *= a4[1]; O[d][4 * g + 2] *= a4[2]; O[d][4 * g + 3] *= a4[3]; } }
;                 asm volatile("s_waitcnt lgkmcnt(0)" ::: "memory");
;             }
; #pragma unroll
;             for (int r = 0; r < 16; ++r) { p0[r] -= delta; p1[r] -= delta; }
;             asm volatile("" : "+v"(p0), "+v"(p1));
;         }
; #pragma unroll
;         for (int r = 0; r < 16; ++r) { p0[r] = __builtin_amdgcn_exp2f(p0[r]); p1[r] = __builtin_amdgcn_exp2f(p1[r]); }
; #pragma unroll
;         for (int r = 0; r < 16; r += 2) { ls2 += (f32x2){p0[r], p0[r + 1]}; ls2 += (f32x2){p1[r], p1[r + 1]}; }
;         bf16x8 pa[4]; pa[0] = pack8(p0, 0); pa[1] = pack8(p0, 8); pa[2] = pack8(p1, 0); pa[3] = pack8(p1, 8);
;         LGKM0(); VREADS1(vb, 1); PV1(va, 0); LGKM0(); VREADS1(va, 2); PV1(vb, 1); LGKM0(); VREADS1(vb, 3); PV1(va, 2); LGKM0(); PV1(vb, 3);
.LatA_evret_h2:
	s_waitcnt lgkmcnt(12)
	v_mfma_f32_32x32x16_bf16 v[20:35], v[188:191], v[132:135], v[20:35]
	ds_read_b64_tr_b16 v[236:237], v231 offset:20480
	ds_read_b64_tr_b16 v[238:239], v231 offset:22528
	v_exp_f32_e32 v84, v84
	v_exp_f32_e32 v85, v85
	s_waitcnt lgkmcnt(12)
	v_mfma_f32_32x32x16_bf16 v[36:51], v[188:191], v[136:139], v[36:51]
	ds_read_b64_tr_b16 v[132:133], v228 offset:24576
	ds_read_b64_tr_b16 v[134:135], v228 offset:26624
	v_exp_f32_e32 v86, v86
	v_exp_f32_e32 v87, v87
	s_waitcnt lgkmcnt(12)
	v_mfma_f32_32x32x16_bf16 v[52:67], v[188:191], v[140:143], v[52:67]
	ds_read_b64_tr_b16 v[136:137], v229 offset:24576
	ds_read_b64_tr_b16 v[138:139], v229 offset:26624
	v_exp_f32_e32 v88, v88
	v_pk_add_f32 v[252:253], v[84:85], v[86:87]
	v_exp_f32_e32 v89, v89
	s_waitcnt lgkmcnt(12)
	s_add_u32 m0, s28, 0x4000
	v_mfma_f32_32x32x16_bf16 v[68:83], v[188:191], v[144:147], v[68:83]
	global_load_lds_dwordx4 v172, s[8:9]
	ds_read_b64_tr_b16 v[140:141], v230 offset:24576
	ds_read_b64_tr_b16 v[142:143], v230 offset:26624
	v_cvt_pk_bf16_f32 v84, v84, v85
	v_cvt_pk_bf16_f32 v85, v86, v87
	v_exp_f32_e32 v90, v90
	s_waitcnt lgkmcnt(12)
	v_mfma_f32_32x32x16_bf16 v[20:35], v[192:195], v[220:223], v[20:35]
	ds_read_b64_tr_b16 v[144:145], v231 offset:24576
	ds_read_b64_tr_b16 v[146:147], v231 offset:26624
	v_exp_f32_e32 v91, v91
	v_pk_add_f32 v[252:253], v[252:253], v[88:89]
	s_waitcnt lgkmcnt(12)
	v_mfma_f32_32x32x16_bf16 v[36:51], v[192:195], v[224:227], v[36:51]
	ds_read_b64_tr_b16 v[220:221], v228 offset:28672
	ds_read_b64_tr_b16 v[222:223], v228 offset:30720
	v_pk_add_f32 v[252:253], v[252:253], v[90:91]
	v_cvt_pk_bf16_f32 v86, v88, v89
	v_cvt_pk_bf16_f32 v87, v90, v91
	v_exp_f32_e32 v92, v92
	s_waitcnt lgkmcnt(12)
	v_mfma_f32_32x32x16_bf16 v[52:67], v[192:195], v[232:235], v[52:67]
	ds_read_b64_tr_b16 v[224:225], v229 offset:28672
	ds_read_b64_tr_b16 v[226:227], v229 offset:30720
	v_exp_f32_e32 v93, v93
	v_exp_f32_e32 v94, v94
	s_waitcnt lgkmcnt(12)
	s_mov_b32 m0, s29
	v_mfma_f32_32x32x16_bf16 v[68:83], v[192:195], v[236:239], v[68:83]
	global_load_lds_dwordx4 v174, s[8:9]
	ds_read_b64_tr_b16 v[232:233], v230 offset:28672
	ds_read_b64_tr_b16 v[234:235], v230 offset:30720
	v_exp_f32_e32 v95, v95
	v_pk_add_f32 v[252:253], v[252:253], v[92:93]
	s_waitcnt lgkmcnt(12)
	v_mfma_f32_32x32x16_bf16 v[20:35], v[204:207], v[132:135], v[20:35]
	ds_read_b64_tr_b16 v[236:237], v231 offset:28672
	ds_read_b64_tr_b16 v[238:239], v231 offset:30720
	v_pk_add_f32 v[252:253], v[252:253], v[94:95]
	v_exp_f32_e32 v96, v96
	s_waitcnt lgkmcnt(12)
	v_mfma_f32_32x32x16_bf16 v[36:51], v[204:207], v[136:139], v[36:51]
	ds_read_b128 v[132:135], v164
	v_exp_f32_e32 v97, v97
	v_cvt_pk_bf16_f32 v88, v92, v93
	v_cvt_pk_bf16_f32 v89, v94, v95
	v_exp_f32_e32 v98, v98
	s_waitcnt lgkmcnt(11)
	v_mfma_f32_32x32x16_bf16 v[52:67], v[204:207], v[140:143], v[52:67]
	ds_read_b128 v[136:139], v164 offset:8192
	v_exp_f32_e32 v99, v99
	v_pk_add_f32 v[252:253], v[252:253], v[96:97]
	s_waitcnt lgkmcnt(10)
	s_add_u32 m0, s28, 0x6000
	v_mfma_f32_32x32x16_bf16 v[68:83], v[204:207], v[144:147], v[68:83]
	global_load_lds_dwordx4 v173, s[8:9]
	ds_read_b128 v[140:143], v165
	v_pk_add_f32 v[252:253], v[252:253], v[98:99]
	v_cvt_pk_bf16_f32 v90, v96, v97
	v_cvt_pk_bf16_f32 v91, v98, v99
	s_waitcnt lgkmcnt(9)
	v_mfma_f32_32x32x16_bf16 v[20:35], v[208:211], v[220:223], v[20:35]
	ds_read_b128 v[144:147], v165 offset:8192
	v_exp_f32_e32 v100, v100
	v_exp_f32_e32 v101, v101
	v_exp_f32_e32 v102, v102
	s_waitcnt lgkmcnt(8)
	v_mfma_f32_32x32x16_bf16 v[36:51], v[208:211], v[224:227], v[36:51]
	ds_read_b128 v[220:223], v166
	v_exp_f32_e32 v103, v103
	v_pk_add_f32 v[252:253], v[252:253], v[100:101]
	s_waitcnt lgkmcnt(7)
	v_mfma_f32_32x32x16_bf16 v[52:67], v[208:211], v[232:235], v[52:67]
	ds_read_b128 v[224:227], v166 offset:8192
	v_pk_add_f32 v[252:253], v[252:253], v[102:103]
	v_exp_f32_e32 v104, v104
	s_waitcnt lgkmcnt(6)
	s_add_u32 m0, s29, 0x2000
	v_mfma_f32_32x32x16_bf16 v[68:83], v[208:211], v[236:239], v[68:83]
	global_load_lds_dwordx4 v175, s[8:9]
	ds_read_b128 v[232:235], v167
	v_exp_f32_e32 v105, v105
	v_cvt_pk_bf16_f32 v100, v100, v101
	v_cvt_pk_bf16_f32 v101, v102, v103
	s_waitcnt lgkmcnt(6)
	v_mfma_f32_32x32x16_bf16 v[188:203], v[132:135], v[116:119], v[2:17]
	ds_read_b128 v[236:239], v167 offset:8192
	v_exp_f32_e32 v106, v106
	v_exp_f32_e32 v107, v107
	v_pk_add_f32 v[252:253], v[252:253], v[104:105]
	s_waitcnt lgkmcnt(6)
	v_mfma_f32_32x32x16_bf16 v[204:219], v[136:139], v[116:119], v[2:17]
	ds_read_b64_tr_b16 v[132:133], v228 offset:32768
	ds_read_b64_tr_b16 v[134:135], v228 offset:34816
	v_pk_add_f32 v[252:253], v[252:253], v[106:107]
	v_cvt_pk_bf16_f32 v102, v104, v105
	v_cvt_pk_bf16_f32 v103, v106, v107
	s_waitcnt lgkmcnt(7)
	v_mfma_f32_32x32x16_bf16 v[188:203], v[140:143], v[120:123], v[188:203]
	ds_read_b64_tr_b16 v[136:137], v229 offset:32768
	ds_read_b64_tr_b16 v[138:139], v229 offset:34816
	v_exp_f32_e32 v108, v108
	v_exp_f32_e32 v109, v109
	s_waitcnt lgkmcnt(8)
	v_mfma_f32_32x32x16_bf16 v[204:219], v[144:147], v[120:123], v[204:219]
	ds_read_b64_tr_b16 v[140:141], v230 offset:32768
	ds_read_b64_tr_b16 v[142:143], v230 offset:34816
	v_exp_f32_e32 v110, v110
	v_exp_f32_e32 v111, v111
	v_pk_add_f32 v[252:253], v[252:253], v[108:109]
	s_waitcnt lgkmcnt(9)
	v_mfma_f32_32x32x16_bf16 v[188:203], v[220:223], v[124:127], v[188:203]
	ds_read_b64_tr_b16 v[144:145], v231 offset:32768
	ds_read_b64_tr_b16 v[146:147], v231 offset:34816
	v_pk_add_f32 v[252:253], v[252:253], v[110:111]
	v_exp_f32_e32 v112, v112
	s_waitcnt lgkmcnt(10)
	v_mfma_f32_32x32x16_bf16 v[204:219], v[224:227], v[124:127], v[204:219]
	ds_read_b64_tr_b16 v[220:221], v228 offset:36864
	ds_read_b64_tr_b16 v[222:223], v228 offset:38912
	v_exp_f32_e32 v113, v113
	v_cvt_pk_bf16_f32 v104, v108, v109
	v_cvt_pk_bf16_f32 v105, v110, v111
	s_waitcnt lgkmcnt(11)
	v_mfma_f32_32x32x16_bf16 v[188:203], v[232:235], v[128:131], v[188:203]
	ds_read_b64_tr_b16 v[224:225], v229 offset:36864
	ds_read_b64_tr_b16 v[226:227], v229 offset:38912
	v_exp_f32_e32 v114, v114
	v_exp_f32_e32 v115, v115
	s_waitcnt lgkmcnt(12)
	v_mfma_f32_32x32x16_bf16 v[204:219], v[236:239], v[128:131], v[204:219]
	ds_read_b64_tr_b16 v[232:233], v230 offset:36864
	ds_read_b64_tr_b16 v[234:235], v230 offset:38912
	v_pk_add_f32 v[252:253], v[252:253], v[112:113]
	v_pk_add_f32 v[252:253], v[252:253], v[114:115]
	v_cvt_pk_bf16_f32 v106, v112, v113
	v_cvt_pk_bf16_f32 v107, v114, v115
	v_max_f32_e32 v251, v252, v253
	v_cmp_nge_f32_e32 vcc, 0x45800000, v251
	s_cbranch_vccnz .LatA_recs_h2

; #define LAS __attribute__((address_space(3)))
; __device__ __forceinline__ void attn_unit(LAS unsigned char* lds, const bf16_t* Z, bf16_t* A2, const float* tabg, int seq_base, int S, int h, int qb, float lam) {
;     ...
;         float mx = max2f(max16f(p0), max16f(p1));
;         const bool first = (t == 0);
;         if (first || __any(mx > THR)) {
;             { auto rr = __builtin_amdgcn_permlane32_swap(__float_as_uint(mx), __float_as_uint(mx), false, false); mx = max2f(__uint_as_float(rr[0]), __uint_as_float(rr[1])); }
;             const float delta = first ? mx : fmaxf(mx, 0.f);
;             const float alpha = first ? 1.0f : __builtin_amdgcn_exp2f(-delta);
;             mu += delta; ls2 *= alpha;
;             if (!first) {
;                 asm volatile("" ::: "memory");
;                 scr[r32] = alpha;
;                 asm volatile("s_waitcnt lgkmcnt(0)" ::: "memory");
; #pragma unroll
;                 for (int g = 0; g < 4; ++g) { const f32x4 a4 = *(const LAS f32x4*)(scr + 8 * g + 4 * hi);
; #pragma unroll
;                     for (int d = 0; d < 4; ++d) { O[d][4 * g + 0] *= a4[0]; O[d][4 * g + 1] *= a4[1]; O[d][4 * g + 2] *= a4[2]; O[d][4 * g + 3] *= a4[3]; } }
;                 asm volatile("s_waitcnt lgkmcnt(0)" ::: "memory");
;             }
; #pragma unroll
;             for (int r = 0; r < 16; ++r) { p0[r] -= delta; p1[r] -= delta; }
;             asm volatile("" : "+v"(p0), "+v"(p1));
;         }
; #pragma unroll
;         for (int r = 0; r < 16; ++r) { p0[r] = __builtin_amdgcn_exp2f(p0[r]); p1[r] = __builtin_amdgcn_exp2f(p1[r]); }
; #pragma unroll
;         for (int r = 0; r < 16; r += 2) { ls2 += (f32x2){p0[r], p0[r + 1]}; ls2 += (f32x2){p1[r], p1[r + 1]}; }
;         bf16x8 pa[4]; pa[0] = pack8(p0, 0); pa[1] = pack8(p0, 8); pa[2] = pack8(p1, 0); pa[3] = pack8(p1, 8);
;         LGKM0(); VREADS1(vb, 1); PV1(va, 0); LGKM0(); VREADS1(va, 2); PV1(vb, 1); LGKM0(); VREADS1(vb, 3); PV1(va, 2); LGKM0(); PV1(vb, 3);
;     ...
;         if (t + 2 < NT) asm volatile("s_waitcnt vmcnt(4) lgkmcnt(0)" ::: "memory"); else asm volatile("s_waitcnt vmcnt(0) lgkmcnt(0)" ::: "memory");
;         __builtin_amdgcn_s_barrier(); asm volatile("" ::: "memory");
;         bc = (bc == NST - 1) ? 0 : bc + 1; bn = (bn == NST - 1) ? 0 : bn + 1;
.LatA_evret_h3:
	s_waitcnt lgkmcnt(12)
	v_mfma_f32_32x32x16_bf16 v[20:35], v[84:87], v[132:135], v[20:35]
	ds_read_b64_tr_b16 v[236:237], v231 offset:36864
	ds_read_b64_tr_b16 v[238:239], v231 offset:38912
	v_exp_f32_e32 v188, v188
	v_exp_f32_e32 v189, v189
	s_waitcnt lgkmcnt(12)
	v_mfma_f32_32x32x16_bf16 v[36:51], v[84:87], v[136:139], v[36:51]
	ds_read_b64_tr_b16 v[132:133], v228 offset:40960
	ds_read_b64_tr_b16 v[134:135], v228 offset:43008
	v_exp_f32_e32 v190, v190
	v_exp_f32_e32 v191, v191
	s_waitcnt lgkmcnt(12)
	v_mfma_f32_32x32x16_bf16 v[52:67], v[84:87], v[140:143], v[52:67]
	ds_read_b64_tr_b16 v[136:137], v229 offset:40960
	ds_read_b64_tr_b16 v[138:139], v229 offset:43008
	v_exp_f32_e32 v192, v192
	v_pk_add_f32 v[252:253], v[188:189], v[190:191]
	v_exp_f32_e32 v193, v193
	s_waitcnt lgkmcnt(12)
	s_add_u32 m0, s28, 0x8000
	v_mfma_f32_32x32x16_bf16 v[68:83], v[84:87], v[144:147], v[68:83]
	global_load_lds_dwordx4 v172, s[8:9]
	ds_read_b64_tr_b16 v[140:141], v230 offset:40960
	ds_read_b64_tr_b16 v[142:143], v230 offset:43008
	v_cvt_pk_bf16_f32 v188, v188, v189
	v_cvt_pk_bf16_f32 v189, v190, v191
	v_exp_f32_e32 v194, v194
	s_waitcnt lgkmcnt(12)
	v_mfma_f32_32x32x16_bf16 v[20:35], v[88:91], v[220:223], v[20:35]
	ds_read_b64_tr_b16 v[144:145], v231 offset:40960
	ds_read_b64_tr_b16 v[146:147], v231 offset:43008
	v_exp_f32_e32 v195, v195
	v_pk_add_f32 v[252:253], v[252:253], v[192:193]
	s_waitcnt lgkmcnt(12)
	v_mfma_f32_32x32x16_bf16 v[36:51], v[88:91], v[224:227], v[36:51]
	ds_read_b64_tr_b16 v[220:221], v228 offset:45056
	ds_read_b64_tr_b16 v[222:223], v228 offset:47104
	v_pk_add_f32 v[252:253], v[252:253], v[194:195]
	v_cvt_pk_bf16_f32 v190, v192, v193
	v_cvt_pk_bf16_f32 v191, v194, v195
	v_exp_f32_e32 v196, v196
	s_waitcnt lgkmcnt(12)
	v_mfma_f32_32x32x16_bf16 v[52:67], v[88:91], v[232:235], v[52:67]
	ds_read_b64_tr_b16 v[224:225], v229 offset:45056
	ds_read_b64_tr_b16 v[226:227], v229 offset:47104
	v_exp_f32_e32 v197, v197
	v_exp_f32_e32 v198, v198
	s_waitcnt lgkmcnt(12)
	s_add_u32 m0, s29, 0x4000
	v_mfma_f32_32x32x16_bf16 v[68:83], v[88:91], v[236:239], v[68:83]
	global_load_lds_dwordx4 v174, s[8:9]
	ds_read_b64_tr_b16 v[232:233], v230 offset:45056
	ds_read_b64_tr_b16 v[234:235], v230 offset:47104
	v_exp_f32_e32 v199, v199
	v_pk_add_f32 v[252:253], v[252:253], v[196:197]
	s_waitcnt lgkmcnt(12)
	v_mfma_f32_32x32x16_bf16 v[20:35], v[100:103], v[132:135], v[20:35]
	ds_read_b64_tr_b16 v[236:237], v231 offset:45056
	ds_read_b64_tr_b16 v[238:239], v231 offset:47104
	v_pk_add_f32 v[252:253], v[252:253], v[198:199]
	v_exp_f32_e32 v200, v200
	s_waitcnt lgkmcnt(12)
	v_mfma_f32_32x32x16_bf16 v[36:51], v[100:103], v[136:139], v[36:51]
	ds_read_b128 v[132:135], v19
	v_exp_f32_e32 v201, v201
	v_cvt_pk_bf16_f32 v192, v196, v197
	v_cvt_pk_bf16_f32 v193, v198, v199
	v_exp_f32_e32 v202, v202
	s_waitcnt lgkmcnt(11)
	v_mfma_f32_32x32x16_bf16 v[52:67], v[100:103], v[140:143], v[52:67]
	ds_read_b128 v[136:139], v19 offset:8192
	v_exp_f32_e32 v203, v203
	v_pk_add_f32 v[252:253], v[252:253], v[200:201]
	s_waitcnt lgkmcnt(10)
	s_add_u32 m0, s28, 0xa000
	v_mfma_f32_32x32x16_bf16 v[68:83], v[100:103], v[144:147], v[68:83]
	global_load_lds_dwordx4 v173, s[8:9]
	ds_read_b128 v[140:143], v180
	v_pk_add_f32 v[252:253], v[252:253], v[202:203]
	v_cvt_pk_bf16_f32 v194, v200, v201
	v_cvt_pk_bf16_f32 v195, v202, v203
	s_waitcnt lgkmcnt(9)
	v_mfma_f32_32x32x16_bf16 v[20:35], v[104:107], v[220:223], v[20:35]
	ds_read_b128 v[144:147], v180 offset:8192
	v_exp_f32_e32 v204, v204
	v_exp_f32_e32 v205, v205
	v_exp_f32_e32 v206, v206
	s_waitcnt lgkmcnt(8)
	v_mfma_f32_32x32x16_bf16 v[36:51], v[104:107], v[224:227], v[36:51]
	ds_read_b128 v[220:223], v181
	v_exp_f32_e32 v207, v207
	v_pk_add_f32 v[252:253], v[252:253], v[204:205]
	s_waitcnt lgkmcnt(7)
	v_mfma_f32_32x32x16_bf16 v[52:67], v[104:107], v[232:235], v[52:67]
	ds_read_b128 v[224:227], v181 offset:8192
	v_pk_add_f32 v[252:253], v[252:253], v[206:207]
	v_exp_f32_e32 v208, v208
	s_waitcnt lgkmcnt(6)
	s_add_u32 m0, s29, 0x6000
	v_mfma_f32_32x32x16_bf16 v[68:83], v[104:107], v[236:239], v[68:83]
	global_load_lds_dwordx4 v175, s[8:9]
	ds_read_b128 v[232:235], v182
	v_exp_f32_e32 v209, v209
	v_cvt_pk_bf16_f32 v204, v204, v205
	v_cvt_pk_bf16_f32 v205, v206, v207
	s_waitcnt lgkmcnt(6)
	v_mfma_f32_32x32x16_bf16 v[84:99], v[132:135], v[116:119], v[2:17]
	ds_read_b128 v[236:239], v182 offset:8192
	v_exp_f32_e32 v210, v210
	v_exp_f32_e32 v211, v211
	v_pk_add_f32 v[252:253], v[252:253], v[208:209]
	s_waitcnt lgkmcnt(6)
	v_mfma_f32_32x32x16_bf16 v[100:115], v[136:139], v[116:119], v[2:17]
	ds_read_b64_tr_b16 v[132:133], v168 offset:0
	ds_read_b64_tr_b16 v[134:135], v168 offset:2048
	v_pk_add_f32 v[252:253], v[252:253], v[210:211]
	v_cvt_pk_bf16_f32 v206, v208, v209
	v_cvt_pk_bf16_f32 v207, v210, v211
	s_waitcnt lgkmcnt(7)
	v_mfma_f32_32x32x16_bf16 v[84:99], v[140:143], v[120:123], v[84:99]
	ds_read_b64_tr_b16 v[136:137], v169 offset:0
	ds_read_b64_tr_b16 v[138:139], v169 offset:2048
	v_exp_f32_e32 v212, v212
	v_exp_f32_e32 v213, v213
	s_waitcnt lgkmcnt(8)
	v_mfma_f32_32x32x16_bf16 v[100:115], v[144:147], v[120:123], v[100:115]
	ds_read_b64_tr_b16 v[140:141], v170 offset:0
	ds_read_b64_tr_b16 v[142:143], v170 offset:2048
	v_exp_f32_e32 v214, v214
	v_exp_f32_e32 v215, v215
	v_pk_add_f32 v[252:253], v[252:253], v[212:213]
	s_waitcnt lgkmcnt(9)
	v_mfma_f32_32x32x16_bf16 v[84:99], v[220:223], v[124:127], v[84:99]
	ds_read_b64_tr_b16 v[144:145], v171 offset:0
	ds_read_b64_tr_b16 v[146:147], v171 offset:2048
	v_pk_add_f32 v[252:253], v[252:253], v[214:215]
	v_exp_f32_e32 v216, v216
	s_waitcnt lgkmcnt(10)
	v_mfma_f32_32x32x16_bf16 v[100:115], v[224:227], v[124:127], v[100:115]
	ds_read_b64_tr_b16 v[220:221], v168 offset:4096
	ds_read_b64_tr_b16 v[222:223], v168 offset:6144
	v_exp_f32_e32 v217, v217
	v_cvt_pk_bf16_f32 v208, v212, v213
	v_cvt_pk_bf16_f32 v209, v214, v215
	s_waitcnt lgkmcnt(11)
	v_mfma_f32_32x32x16_bf16 v[84:99], v[232:235], v[128:131], v[84:99]
	ds_read_b64_tr_b16 v[224:225], v169 offset:4096
	ds_read_b64_tr_b16 v[226:227], v169 offset:6144
	v_exp_f32_e32 v218, v218
	v_exp_f32_e32 v219, v219
	s_waitcnt lgkmcnt(12)
	v_mfma_f32_32x32x16_bf16 v[100:115], v[236:239], v[128:131], v[100:115]
	ds_read_b64_tr_b16 v[232:233], v170 offset:4096
	ds_read_b64_tr_b16 v[234:235], v170 offset:6144
	v_pk_add_f32 v[252:253], v[252:253], v[216:217]
	v_pk_add_f32 v[252:253], v[252:253], v[218:219]
	v_cvt_pk_bf16_f32 v210, v216, v217
	v_cvt_pk_bf16_f32 v211, v218, v219
	v_max_f32_e32 v251, v252, v253
	v_cmp_nge_f32_e32 vcc, 0x45800000, v251
	s_cbranch_vccnz .LatA_recs_h3
.LatA_recret_h3:
	v_pk_add_f32 v[150:151], v[150:151], v[252:253]
	s_add_u32 s8, s8, 0x40000
	s_addc_u32 s9, s9, 0
	s_waitcnt vmcnt(4)
	s_barrier
	s_movk_i32 s36, 30

; #define LAS __attribute__((address_space(3)))
; __device__ __forceinline__ float max2f(float a, float b) { float r; asm("v_max_f32_e32 %0, %1, %2" : "=v"(r) : "v"(a), "v"(b)); return r; }
; #define LGKM0() do { __builtin_amdgcn_sched_barrier(0); asm volatile("s_waitcnt lgkmcnt(0)" ::: "memory"); __builtin_amdgcn_sched_barrier(0); } while (0)
; __device__ __forceinline__ void attn_unit(LAS unsigned char* lds, const bf16_t* Z, bf16_t* A2, const float* tabg, int seq_base, int S, int h, int qb, float lam) {
;     ...
;         float mx = max2f(max16f(p0), max16f(p1));
;         const bool first = (t == 0);
;         if (first || __any(mx > THR)) {
;             { auto rr = __builtin_amdgcn_permlane32_swap(__float_as_uint(mx), __float_as_uint(mx), false, false); mx = max2f(__uint_as_float(rr[0]), __uint_as_float(rr[1])); }
;             const float delta = first ? mx : fmaxf(mx, 0.f);
;             const float alpha = first ? 1.0f : __builtin_amdgcn_exp2f(-delta);
;             mu += delta; ls2 *= alpha;
;             if (!first) {
;                 asm volatile("" ::: "memory");
;                 scr[r32] = alpha;
;                 asm volatile("s_waitcnt lgkmcnt(0)" ::: "memory");
; #pragma unroll
;                 for (int g = 0; g < 4; ++g) { const f32x4 a4 = *(const LAS f32x4*)(scr + 8 * g + 4 * hi);
; #pragma unroll
;                     for (int d = 0; d < 4; ++d) { O[d][4 * g + 0] *= a4[0]; O[d][4 * g + 1] *= a4[1]; O[d][4 * g + 2] *= a4[2]; O[d][4 * g + 3] *= a4[3]; } }
;                 asm volatile("s_waitcnt lgkmcnt(0)" ::: "memory");
;             }
; #pragma unroll
;             for (int r = 0; r < 16; ++r) { p0[r] -= delta; p1[r] -= delta; }
;             asm volatile("" : "+v"(p0), "+v"(p1));
;         }
; #pragma unroll
;         for (int r = 0; r < 16; ++r) { p0[r] = __builtin_amdgcn_exp2f(p0[r]); p1[r] = __builtin_amdgcn_exp2f(p1[r]); }
; #pragma unroll
;         for (int r = 0; r < 16; r += 2) { ls2 += (f32x2){p0[r], p0[r + 1]}; ls2 += (f32x2){p1[r], p1[r + 1]}; }
;         bf16x8 pa[4]; pa[0] = pack8(p0, 0); pa[1] = pack8(p0, 8); pa[2] = pack8(p1, 0); pa[3] = pack8(p1, 8);
;         LGKM0(); VREADS1(vb, 1); PV1(va, 0); LGKM0(); VREADS1(va, 2); PV1(vb, 1); LGKM0(); VREADS1(vb, 3); PV1(va, 2); LGKM0(); PV1(vb, 3);
.LatA_evret_m0:
	s_waitcnt lgkmcnt(12)
	v_mfma_f32_32x32x16_bf16 v[20:35], v[188:191], v[132:135], v[20:35]
	ds_read_b64_tr_b16 v[236:237], v171 offset:4096
	ds_read_b64_tr_b16 v[238:239], v171 offset:6144
	v_exp_f32_e32 v84, v84
	v_exp_f32_e32 v85, v85
	s_waitcnt lgkmcnt(12)
	v_mfma_f32_32x32x16_bf16 v[36:51], v[188:191], v[136:139], v[36:51]
	ds_read_b64_tr_b16 v[132:133], v168 offset:8192
	ds_read_b64_tr_b16 v[134:135], v168 offset:10240
	v_exp_f32_e32 v86, v86
	v_exp_f32_e32 v87, v87
	s_waitcnt lgkmcnt(12)
	v_mfma_f32_32x32x16_bf16 v[52:67], v[188:191], v[140:143], v[52:67]
	ds_read_b64_tr_b16 v[136:137], v169 offset:8192
	ds_read_b64_tr_b16 v[138:139], v169 offset:10240
	v_exp_f32_e32 v88, v88
	v_pk_add_f32 v[252:253], v[84:85], v[86:87]
	v_exp_f32_e32 v89, v89
	s_waitcnt lgkmcnt(12)
	s_add_u32 m0, s28, 0x1d000
	v_mfma_f32_32x32x16_bf16 v[68:83], v[188:191], v[144:147], v[68:83]
	global_load_lds_dwordx4 v172, s[8:9]
	ds_read_b64_tr_b16 v[140:141], v170 offset:8192
	ds_read_b64_tr_b16 v[142:143], v170 offset:10240
	v_cvt_pk_bf16_f32 v84, v84, v85
	v_cvt_pk_bf16_f32 v85, v86, v87
	v_exp_f32_e32 v90, v90
	s_waitcnt lgkmcnt(12)
	v_mfma_f32_32x32x16_bf16 v[20:35], v[192:195], v[220:223], v[20:35]
	ds_read_b64_tr_b16 v[144:145], v171 offset:8192
	ds_read_b64_tr_b16 v[146:147], v171 offset:10240
	v_exp_f32_e32 v91, v91
	v_pk_add_f32 v[252:253], v[252:253], v[88:89]
	s_waitcnt lgkmcnt(12)
	v_mfma_f32_32x32x16_bf16 v[36:51], v[192:195], v[224:227], v[36:51]
	ds_read_b64_tr_b16 v[220:221], v168 offset:12288
	ds_read_b64_tr_b16 v[222:223], v168 offset:14336
	v_pk_add_f32 v[252:253], v[252:253], v[90:91]
	v_cvt_pk_bf16_f32 v86, v88, v89
	v_cvt_pk_bf16_f32 v87, v90, v91
	v_exp_f32_e32 v92, v92
	s_waitcnt lgkmcnt(12)
	v_mfma_f32_32x32x16_bf16 v[52:67], v[192:195], v[232:235], v[52:67]
	ds_read_b64_tr_b16 v[224:225], v169 offset:12288
	ds_read_b64_tr_b16 v[226:227], v169 offset:14336
	v_exp_f32_e32 v93, v93
	v_exp_f32_e32 v94, v94
	s_waitcnt lgkmcnt(12)
	s_add_u32 m0, s29, 0x8000
	v_mfma_f32_32x32x16_bf16 v[68:83], v[192:195], v[236:239], v[68:83]
	global_load_lds_dwordx4 v174, s[8:9]
	ds_read_b64_tr_b16 v[232:233], v170 offset:12288
	ds_read_b64_tr_b16 v[234:235], v170 offset:14336
	v_exp_f32_e32 v95, v95
	v_pk_add_f32 v[252:253], v[252:253], v[92:93]
	s_waitcnt lgkmcnt(12)
	v_mfma_f32_32x32x16_bf16 v[20:35], v[204:207], v[132:135], v[20:35]
	ds_read_b64_tr_b16 v[236:237], v171 offset:12288
	ds_read_b64_tr_b16 v[238:239], v171 offset:14336
	v_pk_add_f32 v[252:253], v[252:253], v[94:95]
	v_exp_f32_e32 v96, v96
	s_waitcnt lgkmcnt(12)
	v_mfma_f32_32x32x16_bf16 v[36:51], v[204:207], v[136:139], v[36:51]
	ds_read_b128 v[132:135], v19 offset:16384
	v_exp_f32_e32 v97, v97
	v_cvt_pk_bf16_f32 v88, v92, v93
	v_cvt_pk_bf16_f32 v89, v94, v95
	v_exp_f32_e32 v98, v98
	s_waitcnt lgkmcnt(11)
	v_mfma_f32_32x32x16_bf16 v[52:67], v[204:207], v[140:143], v[52:67]
	ds_read_b128 v[136:139], v19 offset:24576
	v_exp_f32_e32 v99, v99
	v_pk_add_f32 v[252:253], v[252:253], v[96:97]
	s_waitcnt lgkmcnt(10)
	s_add_u32 m0, s28, 0x1f000
	v_mfma_f32_32x32x16_bf16 v[68:83], v[204:207], v[144:147], v[68:83]
	global_load_lds_dwordx4 v173, s[8:9]
	ds_read_b128 v[140:143], v180 offset:16384
	v_pk_add_f32 v[252:253], v[252:253], v[98:99]
	v_cvt_pk_bf16_f32 v90, v96, v97
	v_cvt_pk_bf16_f32 v91, v98, v99
	s_waitcnt lgkmcnt(9)
	v_mfma_f32_32x32x16_bf16 v[20:35], v[208:211], v[220:223], v[20:35]
	ds_read_b128 v[144:147], v180 offset:24576
	v_exp_f32_e32 v100, v100
	v_exp_f32_e32 v101, v101
	v_exp_f32_e32 v102, v102
	s_waitcnt lgkmcnt(8)
	v_mfma_f32_32x32x16_bf16 v[36:51], v[208:211], v[224:227], v[36:51]
	ds_read_b128 v[220:223], v181 offset:16384
	v_exp_f32_e32 v103, v103
	v_pk_add_f32 v[252:253], v[252:253], v[100:101]
	s_waitcnt lgkmcnt(7)
	v_mfma_f32_32x32x16_bf16 v[52:67], v[208:211], v[232:235], v[52:67]
	ds_read_b128 v[224:227], v181 offset:24576
	v_pk_add_f32 v[252:253], v[252:253], v[102:103]
	v_exp_f32_e32 v104, v104
	s_waitcnt lgkmcnt(6)
	s_add_u32 m0, s29, 0xa000
	v_mfma_f32_32x32x16_bf16 v[68:83], v[208:211], v[236:239], v[68:83]
	global_load_lds_dwordx4 v175, s[8:9]
	ds_read_b128 v[232:235], v182 offset:16384
	v_exp_f32_e32 v105, v105
	v_cvt_pk_bf16_f32 v100, v100, v101
	v_cvt_pk_bf16_f32 v101, v102, v103
	s_waitcnt lgkmcnt(6)
	v_mfma_f32_32x32x16_bf16 v[188:203], v[132:135], v[116:119], v[2:17]
	ds_read_b128 v[236:239], v182 offset:24576
	v_exp_f32_e32 v106, v106
	v_exp_f32_e32 v107, v107
	v_pk_add_f32 v[252:253], v[252:253], v[104:105]
	s_waitcnt lgkmcnt(6)
	v_mfma_f32_32x32x16_bf16 v[204:219], v[136:139], v[116:119], v[2:17]
	ds_read_b64_tr_b16 v[132:133], v228 offset:0
	ds_read_b64_tr_b16 v[134:135], v228 offset:2048
	v_pk_add_f32 v[252:253], v[252:253], v[106:107]
	v_cvt_pk_bf16_f32 v102, v104, v105
	v_cvt_pk_bf16_f32 v103, v106, v107
	s_waitcnt lgkmcnt(7)
	v_mfma_f32_32x32x16_bf16 v[188:203], v[140:143], v[120:123], v[188:203]
	ds_read_b64_tr_b16 v[136:137], v229 offset:0
	ds_read_b64_tr_b16 v[138:139], v229 offset:2048
	v_exp_f32_e32 v108, v108
	v_exp_f32_e32 v109, v109
	s_waitcnt lgkmcnt(8)
	v_mfma_f32_32x32x16_bf16 v[204:219], v[144:147], v[120:123], v[204:219]
	ds_read_b64_tr_b16 v[140:141], v230 offset:0
	ds_read_b64_tr_b16 v[142:143], v230 offset:2048
	v_exp_f32_e32 v110, v110
	v_exp_f32_e32 v111, v111
	v_pk_add_f32 v[252:253], v[252:253], v[108:109]
	s_waitcnt lgkmcnt(9)
	v_mfma_f32_32x32x16_bf16 v[188:203], v[220:223], v[124:127], v[188:203]
	ds_read_b64_tr_b16 v[144:145], v231 offset:0
	ds_read_b64_tr_b16 v[146:147], v231 offset:2048
	v_pk_add_f32 v[252:253], v[252:253], v[110:111]
	v_exp_f32_e32 v112, v112
	s_waitcnt lgkmcnt(10)
	v_mfma_f32_32x32x16_bf16 v[204:219], v[224:227], v[124:127], v[204:219]
	ds_read_b64_tr_b16 v[220:221], v228 offset:4096
	ds_read_b64_tr_b16 v[222:223], v228 offset:6144
	v_exp_f32_e32 v113, v113
	v_cvt_pk_bf16_f32 v104, v108, v109
	v_cvt_pk_bf16_f32 v105, v110, v111
	s_waitcnt lgkmcnt(11)
	v_mfma_f32_32x32x16_bf16 v[188:203], v[232:235], v[128:131], v[188:203]
	ds_read_b64_tr_b16 v[224:225], v229 offset:4096
	ds_read_b64_tr_b16 v[226:227], v229 offset:6144
	v_exp_f32_e32 v114, v114
	v_exp_f32_e32 v115, v115
	s_waitcnt lgkmcnt(12)
	v_mfma_f32_32x32x16_bf16 v[204:219], v[236:239], v[128:131], v[204:219]
	ds_read_b64_tr_b16 v[232:233], v230 offset:4096
	ds_read_b64_tr_b16 v[234:235], v230 offset:6144
	v_pk_add_f32 v[252:253], v[252:253], v[112:113]
	v_pk_add_f32 v[252:253], v[252:253], v[114:115]
	v_cvt_pk_bf16_f32 v106, v112, v113
	v_cvt_pk_bf16_f32 v107, v114, v115
	v_max_f32_e32 v251, v252, v253
	v_cmp_nge_f32_e32 vcc, 0x45800000, v251
	s_cbranch_vccnz .LatA_recs_m0

; __device__ __forceinline__ void attn_unit(LAS unsigned char* lds, const bf16_t* Z, bf16_t* A2, const float* tabg, int seq_base, int S, int h, int qb, float lam) {
;     ...
;     for (int t = 0; t < NT; ++t) {
;     ...
;         if (t + 2 < NT) asm volatile("s_waitcnt vmcnt(4) lgkmcnt(0)" ::: "memory"); else asm volatile("s_waitcnt vmcnt(0) lgkmcnt(0)" ::: "memory");
;         __builtin_amdgcn_s_barrier(); asm volatile("" ::: "memory");
;         bc = (bc == NST - 1) ? 0 : bc + 1; bn = (bn == NST - 1) ? 0 : bn + 1;
.LatA_recret_m3:
	v_pk_add_f32 v[150:151], v[150:151], v[252:253]
	s_add_u32 s8, s8, 0x40000
	s_addc_u32 s9, s9, 0
	s_waitcnt vmcnt(4)
	s_barrier
	s_sub_u32 s36, s36, 1
	s_cmp_lg_u32 s36, 0
	s_cbranch_scc1 .LatA_loop
	s_sub_u32 s10, s10, 1
	s_cbranch_scc1 .LatA_evs_x4

; #define LAS __attribute__((address_space(3)))
; __device__ __forceinline__ float max2f(float a, float b) { float r; asm("v_max_f32_e32 %0, %1, %2" : "=v"(r) : "v"(a), "v"(b)); return r; }
; #define LGKM0() do { __builtin_amdgcn_sched_barrier(0); asm volatile("s_waitcnt lgkmcnt(0)" ::: "memory"); __builtin_amdgcn_sched_barrier(0); } while (0)
; __device__ __forceinline__ void attn_unit(LAS unsigned char* lds, const bf16_t* Z, bf16_t* A2, const float* tabg, int seq_base, int S, int h, int qb, float lam) {
;     ...
;         float mx = max2f(max16f(p0), max16f(p1));
;         const bool first = (t == 0);
;         if (first || __any(mx > THR)) {
;             { auto rr = __builtin_amdgcn_permlane32_swap(__float_as_uint(mx), __float_as_uint(mx), false, false); mx = max2f(__uint_as_float(rr[0]), __uint_as_float(rr[1])); }
;             const float delta = first ? mx : fmaxf(mx, 0.f);
;             const float alpha = first ? 1.0f : __builtin_amdgcn_exp2f(-delta);
;             mu += delta; ls2 *= alpha;
;             if (!first) {
;                 asm volatile("" ::: "memory");
;                 scr[r32] = alpha;
;                 asm volatile("s_waitcnt lgkmcnt(0)" ::: "memory");
; #pragma unroll
;                 for (int g = 0; g < 4; ++g) { const f32x4 a4 = *(const LAS f32x4*)(scr + 8 * g + 4 * hi);
; #pragma unroll
;                     for (int d = 0; d < 4; ++d) { O[d][4 * g + 0] *= a4[0]; O[d][4 * g + 1] *= a4[1]; O[d][4 * g + 2] *= a4[2]; O[d][4 * g + 3] *= a4[3]; } }
;                 asm volatile("s_waitcnt lgkmcnt(0)" ::: "memory");
;             }
; #pragma unroll
;             for (int r = 0; r < 16; ++r) { p0[r] -= delta; p1[r] -= delta; }
;             asm volatile("" : "+v"(p0), "+v"(p1));
;         }
; #pragma unroll
;         for (int r = 0; r < 16; ++r) { p0[r] = __builtin_amdgcn_exp2f(p0[r]); p1[r] = __builtin_amdgcn_exp2f(p1[r]); }
; #pragma unroll
;         for (int r = 0; r < 16; r += 2) { ls2 += (f32x2){p0[r], p0[r + 1]}; ls2 += (f32x2){p1[r], p1[r + 1]}; }
;         bf16x8 pa[4]; pa[0] = pack8(p0, 0); pa[1] = pack8(p0, 8); pa[2] = pack8(p1, 0); pa[3] = pack8(p1, 8);
;         LGKM0(); VREADS1(vb, 1); PV1(va, 0); LGKM0(); VREADS1(va, 2); PV1(vb, 1); LGKM0(); VREADS1(vb, 3); PV1(va, 2); LGKM0(); PV1(vb, 3);
.LatA_evret_x3:
	s_waitcnt lgkmcnt(12)
	v_mfma_f32_32x32x16_bf16 v[20:35], v[84:87], v[132:135], v[20:35]
	ds_read_b64_tr_b16 v[236:237], v231 offset:4096
	ds_read_b64_tr_b16 v[238:239], v231 offset:6144
	v_exp_f32_e32 v188, v188
	v_exp_f32_e32 v189, v189
	s_waitcnt lgkmcnt(12)
	v_mfma_f32_32x32x16_bf16 v[36:51], v[84:87], v[136:139], v[36:51]
	ds_read_b64_tr_b16 v[132:133], v228 offset:8192
	ds_read_b64_tr_b16 v[134:135], v228 offset:10240
	v_exp_f32_e32 v190, v190
	v_exp_f32_e32 v191, v191
	s_waitcnt lgkmcnt(12)
	v_mfma_f32_32x32x16_bf16 v[52:67], v[84:87], v[140:143], v[52:67]
	ds_read_b64_tr_b16 v[136:137], v229 offset:8192
	ds_read_b64_tr_b16 v[138:139], v229 offset:10240
	v_exp_f32_e32 v192, v192
	v_pk_add_f32 v[252:253], v[188:189], v[190:191]
	v_exp_f32_e32 v193, v193
	s_waitcnt lgkmcnt(12)
	v_mfma_f32_32x32x16_bf16 v[68:83], v[84:87], v[144:147], v[68:83]
	ds_read_b64_tr_b16 v[140:141], v230 offset:8192
	ds_read_b64_tr_b16 v[142:143], v230 offset:10240
	v_cvt_pk_bf16_f32 v188, v188, v189
	v_cvt_pk_bf16_f32 v189, v190, v191
	v_exp_f32_e32 v194, v194
	s_waitcnt lgkmcnt(12)
	v_mfma_f32_32x32x16_bf16 v[20:35], v[88:91], v[220:223], v[20:35]
	ds_read_b64_tr_b16 v[144:145], v231 offset:8192
	ds_read_b64_tr_b16 v[146:147], v231 offset:10240
	v_exp_f32_e32 v195, v195
	v_pk_add_f32 v[252:253], v[252:253], v[192:193]
	s_waitcnt lgkmcnt(12)
	v_mfma_f32_32x32x16_bf16 v[36:51], v[88:91], v[224:227], v[36:51]
	ds_read_b64_tr_b16 v[220:221], v228 offset:12288
	ds_read_b64_tr_b16 v[222:223], v228 offset:14336
	v_pk_add_f32 v[252:253], v[252:253], v[194:195]
	v_cvt_pk_bf16_f32 v190, v192, v193
	v_cvt_pk_bf16_f32 v191, v194, v195
	v_exp_f32_e32 v196, v196
	s_waitcnt lgkmcnt(12)
	v_mfma_f32_32x32x16_bf16 v[52:67], v[88:91], v[232:235], v[52:67]
	ds_read_b64_tr_b16 v[224:225], v229 offset:12288
	ds_read_b64_tr_b16 v[226:227], v229 offset:14336
	v_exp_f32_e32 v197, v197
	v_exp_f32_e32 v198, v198
	s_waitcnt lgkmcnt(12)
	s_add_u32 m0, s29, 0xd000
	v_mfma_f32_32x32x16_bf16 v[68:83], v[88:91], v[236:239], v[68:83]
	global_load_lds_dwordx4 v174, s[8:9]
	ds_read_b64_tr_b16 v[232:233], v230 offset:12288
	ds_read_b64_tr_b16 v[234:235], v230 offset:14336
	v_exp_f32_e32 v199, v199
	v_pk_add_f32 v[252:253], v[252:253], v[196:197]
	s_waitcnt lgkmcnt(12)
	v_mfma_f32_32x32x16_bf16 v[20:35], v[100:103], v[132:135], v[20:35]
	ds_read_b64_tr_b16 v[236:237], v231 offset:12288
	ds_read_b64_tr_b16 v[238:239], v231 offset:14336
	v_pk_add_f32 v[252:253], v[252:253], v[198:199]
	v_exp_f32_e32 v200, v200
	s_waitcnt lgkmcnt(12)
	v_mfma_f32_32x32x16_bf16 v[36:51], v[100:103], v[136:139], v[36:51]
	ds_read_b128 v[132:135], v19 offset:32768
	v_exp_f32_e32 v201, v201
	v_cvt_pk_bf16_f32 v192, v196, v197
	v_cvt_pk_bf16_f32 v193, v198, v199
	v_exp_f32_e32 v202, v202
	s_waitcnt lgkmcnt(11)
	v_mfma_f32_32x32x16_bf16 v[52:67], v[100:103], v[140:143], v[52:67]
	ds_read_b128 v[136:139], v19 offset:40960
	v_exp_f32_e32 v203, v203
	v_pk_add_f32 v[252:253], v[252:253], v[200:201]
	s_waitcnt lgkmcnt(10)
	v_mfma_f32_32x32x16_bf16 v[68:83], v[100:103], v[144:147], v[68:83]
	ds_read_b128 v[140:143], v180 offset:32768
	v_pk_add_f32 v[252:253], v[252:253], v[202:203]
	v_cvt_pk_bf16_f32 v194, v200, v201
	v_cvt_pk_bf16_f32 v195, v202, v203
	s_waitcnt lgkmcnt(9)
	v_mfma_f32_32x32x16_bf16 v[20:35], v[104:107], v[220:223], v[20:35]
	ds_read_b128 v[144:147], v180 offset:40960
	v_exp_f32_e32 v204, v204
	v_exp_f32_e32 v205, v205
	v_exp_f32_e32 v206, v206
	s_waitcnt lgkmcnt(8)
	v_mfma_f32_32x32x16_bf16 v[36:51], v[104:107], v[224:227], v[36:51]
	ds_read_b128 v[220:223], v181 offset:32768
	v_exp_f32_e32 v207, v207
	v_pk_add_f32 v[252:253], v[252:253], v[204:205]
	s_waitcnt lgkmcnt(7)
	v_mfma_f32_32x32x16_bf16 v[52:67], v[104:107], v[232:235], v[52:67]
	ds_read_b128 v[224:227], v181 offset:40960
	v_pk_add_f32 v[252:253], v[252:253], v[206:207]
	v_exp_f32_e32 v208, v208
	s_waitcnt lgkmcnt(6)
	s_add_u32 m0, s29, 0xf000
	v_mfma_f32_32x32x16_bf16 v[68:83], v[104:107], v[236:239], v[68:83]
	global_load_lds_dwordx4 v175, s[8:9]
	ds_read_b128 v[232:235], v182 offset:32768
	v_exp_f32_e32 v209, v209
	v_cvt_pk_bf16_f32 v204, v204, v205
	v_cvt_pk_bf16_f32 v205, v206, v207
	s_waitcnt lgkmcnt(6)
	v_mfma_f32_32x32x16_bf16 v[84:99], v[132:135], v[116:119], v[2:17]
	ds_read_b128 v[236:239], v182 offset:40960
	v_exp_f32_e32 v210, v210
	v_exp_f32_e32 v211, v211
	v_pk_add_f32 v[252:253], v[252:253], v[208:209]
	s_waitcnt lgkmcnt(6)
	v_mfma_f32_32x32x16_bf16 v[100:115], v[136:139], v[116:119], v[2:17]
	ds_read_b64_tr_b16 v[132:133], v228 offset:16384
	ds_read_b64_tr_b16 v[134:135], v228 offset:18432
	v_pk_add_f32 v[252:253], v[252:253], v[210:211]
	v_cvt_pk_bf16_f32 v206, v208, v209
	v_cvt_pk_bf16_f32 v207, v210, v211
	s_waitcnt lgkmcnt(7)
	v_mfma_f32_32x32x16_bf16 v[84:99], v[140:143], v[120:123], v[84:99]
	ds_read_b64_tr_b16 v[136:137], v229 offset:16384
	ds_read_b64_tr_b16 v[138:139], v229 offset:18432
	v_exp_f32_e32 v212, v212
	v_exp_f32_e32 v213, v213
	s_waitcnt lgkmcnt(8)
	v_mfma_f32_32x32x16_bf16 v[100:115], v[144:147], v[120:123], v[100:115]
	ds_read_b64_tr_b16 v[140:141], v230 offset:16384
	ds_read_b64_tr_b16 v[142:143], v230 offset:18432
	v_exp_f32_e32 v214, v214
	v_exp_f32_e32 v215, v215
	v_pk_add_f32 v[252:253], v[252:253], v[212:213]
	s_waitcnt lgkmcnt(9)
	v_mfma_f32_32x32x16_bf16 v[84:99], v[220:223], v[124:127], v[84:99]
	ds_read_b64_tr_b16 v[144:145], v231 offset:16384
	ds_read_b64_tr_b16 v[146:147], v231 offset:18432
	v_pk_add_f32 v[252:253], v[252:253], v[214:215]
	v_exp_f32_e32 v216, v216
	s_waitcnt lgkmcnt(10)
	v_mfma_f32_32x32x16_bf16 v[100:115], v[224:227], v[124:127], v[100:115]
	ds_read_b64_tr_b16 v[220:221], v228 offset:20480
	ds_read_b64_tr_b16 v[222:223], v228 offset:22528
	v_exp_f32_e32 v217, v217
	v_cvt_pk_bf16_f32 v208, v212, v213
	v_cvt_pk_bf16_f32 v209, v214, v215
	s_waitcnt lgkmcnt(11)
	v_mfma_f32_32x32x16_bf16 v[84:99], v[232:235], v[128:131], v[84:99]
	ds_read_b64_tr_b16 v[224:225], v229 offset:20480
	ds_read_b64_tr_b16 v[226:227], v229 offset:22528
	v_exp_f32_e32 v218, v218
	v_exp_f32_e32 v219, v219
	s_waitcnt lgkmcnt(12)
	v_mfma_f32_32x32x16_bf16 v[100:115], v[236:239], v[128:131], v[100:115]
	ds_read_b64_tr_b16 v[232:233], v230 offset:20480
	ds_read_b64_tr_b16 v[234:235], v230 offset:22528
	v_pk_add_f32 v[252:253], v[252:253], v[216:217]
	v_pk_add_f32 v[252:253], v[252:253], v[218:219]
	v_cvt_pk_bf16_f32 v210, v216, v217
	v_cvt_pk_bf16_f32 v211, v218, v219
	v_max_f32_e32 v251, v252, v253
	v_cmp_nge_f32_e32 vcc, 0x45800000, v251
	s_cbranch_vccnz .LatA_recs_x3
; #define LAS __attribute__((address_space(3)))
; __device__ __forceinline__ void attn_unit(LAS unsigned char* lds, const bf16_t* Z, bf16_t* A2, const float* tabg, int seq_base, int S, int h, int qb, float lam) {
;     ...
;         float mx = max2f(max16f(p0), max16f(p1));
;         const bool first = (t == 0);
;         if (first || __any(mx > THR)) {
;             { auto rr = __builtin_amdgcn_permlane32_swap(__float_as_uint(mx), __float_as_uint(mx), false, false); mx = max2f(__uint_as_float(rr[0]), __uint_as_float(rr[1])); }
;             const float delta = first ? mx : fmaxf(mx, 0.f);
;             const float alpha = first ? 1.0f : __builtin_amdgcn_exp2f(-delta);
;             mu += delta; ls2 *= alpha;
;             if (!first) {
;                 asm volatile("" ::: "memory");
;                 scr[r32] = alpha;
;                 asm volatile("s_waitcnt lgkmcnt(0)" ::: "memory");
; #pragma unroll
;                 for (int g = 0; g < 4; ++g) { const f32x4 a4 = *(const LAS f32x4*)(scr + 8 * g + 4 * hi);
; #pragma unroll
;                     for (int d = 0; d < 4; ++d) { O[d][4 * g + 0] *= a4[0]; O[d][4 * g + 1] *= a4[1]; O[d][4 * g + 2] *= a4[2]; O[d][4 * g + 3] *= a4[3]; } }
;                 asm volatile("s_waitcnt lgkmcnt(0)" ::: "memory");
;             }
; #pragma unroll
;             for (int r = 0; r < 16; ++r) { p0[r] -= delta; p1[r] -= delta; }
;             asm volatile("" : "+v"(p0), "+v"(p1));
;         }
; #pragma unroll
;         for (int r = 0; r < 16; ++r) { p0[r] = __builtin_amdgcn_exp2f(p0[r]); p1[r] = __builtin_amdgcn_exp2f(p1[r]); }
; #pragma unroll
;         for (int r = 0; r < 16; r += 2) { ls2 += (f32x2){p0[r], p0[r + 1]}; ls2 += (f32x2){p1[r], p1[r + 1]}; }
;         bf16x8 pa[4]; pa[0] = pack8(p0, 0); pa[1] = pack8(p0, 8); pa[2] = pack8(p1, 0); pa[3] = pack8(p1, 8);
;         LGKM0(); VREADS1(vb, 1); PV1(va, 0); LGKM0(); VREADS1(va, 2); PV1(vb, 1); LGKM0(); VREADS1(vb, 3); PV1(va, 2); LGKM0(); PV1(vb, 3);
;     ...
;         if (t + 2 < NT) asm volatile("s_waitcnt vmcnt(4) lgkmcnt(0)" ::: "memory"); else asm volatile("s_waitcnt vmcnt(0) lgkmcnt(0)" ::: "memory");
;         __builtin_amdgcn_s_barrier(); asm volatile("" ::: "memory");
;         bc = (bc == NST - 1) ? 0 : bc + 1; bn = (bn == NST - 1) ? 0 : bn + 1;
.LatA_recret_x3:
	v_pk_add_f32 v[150:151], v[150:151], v[252:253]
	s_add_u32 s8, s8, 0x40000
	s_addc_u32 s9, s9, 0
	s_waitcnt vmcnt(2)
	s_barrier
	s_sub_u32 s10, s10, 1
	s_cbranch_scc1 .LatA_evs_x2
.LatA_evret_x2:
	s_waitcnt lgkmcnt(12)
	v_mfma_f32_32x32x16_bf16 v[20:35], v[188:191], v[132:135], v[20:35]
	ds_read_b64_tr_b16 v[236:237], v231 offset:20480
	ds_read_b64_tr_b16 v[238:239], v231 offset:22528
	v_exp_f32_e32 v84, v84
	v_exp_f32_e32 v85, v85
	s_waitcnt lgkmcnt(12)
	v_mfma_f32_32x32x16_bf16 v[36:51], v[188:191], v[136:139], v[36:51]
	ds_read_b64_tr_b16 v[132:133], v228 offset:24576
	ds_read_b64_tr_b16 v[134:135], v228 offset:26624
	v_exp_f32_e32 v86, v86
	v_exp_f32_e32 v87, v87
	s_waitcnt lgkmcnt(12)
	v_mfma_f32_32x32x16_bf16 v[52:67], v[188:191], v[140:143], v[52:67]
	ds_read_b64_tr_b16 v[136:137], v229 offset:24576
	ds_read_b64_tr_b16 v[138:139], v229 offset:26624
	v_exp_f32_e32 v88, v88
	v_pk_add_f32 v[252:253], v[84:85], v[86:87]
	v_exp_f32_e32 v89, v89
	s_waitcnt lgkmcnt(12)
	v_mfma_f32_32x32x16_bf16 v[68:83], v[188:191], v[144:147], v[68:83]
	ds_read_b64_tr_b16 v[140:141], v230 offset:24576
	ds_read_b64_tr_b16 v[142:143], v230 offset:26624
	v_cvt_pk_bf16_f32 v84, v84, v85
	v_cvt_pk_bf16_f32 v85, v86, v87
	v_exp_f32_e32 v90, v90
	s_waitcnt lgkmcnt(12)
	v_mfma_f32_32x32x16_bf16 v[20:35], v[192:195], v[220:223], v[20:35]
	ds_read_b64_tr_b16 v[144:145], v231 offset:24576
	ds_read_b64_tr_b16 v[146:147], v231 offset:26624
	v_exp_f32_e32 v91, v91
	v_pk_add_f32 v[252:253], v[252:253], v[88:89]
	s_waitcnt lgkmcnt(12)
	v_mfma_f32_32x32x16_bf16 v[36:51], v[192:195], v[224:227], v[36:51]
	ds_read_b64_tr_b16 v[220:221], v228 offset:28672
	ds_read_b64_tr_b16 v[222:223], v228 offset:30720
	v_pk_add_f32 v[252:253], v[252:253], v[90:91]
	v_cvt_pk_bf16_f32 v86, v88, v89
	v_cvt_pk_bf16_f32 v87, v90, v91
	v_exp_f32_e32 v92, v92
	s_waitcnt lgkmcnt(12)
	v_mfma_f32_32x32x16_bf16 v[52:67], v[192:195], v[232:235], v[52:67]
	ds_read_b64_tr_b16 v[224:225], v229 offset:28672
	ds_read_b64_tr_b16 v[226:227], v229 offset:30720
	v_exp_f32_e32 v93, v93
	v_exp_f32_e32 v94, v94
	s_waitcnt lgkmcnt(12)
	v_mfma_f32_32x32x16_bf16 v[68:83], v[192:195], v[236:239], v[68:83]
	ds_read_b64_tr_b16 v[232:233], v230 offset:28672
	ds_read_b64_tr_b16 v[234:235], v230 offset:30720
	v_exp_f32_e32 v95, v95
	v_pk_add_f32 v[252:253], v[252:253], v[92:93]
	s_waitcnt lgkmcnt(12)
	v_mfma_f32_32x32x16_bf16 v[20:35], v[204:207], v[132:135], v[20:35]
	ds_read_b64_tr_b16 v[236:237], v231 offset:28672
	ds_read_b64_tr_b16 v[238:239], v231 offset:30720
	v_pk_add_f32 v[252:253], v[252:253], v[94:95]
	v_exp_f32_e32 v96, v96
	s_waitcnt lgkmcnt(12)
	v_mfma_f32_32x32x16_bf16 v[36:51], v[204:207], v[136:139], v[36:51]
	ds_read_b128 v[132:135], v164
	v_exp_f32_e32 v97, v97
	v_cvt_pk_bf16_f32 v88, v92, v93
	v_cvt_pk_bf16_f32 v89, v94, v95
	v_exp_f32_e32 v98, v98
	s_waitcnt lgkmcnt(11)
	v_mfma_f32_32x32x16_bf16 v[52:67], v[204:207], v[140:143], v[52:67]
	ds_read_b128 v[136:139], v164 offset:8192
	v_exp_f32_e32 v99, v99
	v_pk_add_f32 v[252:253], v[252:253], v[96:97]
	s_waitcnt lgkmcnt(10)
	v_mfma_f32_32x32x16_bf16 v[68:83], v[204:207], v[144:147], v[68:83]
	ds_read_b128 v[140:143], v165
	v_pk_add_f32 v[252:253], v[252:253], v[98:99]
	v_cvt_pk_bf16_f32 v90, v96, v97
	v_cvt_pk_bf16_f32 v91, v98, v99
	s_waitcnt lgkmcnt(9)
	v_mfma_f32_32x32x16_bf16 v[20:35], v[208:211], v[220:223], v[20:35]
	ds_read_b128 v[144:147], v165 offset:8192
	v_exp_f32_e32 v100, v100
	v_exp_f32_e32 v101, v101
	v_exp_f32_e32 v102, v102
	s_waitcnt lgkmcnt(8)
	v_mfma_f32_32x32x16_bf16 v[36:51], v[208:211], v[224:227], v[36:51]
	ds_read_b128 v[220:223], v166
	v_exp_f32_e32 v103, v103
	v_pk_add_f32 v[252:253], v[252:253], v[100:101]
	s_waitcnt lgkmcnt(7)
	v_mfma_f32_32x32x16_bf16 v[52:67], v[208:211], v[232:235], v[52:67]
	ds_read_b128 v[224:227], v166 offset:8192
	v_pk_add_f32 v[252:253], v[252:253], v[102:103]
	v_exp_f32_e32 v104, v104
	s_waitcnt lgkmcnt(6)
	v_mfma_f32_32x32x16_bf16 v[68:83], v[208:211], v[236:239], v[68:83]
	ds_read_b128 v[232:235], v167
	v_exp_f32_e32 v105, v105
	v_cvt_pk_bf16_f32 v100, v100, v101
	v_cvt_pk_bf16_f32 v101, v102, v103
	s_waitcnt lgkmcnt(6)
	v_mfma_f32_32x32x16_bf16 v[188:203], v[132:135], v[116:119], v[2:17]
	ds_read_b128 v[236:239], v167 offset:8192
	v_exp_f32_e32 v106, v106
	v_exp_f32_e32 v107, v107
	v_pk_add_f32 v[252:253], v[252:253], v[104:105]
	s_waitcnt lgkmcnt(6)
	v_mfma_f32_32x32x16_bf16 v[204:219], v[136:139], v[116:119], v[2:17]
	ds_read_b64_tr_b16 v[132:133], v228 offset:32768
	ds_read_b64_tr_b16 v[134:135], v228 offset:34816
	v_pk_add_f32 v[252:253], v[252:253], v[106:107]
	v_cvt_pk_bf16_f32 v102, v104, v105
	v_cvt_pk_bf16_f32 v103, v106, v107
	s_waitcnt lgkmcnt(7)
	v_mfma_f32_32x32x16_bf16 v[188:203], v[140:143], v[120:123], v[188:203]
	ds_read_b64_tr_b16 v[136:137], v229 offset:32768
	ds_read_b64_tr_b16 v[138:139], v229 offset:34816
	v_exp_f32_e32 v108, v108
	v_exp_f32_e32 v109, v109
	s_waitcnt lgkmcnt(8)
	v_mfma_f32_32x32x16_bf16 v[204:219], v[144:147], v[120:123], v[204:219]
	ds_read_b64_tr_b16 v[140:141], v230 offset:32768
	ds_read_b64_tr_b16 v[142:143], v230 offset:34816
	v_exp_f32_e32 v110, v110
	v_exp_f32_e32 v111, v111
	v_pk_add_f32 v[252:253], v[252:253], v[108:109]
	s_waitcnt lgkmcnt(9)
	v_mfma_f32_32x32x16_bf16 v[188:203], v[220:223], v[124:127], v[188:203]
	ds_read_b64_tr_b16 v[144:145], v231 offset:32768
	ds_read_b64_tr_b16 v[146:147], v231 offset:34816
	v_pk_add_f32 v[252:253], v[252:253], v[110:111]
	v_exp_f32_e32 v112, v112
	s_waitcnt lgkmcnt(10)
	v_mfma_f32_32x32x16_bf16 v[204:219], v[224:227], v[124:127], v[204:219]
	ds_read_b64_tr_b16 v[220:221], v228 offset:36864
	ds_read_b64_tr_b16 v[222:223], v228 offset:38912
	v_exp_f32_e32 v113, v113
	v_cvt_pk_bf16_f32 v104, v108, v109
	v_cvt_pk_bf16_f32 v105, v110, v111
	s_waitcnt lgkmcnt(11)
	v_mfma_f32_32x32x16_bf16 v[188:203], v[232:235], v[128:131], v[188:203]
	ds_read_b64_tr_b16 v[224:225], v229 offset:36864
	ds_read_b64_tr_b16 v[226:227], v229 offset:38912
	v_exp_f32_e32 v114, v114
	v_exp_f32_e32 v115, v115
	s_waitcnt lgkmcnt(12)
	v_mfma_f32_32x32x16_bf16 v[204:219], v[236:239], v[128:131], v[204:219]
	ds_read_b64_tr_b16 v[232:233], v230 offset:36864
	ds_read_b64_tr_b16 v[234:235], v230 offset:38912
	v_pk_add_f32 v[252:253], v[252:253], v[112:113]
	v_pk_add_f32 v[252:253], v[252:253], v[114:115]
	v_cvt_pk_bf16_f32 v106, v112, v113
	v_cvt_pk_bf16_f32 v107, v114, v115
	v_max_f32_e32 v251, v252, v253
	v_cmp_nge_f32_e32 vcc, 0x45800000, v251
	s_cbranch_vccnz .LatA_recs_x2
; #define LAS __attribute__((address_space(3)))
; __device__ __forceinline__ void attn_unit(LAS unsigned char* lds, const bf16_t* Z, bf16_t* A2, const float* tabg, int seq_base, int S, int h, int qb, float lam) {
;     ...
;         float mx = max2f(max16f(p0), max16f(p1));
;         const bool first = (t == 0);
;         if (first || __any(mx > THR)) {
;             { auto rr = __builtin_amdgcn_permlane32_swap(__float_as_uint(mx), __float_as_uint(mx), false, false); mx = max2f(__uint_as_float(rr[0]), __uint_as_float(rr[1])); }
;             const float delta = first ? mx : fmaxf(mx, 0.f);
;             const float alpha = first ? 1.0f : __builtin_amdgcn_exp2f(-delta);
;             mu += delta; ls2 *= alpha;
;             if (!first) {
;                 asm volatile("" ::: "memory");
;                 scr[r32] = alpha;
;                 asm volatile("s_waitcnt lgkmcnt(0)" ::: "memory");
; #pragma unroll
;                 for (int g = 0; g < 4; ++g) { const f32x4 a4 = *(const LAS f32x4*)(scr + 8 * g + 4 * hi);
; #pragma unroll
;                     for (int d = 0; d < 4; ++d) { O[d][4 * g + 0] *= a4[0]; O[d][4 * g + 1] *= a4[1]; O[d][4 * g + 2] *= a4[2]; O[d][4 * g + 3] *= a4[3]; } }
;                 asm volatile("s_waitcnt lgkmcnt(0)" ::: "memory");
;             }
; #pragma unroll
;             for (int r = 0; r < 16; ++r) { p0[r] -= delta; p1[r] -= delta; }
;             asm volatile("" : "+v"(p0), "+v"(p1));
;         }
; #pragma unroll
;         for (int r = 0; r < 16; ++r) { p0[r] = __builtin_amdgcn_exp2f(p0[r]); p1[r] = __builtin_amdgcn_exp2f(p1[r]); }
; #pragma unroll
;         for (int r = 0; r < 16; r += 2) { ls2 += (f32x2){p0[r], p0[r + 1]}; ls2 += (f32x2){p1[r], p1[r + 1]}; }
;         bf16x8 pa[4]; pa[0] = pack8(p0, 0); pa[1] = pack8(p0, 8); pa[2] = pack8(p1, 0); pa[3] = pack8(p1, 8);
;         LGKM0(); VREADS1(vb, 1); PV1(va, 0); LGKM0(); VREADS1(va, 2); PV1(vb, 1); LGKM0(); VREADS1(vb, 3); PV1(va, 2); LGKM0(); PV1(vb, 3);
;     ...
;         if (t + 2 < NT) asm volatile("s_waitcnt vmcnt(4) lgkmcnt(0)" ::: "memory"); else asm volatile("s_waitcnt vmcnt(0) lgkmcnt(0)" ::: "memory");
;         __builtin_amdgcn_s_barrier(); asm volatile("" ::: "memory");
;         bc = (bc == NST - 1) ? 0 : bc + 1; bn = (bn == NST - 1) ? 0 : bn + 1;
.LatA_recret_x2:
	v_pk_add_f32 v[150:151], v[150:151], v[252:253]
	s_add_u32 s8, s8, 0x40000
	s_addc_u32 s9, s9, 0
	s_waitcnt vmcnt(0)
	s_barrier
	s_sub_u32 s10, s10, 1
	s_cbranch_scc1 .LatA_evs_x1
.LatA_evret_x1:
	s_waitcnt lgkmcnt(12)
	v_mfma_f32_32x32x16_bf16 v[20:35], v[84:87], v[132:135], v[20:35]
	ds_read_b64_tr_b16 v[236:237], v231 offset:36864
	ds_read_b64_tr_b16 v[238:239], v231 offset:38912
	v_exp_f32_e32 v188, v188
	v_exp_f32_e32 v189, v189
	v_exp_f32_e32 v190, v190
	s_waitcnt lgkmcnt(12)
	v_mfma_f32_32x32x16_bf16 v[36:51], v[84:87], v[136:139], v[36:51]
	ds_read_b64_tr_b16 v[132:133], v228 offset:40960
	ds_read_b64_tr_b16 v[134:135], v228 offset:43008
	v_exp_f32_e32 v191, v191
	v_exp_f32_e32 v192, v192
	v_pk_add_f32 v[252:253], v[188:189], v[190:191]
	v_exp_f32_e32 v193, v193
	s_waitcnt lgkmcnt(12)
	v_mfma_f32_32x32x16_bf16 v[52:67], v[84:87], v[140:143], v[52:67]
	ds_read_b64_tr_b16 v[136:137], v229 offset:40960
	ds_read_b64_tr_b16 v[138:139], v229 offset:43008
	v_cvt_pk_bf16_f32 v188, v188, v189
	v_cvt_pk_bf16_f32 v189, v190, v191
	v_exp_f32_e32 v194, v194
	v_exp_f32_e32 v195, v195
	s_waitcnt lgkmcnt(12)
	v_mfma_f32_32x32x16_bf16 v[68:83], v[84:87], v[144:147], v[68:83]
	ds_read_b64_tr_b16 v[140:141], v230 offset:40960
	ds_read_b64_tr_b16 v[142:143], v230 offset:43008
	v_pk_add_f32 v[252:253], v[252:253], v[192:193]
	v_pk_add_f32 v[252:253], v[252:253], v[194:195]
	v_cvt_pk_bf16_f32 v190, v192, v193
	v_cvt_pk_bf16_f32 v191, v194, v195
	v_exp_f32_e32 v196, v196
	s_waitcnt lgkmcnt(12)
	v_mfma_f32_32x32x16_bf16 v[20:35], v[88:91], v[220:223], v[20:35]
	ds_read_b64_tr_b16 v[144:145], v231 offset:40960
	ds_read_b64_tr_b16 v[146:147], v231 offset:43008
	v_exp_f32_e32 v197, v197
	v_exp_f32_e32 v198, v198
	v_exp_f32_e32 v199, v199
	s_waitcnt lgkmcnt(12)
	v_mfma_f32_32x32x16_bf16 v[36:51], v[88:91], v[224:227], v[36:51]
	ds_read_b64_tr_b16 v[220:221], v228 offset:45056
	ds_read_b64_tr_b16 v[222:223], v228 offset:47104
	v_pk_add_f32 v[252:253], v[252:253], v[196:197]
	v_pk_add_f32 v[252:253], v[252:253], v[198:199]
	v_exp_f32_e32 v200, v200
	s_waitcnt lgkmcnt(12)
	v_mfma_f32_32x32x16_bf16 v[52:67], v[88:91], v[232:235], v[52:67]
	ds_read_b64_tr_b16 v[224:225], v229 offset:45056
	ds_read_b64_tr_b16 v[226:227], v229 offset:47104
	v_exp_f32_e32 v201, v201
	v_cvt_pk_bf16_f32 v192, v196, v197
	v_cvt_pk_bf16_f32 v193, v198, v199
	v_exp_f32_e32 v202, v202
	v_exp_f32_e32 v203, v203
	s_waitcnt lgkmcnt(12)
	v_mfma_f32_32x32x16_bf16 v[68:83], v[88:91], v[236:239], v[68:83]
	ds_read_b64_tr_b16 v[232:233], v230 offset:45056
	ds_read_b64_tr_b16 v[234:235], v230 offset:47104
	v_pk_add_f32 v[252:253], v[252:253], v[200:201]
	v_pk_add_f32 v[252:253], v[252:253], v[202:203]
	v_cvt_pk_bf16_f32 v194, v200, v201
	v_cvt_pk_bf16_f32 v195, v202, v203
	s_waitcnt lgkmcnt(12)
	v_mfma_f32_32x32x16_bf16 v[20:35], v[100:103], v[132:135], v[20:35]
	ds_read_b64_tr_b16 v[236:237], v231 offset:45056
	ds_read_b64_tr_b16 v[238:239], v231 offset:47104
	v_exp_f32_e32 v204, v204
	v_exp_f32_e32 v205, v205
	v_exp_f32_e32 v206, v206
	v_exp_f32_e32 v207, v207
	s_waitcnt lgkmcnt(12)
	v_mfma_f32_32x32x16_bf16 v[36:51], v[100:103], v[136:139], v[36:51]
	ds_read_b64_tr_b16 v[132:133], v168 offset:0
	ds_read_b64_tr_b16 v[134:135], v168 offset:2048
	v_pk_add_f32 v[252:253], v[252:253], v[204:205]
	v_pk_add_f32 v[252:253], v[252:253], v[206:207]
	v_exp_f32_e32 v208, v208
	s_waitcnt lgkmcnt(12)
	v_mfma_f32_32x32x16_bf16 v[52:67], v[100:103], v[140:143], v[52:67]
	ds_read_b64_tr_b16 v[136:137], v169 offset:0
	ds_read_b64_tr_b16 v[138:139], v169 offset:2048
	v_exp_f32_e32 v209, v209
	v_cvt_pk_bf16_f32 v204, v204, v205
	v_cvt_pk_bf16_f32 v205, v206, v207
	v_exp_f32_e32 v210, v210
	v_exp_f32_e32 v211, v211
	s_waitcnt lgkmcnt(12)
	v_mfma_f32_32x32x16_bf16 v[68:83], v[100:103], v[144:147], v[68:83]
	ds_read_b64_tr_b16 v[140:141], v170 offset:0
	ds_read_b64_tr_b16 v[142:143], v170 offset:2048
	v_pk_add_f32 v[252:253], v[252:253], v[208:209]
	v_pk_add_f32 v[252:253], v[252:253], v[210:211]
	v_cvt_pk_bf16_f32 v206, v208, v209
	v_cvt_pk_bf16_f32 v207, v210, v211
	s_waitcnt lgkmcnt(12)
	v_mfma_f32_32x32x16_bf16 v[20:35], v[104:107], v[220:223], v[20:35]
	ds_read_b64_tr_b16 v[144:145], v171 offset:0
	ds_read_b64_tr_b16 v[146:147], v171 offset:2048
	v_exp_f32_e32 v212, v212
	v_exp_f32_e32 v213, v213
	v_exp_f32_e32 v214, v214
	s_waitcnt lgkmcnt(12)
	v_mfma_f32_32x32x16_bf16 v[36:51], v[104:107], v[224:227], v[36:51]
	ds_read_b64_tr_b16 v[220:221], v168 offset:4096
	ds_read_b64_tr_b16 v[222:223], v168 offset:6144
	v_exp_f32_e32 v215, v215
	v_pk_add_f32 v[252:253], v[252:253], v[212:213]
	v_pk_add_f32 v[252:253], v[252:253], v[214:215]
	v_exp_f32_e32 v216, v216
	s_waitcnt lgkmcnt(12)
	v_mfma_f32_32x32x16_bf16 v[52:67], v[104:107], v[232:235], v[52:67]
	ds_read_b64_tr_b16 v[224:225], v169 offset:4096
	ds_read_b64_tr_b16 v[226:227], v169 offset:6144
	v_exp_f32_e32 v217, v217
	v_cvt_pk_bf16_f32 v208, v212, v213
	v_cvt_pk_bf16_f32 v209, v214, v215
	v_exp_f32_e32 v218, v218
	s_waitcnt lgkmcnt(12)
	v_mfma_f32_32x32x16_bf16 v[68:83], v[104:107], v[236:239], v[68:83]
	ds_read_b64_tr_b16 v[232:233], v170 offset:4096
	ds_read_b64_tr_b16 v[234:235], v170 offset:6144
	v_exp_f32_e32 v219, v219
	v_pk_add_f32 v[252:253], v[252:253], v[216:217]
	v_pk_add_f32 v[252:253], v[252:253], v[218:219]
	v_cvt_pk_bf16_f32 v210, v216, v217
	v_cvt_pk_bf16_f32 v211, v218, v219
	v_max_f32_e32 v251, v252, v253
	v_cmp_nge_f32_e32 vcc, 0x45800000, v251
	s_cbranch_vccnz .LatA_recs_x1
; #define VREADS1(arr, d_) do { const unsigned ad_ = vbase ^ (unsigned)((d_) << 6); __builtin_amdgcn_sched_barrier(0); \
;         _Pragma("unroll") for (int ks_ = 0; ks_ < 4; ++ks_) { VTR(arr[ks_ * 2], ad_, ks_ * 4096); VTR(arr[ks_ * 2 + 1], ad_, ks_ * 4096 + 2048); } __builtin_amdgcn_sched_barrier(0); } while (0)
; #define PV1(arr, d_) do { _Pragma("unroll") for (int ks_ = 0; ks_ < 4; ++ks_) { const s16x4 lo_ = arr[ks_ * 2], hh_ = arr[ks_ * 2 + 1]; \
;         const bf16x8 bv_ = (bf16x8){lo_[0], lo_[1], lo_[2], lo_[3], hh_[0], hh_[1], hh_[2], hh_[3]}; \
;         O[d_] = __builtin_amdgcn_mfma_f32_32x32x16_bf16(pa[ks_], bv_, O[d_], 0, 0, 0); } __builtin_amdgcn_sched_barrier(0); } while (0)
; #define LGKM0() do { __builtin_amdgcn_sched_barrier(0); asm volatile("s_waitcnt lgkmcnt(0)" ::: "memory"); __builtin_amdgcn_sched_barrier(0); } while (0)
; __device__ __forceinline__ void attn_unit(LAS unsigned char* lds, const bf16_t* Z, bf16_t* A2, const float* tabg, int seq_base, int S, int h, int qb, float lam) {
;     ...
;         LGKM0(); VREADS1(vb, 1); PV1(va, 0); LGKM0(); VREADS1(va, 2); PV1(vb, 1); LGKM0(); VREADS1(vb, 3); PV1(va, 2); LGKM0(); PV1(vb, 3);
;     ...
;         if (t + 2 < NT) asm volatile("s_waitcnt vmcnt(4) lgkmcnt(0)" ::: "memory"); else asm volatile("s_waitcnt vmcnt(0) lgkmcnt(0)" ::: "memory");
;         __builtin_amdgcn_s_barrier(); asm volatile("" ::: "memory");
;         bc = (bc == NST - 1) ? 0 : bc + 1; bn = (bn == NST - 1) ? 0 : bn + 1;
;     }
.LatA_recret_x1:
	v_pk_add_f32 v[150:151], v[150:151], v[252:253]
	s_add_u32 s8, s8, 0x40000
	s_addc_u32 s9, s9, 0
	s_waitcnt vmcnt(0)
	s_barrier
	s_waitcnt lgkmcnt(12)
	v_mfma_f32_32x32x16_bf16 v[20:35], v[188:191], v[132:135], v[20:35]
	ds_read_b64_tr_b16 v[236:237], v171 offset:4096
	ds_read_b64_tr_b16 v[238:239], v171 offset:6144
	s_waitcnt lgkmcnt(12)
	v_mfma_f32_32x32x16_bf16 v[36:51], v[188:191], v[136:139], v[36:51]
	ds_read_b64_tr_b16 v[132:133], v168 offset:8192
	ds_read_b64_tr_b16 v[134:135], v168 offset:10240
	s_waitcnt lgkmcnt(12)
	v_mfma_f32_32x32x16_bf16 v[52:67], v[188:191], v[140:143], v[52:67]
	ds_read_b64_tr_b16 v[136:137], v169 offset:8192
	ds_read_b64_tr_b16 v[138:139], v169 offset:10240
	s_waitcnt lgkmcnt(12)
	v_mfma_f32_32x32x16_bf16 v[68:83], v[188:191], v[144:147], v[68:83]
	ds_read_b64_tr_b16 v[140:141], v170 offset:8192
	ds_read_b64_tr_b16 v[142:143], v170 offset:10240
	s_waitcnt lgkmcnt(12)
	v_mfma_f32_32x32x16_bf16 v[20:35], v[192:195], v[220:223], v[20:35]
	ds_read_b64_tr_b16 v[144:145], v171 offset:8192
	ds_read_b64_tr_b16 v[146:147], v171 offset:10240
	s_waitcnt lgkmcnt(12)
	v_mfma_f32_32x32x16_bf16 v[36:51], v[192:195], v[224:227], v[36:51]
	ds_read_b64_tr_b16 v[220:221], v168 offset:12288
	ds_read_b64_tr_b16 v[222:223], v168 offset:14336
	s_waitcnt lgkmcnt(12)
	v_mfma_f32_32x32x16_bf16 v[52:67], v[192:195], v[232:235], v[52:67]
	ds_read_b64_tr_b16 v[224:225], v169 offset:12288
	ds_read_b64_tr_b16 v[226:227], v169 offset:14336
	s_waitcnt lgkmcnt(12)
	v_mfma_f32_32x32x16_bf16 v[68:83], v[192:195], v[236:239], v[68:83]
	ds_read_b64_tr_b16 v[232:233], v170 offset:12288
	ds_read_b64_tr_b16 v[234:235], v170 offset:14336
	s_waitcnt lgkmcnt(12)
	v_mfma_f32_32x32x16_bf16 v[20:35], v[204:207], v[132:135], v[20:35]
	ds_read_b64_tr_b16 v[236:237], v171 offset:12288
	ds_read_b64_tr_b16 v[238:239], v171 offset:14336
	s_waitcnt lgkmcnt(12)
	v_mfma_f32_32x32x16_bf16 v[36:51], v[204:207], v[136:139], v[36:51]
	s_waitcnt lgkmcnt(10)
	v_mfma_f32_32x32x16_bf16 v[52:67], v[204:207], v[140:143], v[52:67]
	s_waitcnt lgkmcnt(8)
	v_mfma_f32_32x32x16_bf16 v[68:83], v[204:207], v[144:147], v[68:83]
	s_waitcnt lgkmcnt(6)
	v_mfma_f32_32x32x16_bf16 v[20:35], v[208:211], v[220:223], v[20:35]
	s_waitcnt lgkmcnt(4)
	v_mfma_f32_32x32x16_bf16 v[36:51], v[208:211], v[224:227], v[36:51]
	s_waitcnt lgkmcnt(2)
	v_mfma_f32_32x32x16_bf16 v[52:67], v[208:211], v[232:235], v[52:67]
	s_waitcnt lgkmcnt(0)
	v_mfma_f32_32x32x16_bf16 v[68:83], v[208:211], v[236:239], v[68:83]
	s_waitcnt lgkmcnt(0)
	s_barrier
	s_mov_b32 m0, s32
	v_mov_b64_e32 v[164:165], 0x200
	v_mov_b64_e32 v[166:167], 0x1ff
	v_mov_b64_e32 v[168:169], 0x5ac
	v_mov_b64_e32 v[170:171], 0x5ab
	v_mov_b64_e32 v[172:173], 0x100
	v_mov_b64_e32 v[174:175], 0xff
	s_nop 15
	s_branch .LatA_done

; __device__ __forceinline__ void attn_unit(LAS unsigned char* lds, const bf16_t* Z, bf16_t* A2, const float* tabg, int seq_base, int S, int h, int qb, float lam) {
;     ...
;         if (kv0 - (qlo + 31) >= 128) { near = false; cc = tabR; } else if (qlo - (kv0 + 63) >= 128) { near = false; cc = tabL; }
;         { const float coff = cc - mu;
;           if (__any(!(coff == coff_cur))) { coff_cur = coff;
; #pragma unroll
;               for (int r = 0; r < 16; ++r) cblk[r] = coff;
;               asm volatile("" : "+v"(cblk)); } }
;     ...
;         if (first || __any(mx > THR)) {
.LatA_evs_m0:
	s_mov_b32 s42, 1
	s_branch .LatA_ev_01
.LatA_recs_m0:
	s_mov_b32 s42, 1
	s_branch .LatA_rec_0

; __device__ __forceinline__ void attn_unit(LAS unsigned char* lds, const bf16_t* Z, bf16_t* A2, const float* tabg, int seq_base, int S, int h, int qb, float lam) {
;     ...
;         if (kv0 - (qlo + 31) >= 128) { near = false; cc = tabR; } else if (qlo - (kv0 + 63) >= 128) { near = false; cc = tabL; }
;         { const float coff = cc - mu;
;           if (__any(!(coff == coff_cur))) { coff_cur = coff;
; #pragma unroll
;               for (int r = 0; r < 16; ++r) cblk[r] = coff;
;               asm volatile("" : "+v"(cblk)); } }
;     ...
;         if (first || __any(mx > THR)) {
.LatA_evs_x4:
	s_mov_b32 s42, 3
	s_branch .LatA_ev_01
.LatA_recs_x4:
	s_mov_b32 s42, 2
	s_branch .LatA_rec_0

; #define LAS __attribute__((address_space(3)))
; __device__ __forceinline__ void attn_unit(LAS unsigned char* lds, const bf16_t* Z, bf16_t* A2, const float* tabg, int seq_base, int S, int h, int qb, float lam) {
;     ...
;         if (kv0 - (qlo + 31) >= 128) { near = false; cc = tabR; } else if (qlo - (kv0 + 63) >= 128) { near = false; cc = tabL; }
;     ...
;         if (near) {
;             const LAS float* tp = tab + (kv0 + 4 * hi - (qlo + r32) + 224);
; #pragma unroll
;             for (int r = 0; r < 16; ++r) { p0[r] += tp[(r & 3) + 8 * (r >> 2)]; p1[r] += tp[32 + (r & 3) + 8 * (r >> 2)]; }
;         }
.LatA_recs_x1:
	s_mov_b32 s42, 2
	s_branch .LatA_rec_3
.LatA_ev_11:
	s_sub_u32 s5, s8, s4
	s_lshr_b32 s5, s5, 12
	s_sub_u32 s5, s5, 64
	s_cmp_ge_u32 s5, s11
	s_cselect_b32 s37, 1, 0
	s_cmp_le_u32 s5, s31
	s_cselect_b32 s38, 1, 0
	s_and_b32 s37, s37, s38
	s_add_u32 s38, s5, 64
	s_cmp_le_u32 s38, s31
	s_cselect_b32 s10, 0, 0x7fffffff
	s_cmp_eq_u32 s37, 0
	s_cbranch_scc1 .LatA_evnn_11
	s_lshl_b32 s38, s5, 2
	s_add_i32 s38, s38, 0x18b80
	v_add_u32_e32 v187, s38, v162
	ds_read2_b32 v[92:93], v187 offset0:0 offset1:1
	ds_read2_b32 v[94:95], v187 offset0:2 offset1:3
	ds_read2_b32 v[96:97], v187 offset0:8 offset1:9
	ds_read2_b32 v[98:99], v187 offset0:10 offset1:11
	ds_read2_b32 v[108:109], v187 offset0:16 offset1:17
	ds_read2_b32 v[110:111], v187 offset0:18 offset1:19
	ds_read2_b32 v[112:113], v187 offset0:24 offset1:25
	ds_read2_b32 v[114:115], v187 offset0:26 offset1:27
	s_waitcnt lgkmcnt(0)
	v_pk_add_f32 v[188:189], v[188:189], v[92:93]
	v_pk_add_f32 v[190:191], v[190:191], v[94:95]
	v_pk_add_f32 v[192:193], v[192:193], v[96:97]
	v_pk_add_f32 v[194:195], v[194:195], v[98:99]
	v_pk_add_f32 v[196:197], v[196:197], v[108:109]
	v_pk_add_f32 v[198:199], v[198:199], v[110:111]
	v_pk_add_f32 v[200:201], v[200:201], v[112:113]
	v_pk_add_f32 v[202:203], v[202:203], v[114:115]
	ds_read2_b32 v[92:93], v187 offset0:32 offset1:33
	ds_read2_b32 v[94:95], v187 offset0:34 offset1:35
	ds_read2_b32 v[96:97], v187 offset0:40 offset1:41
	ds_read2_b32 v[98:99], v187 offset0:42 offset1:43
	ds_read2_b32 v[108:109], v187 offset0:48 offset1:49
	ds_read2_b32 v[110:111], v187 offset0:50 offset1:51
	ds_read2_b32 v[112:113], v187 offset0:56 offset1:57
	ds_read2_b32 v[114:115], v187 offset0:58 offset1:59
	s_waitcnt lgkmcnt(0)
	v_pk_add_f32 v[204:205], v[204:205], v[92:93]
	v_pk_add_f32 v[206:207], v[206:207], v[94:95]
	v_pk_add_f32 v[208:209], v[208:209], v[96:97]
	v_pk_add_f32 v[210:211], v[210:211], v[98:99]
	v_pk_add_f32 v[212:213], v[212:213], v[108:109]
	v_pk_add_f32 v[214:215], v[214:215], v[110:111]
	v_pk_add_f32 v[216:217], v[216:217], v[112:113]
	v_pk_add_f32 v[218:219], v[218:219], v[114:115]

; #define LAS __attribute__((address_space(3)))
; __device__ __forceinline__ void attn_unit(LAS unsigned char* lds, const bf16_t* Z, bf16_t* A2, const float* tabg, int seq_base, int S, int h, int qb, float lam) {
;     ...
;             for (int ds = 0; ds < 4; ++ds) { kf[2 * ds] = *(const LAS bf16x8*)(Kt + (kfo ^ (unsigned)(ds << 5))); kf[2 * ds + 1] = *(const LAS bf16x8*)(Kt + 32 * 256 + (kfo ^ (unsigned)(ds << 5))); }
;             __builtin_amdgcn_sched_barrier(0);
;             p0 = __builtin_amdgcn_mfma_f32_32x32x16_bf16(kf[0], qf[0], cblk, 0, 0, 0);
;             p1 = __builtin_amdgcn_mfma_f32_32x32x16_bf16(kf[1], qf[0], cblk, 0, 0, 0);
; #pragma unroll
;             for (int ds = 1; ds < 4; ++ds) {
;                 p0 = __builtin_amdgcn_mfma_f32_32x32x16_bf16(kf[2 * ds], qf[ds], p0, 0, 0, 0);
;                 p1 = __builtin_amdgcn_mfma_f32_32x32x16_bf16(kf[2 * ds + 1], qf[ds], p1, 0, 0, 0);
;             }
;         }
;     ...
;         const unsigned vbase = (unsigned)(size_t)Vt + vfo;
;         s16x4 va[8], vb[8];
;         VREADS1(va, 0);
;         if (near) {
;             const LAS float* tp = tab + (kv0 + 4 * hi - (qlo + r32) + 224);
; #pragma unroll
;             for (int r = 0; r < 16; ++r) { p0[r] += tp[(r & 3) + 8 * (r >> 2)]; p1[r] += tp[32 + (r & 3) + 8 * (r >> 2)]; }
;         }
;         float mx = max2f(max16f(p0), max16f(p1));
;         const bool first = (t == 0);
;         if (first || __any(mx > THR)) {
;             { auto rr = __builtin_amdgcn_permlane32_swap(__float_as_uint(mx), __float_as_uint(mx), false, false); mx = max2f(__uint_as_float(rr[0]), __uint_as_float(rr[1])); }
;             const float delta = first ? mx : fmaxf(mx, 0.f);
;             const float alpha = first ? 1.0f : __builtin_amdgcn_exp2f(-delta);
;             mu += delta; ls2 *= alpha;
;             if (!first) {
;                 asm volatile("" ::: "memory");
;                 scr[r32] = alpha;
;                 asm volatile("s_waitcnt lgkmcnt(0)" ::: "memory");
; #pragma unroll
;                 for (int g = 0; g < 4; ++g) { const f32x4 a4 = *(const LAS f32x4*)(scr + 8 * g + 4 * hi);
; #pragma unroll
;                     for (int d = 0; d < 4; ++d) { O[d][4 * g + 0] *= a4[0]; O[d][4 * g + 1] *= a4[1]; O[d][4 * g + 2] *= a4[2]; O[d][4 * g + 3] *= a4[3]; } }
;                 asm volatile("s_waitcnt lgkmcnt(0)" ::: "memory");
;             }
.LatA_rec_0:
	s_waitcnt lgkmcnt(0)
	s_nop 15
	s_sub_u32 s5, s8, s4
	s_lshr_b32 s5, s5, 12
	s_sub_u32 s5, s5, 64
	s_cmp_lt_u32 s5, s11
	s_cselect_b32 s37, 1, 0
	s_cmp_gt_u32 s5, s31
	s_cselect_b32 s40, 2, 0
	s_or_b32 s37, s37, s40
	s_mov_b32 s43, s35
	s_mov_b32 s35, s37
	v_mov_b32_e32 v251, 0
	s_cmp_eq_u32 s37, 1
	s_cselect_b64 vcc, -1, 0
	v_cndmask_b32_e32 v251, v251, v177, vcc
	s_cmp_eq_u32 s37, 2
	s_cselect_b64 vcc, -1, 0
	v_cndmask_b32_e32 v251, v251, v178, vcc
	v_sub_f32_e32 v2, v251, v186
	v_mov_b32_e32 v3, v2
	v_mov_b64_e32 v[4:5], v[2:3]
	v_mov_b64_e32 v[6:7], v[2:3]
	v_mov_b64_e32 v[8:9], v[2:3]
	v_mov_b64_e32 v[10:11], v[2:3]
	v_mov_b64_e32 v[12:13], v[2:3]
	v_mov_b64_e32 v[14:15], v[2:3]
	v_mov_b64_e32 v[16:17], v[2:3]
	s_nop 1
	ds_read_b128 v[132:135], v19
	ds_read_b128 v[136:139], v19 offset:8192
	ds_read_b128 v[140:143], v180
	ds_read_b128 v[144:147], v180 offset:8192
	ds_read_b128 v[220:223], v181
	ds_read_b128 v[224:227], v181 offset:8192
	ds_read_b128 v[232:235], v182
	ds_read_b128 v[236:239], v182 offset:8192
	s_waitcnt lgkmcnt(7)
	v_mfma_f32_32x32x16_bf16 v[84:99], v[132:135], v[116:119], v[2:17]
	s_waitcnt lgkmcnt(6)
	v_mfma_f32_32x32x16_bf16 v[100:115], v[136:139], v[116:119], v[2:17]
	s_waitcnt lgkmcnt(5)
	v_mfma_f32_32x32x16_bf16 v[84:99], v[140:143], v[120:123], v[84:99]
	s_waitcnt lgkmcnt(4)
	v_mfma_f32_32x32x16_bf16 v[100:115], v[144:147], v[120:123], v[100:115]
	s_waitcnt lgkmcnt(3)
	v_mfma_f32_32x32x16_bf16 v[84:99], v[220:223], v[124:127], v[84:99]
	s_waitcnt lgkmcnt(2)
	v_mfma_f32_32x32x16_bf16 v[100:115], v[224:227], v[124:127], v[100:115]
	s_waitcnt lgkmcnt(1)
	v_mfma_f32_32x32x16_bf16 v[84:99], v[232:235], v[128:131], v[84:99]
	s_waitcnt lgkmcnt(0)
	v_mfma_f32_32x32x16_bf16 v[100:115], v[236:239], v[128:131], v[100:115]
	s_nop 15
	s_nop 15
	s_cmp_lg_u32 s35, 0
	s_cbranch_scc1 .LatA_recnn_0
	s_lshl_b32 s38, s5, 2
	s_add_i32 s38, s38, 0x18b80
	v_add_u32_e32 v187, s38, v162
	ds_read2_b32 v[132:133], v187 offset0:0 offset1:1
	ds_read2_b32 v[134:135], v187 offset0:2 offset1:3
	ds_read2_b32 v[136:137], v187 offset0:8 offset1:9
	ds_read2_b32 v[138:139], v187 offset0:10 offset1:11
	ds_read2_b32 v[140:141], v187 offset0:16 offset1:17
	ds_read2_b32 v[142:143], v187 offset0:18 offset1:19
	ds_read2_b32 v[144:145], v187 offset0:24 offset1:25
	ds_read2_b32 v[146:147], v187 offset0:26 offset1:27
	s_waitcnt lgkmcnt(0)
	v_pk_add_f32 v[84:85], v[84:85], v[132:133]
	v_pk_add_f32 v[86:87], v[86:87], v[134:135]
	v_pk_add_f32 v[88:89], v[88:89], v[136:137]
	v_pk_add_f32 v[90:91], v[90:91], v[138:139]
	v_pk_add_f32 v[92:93], v[92:93], v[140:141]
	v_pk_add_f32 v[94:95], v[94:95], v[142:143]
	v_pk_add_f32 v[96:97], v[96:97], v[144:145]
	v_pk_add_f32 v[98:99], v[98:99], v[146:147]
	ds_read2_b32 v[132:133], v187 offset0:32 offset1:33
	ds_read2_b32 v[134:135], v187 offset0:34 offset1:35
	ds_read2_b32 v[136:137], v187 offset0:40 offset1:41
	ds_read2_b32 v[138:139], v187 offset0:42 offset1:43
	ds_read2_b32 v[140:141], v187 offset0:48 offset1:49
	ds_read2_b32 v[142:143], v187 offset0:50 offset1:51
	ds_read2_b32 v[144:145], v187 offset0:56 offset1:57
	ds_read2_b32 v[146:147], v187 offset0:58 offset1:59
	s_waitcnt lgkmcnt(0)
	v_pk_add_f32 v[100:101], v[100:101], v[132:133]
	v_pk_add_f32 v[102:103], v[102:103], v[134:135]
	v_pk_add_f32 v[104:105], v[104:105], v[136:137]
	v_pk_add_f32 v[106:107], v[106:107], v[138:139]
	v_pk_add_f32 v[108:109], v[108:109], v[140:141]
	v_pk_add_f32 v[110:111], v[110:111], v[142:143]
	v_pk_add_f32 v[112:113], v[112:113], v[144:145]
	v_pk_add_f32 v[114:115], v[114:115], v[146:147]
.LatA_recnn_0:
	v_max3_f32 v251, v84, v85, v86
	v_max3_f32 v252, v87, v88, v89
	v_max3_f32 v251, v251, v90, v91
	v_max3_f32 v252, v252, v92, v93
	v_max3_f32 v251, v251, v94, v95
	v_max3_f32 v252, v252, v96, v97
	v_max3_f32 v251, v251, v98, v99
	v_max3_f32 v252, v252, v100, v101
	v_max3_f32 v251, v251, v102, v103
	v_max3_f32 v252, v252, v104, v105
	v_max3_f32 v251, v251, v106, v107
	v_max3_f32 v252, v252, v108, v109
	v_max3_f32 v251, v251, v110, v111
	v_max3_f32 v252, v252, v112, v113
	v_max3_f32 v251, v251, v114, v115
	v_max_f32_e32 v251, v251, v252
	v_mov_b32_e32 v252, v251
	s_nop 1
	v_permlane32_swap_b32_e32 v251, v252
	v_max_f32_e32 v251, v251, v252
	v_max_f32_e32 v253, 0, v251
	v_exp_f32_e64 v254, -v253
	v_add_f32_e32 v186, v186, v253
	s_nop 0
	v_mul_f32_e32 v150, v150, v254
	v_mul_f32_e32 v151, v151, v254
	ds_write_b32 v184, v254
	s_waitcnt lgkmcnt(0)
	ds_read_b128 v[132:135], v185
	ds_read_b128 v[136:139], v185 offset:32
	ds_read_b128 v[140:143], v185 offset:64
	ds_read_b128 v[144:147], v185 offset:96
	s_waitcnt lgkmcnt(0)
; #define LAS __attribute__((address_space(3)))
; __device__ __forceinline__ void attn_unit(LAS unsigned char* lds, const bf16_t* Z, bf16_t* A2, const float* tabg, int seq_base, int S, int h, int qb, float lam) {
;     ...
;                 for (int g = 0; g < 4; ++g) { const f32x4 a4 = *(const LAS f32x4*)(scr + 8 * g + 4 * hi);
; #pragma unroll
;                     for (int d = 0; d < 4; ++d) { O[d][4 * g + 0] *= a4[0]; O[d][4 * g + 1] *= a4[1]; O[d][4 * g + 2] *= a4[2]; O[d][4 * g + 3] *= a4[3]; } }
;                 asm volatile("s_waitcnt lgkmcnt(0)" ::: "memory");
;             }
; #pragma unroll
;             for (int r = 0; r < 16; ++r) { p0[r] -= delta; p1[r] -= delta; }
;             asm volatile("" : "+v"(p0), "+v"(p1));
;         }
; #pragma unroll
;         for (int r = 0; r < 16; ++r) { p0[r] = __builtin_amdgcn_exp2f(p0[r]); p1[r] = __builtin_amdgcn_exp2f(p1[r]); }
; #pragma unroll
;         for (int r = 0; r < 16; r += 2) { ls2 += (f32x2){p0[r], p0[r + 1]}; ls2 += (f32x2){p1[r], p1[r + 1]}; }
;         bf16x8 pa[4]; pa[0] = pack8(p0, 0); pa[1] = pack8(p0, 8); pa[2] = pack8(p1, 0); pa[3] = pack8(p1, 8);
	v_pk_mul_f32 v[20:21], v[20:21], v[132:133]
	v_pk_mul_f32 v[22:23], v[22:23], v[134:135]
	v_pk_mul_f32 v[24:25], v[24:25], v[136:137]
	v_pk_mul_f32 v[26:27], v[26:27], v[138:139]
	v_pk_mul_f32 v[28:29], v[28:29], v[140:141]
	v_pk_mul_f32 v[30:31], v[30:31], v[142:143]
	v_pk_mul_f32 v[32:33], v[32:33], v[144:145]
	v_pk_mul_f32 v[34:35], v[34:35], v[146:147]
	v_pk_mul_f32 v[36:37], v[36:37], v[132:133]
	v_pk_mul_f32 v[38:39], v[38:39], v[134:135]
	v_pk_mul_f32 v[40:41], v[40:41], v[136:137]
	v_pk_mul_f32 v[42:43], v[42:43], v[138:139]
	v_pk_mul_f32 v[44:45], v[44:45], v[140:141]
	v_pk_mul_f32 v[46:47], v[46:47], v[142:143]
	v_pk_mul_f32 v[48:49], v[48:49], v[144:145]
	v_pk_mul_f32 v[50:51], v[50:51], v[146:147]
	v_pk_mul_f32 v[52:53], v[52:53], v[132:133]
	v_pk_mul_f32 v[54:55], v[54:55], v[134:135]
	v_pk_mul_f32 v[56:57], v[56:57], v[136:137]
	v_pk_mul_f32 v[58:59], v[58:59], v[138:139]
	v_pk_mul_f32 v[60:61], v[60:61], v[140:141]
	v_pk_mul_f32 v[62:63], v[62:63], v[142:143]
	v_pk_mul_f32 v[64:65], v[64:65], v[144:145]
	v_pk_mul_f32 v[66:67], v[66:67], v[146:147]
	v_pk_mul_f32 v[68:69], v[68:69], v[132:133]
	v_pk_mul_f32 v[70:71], v[70:71], v[134:135]
	v_pk_mul_f32 v[72:73], v[72:73], v[136:137]
	v_pk_mul_f32 v[74:75], v[74:75], v[138:139]
	v_pk_mul_f32 v[76:77], v[76:77], v[140:141]
	v_pk_mul_f32 v[78:79], v[78:79], v[142:143]
	v_pk_mul_f32 v[80:81], v[80:81], v[144:145]
	v_pk_mul_f32 v[82:83], v[82:83], v[146:147]
	v_mov_b32_e32 v252, v253
	v_pk_add_f32 v[84:85], v[84:85], v[252:253] neg_lo:[0,1] neg_hi:[0,1]
	v_pk_add_f32 v[86:87], v[86:87], v[252:253] neg_lo:[0,1] neg_hi:[0,1]
	v_pk_add_f32 v[88:89], v[88:89], v[252:253] neg_lo:[0,1] neg_hi:[0,1]
	v_pk_add_f32 v[90:91], v[90:91], v[252:253] neg_lo:[0,1] neg_hi:[0,1]
	v_pk_add_f32 v[92:93], v[92:93], v[252:253] neg_lo:[0,1] neg_hi:[0,1]
	v_pk_add_f32 v[94:95], v[94:95], v[252:253] neg_lo:[0,1] neg_hi:[0,1]
	v_pk_add_f32 v[96:97], v[96:97], v[252:253] neg_lo:[0,1] neg_hi:[0,1]
	v_pk_add_f32 v[98:99], v[98:99], v[252:253] neg_lo:[0,1] neg_hi:[0,1]
	v_pk_add_f32 v[100:101], v[100:101], v[252:253] neg_lo:[0,1] neg_hi:[0,1]
	v_pk_add_f32 v[102:103], v[102:103], v[252:253] neg_lo:[0,1] neg_hi:[0,1]
	v_pk_add_f32 v[104:105], v[104:105], v[252:253] neg_lo:[0,1] neg_hi:[0,1]
	v_pk_add_f32 v[106:107], v[106:107], v[252:253] neg_lo:[0,1] neg_hi:[0,1]
	v_pk_add_f32 v[108:109], v[108:109], v[252:253] neg_lo:[0,1] neg_hi:[0,1]
	v_pk_add_f32 v[110:111], v[110:111], v[252:253] neg_lo:[0,1] neg_hi:[0,1]
	v_pk_add_f32 v[112:113], v[112:113], v[252:253] neg_lo:[0,1] neg_hi:[0,1]
	v_pk_add_f32 v[114:115], v[114:115], v[252:253] neg_lo:[0,1] neg_hi:[0,1]
	v_pk_add_f32 v[188:189], v[188:189], v[252:253] neg_lo:[0,1] neg_hi:[0,1]
	v_pk_add_f32 v[190:191], v[190:191], v[252:253] neg_lo:[0,1] neg_hi:[0,1]
	v_pk_add_f32 v[192:193], v[192:193], v[252:253] neg_lo:[0,1] neg_hi:[0,1]
	v_pk_add_f32 v[194:195], v[194:195], v[252:253] neg_lo:[0,1] neg_hi:[0,1]
	v_pk_add_f32 v[196:197], v[196:197], v[252:253] neg_lo:[0,1] neg_hi:[0,1]
	v_pk_add_f32 v[198:199], v[198:199], v[252:253] neg_lo:[0,1] neg_hi:[0,1]
	v_pk_add_f32 v[200:201], v[200:201], v[252:253] neg_lo:[0,1] neg_hi:[0,1]
	v_pk_add_f32 v[202:203], v[202:203], v[252:253] neg_lo:[0,1] neg_hi:[0,1]
	v_pk_add_f32 v[204:205], v[204:205], v[252:253] neg_lo:[0,1] neg_hi:[0,1]
	v_pk_add_f32 v[206:207], v[206:207], v[252:253] neg_lo:[0,1] neg_hi:[0,1]
	v_pk_add_f32 v[208:209], v[208:209], v[252:253] neg_lo:[0,1] neg_hi:[0,1]
	v_pk_add_f32 v[210:211], v[210:211], v[252:253] neg_lo:[0,1] neg_hi:[0,1]
	v_pk_add_f32 v[212:213], v[212:213], v[252:253] neg_lo:[0,1] neg_hi:[0,1]
	v_pk_add_f32 v[214:215], v[214:215], v[252:253] neg_lo:[0,1] neg_hi:[0,1]
	v_pk_add_f32 v[216:217], v[216:217], v[252:253] neg_lo:[0,1] neg_hi:[0,1]
	v_pk_add_f32 v[218:219], v[218:219], v[252:253] neg_lo:[0,1] neg_hi:[0,1]
	v_exp_f32_e32 v84, v84
	v_exp_f32_e32 v85, v85
	v_exp_f32_e32 v86, v86
	v_exp_f32_e32 v87, v87
	v_exp_f32_e32 v88, v88
	v_pk_add_f32 v[252:253], v[84:85], v[86:87]
	v_exp_f32_e32 v89, v89
	v_cvt_pk_bf16_f32 v84, v84, v85
	v_cvt_pk_bf16_f32 v85, v86, v87
	v_exp_f32_e32 v90, v90
	v_exp_f32_e32 v91, v91
	v_pk_add_f32 v[252:253], v[252:253], v[88:89]
	v_pk_add_f32 v[252:253], v[252:253], v[90:91]
	v_cvt_pk_bf16_f32 v86, v88, v89
	v_cvt_pk_bf16_f32 v87, v90, v91
	v_exp_f32_e32 v92, v92
	v_exp_f32_e32 v93, v93
	v_exp_f32_e32 v94, v94
	v_exp_f32_e32 v95, v95
	v_pk_add_f32 v[252:253], v[252:253], v[92:93]
	v_pk_add_f32 v[252:253], v[252:253], v[94:95]
	v_exp_f32_e32 v96, v96
	v_exp_f32_e32 v97, v97
	v_cvt_pk_bf16_f32 v88, v92, v93
	v_cvt_pk_bf16_f32 v89, v94, v95
	v_exp_f32_e32 v98, v98
	v_exp_f32_e32 v99, v99
	v_pk_add_f32 v[252:253], v[252:253], v[96:97]
	v_pk_add_f32 v[252:253], v[252:253], v[98:99]
	v_cvt_pk_bf16_f32 v90, v96, v97
	v_cvt_pk_bf16_f32 v91, v98, v99
	v_exp_f32_e32 v100, v100
	v_exp_f32_e32 v101, v101
	v_exp_f32_e32 v102, v102
	v_exp_f32_e32 v103, v103
	v_pk_add_f32 v[252:253], v[252:253], v[100:101]
	v_pk_add_f32 v[252:253], v[252:253], v[102:103]
	v_exp_f32_e32 v104, v104
	v_exp_f32_e32 v105, v105
	v_cvt_pk_bf16_f32 v100, v100, v101
	v_cvt_pk_bf16_f32 v101, v102, v103
	v_exp_f32_e32 v106, v106
	v_exp_f32_e32 v107, v107
	v_pk_add_f32 v[252:253], v[252:253], v[104:105]
	v_pk_add_f32 v[252:253], v[252:253], v[106:107]
	v_cvt_pk_bf16_f32 v102, v104, v105
	v_cvt_pk_bf16_f32 v103, v106, v107
	v_exp_f32_e32 v108, v108
	v_exp_f32_e32 v109, v109
	v_exp_f32_e32 v110, v110
	v_exp_f32_e32 v111, v111
	v_pk_add_f32 v[252:253], v[252:253], v[108:109]
	v_pk_add_f32 v[252:253], v[252:253], v[110:111]
	v_exp_f32_e32 v112, v112
	v_exp_f32_e32 v113, v113
	v_cvt_pk_bf16_f32 v104, v108, v109
; #define LAS __attribute__((address_space(3)))
; #define VREADS1(arr, d_) do { const unsigned ad_ = vbase ^ (unsigned)((d_) << 6); __builtin_amdgcn_sched_barrier(0); \
;         _Pragma("unroll") for (int ks_ = 0; ks_ < 4; ++ks_) { VTR(arr[ks_ * 2], ad_, ks_ * 4096); VTR(arr[ks_ * 2 + 1], ad_, ks_ * 4096 + 2048); } __builtin_amdgcn_sched_barrier(0); } while (0)
; __device__ __forceinline__ void attn_unit(LAS unsigned char* lds, const bf16_t* Z, bf16_t* A2, const float* tabg, int seq_base, int S, int h, int qb, float lam) {
;     ...
;         { const float coff = cc - mu;
;           if (__any(!(coff == coff_cur))) { coff_cur = coff;
; #pragma unroll
;               for (int r = 0; r < 16; ++r) cblk[r] = coff;
;               asm volatile("" : "+v"(cblk)); } }
;         f32x16 p0, p1;
;         {
;             bf16x8 kf[8];
; #pragma unroll
;             for (int ds = 0; ds < 4; ++ds) { kf[2 * ds] = *(const LAS bf16x8*)(Kt + (kfo ^ (unsigned)(ds << 5))); kf[2 * ds + 1] = *(const LAS bf16x8*)(Kt + 32 * 256 + (kfo ^ (unsigned)(ds << 5))); }
;             __builtin_amdgcn_sched_barrier(0);
;             p0 = __builtin_amdgcn_mfma_f32_32x32x16_bf16(kf[0], qf[0], cblk, 0, 0, 0);
;             p1 = __builtin_amdgcn_mfma_f32_32x32x16_bf16(kf[1], qf[0], cblk, 0, 0, 0);
; #pragma unroll
;             for (int ds = 1; ds < 4; ++ds) {
;                 p0 = __builtin_amdgcn_mfma_f32_32x32x16_bf16(kf[2 * ds], qf[ds], p0, 0, 0, 0);
;                 p1 = __builtin_amdgcn_mfma_f32_32x32x16_bf16(kf[2 * ds + 1], qf[ds], p1, 0, 0, 0);
;             }
;         }
;     ...
;         const unsigned vbase = (unsigned)(size_t)Vt + vfo;
;         s16x4 va[8], vb[8];
;         VREADS1(va, 0);
;         if (near) {
;             const LAS float* tp = tab + (kv0 + 4 * hi - (qlo + r32) + 224);
; #pragma unroll
;             for (int r = 0; r < 16; ++r) { p0[r] += tp[(r & 3) + 8 * (r >> 2)]; p1[r] += tp[32 + (r & 3) + 8 * (r >> 2)]; }
;         }
	v_cvt_pk_bf16_f32 v105, v110, v111
	v_exp_f32_e32 v114, v114
	v_exp_f32_e32 v115, v115
	v_pk_add_f32 v[252:253], v[252:253], v[112:113]
	v_pk_add_f32 v[252:253], v[252:253], v[114:115]
	v_cvt_pk_bf16_f32 v106, v112, v113
	v_cvt_pk_bf16_f32 v107, v114, v115
	s_mov_b32 s37, s43
	s_mov_b32 s35, s37
	v_mov_b32_e32 v251, 0
	s_cmp_eq_u32 s37, 1
	s_cselect_b64 vcc, -1, 0
	v_cndmask_b32_e32 v251, v251, v177, vcc
	s_cmp_eq_u32 s37, 2
	s_cselect_b64 vcc, -1, 0
	v_cndmask_b32_e32 v251, v251, v178, vcc
	v_sub_f32_e32 v2, v251, v186
	v_mov_b32_e32 v3, v2
	v_mov_b64_e32 v[4:5], v[2:3]
	v_mov_b64_e32 v[6:7], v[2:3]
	v_mov_b64_e32 v[8:9], v[2:3]
	v_mov_b64_e32 v[10:11], v[2:3]
	v_mov_b64_e32 v[12:13], v[2:3]
	v_mov_b64_e32 v[14:15], v[2:3]
	v_mov_b64_e32 v[16:17], v[2:3]
	ds_read_b64_tr_b16 v[132:133], v228 offset:0
	ds_read_b64_tr_b16 v[134:135], v228 offset:2048
	ds_read_b64_tr_b16 v[136:137], v229 offset:0
	ds_read_b64_tr_b16 v[138:139], v229 offset:2048
	ds_read_b64_tr_b16 v[140:141], v230 offset:0
	ds_read_b64_tr_b16 v[142:143], v230 offset:2048
	ds_read_b64_tr_b16 v[144:145], v231 offset:0
	ds_read_b64_tr_b16 v[146:147], v231 offset:2048
	ds_read_b64_tr_b16 v[220:221], v228 offset:4096
	ds_read_b64_tr_b16 v[222:223], v228 offset:6144
	ds_read_b64_tr_b16 v[224:225], v229 offset:4096
	ds_read_b64_tr_b16 v[226:227], v229 offset:6144
	ds_read_b64_tr_b16 v[232:233], v230 offset:4096
	ds_read_b64_tr_b16 v[234:235], v230 offset:6144
	s_nop 1
	s_cmp_eq_u32 s42, 0
	s_cbranch_scc1 .LatA_recret_h0
	s_cmp_eq_u32 s42, 1
	s_cbranch_scc1 .LatA_recret_m0
	s_branch .LatA_recret_x4
.LatA_rec_1:
	s_waitcnt lgkmcnt(0)
	s_nop 15
	s_sub_u32 s5, s8, s4
	s_lshr_b32 s5, s5, 12
	s_sub_u32 s5, s5, 64
	s_cmp_lt_u32 s5, s11
	s_cselect_b32 s37, 1, 0
	s_cmp_gt_u32 s5, s31
	s_cselect_b32 s40, 2, 0
	s_or_b32 s37, s37, s40
	s_mov_b32 s43, s35
	s_mov_b32 s35, s37
	v_mov_b32_e32 v251, 0
	s_cmp_eq_u32 s37, 1
	s_cselect_b64 vcc, -1, 0
	v_cndmask_b32_e32 v251, v251, v177, vcc
	s_cmp_eq_u32 s37, 2
	s_cselect_b64 vcc, -1, 0
	v_cndmask_b32_e32 v251, v251, v178, vcc
	v_sub_f32_e32 v2, v251, v186
	v_mov_b32_e32 v3, v2
	v_mov_b64_e32 v[4:5], v[2:3]
	v_mov_b64_e32 v[6:7], v[2:3]
	v_mov_b64_e32 v[8:9], v[2:3]
	v_mov_b64_e32 v[10:11], v[2:3]
	v_mov_b64_e32 v[12:13], v[2:3]
	v_mov_b64_e32 v[14:15], v[2:3]
	v_mov_b64_e32 v[16:17], v[2:3]
	s_nop 1
	ds_read_b128 v[132:135], v19 offset:16384
	ds_read_b128 v[136:139], v19 offset:24576
	ds_read_b128 v[140:143], v180 offset:16384
	ds_read_b128 v[144:147], v180 offset:24576
	ds_read_b128 v[220:223], v181 offset:16384
	ds_read_b128 v[224:227], v181 offset:24576
	ds_read_b128 v[232:235], v182 offset:16384
	ds_read_b128 v[236:239], v182 offset:24576
	s_waitcnt lgkmcnt(7)
	v_mfma_f32_32x32x16_bf16 v[188:203], v[132:135], v[116:119], v[2:17]
	s_waitcnt lgkmcnt(6)
	v_mfma_f32_32x32x16_bf16 v[204:219], v[136:139], v[116:119], v[2:17]
	s_waitcnt lgkmcnt(5)
	v_mfma_f32_32x32x16_bf16 v[188:203], v[140:143], v[120:123], v[188:203]
	s_waitcnt lgkmcnt(4)
	v_mfma_f32_32x32x16_bf16 v[204:219], v[144:147], v[120:123], v[204:219]
	s_waitcnt lgkmcnt(3)
	v_mfma_f32_32x32x16_bf16 v[188:203], v[220:223], v[124:127], v[188:203]
	s_waitcnt lgkmcnt(2)
	v_mfma_f32_32x32x16_bf16 v[204:219], v[224:227], v[124:127], v[204:219]
	s_waitcnt lgkmcnt(1)
	v_mfma_f32_32x32x16_bf16 v[188:203], v[232:235], v[128:131], v[188:203]
	s_waitcnt lgkmcnt(0)
	v_mfma_f32_32x32x16_bf16 v[204:219], v[236:239], v[128:131], v[204:219]
	s_nop 15
	s_nop 15
	s_cmp_lg_u32 s35, 0
	s_cbranch_scc1 .LatA_recnn_1
	s_lshl_b32 s38, s5, 2
	s_add_i32 s38, s38, 0x18b80
	v_add_u32_e32 v187, s38, v162
	ds_read2_b32 v[132:133], v187 offset0:0 offset1:1
	ds_read2_b32 v[134:135], v187 offset0:2 offset1:3
	ds_read2_b32 v[136:137], v187 offset0:8 offset1:9
	ds_read2_b32 v[138:139], v187 offset0:10 offset1:11
	ds_read2_b32 v[140:141], v187 offset0:16 offset1:17
	ds_read2_b32 v[142:143], v187 offset0:18 offset1:19
	ds_read2_b32 v[144:145], v187 offset0:24 offset1:25
	ds_read2_b32 v[146:147], v187 offset0:26 offset1:27
	s_waitcnt lgkmcnt(0)
	v_pk_add_f32 v[188:189], v[188:189], v[132:133]
	v_pk_add_f32 v[190:191], v[190:191], v[134:135]
	v_pk_add_f32 v[192:193], v[192:193], v[136:137]
	v_pk_add_f32 v[194:195], v[194:195], v[138:139]
	v_pk_add_f32 v[196:197], v[196:197], v[140:141]
	v_pk_add_f32 v[198:199], v[198:199], v[142:143]
	v_pk_add_f32 v[200:201], v[200:201], v[144:145]
	v_pk_add_f32 v[202:203], v[202:203], v[146:147]
	ds_read2_b32 v[132:133], v187 offset0:32 offset1:33
	ds_read2_b32 v[134:135], v187 offset0:34 offset1:35
	ds_read2_b32 v[136:137], v187 offset0:40 offset1:41
	ds_read2_b32 v[138:139], v187 offset0:42 offset1:43
	ds_read2_b32 v[140:141], v187 offset0:48 offset1:49
	ds_read2_b32 v[142:143], v187 offset0:50 offset1:51
	ds_read2_b32 v[144:145], v187 offset0:56 offset1:57
	ds_read2_b32 v[146:147], v187 offset0:58 offset1:59
	s_waitcnt lgkmcnt(0)
	v_pk_add_f32 v[204:205], v[204:205], v[132:133]
	v_pk_add_f32 v[206:207], v[206:207], v[134:135]
	v_pk_add_f32 v[208:209], v[208:209], v[136:137]
	v_pk_add_f32 v[210:211], v[210:211], v[138:139]
	v_pk_add_f32 v[212:213], v[212:213], v[140:141]
	v_pk_add_f32 v[214:215], v[214:215], v[142:143]
	v_pk_add_f32 v[216:217], v[216:217], v[144:145]
	v_pk_add_f32 v[218:219], v[218:219], v[146:147]
; #define LAS __attribute__((address_space(3)))
; __device__ __forceinline__ float max2f(float a, float b) { float r; asm("v_max_f32_e32 %0, %1, %2" : "=v"(r) : "v"(a), "v"(b)); return r; }
; __device__ __forceinline__ void attn_unit(LAS unsigned char* lds, const bf16_t* Z, bf16_t* A2, const float* tabg, int seq_base, int S, int h, int qb, float lam) {
;     ...
;         float mx = max2f(max16f(p0), max16f(p1));
;         const bool first = (t == 0);
;         if (first || __any(mx > THR)) {
;             { auto rr = __builtin_amdgcn_permlane32_swap(__float_as_uint(mx), __float_as_uint(mx), false, false); mx = max2f(__uint_as_float(rr[0]), __uint_as_float(rr[1])); }
;             const float delta = first ? mx : fmaxf(mx, 0.f);
;             const float alpha = first ? 1.0f : __builtin_amdgcn_exp2f(-delta);
;             mu += delta; ls2 *= alpha;
;             if (!first) {
;                 asm volatile("" ::: "memory");
;                 scr[r32] = alpha;
;                 asm volatile("s_waitcnt lgkmcnt(0)" ::: "memory");
; #pragma unroll
;                 for (int g = 0; g < 4; ++g) { const f32x4 a4 = *(const LAS f32x4*)(scr + 8 * g + 4 * hi);
; #pragma unroll
;                     for (int d = 0; d < 4; ++d) { O[d][4 * g + 0] *= a4[0]; O[d][4 * g + 1] *= a4[1]; O[d][4 * g + 2] *= a4[2]; O[d][4 * g + 3] *= a4[3]; } }
;                 asm volatile("s_waitcnt lgkmcnt(0)" ::: "memory");
;             }
; #pragma unroll
;             for (int r = 0; r < 16; ++r) { p0[r] -= delta; p1[r] -= delta; }
;             asm volatile("" : "+v"(p0), "+v"(p1));
;         }
; #pragma unroll
;         for (int r = 0; r < 16; ++r) { p0[r] = __builtin_amdgcn_exp2f(p0[r]); p1[r] = __builtin_amdgcn_exp2f(p1[r]); }
; #pragma unroll
;         for (int r = 0; r < 16; r += 2) { ls2 += (f32x2){p0[r], p0[r + 1]}; ls2 += (f32x2){p1[r], p1[r + 1]}; }
;         bf16x8 pa[4]; pa[0] = pack8(p0, 0); pa[1] = pack8(p0, 8); pa[2] = pack8(p1, 0); pa[3] = pack8(p1, 8);
.LatA_recnn_1:
	v_max3_f32 v251, v188, v189, v190
	v_max3_f32 v252, v191, v192, v193
	v_max3_f32 v251, v251, v194, v195
	v_max3_f32 v252, v252, v196, v197
	v_max3_f32 v251, v251, v198, v199
	v_max3_f32 v252, v252, v200, v201
	v_max3_f32 v251, v251, v202, v203
	v_max3_f32 v252, v252, v204, v205
	v_max3_f32 v251, v251, v206, v207
	v_max3_f32 v252, v252, v208, v209
	v_max3_f32 v251, v251, v210, v211
	v_max3_f32 v252, v252, v212, v213
	v_max3_f32 v251, v251, v214, v215
	v_max3_f32 v252, v252, v216, v217
	v_max3_f32 v251, v251, v218, v219
	v_max_f32_e32 v251, v251, v252
	v_mov_b32_e32 v252, v251
	s_nop 1
	v_permlane32_swap_b32_e32 v251, v252
	v_max_f32_e32 v251, v251, v252
	v_max_f32_e32 v253, 0, v251
	v_exp_f32_e64 v254, -v253
	v_add_f32_e32 v186, v186, v253
	s_nop 0
	v_mul_f32_e32 v150, v150, v254
	v_mul_f32_e32 v151, v151, v254
	ds_write_b32 v184, v254
	s_waitcnt lgkmcnt(0)
	ds_read_b128 v[132:135], v185
	ds_read_b128 v[136:139], v185 offset:32
	ds_read_b128 v[140:143], v185 offset:64
	ds_read_b128 v[144:147], v185 offset:96
	s_waitcnt lgkmcnt(0)
	v_pk_mul_f32 v[20:21], v[20:21], v[132:133]
	v_pk_mul_f32 v[22:23], v[22:23], v[134:135]
	v_pk_mul_f32 v[24:25], v[24:25], v[136:137]
	v_pk_mul_f32 v[26:27], v[26:27], v[138:139]
	v_pk_mul_f32 v[28:29], v[28:29], v[140:141]
	v_pk_mul_f32 v[30:31], v[30:31], v[142:143]
	v_pk_mul_f32 v[32:33], v[32:33], v[144:145]
	v_pk_mul_f32 v[34:35], v[34:35], v[146:147]
	v_pk_mul_f32 v[36:37], v[36:37], v[132:133]
	v_pk_mul_f32 v[38:39], v[38:39], v[134:135]
	v_pk_mul_f32 v[40:41], v[40:41], v[136:137]
	v_pk_mul_f32 v[42:43], v[42:43], v[138:139]
	v_pk_mul_f32 v[44:45], v[44:45], v[140:141]
	v_pk_mul_f32 v[46:47], v[46:47], v[142:143]
	v_pk_mul_f32 v[48:49], v[48:49], v[144:145]
	v_pk_mul_f32 v[50:51], v[50:51], v[146:147]
	v_pk_mul_f32 v[52:53], v[52:53], v[132:133]
	v_pk_mul_f32 v[54:55], v[54:55], v[134:135]
	v_pk_mul_f32 v[56:57], v[56:57], v[136:137]
	v_pk_mul_f32 v[58:59], v[58:59], v[138:139]
	v_pk_mul_f32 v[60:61], v[60:61], v[140:141]
	v_pk_mul_f32 v[62:63], v[62:63], v[142:143]
	v_pk_mul_f32 v[64:65], v[64:65], v[144:145]
	v_pk_mul_f32 v[66:67], v[66:67], v[146:147]
	v_pk_mul_f32 v[68:69], v[68:69], v[132:133]
	v_pk_mul_f32 v[70:71], v[70:71], v[134:135]
	v_pk_mul_f32 v[72:73], v[72:73], v[136:137]
	v_pk_mul_f32 v[74:75], v[74:75], v[138:139]
	v_pk_mul_f32 v[76:77], v[76:77], v[140:141]
	v_pk_mul_f32 v[78:79], v[78:79], v[142:143]
	v_pk_mul_f32 v[80:81], v[80:81], v[144:145]
	v_pk_mul_f32 v[82:83], v[82:83], v[146:147]
	v_mov_b32_e32 v252, v253
	v_pk_add_f32 v[188:189], v[188:189], v[252:253] neg_lo:[0,1] neg_hi:[0,1]
	v_pk_add_f32 v[190:191], v[190:191], v[252:253] neg_lo:[0,1] neg_hi:[0,1]
	v_pk_add_f32 v[192:193], v[192:193], v[252:253] neg_lo:[0,1] neg_hi:[0,1]
	v_pk_add_f32 v[194:195], v[194:195], v[252:253] neg_lo:[0,1] neg_hi:[0,1]
	v_pk_add_f32 v[196:197], v[196:197], v[252:253] neg_lo:[0,1] neg_hi:[0,1]
	v_pk_add_f32 v[198:199], v[198:199], v[252:253] neg_lo:[0,1] neg_hi:[0,1]
	v_pk_add_f32 v[200:201], v[200:201], v[252:253] neg_lo:[0,1] neg_hi:[0,1]
	v_pk_add_f32 v[202:203], v[202:203], v[252:253] neg_lo:[0,1] neg_hi:[0,1]
	v_pk_add_f32 v[204:205], v[204:205], v[252:253] neg_lo:[0,1] neg_hi:[0,1]
	v_pk_add_f32 v[206:207], v[206:207], v[252:253] neg_lo:[0,1] neg_hi:[0,1]
	v_pk_add_f32 v[208:209], v[208:209], v[252:253] neg_lo:[0,1] neg_hi:[0,1]
	v_pk_add_f32 v[210:211], v[210:211], v[252:253] neg_lo:[0,1] neg_hi:[0,1]
	v_pk_add_f32 v[212:213], v[212:213], v[252:253] neg_lo:[0,1] neg_hi:[0,1]
	v_pk_add_f32 v[214:215], v[214:215], v[252:253] neg_lo:[0,1] neg_hi:[0,1]
	v_pk_add_f32 v[216:217], v[216:217], v[252:253] neg_lo:[0,1] neg_hi:[0,1]
	v_pk_add_f32 v[218:219], v[218:219], v[252:253] neg_lo:[0,1] neg_hi:[0,1]
	v_pk_add_f32 v[84:85], v[84:85], v[252:253] neg_lo:[0,1] neg_hi:[0,1]
	v_pk_add_f32 v[86:87], v[86:87], v[252:253] neg_lo:[0,1] neg_hi:[0,1]
	v_pk_add_f32 v[88:89], v[88:89], v[252:253] neg_lo:[0,1] neg_hi:[0,1]
	v_pk_add_f32 v[90:91], v[90:91], v[252:253] neg_lo:[0,1] neg_hi:[0,1]
	v_pk_add_f32 v[92:93], v[92:93], v[252:253] neg_lo:[0,1] neg_hi:[0,1]
	v_pk_add_f32 v[94:95], v[94:95], v[252:253] neg_lo:[0,1] neg_hi:[0,1]
	v_pk_add_f32 v[96:97], v[96:97], v[252:253] neg_lo:[0,1] neg_hi:[0,1]
	v_pk_add_f32 v[98:99], v[98:99], v[252:253] neg_lo:[0,1] neg_hi:[0,1]
	v_pk_add_f32 v[100:101], v[100:101], v[252:253] neg_lo:[0,1] neg_hi:[0,1]
	v_pk_add_f32 v[102:103], v[102:103], v[252:253] neg_lo:[0,1] neg_hi:[0,1]
	v_pk_add_f32 v[104:105], v[104:105], v[252:253] neg_lo:[0,1] neg_hi:[0,1]
	v_pk_add_f32 v[106:107], v[106:107], v[252:253] neg_lo:[0,1] neg_hi:[0,1]
	v_pk_add_f32 v[108:109], v[108:109], v[252:253] neg_lo:[0,1] neg_hi:[0,1]
	v_pk_add_f32 v[110:111], v[110:111], v[252:253] neg_lo:[0,1] neg_hi:[0,1]
	v_pk_add_f32 v[112:113], v[112:113], v[252:253] neg_lo:[0,1] neg_hi:[0,1]
	v_pk_add_f32 v[114:115], v[114:115], v[252:253] neg_lo:[0,1] neg_hi:[0,1]
	v_exp_f32_e32 v188, v188
	v_exp_f32_e32 v189, v189
	v_exp_f32_e32 v190, v190
	v_exp_f32_e32 v191, v191
	v_exp_f32_e32 v192, v192
	v_pk_add_f32 v[252:253], v[188:189], v[190:191]
	v_exp_f32_e32 v193, v193
	v_cvt_pk_bf16_f32 v188, v188, v189
	v_cvt_pk_bf16_f32 v189, v190, v191
	v_exp_f32_e32 v194, v194
	v_exp_f32_e32 v195, v195
	v_pk_add_f32 v[252:253], v[252:253], v[192:193]
	v_pk_add_f32 v[252:253], v[252:253], v[194:195]
	v_cvt_pk_bf16_f32 v190, v192, v193
	v_cvt_pk_bf16_f32 v191, v194, v195
	v_exp_f32_e32 v196, v196
	v_exp_f32_e32 v197, v197
	v_exp_f32_e32 v198, v198
	v_exp_f32_e32 v199, v199
	v_pk_add_f32 v[252:253], v[252:253], v[196:197]
	v_pk_add_f32 v[252:253], v[252:253], v[198:199]
	v_exp_f32_e32 v200, v200
	v_exp_f32_e32 v201, v201
; #define LAS __attribute__((address_space(3)))
; #define VREADS1(arr, d_) do { const unsigned ad_ = vbase ^ (unsigned)((d_) << 6); __builtin_amdgcn_sched_barrier(0); \
;         _Pragma("unroll") for (int ks_ = 0; ks_ < 4; ++ks_) { VTR(arr[ks_ * 2], ad_, ks_ * 4096); VTR(arr[ks_ * 2 + 1], ad_, ks_ * 4096 + 2048); } __builtin_amdgcn_sched_barrier(0); } while (0)
; __device__ __forceinline__ void attn_unit(LAS unsigned char* lds, const bf16_t* Z, bf16_t* A2, const float* tabg, int seq_base, int S, int h, int qb, float lam) {
;     ...
;         { const float coff = cc - mu;
;           if (__any(!(coff == coff_cur))) { coff_cur = coff;
; #pragma unroll
;               for (int r = 0; r < 16; ++r) cblk[r] = coff;
;               asm volatile("" : "+v"(cblk)); } }
;         f32x16 p0, p1;
;         {
;             bf16x8 kf[8];
; #pragma unroll
;             for (int ds = 0; ds < 4; ++ds) { kf[2 * ds] = *(const LAS bf16x8*)(Kt + (kfo ^ (unsigned)(ds << 5))); kf[2 * ds + 1] = *(const LAS bf16x8*)(Kt + 32 * 256 + (kfo ^ (unsigned)(ds << 5))); }
;             __builtin_amdgcn_sched_barrier(0);
;             p0 = __builtin_amdgcn_mfma_f32_32x32x16_bf16(kf[0], qf[0], cblk, 0, 0, 0);
;             p1 = __builtin_amdgcn_mfma_f32_32x32x16_bf16(kf[1], qf[0], cblk, 0, 0, 0);
; #pragma unroll
;             for (int ds = 1; ds < 4; ++ds) {
;                 p0 = __builtin_amdgcn_mfma_f32_32x32x16_bf16(kf[2 * ds], qf[ds], p0, 0, 0, 0);
;                 p1 = __builtin_amdgcn_mfma_f32_32x32x16_bf16(kf[2 * ds + 1], qf[ds], p1, 0, 0, 0);
;             }
;         }
;     ...
;         const unsigned vbase = (unsigned)(size_t)Vt + vfo;
;         s16x4 va[8], vb[8];
;         VREADS1(va, 0);
;         if (near) {
;             const LAS float* tp = tab + (kv0 + 4 * hi - (qlo + r32) + 224);
; #pragma unroll
;             for (int r = 0; r < 16; ++r) { p0[r] += tp[(r & 3) + 8 * (r >> 2)]; p1[r] += tp[32 + (r & 3) + 8 * (r >> 2)]; }
;         }
	v_cvt_pk_bf16_f32 v192, v196, v197
	v_cvt_pk_bf16_f32 v193, v198, v199
	v_exp_f32_e32 v202, v202
	v_exp_f32_e32 v203, v203
	v_pk_add_f32 v[252:253], v[252:253], v[200:201]
	v_pk_add_f32 v[252:253], v[252:253], v[202:203]
	v_cvt_pk_bf16_f32 v194, v200, v201
	v_cvt_pk_bf16_f32 v195, v202, v203
	v_exp_f32_e32 v204, v204
	v_exp_f32_e32 v205, v205
	v_exp_f32_e32 v206, v206
	v_exp_f32_e32 v207, v207
	v_pk_add_f32 v[252:253], v[252:253], v[204:205]
	v_pk_add_f32 v[252:253], v[252:253], v[206:207]
	v_exp_f32_e32 v208, v208
	v_exp_f32_e32 v209, v209
	v_cvt_pk_bf16_f32 v204, v204, v205
	v_cvt_pk_bf16_f32 v205, v206, v207
	v_exp_f32_e32 v210, v210
	v_exp_f32_e32 v211, v211
	v_pk_add_f32 v[252:253], v[252:253], v[208:209]
	v_pk_add_f32 v[252:253], v[252:253], v[210:211]
	v_cvt_pk_bf16_f32 v206, v208, v209
	v_cvt_pk_bf16_f32 v207, v210, v211
	v_exp_f32_e32 v212, v212
	v_exp_f32_e32 v213, v213
	v_exp_f32_e32 v214, v214
	v_exp_f32_e32 v215, v215
	v_pk_add_f32 v[252:253], v[252:253], v[212:213]
	v_pk_add_f32 v[252:253], v[252:253], v[214:215]
	v_exp_f32_e32 v216, v216
	v_exp_f32_e32 v217, v217
	v_cvt_pk_bf16_f32 v208, v212, v213
	v_cvt_pk_bf16_f32 v209, v214, v215
	v_exp_f32_e32 v218, v218
	v_exp_f32_e32 v219, v219
	v_pk_add_f32 v[252:253], v[252:253], v[216:217]
	v_pk_add_f32 v[252:253], v[252:253], v[218:219]
	v_cvt_pk_bf16_f32 v210, v216, v217
	v_cvt_pk_bf16_f32 v211, v218, v219
	s_mov_b32 s37, s43
	s_mov_b32 s35, s37
	v_mov_b32_e32 v251, 0
	s_cmp_eq_u32 s37, 1
	s_cselect_b64 vcc, -1, 0
	v_cndmask_b32_e32 v251, v251, v177, vcc
	s_cmp_eq_u32 s37, 2
	s_cselect_b64 vcc, -1, 0
	v_cndmask_b32_e32 v251, v251, v178, vcc
	v_sub_f32_e32 v2, v251, v186
	v_mov_b32_e32 v3, v2
	v_mov_b64_e32 v[4:5], v[2:3]
	v_mov_b64_e32 v[6:7], v[2:3]
	v_mov_b64_e32 v[8:9], v[2:3]
	v_mov_b64_e32 v[10:11], v[2:3]
	v_mov_b64_e32 v[12:13], v[2:3]
	v_mov_b64_e32 v[14:15], v[2:3]
	v_mov_b64_e32 v[16:17], v[2:3]
	ds_read_b64_tr_b16 v[132:133], v228 offset:16384
	ds_read_b64_tr_b16 v[134:135], v228 offset:18432
	ds_read_b64_tr_b16 v[136:137], v229 offset:16384
	ds_read_b64_tr_b16 v[138:139], v229 offset:18432
	ds_read_b64_tr_b16 v[140:141], v230 offset:16384
	ds_read_b64_tr_b16 v[142:143], v230 offset:18432
	ds_read_b64_tr_b16 v[144:145], v231 offset:16384
	ds_read_b64_tr_b16 v[146:147], v231 offset:18432
	ds_read_b64_tr_b16 v[220:221], v228 offset:20480
	ds_read_b64_tr_b16 v[222:223], v228 offset:22528
	ds_read_b64_tr_b16 v[224:225], v229 offset:20480
	ds_read_b64_tr_b16 v[226:227], v229 offset:22528
	ds_read_b64_tr_b16 v[232:233], v230 offset:20480
	ds_read_b64_tr_b16 v[234:235], v230 offset:22528
	s_nop 1
	s_cmp_eq_u32 s42, 0
	s_cbranch_scc1 .LatA_recret_h1
	s_cmp_eq_u32 s42, 1
	s_cbranch_scc1 .LatA_recret_m1
	s_branch .LatA_recret_x3
.LatA_rec_2:
	s_waitcnt lgkmcnt(0)
	s_nop 15
	s_sub_u32 s5, s8, s4
	s_lshr_b32 s5, s5, 12
	s_sub_u32 s5, s5, 64
	s_cmp_lt_u32 s5, s11
	s_cselect_b32 s37, 1, 0
	s_cmp_gt_u32 s5, s31
	s_cselect_b32 s40, 2, 0
	s_or_b32 s37, s37, s40
	s_mov_b32 s43, s35
	s_mov_b32 s35, s37
	v_mov_b32_e32 v251, 0
	s_cmp_eq_u32 s37, 1
	s_cselect_b64 vcc, -1, 0
	v_cndmask_b32_e32 v251, v251, v177, vcc
	s_cmp_eq_u32 s37, 2
	s_cselect_b64 vcc, -1, 0
	v_cndmask_b32_e32 v251, v251, v178, vcc
	v_sub_f32_e32 v2, v251, v186
	v_mov_b32_e32 v3, v2
	v_mov_b64_e32 v[4:5], v[2:3]
	v_mov_b64_e32 v[6:7], v[2:3]
	v_mov_b64_e32 v[8:9], v[2:3]
	v_mov_b64_e32 v[10:11], v[2:3]
	v_mov_b64_e32 v[12:13], v[2:3]
	v_mov_b64_e32 v[14:15], v[2:3]
	v_mov_b64_e32 v[16:17], v[2:3]
	s_nop 1
	ds_read_b128 v[132:135], v19 offset:32768
	ds_read_b128 v[136:139], v19 offset:40960
	ds_read_b128 v[140:143], v180 offset:32768
	ds_read_b128 v[144:147], v180 offset:40960
	ds_read_b128 v[220:223], v181 offset:32768
	ds_read_b128 v[224:227], v181 offset:40960
	ds_read_b128 v[232:235], v182 offset:32768
	ds_read_b128 v[236:239], v182 offset:40960
	s_waitcnt lgkmcnt(7)
	v_mfma_f32_32x32x16_bf16 v[84:99], v[132:135], v[116:119], v[2:17]
	s_waitcnt lgkmcnt(6)
	v_mfma_f32_32x32x16_bf16 v[100:115], v[136:139], v[116:119], v[2:17]
	s_waitcnt lgkmcnt(5)
	v_mfma_f32_32x32x16_bf16 v[84:99], v[140:143], v[120:123], v[84:99]
	s_waitcnt lgkmcnt(4)
	v_mfma_f32_32x32x16_bf16 v[100:115], v[144:147], v[120:123], v[100:115]
	s_waitcnt lgkmcnt(3)
	v_mfma_f32_32x32x16_bf16 v[84:99], v[220:223], v[124:127], v[84:99]
	s_waitcnt lgkmcnt(2)
	v_mfma_f32_32x32x16_bf16 v[100:115], v[224:227], v[124:127], v[100:115]
	s_waitcnt lgkmcnt(1)
	v_mfma_f32_32x32x16_bf16 v[84:99], v[232:235], v[128:131], v[84:99]
	s_waitcnt lgkmcnt(0)
	v_mfma_f32_32x32x16_bf16 v[100:115], v[236:239], v[128:131], v[100:115]
	s_nop 15
	s_nop 15
	s_cmp_lg_u32 s35, 0
	s_cbranch_scc1 .LatA_recnn_2
	s_lshl_b32 s38, s5, 2
	s_add_i32 s38, s38, 0x18b80
	v_add_u32_e32 v187, s38, v162
	ds_read2_b32 v[132:133], v187 offset0:0 offset1:1
	ds_read2_b32 v[134:135], v187 offset0:2 offset1:3
	ds_read2_b32 v[136:137], v187 offset0:8 offset1:9
	ds_read2_b32 v[138:139], v187 offset0:10 offset1:11
	ds_read2_b32 v[140:141], v187 offset0:16 offset1:17
	ds_read2_b32 v[142:143], v187 offset0:18 offset1:19
	ds_read2_b32 v[144:145], v187 offset0:24 offset1:25
	ds_read2_b32 v[146:147], v187 offset0:26 offset1:27
	s_waitcnt lgkmcnt(0)
	v_pk_add_f32 v[84:85], v[84:85], v[132:133]
	v_pk_add_f32 v[86:87], v[86:87], v[134:135]
	v_pk_add_f32 v[88:89], v[88:89], v[136:137]
	v_pk_add_f32 v[90:91], v[90:91], v[138:139]
	v_pk_add_f32 v[92:93], v[92:93], v[140:141]
	v_pk_add_f32 v[94:95], v[94:95], v[142:143]
	v_pk_add_f32 v[96:97], v[96:97], v[144:145]
	v_pk_add_f32 v[98:99], v[98:99], v[146:147]
	ds_read2_b32 v[132:133], v187 offset0:32 offset1:33
	ds_read2_b32 v[134:135], v187 offset0:34 offset1:35
	ds_read2_b32 v[136:137], v187 offset0:40 offset1:41
	ds_read2_b32 v[138:139], v187 offset0:42 offset1:43
	ds_read2_b32 v[140:141], v187 offset0:48 offset1:49
	ds_read2_b32 v[142:143], v187 offset0:50 offset1:51
	ds_read2_b32 v[144:145], v187 offset0:56 offset1:57
	ds_read2_b32 v[146:147], v187 offset0:58 offset1:59
	s_waitcnt lgkmcnt(0)
	v_pk_add_f32 v[100:101], v[100:101], v[132:133]
	v_pk_add_f32 v[102:103], v[102:103], v[134:135]
	v_pk_add_f32 v[104:105], v[104:105], v[136:137]
	v_pk_add_f32 v[106:107], v[106:107], v[138:139]
	v_pk_add_f32 v[108:109], v[108:109], v[140:141]
	v_pk_add_f32 v[110:111], v[110:111], v[142:143]
	v_pk_add_f32 v[112:113], v[112:113], v[144:145]
	v_pk_add_f32 v[114:115], v[114:115], v[146:147]
; #define LAS __attribute__((address_space(3)))
; __device__ __forceinline__ float max2f(float a, float b) { float r; asm("v_max_f32_e32 %0, %1, %2" : "=v"(r) : "v"(a), "v"(b)); return r; }
; __device__ __forceinline__ void attn_unit(LAS unsigned char* lds, const bf16_t* Z, bf16_t* A2, const float* tabg, int seq_base, int S, int h, int qb, float lam) {
;     ...
;         float mx = max2f(max16f(p0), max16f(p1));
;         const bool first = (t == 0);
;         if (first || __any(mx > THR)) {
;             { auto rr = __builtin_amdgcn_permlane32_swap(__float_as_uint(mx), __float_as_uint(mx), false, false); mx = max2f(__uint_as_float(rr[0]), __uint_as_float(rr[1])); }
;             const float delta = first ? mx : fmaxf(mx, 0.f);
;             const float alpha = first ? 1.0f : __builtin_amdgcn_exp2f(-delta);
;             mu += delta; ls2 *= alpha;
;             if (!first) {
;                 asm volatile("" ::: "memory");
;                 scr[r32] = alpha;
;                 asm volatile("s_waitcnt lgkmcnt(0)" ::: "memory");
; #pragma unroll
;                 for (int g = 0; g < 4; ++g) { const f32x4 a4 = *(const LAS f32x4*)(scr + 8 * g + 4 * hi);
; #pragma unroll
;                     for (int d = 0; d < 4; ++d) { O[d][4 * g + 0] *= a4[0]; O[d][4 * g + 1] *= a4[1]; O[d][4 * g + 2] *= a4[2]; O[d][4 * g + 3] *= a4[3]; } }
;                 asm volatile("s_waitcnt lgkmcnt(0)" ::: "memory");
;             }
; #pragma unroll
;             for (int r = 0; r < 16; ++r) { p0[r] -= delta; p1[r] -= delta; }
;             asm volatile("" : "+v"(p0), "+v"(p1));
;         }
; #pragma unroll
;         for (int r = 0; r < 16; ++r) { p0[r] = __builtin_amdgcn_exp2f(p0[r]); p1[r] = __builtin_amdgcn_exp2f(p1[r]); }
; #pragma unroll
;         for (int r = 0; r < 16; r += 2) { ls2 += (f32x2){p0[r], p0[r + 1]}; ls2 += (f32x2){p1[r], p1[r + 1]}; }
;         bf16x8 pa[4]; pa[0] = pack8(p0, 0); pa[1] = pack8(p0, 8); pa[2] = pack8(p1, 0); pa[3] = pack8(p1, 8);
.LatA_recnn_2:
	v_max3_f32 v251, v84, v85, v86
	v_max3_f32 v252, v87, v88, v89
	v_max3_f32 v251, v251, v90, v91
	v_max3_f32 v252, v252, v92, v93
	v_max3_f32 v251, v251, v94, v95
	v_max3_f32 v252, v252, v96, v97
	v_max3_f32 v251, v251, v98, v99
	v_max3_f32 v252, v252, v100, v101
	v_max3_f32 v251, v251, v102, v103
	v_max3_f32 v252, v252, v104, v105
	v_max3_f32 v251, v251, v106, v107
	v_max3_f32 v252, v252, v108, v109
	v_max3_f32 v251, v251, v110, v111
	v_max3_f32 v252, v252, v112, v113
	v_max3_f32 v251, v251, v114, v115
	v_max_f32_e32 v251, v251, v252
	v_mov_b32_e32 v252, v251
	s_nop 1
	v_permlane32_swap_b32_e32 v251, v252
	v_max_f32_e32 v251, v251, v252
	v_max_f32_e32 v253, 0, v251
	v_exp_f32_e64 v254, -v253
	v_add_f32_e32 v186, v186, v253
	s_nop 0
	v_mul_f32_e32 v150, v150, v254
	v_mul_f32_e32 v151, v151, v254
	ds_write_b32 v184, v254
	s_waitcnt lgkmcnt(0)
	ds_read_b128 v[132:135], v185
	ds_read_b128 v[136:139], v185 offset:32
	ds_read_b128 v[140:143], v185 offset:64
	ds_read_b128 v[144:147], v185 offset:96
	s_waitcnt lgkmcnt(0)
	v_pk_mul_f32 v[20:21], v[20:21], v[132:133]
	v_pk_mul_f32 v[22:23], v[22:23], v[134:135]
	v_pk_mul_f32 v[24:25], v[24:25], v[136:137]
	v_pk_mul_f32 v[26:27], v[26:27], v[138:139]
	v_pk_mul_f32 v[28:29], v[28:29], v[140:141]
	v_pk_mul_f32 v[30:31], v[30:31], v[142:143]
	v_pk_mul_f32 v[32:33], v[32:33], v[144:145]
	v_pk_mul_f32 v[34:35], v[34:35], v[146:147]
	v_pk_mul_f32 v[36:37], v[36:37], v[132:133]
	v_pk_mul_f32 v[38:39], v[38:39], v[134:135]
	v_pk_mul_f32 v[40:41], v[40:41], v[136:137]
	v_pk_mul_f32 v[42:43], v[42:43], v[138:139]
	v_pk_mul_f32 v[44:45], v[44:45], v[140:141]
	v_pk_mul_f32 v[46:47], v[46:47], v[142:143]
	v_pk_mul_f32 v[48:49], v[48:49], v[144:145]
	v_pk_mul_f32 v[50:51], v[50:51], v[146:147]
	v_pk_mul_f32 v[52:53], v[52:53], v[132:133]
	v_pk_mul_f32 v[54:55], v[54:55], v[134:135]
	v_pk_mul_f32 v[56:57], v[56:57], v[136:137]
	v_pk_mul_f32 v[58:59], v[58:59], v[138:139]
	v_pk_mul_f32 v[60:61], v[60:61], v[140:141]
	v_pk_mul_f32 v[62:63], v[62:63], v[142:143]
	v_pk_mul_f32 v[64:65], v[64:65], v[144:145]
	v_pk_mul_f32 v[66:67], v[66:67], v[146:147]
	v_pk_mul_f32 v[68:69], v[68:69], v[132:133]
	v_pk_mul_f32 v[70:71], v[70:71], v[134:135]
	v_pk_mul_f32 v[72:73], v[72:73], v[136:137]
	v_pk_mul_f32 v[74:75], v[74:75], v[138:139]
	v_pk_mul_f32 v[76:77], v[76:77], v[140:141]
	v_pk_mul_f32 v[78:79], v[78:79], v[142:143]
	v_pk_mul_f32 v[80:81], v[80:81], v[144:145]
	v_pk_mul_f32 v[82:83], v[82:83], v[146:147]
	v_mov_b32_e32 v252, v253
	v_pk_add_f32 v[84:85], v[84:85], v[252:253] neg_lo:[0,1] neg_hi:[0,1]
	v_pk_add_f32 v[86:87], v[86:87], v[252:253] neg_lo:[0,1] neg_hi:[0,1]
	v_pk_add_f32 v[88:89], v[88:89], v[252:253] neg_lo:[0,1] neg_hi:[0,1]
	v_pk_add_f32 v[90:91], v[90:91], v[252:253] neg_lo:[0,1] neg_hi:[0,1]
	v_pk_add_f32 v[92:93], v[92:93], v[252:253] neg_lo:[0,1] neg_hi:[0,1]
	v_pk_add_f32 v[94:95], v[94:95], v[252:253] neg_lo:[0,1] neg_hi:[0,1]
	v_pk_add_f32 v[96:97], v[96:97], v[252:253] neg_lo:[0,1] neg_hi:[0,1]
	v_pk_add_f32 v[98:99], v[98:99], v[252:253] neg_lo:[0,1] neg_hi:[0,1]
	v_pk_add_f32 v[100:101], v[100:101], v[252:253] neg_lo:[0,1] neg_hi:[0,1]
	v_pk_add_f32 v[102:103], v[102:103], v[252:253] neg_lo:[0,1] neg_hi:[0,1]
	v_pk_add_f32 v[104:105], v[104:105], v[252:253] neg_lo:[0,1] neg_hi:[0,1]
	v_pk_add_f32 v[106:107], v[106:107], v[252:253] neg_lo:[0,1] neg_hi:[0,1]
	v_pk_add_f32 v[108:109], v[108:109], v[252:253] neg_lo:[0,1] neg_hi:[0,1]
	v_pk_add_f32 v[110:111], v[110:111], v[252:253] neg_lo:[0,1] neg_hi:[0,1]
	v_pk_add_f32 v[112:113], v[112:113], v[252:253] neg_lo:[0,1] neg_hi:[0,1]
	v_pk_add_f32 v[114:115], v[114:115], v[252:253] neg_lo:[0,1] neg_hi:[0,1]
	v_pk_add_f32 v[188:189], v[188:189], v[252:253] neg_lo:[0,1] neg_hi:[0,1]
	v_pk_add_f32 v[190:191], v[190:191], v[252:253] neg_lo:[0,1] neg_hi:[0,1]
	v_pk_add_f32 v[192:193], v[192:193], v[252:253] neg_lo:[0,1] neg_hi:[0,1]
	v_pk_add_f32 v[194:195], v[194:195], v[252:253] neg_lo:[0,1] neg_hi:[0,1]
	v_pk_add_f32 v[196:197], v[196:197], v[252:253] neg_lo:[0,1] neg_hi:[0,1]
	v_pk_add_f32 v[198:199], v[198:199], v[252:253] neg_lo:[0,1] neg_hi:[0,1]
	v_pk_add_f32 v[200:201], v[200:201], v[252:253] neg_lo:[0,1] neg_hi:[0,1]
	v_pk_add_f32 v[202:203], v[202:203], v[252:253] neg_lo:[0,1] neg_hi:[0,1]
	v_pk_add_f32 v[204:205], v[204:205], v[252:253] neg_lo:[0,1] neg_hi:[0,1]
	v_pk_add_f32 v[206:207], v[206:207], v[252:253] neg_lo:[0,1] neg_hi:[0,1]
	v_pk_add_f32 v[208:209], v[208:209], v[252:253] neg_lo:[0,1] neg_hi:[0,1]
	v_pk_add_f32 v[210:211], v[210:211], v[252:253] neg_lo:[0,1] neg_hi:[0,1]
	v_pk_add_f32 v[212:213], v[212:213], v[252:253] neg_lo:[0,1] neg_hi:[0,1]
	v_pk_add_f32 v[214:215], v[214:215], v[252:253] neg_lo:[0,1] neg_hi:[0,1]
	v_pk_add_f32 v[216:217], v[216:217], v[252:253] neg_lo:[0,1] neg_hi:[0,1]
	v_pk_add_f32 v[218:219], v[218:219], v[252:253] neg_lo:[0,1] neg_hi:[0,1]
	v_exp_f32_e32 v84, v84
	v_exp_f32_e32 v85, v85
	v_exp_f32_e32 v86, v86
	v_exp_f32_e32 v87, v87
	v_exp_f32_e32 v88, v88
	v_pk_add_f32 v[252:253], v[84:85], v[86:87]
	v_exp_f32_e32 v89, v89
	v_cvt_pk_bf16_f32 v84, v84, v85
	v_cvt_pk_bf16_f32 v85, v86, v87
	v_exp_f32_e32 v90, v90
	v_exp_f32_e32 v91, v91
	v_pk_add_f32 v[252:253], v[252:253], v[88:89]
	v_pk_add_f32 v[252:253], v[252:253], v[90:91]
	v_cvt_pk_bf16_f32 v86, v88, v89
	v_cvt_pk_bf16_f32 v87, v90, v91
	v_exp_f32_e32 v92, v92
	v_exp_f32_e32 v93, v93
	v_exp_f32_e32 v94, v94
	v_exp_f32_e32 v95, v95
	v_pk_add_f32 v[252:253], v[252:253], v[92:93]
	v_pk_add_f32 v[252:253], v[252:253], v[94:95]
	v_exp_f32_e32 v96, v96
	v_exp_f32_e32 v97, v97
	v_cvt_pk_bf16_f32 v88, v92, v93
	v_cvt_pk_bf16_f32 v89, v94, v95
; #define LAS __attribute__((address_space(3)))
; #define VREADS1(arr, d_) do { const unsigned ad_ = vbase ^ (unsigned)((d_) << 6); __builtin_amdgcn_sched_barrier(0); \
;         _Pragma("unroll") for (int ks_ = 0; ks_ < 4; ++ks_) { VTR(arr[ks_ * 2], ad_, ks_ * 4096); VTR(arr[ks_ * 2 + 1], ad_, ks_ * 4096 + 2048); } __builtin_amdgcn_sched_barrier(0); } while (0)
; __device__ __forceinline__ void attn_unit(LAS unsigned char* lds, const bf16_t* Z, bf16_t* A2, const float* tabg, int seq_base, int S, int h, int qb, float lam) {
;     ...
;         { const float coff = cc - mu;
;           if (__any(!(coff == coff_cur))) { coff_cur = coff;
; #pragma unroll
;               for (int r = 0; r < 16; ++r) cblk[r] = coff;
;               asm volatile("" : "+v"(cblk)); } }
;         f32x16 p0, p1;
;         {
;             bf16x8 kf[8];
; #pragma unroll
;             for (int ds = 0; ds < 4; ++ds) { kf[2 * ds] = *(const LAS bf16x8*)(Kt + (kfo ^ (unsigned)(ds << 5))); kf[2 * ds + 1] = *(const LAS bf16x8*)(Kt + 32 * 256 + (kfo ^ (unsigned)(ds << 5))); }
;             __builtin_amdgcn_sched_barrier(0);
;             p0 = __builtin_amdgcn_mfma_f32_32x32x16_bf16(kf[0], qf[0], cblk, 0, 0, 0);
;             p1 = __builtin_amdgcn_mfma_f32_32x32x16_bf16(kf[1], qf[0], cblk, 0, 0, 0);
; #pragma unroll
;             for (int ds = 1; ds < 4; ++ds) {
;                 p0 = __builtin_amdgcn_mfma_f32_32x32x16_bf16(kf[2 * ds], qf[ds], p0, 0, 0, 0);
;                 p1 = __builtin_amdgcn_mfma_f32_32x32x16_bf16(kf[2 * ds + 1], qf[ds], p1, 0, 0, 0);
;             }
;         }
;     ...
;         const unsigned vbase = (unsigned)(size_t)Vt + vfo;
;         s16x4 va[8], vb[8];
;         VREADS1(va, 0);
;         if (near) {
;             const LAS float* tp = tab + (kv0 + 4 * hi - (qlo + r32) + 224);
; #pragma unroll
;             for (int r = 0; r < 16; ++r) { p0[r] += tp[(r & 3) + 8 * (r >> 2)]; p1[r] += tp[32 + (r & 3) + 8 * (r >> 2)]; }
;         }
	v_exp_f32_e32 v98, v98
	v_exp_f32_e32 v99, v99
	v_pk_add_f32 v[252:253], v[252:253], v[96:97]
	v_pk_add_f32 v[252:253], v[252:253], v[98:99]
	v_cvt_pk_bf16_f32 v90, v96, v97
	v_cvt_pk_bf16_f32 v91, v98, v99
	v_exp_f32_e32 v100, v100
	v_exp_f32_e32 v101, v101
	v_exp_f32_e32 v102, v102
	v_exp_f32_e32 v103, v103
	v_pk_add_f32 v[252:253], v[252:253], v[100:101]
	v_pk_add_f32 v[252:253], v[252:253], v[102:103]
	v_exp_f32_e32 v104, v104
	v_exp_f32_e32 v105, v105
	v_cvt_pk_bf16_f32 v100, v100, v101
	v_cvt_pk_bf16_f32 v101, v102, v103
	v_exp_f32_e32 v106, v106
	v_exp_f32_e32 v107, v107
	v_pk_add_f32 v[252:253], v[252:253], v[104:105]
	v_pk_add_f32 v[252:253], v[252:253], v[106:107]
	v_cvt_pk_bf16_f32 v102, v104, v105
	v_cvt_pk_bf16_f32 v103, v106, v107
	v_exp_f32_e32 v108, v108
	v_exp_f32_e32 v109, v109
	v_exp_f32_e32 v110, v110
	v_exp_f32_e32 v111, v111
	v_pk_add_f32 v[252:253], v[252:253], v[108:109]
	v_pk_add_f32 v[252:253], v[252:253], v[110:111]
	v_exp_f32_e32 v112, v112
	v_exp_f32_e32 v113, v113
	v_cvt_pk_bf16_f32 v104, v108, v109
	v_cvt_pk_bf16_f32 v105, v110, v111
	v_exp_f32_e32 v114, v114
	v_exp_f32_e32 v115, v115
	v_pk_add_f32 v[252:253], v[252:253], v[112:113]
	v_pk_add_f32 v[252:253], v[252:253], v[114:115]
	v_cvt_pk_bf16_f32 v106, v112, v113
	v_cvt_pk_bf16_f32 v107, v114, v115
	s_mov_b32 s37, s43
	s_mov_b32 s35, s37
	v_mov_b32_e32 v251, 0
	s_cmp_eq_u32 s37, 1
	s_cselect_b64 vcc, -1, 0
	v_cndmask_b32_e32 v251, v251, v177, vcc
	s_cmp_eq_u32 s37, 2
	s_cselect_b64 vcc, -1, 0
	v_cndmask_b32_e32 v251, v251, v178, vcc
	v_sub_f32_e32 v2, v251, v186
	v_mov_b32_e32 v3, v2
	v_mov_b64_e32 v[4:5], v[2:3]
	v_mov_b64_e32 v[6:7], v[2:3]
	v_mov_b64_e32 v[8:9], v[2:3]
	v_mov_b64_e32 v[10:11], v[2:3]
	v_mov_b64_e32 v[12:13], v[2:3]
	v_mov_b64_e32 v[14:15], v[2:3]
	v_mov_b64_e32 v[16:17], v[2:3]
	ds_read_b64_tr_b16 v[132:133], v228 offset:32768
	ds_read_b64_tr_b16 v[134:135], v228 offset:34816
	ds_read_b64_tr_b16 v[136:137], v229 offset:32768
	ds_read_b64_tr_b16 v[138:139], v229 offset:34816
	ds_read_b64_tr_b16 v[140:141], v230 offset:32768
	ds_read_b64_tr_b16 v[142:143], v230 offset:34816
	ds_read_b64_tr_b16 v[144:145], v231 offset:32768
	ds_read_b64_tr_b16 v[146:147], v231 offset:34816
	ds_read_b64_tr_b16 v[220:221], v228 offset:36864
	ds_read_b64_tr_b16 v[222:223], v228 offset:38912
	ds_read_b64_tr_b16 v[224:225], v229 offset:36864
	ds_read_b64_tr_b16 v[226:227], v229 offset:38912
	ds_read_b64_tr_b16 v[232:233], v230 offset:36864
	ds_read_b64_tr_b16 v[234:235], v230 offset:38912
	s_nop 1
	s_cmp_eq_u32 s42, 0
	s_cbranch_scc1 .LatA_recret_h2
	s_cmp_eq_u32 s42, 1
	s_cbranch_scc1 .LatA_recret_m2
	s_branch .LatA_recret_x2
.LatA_rec_3:
	s_waitcnt lgkmcnt(0)
	s_nop 15
	s_sub_u32 s5, s8, s4
	s_lshr_b32 s5, s5, 12
	s_sub_u32 s5, s5, 64
	s_cmp_lt_u32 s5, s11
	s_cselect_b32 s37, 1, 0
	s_cmp_gt_u32 s5, s31
	s_cselect_b32 s40, 2, 0
	s_or_b32 s37, s37, s40
	s_mov_b32 s43, s35
	s_mov_b32 s35, s37
	v_mov_b32_e32 v251, 0
	s_cmp_eq_u32 s37, 1
	s_cselect_b64 vcc, -1, 0
	v_cndmask_b32_e32 v251, v251, v177, vcc
	s_cmp_eq_u32 s37, 2
	s_cselect_b64 vcc, -1, 0
	v_cndmask_b32_e32 v251, v251, v178, vcc
	v_sub_f32_e32 v2, v251, v186
	v_mov_b32_e32 v3, v2
	v_mov_b64_e32 v[4:5], v[2:3]
	v_mov_b64_e32 v[6:7], v[2:3]
	v_mov_b64_e32 v[8:9], v[2:3]
	v_mov_b64_e32 v[10:11], v[2:3]
	v_mov_b64_e32 v[12:13], v[2:3]
	v_mov_b64_e32 v[14:15], v[2:3]
	v_mov_b64_e32 v[16:17], v[2:3]
	s_nop 1
	ds_read_b128 v[132:135], v164
	ds_read_b128 v[136:139], v164 offset:8192
	ds_read_b128 v[140:143], v165
	ds_read_b128 v[144:147], v165 offset:8192
	ds_read_b128 v[220:223], v166
	ds_read_b128 v[224:227], v166 offset:8192
	ds_read_b128 v[232:235], v167
	ds_read_b128 v[236:239], v167 offset:8192
	s_waitcnt lgkmcnt(7)
	v_mfma_f32_32x32x16_bf16 v[188:203], v[132:135], v[116:119], v[2:17]
	s_waitcnt lgkmcnt(6)
	v_mfma_f32_32x32x16_bf16 v[204:219], v[136:139], v[116:119], v[2:17]
	s_waitcnt lgkmcnt(5)
	v_mfma_f32_32x32x16_bf16 v[188:203], v[140:143], v[120:123], v[188:203]
	s_waitcnt lgkmcnt(4)
	v_mfma_f32_32x32x16_bf16 v[204:219], v[144:147], v[120:123], v[204:219]
	s_waitcnt lgkmcnt(3)
	v_mfma_f32_32x32x16_bf16 v[188:203], v[220:223], v[124:127], v[188:203]
	s_waitcnt lgkmcnt(2)
	v_mfma_f32_32x32x16_bf16 v[204:219], v[224:227], v[124:127], v[204:219]
	s_waitcnt lgkmcnt(1)
	v_mfma_f32_32x32x16_bf16 v[188:203], v[232:235], v[128:131], v[188:203]
	s_waitcnt lgkmcnt(0)
	v_mfma_f32_32x32x16_bf16 v[204:219], v[236:239], v[128:131], v[204:219]
	s_nop 15
	s_nop 15
	s_cmp_lg_u32 s35, 0
	s_cbranch_scc1 .LatA_recnn_3
	s_lshl_b32 s38, s5, 2
	s_add_i32 s38, s38, 0x18b80
	v_add_u32_e32 v187, s38, v162
	ds_read2_b32 v[132:133], v187 offset0:0 offset1:1
	ds_read2_b32 v[134:135], v187 offset0:2 offset1:3
	ds_read2_b32 v[136:137], v187 offset0:8 offset1:9
	ds_read2_b32 v[138:139], v187 offset0:10 offset1:11
	ds_read2_b32 v[140:141], v187 offset0:16 offset1:17
	ds_read2_b32 v[142:143], v187 offset0:18 offset1:19
	ds_read2_b32 v[144:145], v187 offset0:24 offset1:25
	ds_read2_b32 v[146:147], v187 offset0:26 offset1:27
	s_waitcnt lgkmcnt(0)
	v_pk_add_f32 v[188:189], v[188:189], v[132:133]
	v_pk_add_f32 v[190:191], v[190:191], v[134:135]
	v_pk_add_f32 v[192:193], v[192:193], v[136:137]
	v_pk_add_f32 v[194:195], v[194:195], v[138:139]
	v_pk_add_f32 v[196:197], v[196:197], v[140:141]
	v_pk_add_f32 v[198:199], v[198:199], v[142:143]
	v_pk_add_f32 v[200:201], v[200:201], v[144:145]
	v_pk_add_f32 v[202:203], v[202:203], v[146:147]
	ds_read2_b32 v[132:133], v187 offset0:32 offset1:33
	ds_read2_b32 v[134:135], v187 offset0:34 offset1:35
	ds_read2_b32 v[136:137], v187 offset0:40 offset1:41
	ds_read2_b32 v[138:139], v187 offset0:42 offset1:43
	ds_read2_b32 v[140:141], v187 offset0:48 offset1:49
	ds_read2_b32 v[142:143], v187 offset0:50 offset1:51
	ds_read2_b32 v[144:145], v187 offset0:56 offset1:57
	ds_read2_b32 v[146:147], v187 offset0:58 offset1:59
	s_waitcnt lgkmcnt(0)
	v_pk_add_f32 v[204:205], v[204:205], v[132:133]
	v_pk_add_f32 v[206:207], v[206:207], v[134:135]
	v_pk_add_f32 v[208:209], v[208:209], v[136:137]
	v_pk_add_f32 v[210:211], v[210:211], v[138:139]
	v_pk_add_f32 v[212:213], v[212:213], v[140:141]
	v_pk_add_f32 v[214:215], v[214:215], v[142:143]
	v_pk_add_f32 v[216:217], v[216:217], v[144:145]
	v_pk_add_f32 v[218:219], v[218:219], v[146:147]
; #define LAS __attribute__((address_space(3)))
; __device__ __forceinline__ float max2f(float a, float b) { float r; asm("v_max_f32_e32 %0, %1, %2" : "=v"(r) : "v"(a), "v"(b)); return r; }
; __device__ __forceinline__ void attn_unit(LAS unsigned char* lds, const bf16_t* Z, bf16_t* A2, const float* tabg, int seq_base, int S, int h, int qb, float lam) {
;     ...
;         float mx = max2f(max16f(p0), max16f(p1));
;         const bool first = (t == 0);
;         if (first || __any(mx > THR)) {
;             { auto rr = __builtin_amdgcn_permlane32_swap(__float_as_uint(mx), __float_as_uint(mx), false, false); mx = max2f(__uint_as_float(rr[0]), __uint_as_float(rr[1])); }
;             const float delta = first ? mx : fmaxf(mx, 0.f);
;             const float alpha = first ? 1.0f : __builtin_amdgcn_exp2f(-delta);
;             mu += delta; ls2 *= alpha;
;             if (!first) {
;                 asm volatile("" ::: "memory");
;                 scr[r32] = alpha;
;                 asm volatile("s_waitcnt lgkmcnt(0)" ::: "memory");
; #pragma unroll
;                 for (int g = 0; g < 4; ++g) { const f32x4 a4 = *(const LAS f32x4*)(scr + 8 * g + 4 * hi);
; #pragma unroll
;                     for (int d = 0; d < 4; ++d) { O[d][4 * g + 0] *= a4[0]; O[d][4 * g + 1] *= a4[1]; O[d][4 * g + 2] *= a4[2]; O[d][4 * g + 3] *= a4[3]; } }
;                 asm volatile("s_waitcnt lgkmcnt(0)" ::: "memory");
;             }
; #pragma unroll
;             for (int r = 0; r < 16; ++r) { p0[r] -= delta; p1[r] -= delta; }
.LatA_recnn_3:
	v_max3_f32 v251, v188, v189, v190
	v_max3_f32 v252, v191, v192, v193
	v_max3_f32 v251, v251, v194, v195
	v_max3_f32 v252, v252, v196, v197
	v_max3_f32 v251, v251, v198, v199
	v_max3_f32 v252, v252, v200, v201
	v_max3_f32 v251, v251, v202, v203
	v_max3_f32 v252, v252, v204, v205
	v_max3_f32 v251, v251, v206, v207
	v_max3_f32 v252, v252, v208, v209
	v_max3_f32 v251, v251, v210, v211
	v_max3_f32 v252, v252, v212, v213
	v_max3_f32 v251, v251, v214, v215
	v_max3_f32 v252, v252, v216, v217
	v_max3_f32 v251, v251, v218, v219
	v_max_f32_e32 v251, v251, v252
	v_mov_b32_e32 v252, v251
	s_nop 1
	v_permlane32_swap_b32_e32 v251, v252
	v_max_f32_e32 v251, v251, v252
	v_max_f32_e32 v253, 0, v251
	v_exp_f32_e64 v254, -v253
	v_add_f32_e32 v186, v186, v253
	s_nop 0
	v_mul_f32_e32 v150, v150, v254
	v_mul_f32_e32 v151, v151, v254
	ds_write_b32 v184, v254
	s_waitcnt lgkmcnt(0)
	ds_read_b128 v[132:135], v185
	ds_read_b128 v[136:139], v185 offset:32
	ds_read_b128 v[140:143], v185 offset:64
	ds_read_b128 v[144:147], v185 offset:96
	s_waitcnt lgkmcnt(0)
	v_pk_mul_f32 v[20:21], v[20:21], v[132:133]
	v_pk_mul_f32 v[22:23], v[22:23], v[134:135]
	v_pk_mul_f32 v[24:25], v[24:25], v[136:137]
	v_pk_mul_f32 v[26:27], v[26:27], v[138:139]
	v_pk_mul_f32 v[28:29], v[28:29], v[140:141]
	v_pk_mul_f32 v[30:31], v[30:31], v[142:143]
	v_pk_mul_f32 v[32:33], v[32:33], v[144:145]
	v_pk_mul_f32 v[34:35], v[34:35], v[146:147]
	v_pk_mul_f32 v[36:37], v[36:37], v[132:133]
	v_pk_mul_f32 v[38:39], v[38:39], v[134:135]
	v_pk_mul_f32 v[40:41], v[40:41], v[136:137]
	v_pk_mul_f32 v[42:43], v[42:43], v[138:139]
	v_pk_mul_f32 v[44:45], v[44:45], v[140:141]
	v_pk_mul_f32 v[46:47], v[46:47], v[142:143]
	v_pk_mul_f32 v[48:49], v[48:49], v[144:145]
	v_pk_mul_f32 v[50:51], v[50:51], v[146:147]
	v_pk_mul_f32 v[52:53], v[52:53], v[132:133]
	v_pk_mul_f32 v[54:55], v[54:55], v[134:135]
	v_pk_mul_f32 v[56:57], v[56:57], v[136:137]
	v_pk_mul_f32 v[58:59], v[58:59], v[138:139]
	v_pk_mul_f32 v[60:61], v[60:61], v[140:141]
	v_pk_mul_f32 v[62:63], v[62:63], v[142:143]
	v_pk_mul_f32 v[64:65], v[64:65], v[144:145]
	v_pk_mul_f32 v[66:67], v[66:67], v[146:147]
	v_pk_mul_f32 v[68:69], v[68:69], v[132:133]
	v_pk_mul_f32 v[70:71], v[70:71], v[134:135]
	v_pk_mul_f32 v[72:73], v[72:73], v[136:137]
	v_pk_mul_f32 v[74:75], v[74:75], v[138:139]
	v_pk_mul_f32 v[76:77], v[76:77], v[140:141]
	v_pk_mul_f32 v[78:79], v[78:79], v[142:143]
	v_pk_mul_f32 v[80:81], v[80:81], v[144:145]
	v_pk_mul_f32 v[82:83], v[82:83], v[146:147]
	v_mov_b32_e32 v252, v253
	v_pk_add_f32 v[188:189], v[188:189], v[252:253] neg_lo:[0,1] neg_hi:[0,1]
	v_pk_add_f32 v[190:191], v[190:191], v[252:253] neg_lo:[0,1] neg_hi:[0,1]
	v_pk_add_f32 v[192:193], v[192:193], v[252:253] neg_lo:[0,1] neg_hi:[0,1]
	v_pk_add_f32 v[194:195], v[194:195], v[252:253] neg_lo:[0,1] neg_hi:[0,1]
	v_pk_add_f32 v[196:197], v[196:197], v[252:253] neg_lo:[0,1] neg_hi:[0,1]
	v_pk_add_f32 v[198:199], v[198:199], v[252:253] neg_lo:[0,1] neg_hi:[0,1]
	v_pk_add_f32 v[200:201], v[200:201], v[252:253] neg_lo:[0,1] neg_hi:[0,1]
	v_pk_add_f32 v[202:203], v[202:203], v[252:253] neg_lo:[0,1] neg_hi:[0,1]
	v_pk_add_f32 v[204:205], v[204:205], v[252:253] neg_lo:[0,1] neg_hi:[0,1]
	v_pk_add_f32 v[206:207], v[206:207], v[252:253] neg_lo:[0,1] neg_hi:[0,1]
	v_pk_add_f32 v[208:209], v[208:209], v[252:253] neg_lo:[0,1] neg_hi:[0,1]
	v_pk_add_f32 v[210:211], v[210:211], v[252:253] neg_lo:[0,1] neg_hi:[0,1]
	v_pk_add_f32 v[212:213], v[212:213], v[252:253] neg_lo:[0,1] neg_hi:[0,1]
	v_pk_add_f32 v[214:215], v[214:215], v[252:253] neg_lo:[0,1] neg_hi:[0,1]
	v_pk_add_f32 v[216:217], v[216:217], v[252:253] neg_lo:[0,1] neg_hi:[0,1]
	v_pk_add_f32 v[218:219], v[218:219], v[252:253] neg_lo:[0,1] neg_hi:[0,1]
	v_pk_add_f32 v[84:85], v[84:85], v[252:253] neg_lo:[0,1] neg_hi:[0,1]
	v_pk_add_f32 v[86:87], v[86:87], v[252:253] neg_lo:[0,1] neg_hi:[0,1]
	v_pk_add_f32 v[88:89], v[88:89], v[252:253] neg_lo:[0,1] neg_hi:[0,1]
	v_pk_add_f32 v[90:91], v[90:91], v[252:253] neg_lo:[0,1] neg_hi:[0,1]
	v_pk_add_f32 v[92:93], v[92:93], v[252:253] neg_lo:[0,1] neg_hi:[0,1]
	v_pk_add_f32 v[94:95], v[94:95], v[252:253] neg_lo:[0,1] neg_hi:[0,1]
; #define VREADS1(arr, d_) do { const unsigned ad_ = vbase ^ (unsigned)((d_) << 6); __builtin_amdgcn_sched_barrier(0); \
;         _Pragma("unroll") for (int ks_ = 0; ks_ < 4; ++ks_) { VTR(arr[ks_ * 2], ad_, ks_ * 4096); VTR(arr[ks_ * 2 + 1], ad_, ks_ * 4096 + 2048); } __builtin_amdgcn_sched_barrier(0); } while (0)
; #define PV1(arr, d_) do { _Pragma("unroll") for (int ks_ = 0; ks_ < 4; ++ks_) { const s16x4 lo_ = arr[ks_ * 2], hh_ = arr[ks_ * 2 + 1]; \
;         const bf16x8 bv_ = (bf16x8){lo_[0], lo_[1], lo_[2], lo_[3], hh_[0], hh_[1], hh_[2], hh_[3]}; \
;         O[d_] = __builtin_amdgcn_mfma_f32_32x32x16_bf16(pa[ks_], bv_, O[d_], 0, 0, 0); } __builtin_amdgcn_sched_barrier(0); } while (0)
; #define LGKM0() do { __builtin_amdgcn_sched_barrier(0); asm volatile("s_waitcnt lgkmcnt(0)" ::: "memory"); __builtin_amdgcn_sched_barrier(0); } while (0)
; __device__ __forceinline__ void attn_unit(LAS unsigned char* lds, const bf16_t* Z, bf16_t* A2, const float* tabg, int seq_base, int S, int h, int qb, float lam) {
;     ...
;         bool near = true; float cc = 0.f;
;         if (kv0 - (qlo + 31) >= 128) { near = false; cc = tabR; } else if (qlo - (kv0 + 63) >= 128) { near = false; cc = tabL; }
;         { const float coff = cc - mu;
;           if (__any(!(coff == coff_cur))) { coff_cur = coff;
; #pragma unroll
;               for (int r = 0; r < 16; ++r) cblk[r] = coff;
;               asm volatile("" : "+v"(cblk)); } }
;     ...
;             for (int r = 0; r < 16; ++r) { p0[r] -= delta; p1[r] -= delta; }
;             asm volatile("" : "+v"(p0), "+v"(p1));
;         }
; #pragma unroll
;         for (int r = 0; r < 16; ++r) { p0[r] = __builtin_amdgcn_exp2f(p0[r]); p1[r] = __builtin_amdgcn_exp2f(p1[r]); }
; #pragma unroll
;         for (int r = 0; r < 16; r += 2) { ls2 += (f32x2){p0[r], p0[r + 1]}; ls2 += (f32x2){p1[r], p1[r + 1]}; }
;         bf16x8 pa[4]; pa[0] = pack8(p0, 0); pa[1] = pack8(p0, 8); pa[2] = pack8(p1, 0); pa[3] = pack8(p1, 8);
;         LGKM0(); VREADS1(vb, 1); PV1(va, 0); LGKM0(); VREADS1(va, 2); PV1(vb, 1); LGKM0(); VREADS1(vb, 3); PV1(va, 2); LGKM0(); PV1(vb, 3);
	v_pk_add_f32 v[96:97], v[96:97], v[252:253] neg_lo:[0,1] neg_hi:[0,1]
	v_pk_add_f32 v[98:99], v[98:99], v[252:253] neg_lo:[0,1] neg_hi:[0,1]
	v_pk_add_f32 v[100:101], v[100:101], v[252:253] neg_lo:[0,1] neg_hi:[0,1]
	v_pk_add_f32 v[102:103], v[102:103], v[252:253] neg_lo:[0,1] neg_hi:[0,1]
	v_pk_add_f32 v[104:105], v[104:105], v[252:253] neg_lo:[0,1] neg_hi:[0,1]
	v_pk_add_f32 v[106:107], v[106:107], v[252:253] neg_lo:[0,1] neg_hi:[0,1]
	v_pk_add_f32 v[108:109], v[108:109], v[252:253] neg_lo:[0,1] neg_hi:[0,1]
	v_pk_add_f32 v[110:111], v[110:111], v[252:253] neg_lo:[0,1] neg_hi:[0,1]
	v_pk_add_f32 v[112:113], v[112:113], v[252:253] neg_lo:[0,1] neg_hi:[0,1]
	v_pk_add_f32 v[114:115], v[114:115], v[252:253] neg_lo:[0,1] neg_hi:[0,1]
	v_exp_f32_e32 v188, v188
	v_exp_f32_e32 v189, v189
	v_exp_f32_e32 v190, v190
	v_exp_f32_e32 v191, v191
	v_exp_f32_e32 v192, v192
	v_pk_add_f32 v[252:253], v[188:189], v[190:191]
	v_exp_f32_e32 v193, v193
	v_cvt_pk_bf16_f32 v188, v188, v189
	v_cvt_pk_bf16_f32 v189, v190, v191
	v_exp_f32_e32 v194, v194
	v_exp_f32_e32 v195, v195
	v_pk_add_f32 v[252:253], v[252:253], v[192:193]
	v_pk_add_f32 v[252:253], v[252:253], v[194:195]
	v_cvt_pk_bf16_f32 v190, v192, v193
	v_cvt_pk_bf16_f32 v191, v194, v195
	v_exp_f32_e32 v196, v196
	v_exp_f32_e32 v197, v197
	v_exp_f32_e32 v198, v198
	v_exp_f32_e32 v199, v199
	v_pk_add_f32 v[252:253], v[252:253], v[196:197]
	v_pk_add_f32 v[252:253], v[252:253], v[198:199]
	v_exp_f32_e32 v200, v200
	v_exp_f32_e32 v201, v201
	v_cvt_pk_bf16_f32 v192, v196, v197
	v_cvt_pk_bf16_f32 v193, v198, v199
	v_exp_f32_e32 v202, v202
	v_exp_f32_e32 v203, v203
	v_pk_add_f32 v[252:253], v[252:253], v[200:201]
	v_pk_add_f32 v[252:253], v[252:253], v[202:203]
	v_cvt_pk_bf16_f32 v194, v200, v201
	v_cvt_pk_bf16_f32 v195, v202, v203
	v_exp_f32_e32 v204, v204
	v_exp_f32_e32 v205, v205
	v_exp_f32_e32 v206, v206
	v_exp_f32_e32 v207, v207
	v_pk_add_f32 v[252:253], v[252:253], v[204:205]
	v_pk_add_f32 v[252:253], v[252:253], v[206:207]
	v_exp_f32_e32 v208, v208
	v_exp_f32_e32 v209, v209
	v_cvt_pk_bf16_f32 v204, v204, v205
	v_cvt_pk_bf16_f32 v205, v206, v207
	v_exp_f32_e32 v210, v210
	v_exp_f32_e32 v211, v211
	v_pk_add_f32 v[252:253], v[252:253], v[208:209]
	v_pk_add_f32 v[252:253], v[252:253], v[210:211]
	v_cvt_pk_bf16_f32 v206, v208, v209
	v_cvt_pk_bf16_f32 v207, v210, v211
	v_exp_f32_e32 v212, v212
	v_exp_f32_e32 v213, v213
	v_exp_f32_e32 v214, v214
	v_exp_f32_e32 v215, v215
	v_pk_add_f32 v[252:253], v[252:253], v[212:213]
	v_pk_add_f32 v[252:253], v[252:253], v[214:215]
	v_exp_f32_e32 v216, v216
	v_exp_f32_e32 v217, v217
	v_cvt_pk_bf16_f32 v208, v212, v213
	v_cvt_pk_bf16_f32 v209, v214, v215
	v_exp_f32_e32 v218, v218
	v_exp_f32_e32 v219, v219
	v_pk_add_f32 v[252:253], v[252:253], v[216:217]
	v_pk_add_f32 v[252:253], v[252:253], v[218:219]
	v_cvt_pk_bf16_f32 v210, v216, v217
	v_cvt_pk_bf16_f32 v211, v218, v219
	s_mov_b32 s37, s43
	s_mov_b32 s35, s37
	v_mov_b32_e32 v251, 0
	s_cmp_eq_u32 s37, 1
	s_cselect_b64 vcc, -1, 0
	v_cndmask_b32_e32 v251, v251, v177, vcc
	s_cmp_eq_u32 s37, 2
	s_cselect_b64 vcc, -1, 0
	v_cndmask_b32_e32 v251, v251, v178, vcc
	v_sub_f32_e32 v2, v251, v186
	v_mov_b32_e32 v3, v2
	v_mov_b64_e32 v[4:5], v[2:3]
	v_mov_b64_e32 v[6:7], v[2:3]
	v_mov_b64_e32 v[8:9], v[2:3]
	v_mov_b64_e32 v[10:11], v[2:3]
	v_mov_b64_e32 v[12:13], v[2:3]
	v_mov_b64_e32 v[14:15], v[2:3]
	v_mov_b64_e32 v[16:17], v[2:3]
	ds_read_b64_tr_b16 v[132:133], v168 offset:0
	ds_read_b64_tr_b16 v[134:135], v168 offset:2048
	ds_read_b64_tr_b16 v[136:137], v169 offset:0
	ds_read_b64_tr_b16 v[138:139], v169 offset:2048
	ds_read_b64_tr_b16 v[140:141], v170 offset:0
	ds_read_b64_tr_b16 v[142:143], v170 offset:2048
	ds_read_b64_tr_b16 v[144:145], v171 offset:0
	ds_read_b64_tr_b16 v[146:147], v171 offset:2048
	ds_read_b64_tr_b16 v[220:221], v168 offset:4096
	ds_read_b64_tr_b16 v[222:223], v168 offset:6144
	ds_read_b64_tr_b16 v[224:225], v169 offset:4096
	ds_read_b64_tr_b16 v[226:227], v169 offset:6144
	ds_read_b64_tr_b16 v[232:233], v170 offset:4096
	ds_read_b64_tr_b16 v[234:235], v170 offset:6144
	s_nop 1
	s_cmp_eq_u32 s42, 0
	s_cbranch_scc1 .LatA_recret_h3
	s_cmp_eq_u32 s42, 1
	s_cbranch_scc1 .LatA_recret_m3
	s_branch .LatA_recret_x1

; __device__ __forceinline__ void attn_unit(LAS unsigned char* lds, const bf16_t* Z, bf16_t* A2, const float* tabg, int seq_base, int S, int h, int qb, float lam) {
;     ...
;     const int qlo = qb * 128 + rg * 32;
;     bf16x8 qf[4];
;     { const bf16_t* qrow = Z + (size_t)(seq_base + qlo + r32) * NZ + h * 128 + m * 64 + 8 * hi;
; #pragma unroll
;       for (int ds = 0; ds < 4; ++ds) qf[ds] = *(const bf16x8*)(qrow + 16 * ds); }
;     const char* kvbase = (const char*)(Z + (size_t)seq_base * NZ + h * 128);
;     unsigned koff[2], voff[2];
; #pragma unroll
;     for (int i = 0; i < 2; ++i) { const int row = (i * 8 + w) * 4 + (lane >> 4), cp = lane & 15;
;         koff[i] = (unsigned)(row * NZ + 512 + ((cp ^ (row & 15)) << 3)) * 2u; voff[i] = (unsigned)(row * NZ + 1024 + ((cp ^ (4 * (row & 3))) << 3)) * 2u; }
;     const unsigned kb_u = (unsigned)(size_t)Kb + (unsigned)w * 1024u, vb_u = (unsigned)(size_t)Vb + (unsigned)w * 1024u;
;     ...
;     ATT_STAGE(0, 0); ATT_STAGE(1, 1);
;     asm volatile("s_waitcnt vmcnt(4) lgkmcnt(0)" ::: "memory"); __builtin_amdgcn_s_barrier(); asm volatile("" ::: "memory");
; #pragma unroll
;     for (int ds = 0; ds < 4; ++ds) asm volatile("" : "+v"(qf[ds]));
;     const float tabL = tab[0], tabR = tab[448];
;     f32x16 O[4];
; #pragma unroll
;     for (int d = 0; d < 4; ++d)
; #pragma unroll
;         for (int r = 0; r < 16; ++r) O[d][r] = 0.f;
;     float mu = 0.f; f32x2 ls2 = {0.f, 0.f};
;     f32x16 cblk; float coff_cur = __builtin_nanf("");
; #pragma unroll
;     for (int r = 0; r < 16; ++r) cblk[r] = 0.f;
;     const int NT = S >> 6;
;     const unsigned kfo = r32 * 256 + ((unsigned)((m * 8 + hi) ^ (r32 & 15)) << 4);
;     const unsigned vj = (i16 >> 2) & 3;
;     const unsigned vfo = (4 * hi + (i16 >> 2)) * 256 + (vj << 6) + 32 * (g4 & 1) + 8 * (i16 & 3);
;     int bc = 0, bn = 2;
.LBB0_325:
	s_or_b64 exec, exec, s[8:9]
	s_lshl_b32 s9, s21, 6
	s_and_b32 s8, s25, 32
	s_and_b32 s9, s9, 64
	s_or_b32 s8, s9, s8
	s_ashr_i32 s15, s26, 6
	s_or_b32 s8, s8, s23
	s_and_b32 s17, s15, 3
	s_lshl_b32 s8, s8, 7
	s_waitcnt lgkmcnt(0)
	s_lshl_b32 s10, s17, 5
	s_or_b32 s11, s10, s8
	v_and_b32_e32 v148, 31, v68
	s_or_b32 s14, s11, 0x4000
	v_or_b32_e32 v2, s14, v148
	s_ashr_i32 s16, s26, 8
	v_lshlrev_b32_e32 v162, 12, v2
	v_lshl_add_u64 v[2:3], s[4:5], 0, v[162:163]
	s_lshl_b32 s48, s28, 8
	s_lshl_b32 s8, s16, 6
	v_bfe_u32 v159, v68, 5, 1
	v_lshl_add_u64 v[2:3], v[2:3], 0, s[48:49]
	s_ashr_i32 s9, s8, 31
	v_lshl_add_u64 v[2:3], s[8:9], 1, v[2:3]
	v_lshlrev_b32_e32 v162, 4, v159
	v_lshl_add_u64 v[2:3], v[2:3], 0, v[162:163]
	s_mov_b64 s[8:9], 0x7800000
	v_lshl_add_u64 v[4:5], v[2:3], 0, s[8:9]
	s_mov_b32 s8, 0x7800000
	v_add_co_u32_e32 v2, vcc, s8, v2
	v_readlane_b32 s8, v255, 29
	s_nop 0
	v_addc_co_u32_e32 v3, vcc, 0, v3, vcc
	global_load_dwordx4 v[116:119], v[2:3], off
	global_load_dwordx4 v[120:123], v[4:5], off offset:32
	global_load_dwordx4 v[124:127], v[4:5], off offset:64
	global_load_dwordx4 v[128:131], v[4:5], off offset:96
	v_mov_b32_e32 v3, s8
	v_readlane_b32 s8, v255, 30
	v_bfe_u32 v2, v68, 4, 2
	v_lshlrev_b32_e32 v35, 5, v2
	v_mov_b32_e32 v4, s8
	s_lshl_b32 s8, s15, 2
	v_or_b32_e32 v6, s8, v2
	v_bitop3_b32 v2, s8, v68, v2 bitop3:0x36
	s_add_u32 s29, s4, s48
	v_and_b32_e32 v34, 15, v68
	v_lshlrev_b32_e32 v6, 11, v6
	v_lshlrev_b32_e32 v2, 3, v2
	s_addc_u32 s30, s5, 0
	v_lshlrev_b32_e32 v5, 3, v34
	v_and_b32_e32 v2, 0x78, v2
	v_add_u32_e32 v8, 0x10000, v6
	s_add_u32 s8, s29, 0xb800000
	v_bitop3_b32 v7, v6, v35, v5 bitop3:0xf6
	v_or_b32_e32 v6, v2, v6
	v_or_b32_e32 v2, v2, v8
	v_bitop3_b32 v5, v8, v35, v5 bitop3:0xf6
	s_addc_u32 s9, s30, 0
	s_lshl_b32 s27, s15, 10
	s_add_i32 s15, 0, 0xc000
	v_lshl_or_b32 v149, v7, 1, v250
	v_lshl_or_b32 v160, v6, 1, v249
	v_lshl_or_b32 v161, v2, 1, v249
	v_lshl_or_b32 v176, v5, 1, v250
	s_add_i32 s25, s27, 0
	s_add_i32 s27, s27, s15
	s_mov_b32 s31, m0
	s_mov_b32 m0, s25
	s_nop 0
	global_load_lds_dwordx4 v160, s[8:9]
	s_mov_b32 m0, s27
	s_nop 0
	global_load_lds_dwordx4 v149, s[8:9]
	s_add_u32 m0, s25, 0x2000
	s_nop 0
	global_load_lds_dwordx4 v161, s[8:9]
	s_add_u32 m0, s27, 0x2000
	s_nop 0
	global_load_lds_dwordx4 v176, s[8:9]
	s_mov_b32 m0, s31
	s_add_u32 s8, s29, 0xb840000
	s_addc_u32 s9, s30, 0
	s_add_i32 s31, s25, 0x4000
	s_add_i32 s33, s27, 0x4000
	s_mov_b32 s34, m0
	s_mov_b32 m0, s31
	s_nop 0
	global_load_lds_dwordx4 v160, s[8:9]
	s_mov_b32 m0, s33
	s_nop 0
	global_load_lds_dwordx4 v149, s[8:9]
	s_add_u32 m0, s31, 0x2000
	s_nop 0
	global_load_lds_dwordx4 v161, s[8:9]
	s_add_u32 m0, s33, 0x2000
	s_nop 0
	global_load_lds_dwordx4 v176, s[8:9]
	s_mov_b32 m0, s34
	s_mov_b32 s32, m0
	s_add_u32 s8, s29, 0xb800000
	s_addc_u32 s9, s30, 0
	s_mov_b32 s4, s8
	s_add_u32 s8, s8, 0x40000
	s_addc_u32 s9, s9, 0
	s_add_u32 s22, s8, 0x40000
	s_addc_u32 s23, s9, 0
	s_add_u32 m0, s25, 0x8000
	v_add_u32_e32 v172, 0x80000, v160
	global_load_lds_dwordx4 v160, s[22:23]
	s_add_u32 m0, s25, 0xa000
	v_add_u32_e32 v173, 0x80000, v161
	global_load_lds_dwordx4 v161, s[22:23]
	v_add_u32_e32 v174, 0x40000, v149
	v_add_u32_e32 v175, 0x40000, v176
	s_lshl_b32 s15, s28, 7
	s_and_b32 s24, s26, 0x3fffffc0
	s_lshl_b32 s24, s24, 2
	s_add_i32 s28, s24, 0x18000
	v_and_b32_e32 v183, 63, v68
	v_lshl_add_u32 v185, v159, 4, s28
	v_lshl_add_u32 v184, v148, 2, s28
	s_add_i32 s33, s11, 0x9f
	v_add_lshl_u32 v251, s11, v148, 2
	v_lshlrev_b32_e32 v252, 4, v159
	v_sub_u32_e32 v162, v252, v251
	s_add_i32 s34, s11, 0xffffff41
	s_ashr_i32 s11, s34, 6
	s_add_i32 s11, s11, 1
	s_lshl_b32 s11, s11, 6
	s_max_i32 s11, s11, 0
	s_add_i32 s31, s33, 63
	s_andn2_b32 s31, s31, 63
	s_sub_u32 s31, s31, 64
	s_lshr_b32 s10, s11, 6
	s_sub_i32 s10, s10, 2
	s_max_i32 s10, s10, 0
	s_lshl_b32 s24, s16, 3
	v_lshlrev_b32_e32 v19, 8, v148
	v_bitop3_b32 v251, s24, v34, v159 bitop3:0x36
	v_lshlrev_b32_e32 v252, 2, v159
	v_lshrrev_b32_e32 v253, 2, v34
	v_lshlrev_b32_e32 v254, 3, v68
	v_lshl_add_u32 v19, v251, 4, v19
	v_or_b32_e32 v252, v252, v253
	v_and_b32_e32 v254, 24, v254
	v_and_b32_e32 v251, 32, v35
	v_lshlrev_b32_e32 v252, 8, v252
	v_lshl_or_b32 v253, v253, 6, v254
	v_xor_b32_e32 v180, 32, v19
	v_or3_b32 v179, v252, v251, v253
	v_xor_b32_e32 v181, 64, v19
	v_xor_b32_e32 v182, 0x60, v19
	v_add_u32_e32 v228, 0xc000, v179
	v_xor_b32_e32 v229, 0x40, v179
	v_add_u32_e32 v229, 0xc000, v229
	v_xor_b32_e32 v230, 0x80, v179
	v_add_u32_e32 v230, 0xc000, v230
	v_xor_b32_e32 v231, 0xc0, v179
	v_add_u32_e32 v231, 0xc000, v231
	v_add_u32_e32 v164, 0x1d000, v19
	v_add_u32_e32 v168, 0xd000, v228
	v_add_u32_e32 v165, 0x1d000, v180
	v_add_u32_e32 v169, 0xd000, v229
	v_add_u32_e32 v166, 0x1d000, v181
	v_add_u32_e32 v170, 0xd000, v230
	v_add_u32_e32 v167, 0x1d000, v182
	v_add_u32_e32 v171, 0xd000, v231
	v_mov_b64_e32 v[20:21], 0
	v_mov_b64_e32 v[22:23], 0
	v_mov_b64_e32 v[24:25], 0
	v_mov_b64_e32 v[26:27], 0
	v_mov_b64_e32 v[28:29], 0
	v_mov_b64_e32 v[30:31], 0
	v_mov_b64_e32 v[32:33], 0
	v_mov_b64_e32 v[34:35], 0
	v_mov_b64_e32 v[36:37], 0
	v_mov_b64_e32 v[38:39], 0
	v_mov_b64_e32 v[40:41], 0
	v_mov_b64_e32 v[42:43], 0
	v_mov_b64_e32 v[44:45], 0
	v_mov_b64_e32 v[46:47], 0
	v_mov_b64_e32 v[48:49], 0
	v_mov_b64_e32 v[50:51], 0
	v_mov_b64_e32 v[52:53], 0
	v_mov_b64_e32 v[54:55], 0
	v_mov_b64_e32 v[56:57], 0
	v_mov_b64_e32 v[58:59], 0
	v_mov_b64_e32 v[60:61], 0
	v_mov_b64_e32 v[62:63], 0
	v_mov_b64_e32 v[64:65], 0
	v_mov_b64_e32 v[66:67], 0
	v_mov_b64_e32 v[68:69], 0
	v_mov_b64_e32 v[70:71], 0
	v_mov_b64_e32 v[72:73], 0
	v_mov_b64_e32 v[74:75], 0
	v_mov_b64_e32 v[76:77], 0
	v_mov_b64_e32 v[78:79], 0
	v_mov_b64_e32 v[80:81], 0
	v_mov_b64_e32 v[82:83], 0
	v_mov_b64_e32 v[150:151], 0
	v_mov_b32_e32 v186, 0
	s_waitcnt vmcnt(6) lgkmcnt(0)
	s_barrier
; __device__ __forceinline__ void attn_unit(LAS unsigned char* lds, const bf16_t* Z, bf16_t* A2, const float* tabg, int seq_base, int S, int h, int qb, float lam) {
;     ...
;     const float tabL = tab[0], tabR = tab[448];
;     f32x16 O[4];
; #pragma unroll
;     for (int d = 0; d < 4; ++d)
; #pragma unroll
;         for (int r = 0; r < 16; ++r) O[d][r] = 0.f;
;     float mu = 0.f; f32x2 ls2 = {0.f, 0.f};
;     f32x16 cblk; float coff_cur = __builtin_nanf("");
; #pragma unroll
;     for (int r = 0; r < 16; ++r) cblk[r] = 0.f;
;     const int NT = S >> 6;
;     const unsigned kfo = r32 * 256 + ((unsigned)((m * 8 + hi) ^ (r32 & 15)) << 4);
;     const unsigned vj = (i16 >> 2) & 3;
;     const unsigned vfo = (4 * hi + (i16 >> 2)) * 256 + (vj << 6) + 32 * (g4 & 1) + 8 * (i16 & 3);
;     int bc = 0, bn = 2;
;     for (int t = 0; t < NT; ++t) {
;         if (t + 2 < NT) ATT_STAGE(t + 2, bn);
;         const LAS unsigned char* Kt = Kb + bc * KT; const LAS unsigned char* Vt = Vb + bc * VT;
;         const int kv0 = t * 64;
;         bool near = true; float cc = 0.f;
;         if (kv0 - (qlo + 31) >= 128) { near = false; cc = tabR; } else if (qlo - (kv0 + 63) >= 128) { near = false; cc = tabL; }
;         { const float coff = cc - mu;
;           if (__any(!(coff == coff_cur))) { coff_cur = coff;
; #pragma unroll
;               for (int r = 0; r < 16; ++r) cblk[r] = coff;
;               asm volatile("" : "+v"(cblk)); } }
;         f32x16 p0, p1;
;         {
;             bf16x8 kf[8];
; #pragma unroll
;             for (int ds = 0; ds < 4; ++ds) { kf[2 * ds] = *(const LAS bf16x8*)(Kt + (kfo ^ (unsigned)(ds << 5))); kf[2 * ds + 1] = *(const LAS bf16x8*)(Kt + 32 * 256 + (kfo ^ (unsigned)(ds << 5))); }
;             __builtin_amdgcn_sched_barrier(0);
;             p0 = __builtin_amdgcn_mfma_f32_32x32x16_bf16(kf[0], qf[0], cblk, 0, 0, 0);
;             p1 = __builtin_amdgcn_mfma_f32_32x32x16_bf16(kf[1], qf[0], cblk, 0, 0, 0);
; #pragma unroll
;             for (int ds = 1; ds < 4; ++ds) {
;                 p0 = __builtin_amdgcn_mfma_f32_32x32x16_bf16(kf[2 * ds], qf[ds], p0, 0, 0, 0);
;                 p1 = __builtin_amdgcn_mfma_f32_32x32x16_bf16(kf[2 * ds + 1], qf[ds], p1, 0, 0, 0);
;             }
;         }
;     ...
;         const unsigned vbase = (unsigned)(size_t)Vt + vfo;
;         s16x4 va[8], vb[8];
;         VREADS1(va, 0);
;         if (near) {
	v_mov_b32_e32 v187, 0x18800
	ds_read_b32 v177, v187
	ds_read_b32 v178, v187 offset:1792
	ds_read_b128 v[132:135], v19
	ds_read_b128 v[136:139], v19 offset:8192
	ds_read_b128 v[140:143], v180
	ds_read_b128 v[144:147], v180 offset:8192
	ds_read_b128 v[220:223], v181
	ds_read_b128 v[224:227], v181 offset:8192
	ds_read_b128 v[232:235], v182
	ds_read_b128 v[236:239], v182 offset:8192
	s_waitcnt lgkmcnt(8)
	s_cmp_eq_u32 s11, 0
	s_cselect_b32 s24, 0, 1
	s_mov_b32 s35, s24
	v_mov_b32_e32 v251, 0
	s_cmp_eq_u32 s24, 1
	s_cselect_b64 vcc, -1, 0
	v_cndmask_b32_e32 v251, v251, v177, vcc
	s_cmp_eq_u32 s24, 2
	s_cselect_b64 vcc, -1, 0
	v_cndmask_b32_e32 v251, v251, v178, vcc
	v_sub_f32_e32 v2, v251, v186
	v_mov_b32_e32 v3, v2
	v_mov_b64_e32 v[4:5], v[2:3]
	v_mov_b64_e32 v[6:7], v[2:3]
	v_mov_b64_e32 v[8:9], v[2:3]
	v_mov_b64_e32 v[10:11], v[2:3]
	v_mov_b64_e32 v[12:13], v[2:3]
	v_mov_b64_e32 v[14:15], v[2:3]
	v_mov_b64_e32 v[16:17], v[2:3]
	s_nop 1
	s_waitcnt lgkmcnt(7)
	v_mfma_f32_32x32x16_bf16 v[84:99], v[132:135], v[116:119], v[2:17]
	s_waitcnt lgkmcnt(6)
	v_mfma_f32_32x32x16_bf16 v[100:115], v[136:139], v[116:119], v[2:17]
	s_waitcnt lgkmcnt(5)
	v_mfma_f32_32x32x16_bf16 v[84:99], v[140:143], v[120:123], v[84:99]
	s_waitcnt lgkmcnt(4)
	v_mfma_f32_32x32x16_bf16 v[100:115], v[144:147], v[120:123], v[100:115]
	s_waitcnt lgkmcnt(3)
	v_mfma_f32_32x32x16_bf16 v[84:99], v[220:223], v[124:127], v[84:99]
	s_waitcnt lgkmcnt(2)
	v_mfma_f32_32x32x16_bf16 v[100:115], v[224:227], v[124:127], v[100:115]
	s_waitcnt lgkmcnt(1)
	v_mfma_f32_32x32x16_bf16 v[84:99], v[232:235], v[128:131], v[84:99]
	s_waitcnt lgkmcnt(0)
	v_mfma_f32_32x32x16_bf16 v[100:115], v[236:239], v[128:131], v[100:115]
	s_nop 15
	s_nop 15
	s_mov_b32 s5, 0
	s_cmp_lg_u32 s11, 0
	s_cbranch_scc1 .LatB_p0_nonear
	s_lshl_b32 s29, s5, 2
	s_add_i32 s29, s29, 0x18b80
	v_add_u32_e32 v187, s29, v162
	ds_read2_b32 v[196:197], v187 offset0:0 offset1:1
	ds_read2_b32 v[198:199], v187 offset0:2 offset1:3
	ds_read2_b32 v[200:201], v187 offset0:8 offset1:9
	ds_read2_b32 v[202:203], v187 offset0:10 offset1:11
	ds_read2_b32 v[212:213], v187 offset0:16 offset1:17
	ds_read2_b32 v[214:215], v187 offset0:18 offset1:19
	ds_read2_b32 v[216:217], v187 offset0:24 offset1:25
	ds_read2_b32 v[218:219], v187 offset0:26 offset1:27
	s_waitcnt lgkmcnt(0)
	v_pk_add_f32 v[84:85], v[84:85], v[196:197]
	v_pk_add_f32 v[86:87], v[86:87], v[198:199]
	v_pk_add_f32 v[88:89], v[88:89], v[200:201]
	v_pk_add_f32 v[90:91], v[90:91], v[202:203]
	v_pk_add_f32 v[92:93], v[92:93], v[212:213]
	v_pk_add_f32 v[94:95], v[94:95], v[214:215]
	v_pk_add_f32 v[96:97], v[96:97], v[216:217]
	v_pk_add_f32 v[98:99], v[98:99], v[218:219]
	ds_read2_b32 v[196:197], v187 offset0:32 offset1:33
	ds_read2_b32 v[198:199], v187 offset0:34 offset1:35
	ds_read2_b32 v[200:201], v187 offset0:40 offset1:41
	ds_read2_b32 v[202:203], v187 offset0:42 offset1:43
	ds_read2_b32 v[212:213], v187 offset0:48 offset1:49
	ds_read2_b32 v[214:215], v187 offset0:50 offset1:51
	ds_read2_b32 v[216:217], v187 offset0:56 offset1:57
	ds_read2_b32 v[218:219], v187 offset0:58 offset1:59
	s_waitcnt lgkmcnt(0)
	v_pk_add_f32 v[100:101], v[100:101], v[196:197]
	v_pk_add_f32 v[102:103], v[102:103], v[198:199]
	v_pk_add_f32 v[104:105], v[104:105], v[200:201]
	v_pk_add_f32 v[106:107], v[106:107], v[202:203]
	v_pk_add_f32 v[108:109], v[108:109], v[212:213]
	v_pk_add_f32 v[110:111], v[110:111], v[214:215]
	v_pk_add_f32 v[112:113], v[112:113], v[216:217]
	v_pk_add_f32 v[114:115], v[114:115], v[218:219]
; #define LAS __attribute__((address_space(3)))
; __device__ __forceinline__ float max2f(float a, float b) { float r; asm("v_max_f32_e32 %0, %1, %2" : "=v"(r) : "v"(a), "v"(b)); return r; }
; #define LGKM0() do { __builtin_amdgcn_sched_barrier(0); asm volatile("s_waitcnt lgkmcnt(0)" ::: "memory"); __builtin_amdgcn_sched_barrier(0); } while (0)
; __device__ __forceinline__ void attn_unit(LAS unsigned char* lds, const bf16_t* Z, bf16_t* A2, const float* tabg, int seq_base, int S, int h, int qb, float lam) {
;     ...
;         float mx = max2f(max16f(p0), max16f(p1));
;         const bool first = (t == 0);
;         if (first || __any(mx > THR)) {
;             { auto rr = __builtin_amdgcn_permlane32_swap(__float_as_uint(mx), __float_as_uint(mx), false, false); mx = max2f(__uint_as_float(rr[0]), __uint_as_float(rr[1])); }
;             const float delta = first ? mx : fmaxf(mx, 0.f);
;             const float alpha = first ? 1.0f : __builtin_amdgcn_exp2f(-delta);
;             mu += delta; ls2 *= alpha;
;             if (!first) {
;                 asm volatile("" ::: "memory");
;                 scr[r32] = alpha;
;                 asm volatile("s_waitcnt lgkmcnt(0)" ::: "memory");
; #pragma unroll
;                 for (int g = 0; g < 4; ++g) { const f32x4 a4 = *(const LAS f32x4*)(scr + 8 * g + 4 * hi);
; #pragma unroll
;                     for (int d = 0; d < 4; ++d) { O[d][4 * g + 0] *= a4[0]; O[d][4 * g + 1] *= a4[1]; O[d][4 * g + 2] *= a4[2]; O[d][4 * g + 3] *= a4[3]; } }
;                 asm volatile("s_waitcnt lgkmcnt(0)" ::: "memory");
;             }
; #pragma unroll
;             for (int r = 0; r < 16; ++r) { p0[r] -= delta; p1[r] -= delta; }
;             asm volatile("" : "+v"(p0), "+v"(p1));
;         }
; #pragma unroll
;         for (int r = 0; r < 16; ++r) { p0[r] = __builtin_amdgcn_exp2f(p0[r]); p1[r] = __builtin_amdgcn_exp2f(p1[r]); }
; #pragma unroll
;         for (int r = 0; r < 16; r += 2) { ls2 += (f32x2){p0[r], p0[r + 1]}; ls2 += (f32x2){p1[r], p1[r + 1]}; }
;         bf16x8 pa[4]; pa[0] = pack8(p0, 0); pa[1] = pack8(p0, 8); pa[2] = pack8(p1, 0); pa[3] = pack8(p1, 8);
;         LGKM0(); VREADS1(vb, 1); PV1(va, 0); LGKM0(); VREADS1(va, 2); PV1(vb, 1); LGKM0(); VREADS1(vb, 3); PV1(va, 2); LGKM0(); PV1(vb, 3);
.LatB_p0_nonear:
	v_max3_f32 v251, v84, v85, v86
	v_max3_f32 v252, v87, v88, v89
	v_max3_f32 v251, v251, v90, v91
	v_max3_f32 v252, v252, v92, v93
	v_max3_f32 v251, v251, v94, v95
	v_max3_f32 v252, v252, v96, v97
	v_max3_f32 v251, v251, v98, v99
	v_max3_f32 v252, v252, v100, v101
	v_max3_f32 v251, v251, v102, v103
	v_max3_f32 v252, v252, v104, v105
	v_max3_f32 v251, v251, v106, v107
	v_max3_f32 v252, v252, v108, v109
	v_max3_f32 v251, v251, v110, v111
	v_max3_f32 v252, v252, v112, v113
	v_max3_f32 v251, v251, v114, v115
	v_max_f32_e32 v251, v251, v252
	v_mov_b32_e32 v252, v251
	s_nop 1
	v_permlane32_swap_b32_e32 v251, v252
	v_max_f32_e32 v186, v251, v252
	v_sub_f32_e32 v84, v84, v186
	v_sub_f32_e32 v85, v85, v186
	v_sub_f32_e32 v86, v86, v186
	v_sub_f32_e32 v87, v87, v186
	v_sub_f32_e32 v88, v88, v186
	v_sub_f32_e32 v89, v89, v186
	v_sub_f32_e32 v90, v90, v186
	v_sub_f32_e32 v91, v91, v186
	v_sub_f32_e32 v92, v92, v186
	v_sub_f32_e32 v93, v93, v186
	v_sub_f32_e32 v94, v94, v186
	v_sub_f32_e32 v95, v95, v186
	v_sub_f32_e32 v96, v96, v186
	v_sub_f32_e32 v97, v97, v186
	v_sub_f32_e32 v98, v98, v186
	v_sub_f32_e32 v99, v99, v186
	v_sub_f32_e32 v100, v100, v186
	v_sub_f32_e32 v101, v101, v186
	v_sub_f32_e32 v102, v102, v186
	v_sub_f32_e32 v103, v103, v186
	v_sub_f32_e32 v104, v104, v186
	v_sub_f32_e32 v105, v105, v186
	v_sub_f32_e32 v106, v106, v186
	v_sub_f32_e32 v107, v107, v186
	v_sub_f32_e32 v108, v108, v186
	v_sub_f32_e32 v109, v109, v186
	v_sub_f32_e32 v110, v110, v186
	v_sub_f32_e32 v111, v111, v186
	v_sub_f32_e32 v112, v112, v186
	v_sub_f32_e32 v113, v113, v186
	v_sub_f32_e32 v114, v114, v186
	v_sub_f32_e32 v115, v115, v186
	s_add_u32 s29, s5, 64
	s_cmp_lt_u32 s29, s11
	s_cselect_b32 s24, 1, 0
	s_cmp_gt_u32 s29, s31
	s_cselect_b32 s30, 2, 0
	s_or_b32 s24, s24, s30
	s_mov_b32 s35, s24
	v_mov_b32_e32 v251, 0
	s_cmp_eq_u32 s24, 1
	s_cselect_b64 vcc, -1, 0
	v_cndmask_b32_e32 v251, v251, v177, vcc
	s_cmp_eq_u32 s24, 2
	s_cselect_b64 vcc, -1, 0
	v_cndmask_b32_e32 v251, v251, v178, vcc
	v_sub_f32_e32 v2, v251, v186
	v_mov_b32_e32 v3, v2
	v_mov_b64_e32 v[4:5], v[2:3]
	v_mov_b64_e32 v[6:7], v[2:3]
	v_mov_b64_e32 v[8:9], v[2:3]
	v_mov_b64_e32 v[10:11], v[2:3]
	v_mov_b64_e32 v[12:13], v[2:3]
	v_mov_b64_e32 v[14:15], v[2:3]
	v_mov_b64_e32 v[16:17], v[2:3]
	s_waitcnt vmcnt(0)
	s_barrier
	ds_read_b128 v[132:135], v19 offset:16384
	ds_read_b128 v[136:139], v19 offset:24576
	ds_read_b128 v[140:143], v180 offset:16384
	ds_read_b128 v[144:147], v180 offset:24576
	ds_read_b128 v[220:223], v181 offset:16384
	ds_read_b128 v[224:227], v181 offset:24576
	ds_read_b128 v[232:235], v182 offset:16384
	s_waitcnt lgkmcnt(6)
	s_add_u32 m0, s25, 0x1d000
	v_mfma_f32_32x32x16_bf16 v[188:203], v[132:135], v[116:119], v[2:17]
	global_load_lds_dwordx4 v172, s[8:9]
	ds_read_b128 v[236:239], v182 offset:24576
	v_exp_f32_e32 v84, v84
	v_exp_f32_e32 v85, v85
	v_exp_f32_e32 v86, v86
	v_exp_f32_e32 v87, v87
	v_exp_f32_e32 v88, v88
	v_pk_add_f32 v[252:253], v[84:85], v[86:87]
	v_exp_f32_e32 v89, v89
	s_waitcnt lgkmcnt(6)
	s_add_u32 m0, s27, 0x8000
	v_mfma_f32_32x32x16_bf16 v[204:219], v[136:139], v[116:119], v[2:17]
	global_load_lds_dwordx4 v174, s[8:9]
	ds_read_b64_tr_b16 v[132:133], v228 offset:0
	ds_read_b64_tr_b16 v[134:135], v228 offset:2048
	v_cvt_pk_bf16_f32 v84, v84, v85
	v_cvt_pk_bf16_f32 v85, v86, v87
	v_exp_f32_e32 v90, v90
	v_exp_f32_e32 v91, v91
	v_pk_add_f32 v[252:253], v[252:253], v[88:89]
	v_pk_add_f32 v[252:253], v[252:253], v[90:91]
	v_cvt_pk_bf16_f32 v86, v88, v89
	v_cvt_pk_bf16_f32 v87, v90, v91
	v_exp_f32_e32 v92, v92
	s_waitcnt lgkmcnt(7)
	s_add_u32 m0, s25, 0x1f000
	v_mfma_f32_32x32x16_bf16 v[188:203], v[140:143], v[120:123], v[188:203]
	global_load_lds_dwordx4 v173, s[8:9]
	ds_read_b64_tr_b16 v[136:137], v229 offset:0
	ds_read_b64_tr_b16 v[138:139], v229 offset:2048
	v_exp_f32_e32 v93, v93
	v_exp_f32_e32 v94, v94
	v_exp_f32_e32 v95, v95
	v_pk_add_f32 v[252:253], v[252:253], v[92:93]
	v_pk_add_f32 v[252:253], v[252:253], v[94:95]
	v_exp_f32_e32 v96, v96
	s_waitcnt lgkmcnt(8)
	s_add_u32 m0, s27, 0xa000
	v_mfma_f32_32x32x16_bf16 v[204:219], v[144:147], v[120:123], v[204:219]
	global_load_lds_dwordx4 v175, s[8:9]
	ds_read_b64_tr_b16 v[140:141], v230 offset:0
	ds_read_b64_tr_b16 v[142:143], v230 offset:2048
	v_exp_f32_e32 v97, v97
	v_cvt_pk_bf16_f32 v88, v92, v93
	v_cvt_pk_bf16_f32 v89, v94, v95
	v_exp_f32_e32 v98, v98
	v_exp_f32_e32 v99, v99
	v_pk_add_f32 v[252:253], v[252:253], v[96:97]
	v_pk_add_f32 v[252:253], v[252:253], v[98:99]
	v_cvt_pk_bf16_f32 v90, v96, v97
	v_cvt_pk_bf16_f32 v91, v98, v99
	s_waitcnt lgkmcnt(9)
	v_mfma_f32_32x32x16_bf16 v[188:203], v[220:223], v[124:127], v[188:203]
	ds_read_b64_tr_b16 v[144:145], v231 offset:0
	ds_read_b64_tr_b16 v[146:147], v231 offset:2048
	v_exp_f32_e32 v100, v100
	v_exp_f32_e32 v101, v101
	v_exp_f32_e32 v102, v102
	v_exp_f32_e32 v103, v103
	v_pk_add_f32 v[252:253], v[252:253], v[100:101]
	v_pk_add_f32 v[252:253], v[252:253], v[102:103]
	v_exp_f32_e32 v104, v104
	s_waitcnt lgkmcnt(10)
	v_mfma_f32_32x32x16_bf16 v[204:219], v[224:227], v[124:127], v[204:219]
	ds_read_b64_tr_b16 v[220:221], v228 offset:4096
	ds_read_b64_tr_b16 v[222:223], v228 offset:6144
	v_exp_f32_e32 v105, v105
	v_cvt_pk_bf16_f32 v100, v100, v101
	v_cvt_pk_bf16_f32 v101, v102, v103
	v_exp_f32_e32 v106, v106
	v_exp_f32_e32 v107, v107
	v_pk_add_f32 v[252:253], v[252:253], v[104:105]
	v_pk_add_f32 v[252:253], v[252:253], v[106:107]
	v_cvt_pk_bf16_f32 v102, v104, v105
	v_cvt_pk_bf16_f32 v103, v106, v107
	s_waitcnt lgkmcnt(11)
	v_mfma_f32_32x32x16_bf16 v[188:203], v[232:235], v[128:131], v[188:203]
	ds_read_b64_tr_b16 v[224:225], v229 offset:4096
	ds_read_b64_tr_b16 v[226:227], v229 offset:6144
	v_exp_f32_e32 v108, v108
	v_exp_f32_e32 v109, v109
	v_exp_f32_e32 v110, v110
	v_exp_f32_e32 v111, v111
	v_pk_add_f32 v[252:253], v[252:253], v[108:109]
	v_pk_add_f32 v[252:253], v[252:253], v[110:111]
	v_exp_f32_e32 v112, v112
	s_waitcnt lgkmcnt(12)
	v_mfma_f32_32x32x16_bf16 v[204:219], v[236:239], v[128:131], v[204:219]
	ds_read_b64_tr_b16 v[232:233], v230 offset:4096
	ds_read_b64_tr_b16 v[234:235], v230 offset:6144
	v_exp_f32_e32 v113, v113
	v_cvt_pk_bf16_f32 v104, v108, v109
	v_cvt_pk_bf16_f32 v105, v110, v111
	v_exp_f32_e32 v114, v114
	v_exp_f32_e32 v115, v115
	v_pk_add_f32 v[252:253], v[252:253], v[112:113]
	v_pk_add_f32 v[252:253], v[252:253], v[114:115]
	v_cvt_pk_bf16_f32 v106, v112, v113
	v_cvt_pk_bf16_f32 v107, v114, v115
	v_max_f32_e32 v251, v252, v253
	v_cmp_nge_f32_e32 vcc, 0x45800000, v251
	s_cbranch_vccnz .LatB_recs_h0

; __device__ __forceinline__ void attn_unit(LAS unsigned char* lds, const bf16_t* Z, bf16_t* A2, const float* tabg, int seq_base, int S, int h, int qb, float lam) {
;     ...
;             bf16x8 kf[8];
; #pragma unroll
;             for (int ds = 0; ds < 4; ++ds) { kf[2 * ds] = *(const LAS bf16x8*)(Kt + (kfo ^ (unsigned)(ds << 5))); kf[2 * ds + 1] = *(const LAS bf16x8*)(Kt + 32 * 256 + (kfo ^ (unsigned)(ds << 5))); }
;             __builtin_amdgcn_sched_barrier(0);
;             p0 = __builtin_amdgcn_mfma_f32_32x32x16_bf16(kf[0], qf[0], cblk, 0, 0, 0);
;             p1 = __builtin_amdgcn_mfma_f32_32x32x16_bf16(kf[1], qf[0], cblk, 0, 0, 0);
; #pragma unroll
;             for (int ds = 1; ds < 4; ++ds) {
;                 p0 = __builtin_amdgcn_mfma_f32_32x32x16_bf16(kf[2 * ds], qf[ds], p0, 0, 0, 0);
;                 p1 = __builtin_amdgcn_mfma_f32_32x32x16_bf16(kf[2 * ds + 1], qf[ds], p1, 0, 0, 0);
;             }
;         }
;     ...
;         const unsigned vbase = (unsigned)(size_t)Vt + vfo;
;         s16x4 va[8], vb[8];
;         VREADS1(va, 0);
;         if (near) {
;             const LAS float* tp = tab + (kv0 + 4 * hi - (qlo + r32) + 224);
; #pragma unroll
;             for (int r = 0; r < 16; ++r) { p0[r] += tp[(r & 3) + 8 * (r >> 2)]; p1[r] += tp[32 + (r & 3) + 8 * (r >> 2)]; }
;         }
;         float mx = max2f(max16f(p0), max16f(p1));
;         const bool first = (t == 0);
;         if (first || __any(mx > THR)) {
;             { auto rr = __builtin_amdgcn_permlane32_swap(__float_as_uint(mx), __float_as_uint(mx), false, false); mx = max2f(__uint_as_float(rr[0]), __uint_as_float(rr[1])); }
;             const float delta = first ? mx : fmaxf(mx, 0.f);
;             const float alpha = first ? 1.0f : __builtin_amdgcn_exp2f(-delta);
;             mu += delta; ls2 *= alpha;
;             if (!first) {
;                 asm volatile("" ::: "memory");
;                 scr[r32] = alpha;
;                 asm volatile("s_waitcnt lgkmcnt(0)" ::: "memory");
; #pragma unroll
;                 for (int g = 0; g < 4; ++g) { const f32x4 a4 = *(const LAS f32x4*)(scr + 8 * g + 4 * hi);
; #pragma unroll
;                     for (int d = 0; d < 4; ++d) { O[d][4 * g + 0] *= a4[0]; O[d][4 * g + 1] *= a4[1]; O[d][4 * g + 2] *= a4[2]; O[d][4 * g + 3] *= a4[3]; } }
;                 asm volatile("s_waitcnt lgkmcnt(0)" ::: "memory");
;             }
; #pragma unroll
.LatB_evret_h1:
	s_waitcnt lgkmcnt(12)
	v_mfma_f32_32x32x16_bf16 v[20:35], v[84:87], v[132:135], v[20:35]
	ds_read_b64_tr_b16 v[236:237], v231 offset:4096
	ds_read_b64_tr_b16 v[238:239], v231 offset:6144
	v_exp_f32_e32 v188, v188
	v_exp_f32_e32 v189, v189
	s_waitcnt lgkmcnt(12)
	v_mfma_f32_32x32x16_bf16 v[36:51], v[84:87], v[136:139], v[36:51]
	ds_read_b64_tr_b16 v[132:133], v228 offset:8192
	ds_read_b64_tr_b16 v[134:135], v228 offset:10240
	v_exp_f32_e32 v190, v190
	v_exp_f32_e32 v191, v191
	s_waitcnt lgkmcnt(12)
	v_mfma_f32_32x32x16_bf16 v[52:67], v[84:87], v[140:143], v[52:67]
	ds_read_b64_tr_b16 v[136:137], v229 offset:8192
	ds_read_b64_tr_b16 v[138:139], v229 offset:10240
	v_exp_f32_e32 v192, v192
	v_pk_add_f32 v[252:253], v[188:189], v[190:191]
	v_exp_f32_e32 v193, v193
	s_waitcnt lgkmcnt(12)
	s_mov_b32 m0, s25
	v_mfma_f32_32x32x16_bf16 v[68:83], v[84:87], v[144:147], v[68:83]
	global_load_lds_dwordx4 v172, s[8:9]
	ds_read_b64_tr_b16 v[140:141], v230 offset:8192
	ds_read_b64_tr_b16 v[142:143], v230 offset:10240
	v_cvt_pk_bf16_f32 v188, v188, v189
	v_cvt_pk_bf16_f32 v189, v190, v191
	v_exp_f32_e32 v194, v194
	s_waitcnt lgkmcnt(12)
	v_mfma_f32_32x32x16_bf16 v[20:35], v[88:91], v[220:223], v[20:35]
	ds_read_b64_tr_b16 v[144:145], v231 offset:8192
	ds_read_b64_tr_b16 v[146:147], v231 offset:10240
	v_exp_f32_e32 v195, v195
	v_pk_add_f32 v[252:253], v[252:253], v[192:193]
	s_waitcnt lgkmcnt(12)
	v_mfma_f32_32x32x16_bf16 v[36:51], v[88:91], v[224:227], v[36:51]
	ds_read_b64_tr_b16 v[220:221], v228 offset:12288
	ds_read_b64_tr_b16 v[222:223], v228 offset:14336
	v_pk_add_f32 v[252:253], v[252:253], v[194:195]
	v_cvt_pk_bf16_f32 v190, v192, v193
	v_cvt_pk_bf16_f32 v191, v194, v195
	v_exp_f32_e32 v196, v196
	s_waitcnt lgkmcnt(12)
	v_mfma_f32_32x32x16_bf16 v[52:67], v[88:91], v[232:235], v[52:67]
	ds_read_b64_tr_b16 v[224:225], v229 offset:12288
	ds_read_b64_tr_b16 v[226:227], v229 offset:14336
	v_exp_f32_e32 v197, v197
	v_exp_f32_e32 v198, v198
	s_waitcnt lgkmcnt(12)
	s_add_u32 m0, s27, 0xd000
	v_mfma_f32_32x32x16_bf16 v[68:83], v[88:91], v[236:239], v[68:83]
	global_load_lds_dwordx4 v174, s[8:9]
	ds_read_b64_tr_b16 v[232:233], v230 offset:12288
	ds_read_b64_tr_b16 v[234:235], v230 offset:14336
	v_exp_f32_e32 v199, v199
	v_pk_add_f32 v[252:253], v[252:253], v[196:197]
	s_waitcnt lgkmcnt(12)
	v_mfma_f32_32x32x16_bf16 v[20:35], v[100:103], v[132:135], v[20:35]
	ds_read_b64_tr_b16 v[236:237], v231 offset:12288
	ds_read_b64_tr_b16 v[238:239], v231 offset:14336
	v_pk_add_f32 v[252:253], v[252:253], v[198:199]
	v_exp_f32_e32 v200, v200
	s_waitcnt lgkmcnt(12)
	v_mfma_f32_32x32x16_bf16 v[36:51], v[100:103], v[136:139], v[36:51]
	ds_read_b128 v[132:135], v19 offset:32768
	v_exp_f32_e32 v201, v201
	v_cvt_pk_bf16_f32 v192, v196, v197
	v_cvt_pk_bf16_f32 v193, v198, v199
	v_exp_f32_e32 v202, v202
	s_waitcnt lgkmcnt(11)
	v_mfma_f32_32x32x16_bf16 v[52:67], v[100:103], v[140:143], v[52:67]
	ds_read_b128 v[136:139], v19 offset:40960
	v_exp_f32_e32 v203, v203
	v_pk_add_f32 v[252:253], v[252:253], v[200:201]
	s_waitcnt lgkmcnt(10)
	s_add_u32 m0, s25, 0x2000
	v_mfma_f32_32x32x16_bf16 v[68:83], v[100:103], v[144:147], v[68:83]
	global_load_lds_dwordx4 v173, s[8:9]
	ds_read_b128 v[140:143], v180 offset:32768
	v_pk_add_f32 v[252:253], v[252:253], v[202:203]
	v_cvt_pk_bf16_f32 v194, v200, v201
	v_cvt_pk_bf16_f32 v195, v202, v203
	s_waitcnt lgkmcnt(9)
	v_mfma_f32_32x32x16_bf16 v[20:35], v[104:107], v[220:223], v[20:35]
	ds_read_b128 v[144:147], v180 offset:40960
	v_exp_f32_e32 v204, v204
	v_exp_f32_e32 v205, v205
	v_exp_f32_e32 v206, v206
	s_waitcnt lgkmcnt(8)
	v_mfma_f32_32x32x16_bf16 v[36:51], v[104:107], v[224:227], v[36:51]
	ds_read_b128 v[220:223], v181 offset:32768
	v_exp_f32_e32 v207, v207
	v_pk_add_f32 v[252:253], v[252:253], v[204:205]
	s_waitcnt lgkmcnt(7)
	v_mfma_f32_32x32x16_bf16 v[52:67], v[104:107], v[232:235], v[52:67]
	ds_read_b128 v[224:227], v181 offset:40960
	v_pk_add_f32 v[252:253], v[252:253], v[206:207]
	v_exp_f32_e32 v208, v208
	s_waitcnt lgkmcnt(6)
	s_add_u32 m0, s27, 0xf000
	v_mfma_f32_32x32x16_bf16 v[68:83], v[104:107], v[236:239], v[68:83]
	global_load_lds_dwordx4 v175, s[8:9]
	ds_read_b128 v[232:235], v182 offset:32768
	v_exp_f32_e32 v209, v209
	v_cvt_pk_bf16_f32 v204, v204, v205
	v_cvt_pk_bf16_f32 v205, v206, v207
	s_waitcnt lgkmcnt(6)
	v_mfma_f32_32x32x16_bf16 v[84:99], v[132:135], v[116:119], v[2:17]
	ds_read_b128 v[236:239], v182 offset:40960
	v_exp_f32_e32 v210, v210
	v_exp_f32_e32 v211, v211
	v_pk_add_f32 v[252:253], v[252:253], v[208:209]
	s_waitcnt lgkmcnt(6)
	v_mfma_f32_32x32x16_bf16 v[100:115], v[136:139], v[116:119], v[2:17]
	ds_read_b64_tr_b16 v[132:133], v228 offset:16384
	ds_read_b64_tr_b16 v[134:135], v228 offset:18432
	v_pk_add_f32 v[252:253], v[252:253], v[210:211]
	v_cvt_pk_bf16_f32 v206, v208, v209
	v_cvt_pk_bf16_f32 v207, v210, v211
	s_waitcnt lgkmcnt(7)
	v_mfma_f32_32x32x16_bf16 v[84:99], v[140:143], v[120:123], v[84:99]
	ds_read_b64_tr_b16 v[136:137], v229 offset:16384
	ds_read_b64_tr_b16 v[138:139], v229 offset:18432
	v_exp_f32_e32 v212, v212
	v_exp_f32_e32 v213, v213
	s_waitcnt lgkmcnt(8)
	v_mfma_f32_32x32x16_bf16 v[100:115], v[144:147], v[120:123], v[100:115]
	ds_read_b64_tr_b16 v[140:141], v230 offset:16384
	ds_read_b64_tr_b16 v[142:143], v230 offset:18432
	v_exp_f32_e32 v214, v214
	v_exp_f32_e32 v215, v215
	v_pk_add_f32 v[252:253], v[252:253], v[212:213]
	s_waitcnt lgkmcnt(9)
	v_mfma_f32_32x32x16_bf16 v[84:99], v[220:223], v[124:127], v[84:99]
	ds_read_b64_tr_b16 v[144:145], v231 offset:16384
	ds_read_b64_tr_b16 v[146:147], v231 offset:18432
	v_pk_add_f32 v[252:253], v[252:253], v[214:215]
	v_exp_f32_e32 v216, v216
	s_waitcnt lgkmcnt(10)
	v_mfma_f32_32x32x16_bf16 v[100:115], v[224:227], v[124:127], v[100:115]
	ds_read_b64_tr_b16 v[220:221], v228 offset:20480
	ds_read_b64_tr_b16 v[222:223], v228 offset:22528
	v_exp_f32_e32 v217, v217
	v_cvt_pk_bf16_f32 v208, v212, v213
	v_cvt_pk_bf16_f32 v209, v214, v215
	s_waitcnt lgkmcnt(11)
	v_mfma_f32_32x32x16_bf16 v[84:99], v[232:235], v[128:131], v[84:99]
	ds_read_b64_tr_b16 v[224:225], v229 offset:20480
	ds_read_b64_tr_b16 v[226:227], v229 offset:22528
	v_exp_f32_e32 v218, v218
	v_exp_f32_e32 v219, v219
	s_waitcnt lgkmcnt(12)
	v_mfma_f32_32x32x16_bf16 v[100:115], v[236:239], v[128:131], v[100:115]
	ds_read_b64_tr_b16 v[232:233], v230 offset:20480
	ds_read_b64_tr_b16 v[234:235], v230 offset:22528
	v_pk_add_f32 v[252:253], v[252:253], v[216:217]
	v_pk_add_f32 v[252:253], v[252:253], v[218:219]
	v_cvt_pk_bf16_f32 v210, v216, v217
	v_cvt_pk_bf16_f32 v211, v218, v219
	v_max_f32_e32 v251, v252, v253
	v_cmp_nge_f32_e32 vcc, 0x45800000, v251
	s_cbranch_vccnz .LatB_recs_h1

; __device__ __forceinline__ void attn_unit(LAS unsigned char* lds, const bf16_t* Z, bf16_t* A2, const float* tabg, int seq_base, int S, int h, int qb, float lam) {
;     ...
;             bf16x8 kf[8];
; #pragma unroll
;             for (int ds = 0; ds < 4; ++ds) { kf[2 * ds] = *(const LAS bf16x8*)(Kt + (kfo ^ (unsigned)(ds << 5))); kf[2 * ds + 1] = *(const LAS bf16x8*)(Kt + 32 * 256 + (kfo ^ (unsigned)(ds << 5))); }
;             __builtin_amdgcn_sched_barrier(0);
;             p0 = __builtin_amdgcn_mfma_f32_32x32x16_bf16(kf[0], qf[0], cblk, 0, 0, 0);
;             p1 = __builtin_amdgcn_mfma_f32_32x32x16_bf16(kf[1], qf[0], cblk, 0, 0, 0);
; #pragma unroll
;             for (int ds = 1; ds < 4; ++ds) {
;                 p0 = __builtin_amdgcn_mfma_f32_32x32x16_bf16(kf[2 * ds], qf[ds], p0, 0, 0, 0);
;                 p1 = __builtin_amdgcn_mfma_f32_32x32x16_bf16(kf[2 * ds + 1], qf[ds], p1, 0, 0, 0);
;             }
;         }
;     ...
;         const unsigned vbase = (unsigned)(size_t)Vt + vfo;
;         s16x4 va[8], vb[8];
;         VREADS1(va, 0);
;         if (near) {
;             const LAS float* tp = tab + (kv0 + 4 * hi - (qlo + r32) + 224);
; #pragma unroll
;             for (int r = 0; r < 16; ++r) { p0[r] += tp[(r & 3) + 8 * (r >> 2)]; p1[r] += tp[32 + (r & 3) + 8 * (r >> 2)]; }
;         }
;         float mx = max2f(max16f(p0), max16f(p1));
;         const bool first = (t == 0);
;         if (first || __any(mx > THR)) {
;             { auto rr = __builtin_amdgcn_permlane32_swap(__float_as_uint(mx), __float_as_uint(mx), false, false); mx = max2f(__uint_as_float(rr[0]), __uint_as_float(rr[1])); }
;             const float delta = first ? mx : fmaxf(mx, 0.f);
;             const float alpha = first ? 1.0f : __builtin_amdgcn_exp2f(-delta);
;             mu += delta; ls2 *= alpha;
;             if (!first) {
;                 asm volatile("" ::: "memory");
;                 scr[r32] = alpha;
;                 asm volatile("s_waitcnt lgkmcnt(0)" ::: "memory");
; #pragma unroll
;                 for (int g = 0; g < 4; ++g) { const f32x4 a4 = *(const LAS f32x4*)(scr + 8 * g + 4 * hi);
; #pragma unroll
;                     for (int d = 0; d < 4; ++d) { O[d][4 * g + 0] *= a4[0]; O[d][4 * g + 1] *= a4[1]; O[d][4 * g + 2] *= a4[2]; O[d][4 * g + 3] *= a4[3]; } }
;                 asm volatile("s_waitcnt lgkmcnt(0)" ::: "memory");
;             }
; #pragma unroll
.LatB_evret_h2:
	s_waitcnt lgkmcnt(12)
	v_mfma_f32_32x32x16_bf16 v[20:35], v[188:191], v[132:135], v[20:35]
	ds_read_b64_tr_b16 v[236:237], v231 offset:20480
	ds_read_b64_tr_b16 v[238:239], v231 offset:22528
	v_exp_f32_e32 v84, v84
	v_exp_f32_e32 v85, v85
	s_waitcnt lgkmcnt(12)
	v_mfma_f32_32x32x16_bf16 v[36:51], v[188:191], v[136:139], v[36:51]
	ds_read_b64_tr_b16 v[132:133], v228 offset:24576
	ds_read_b64_tr_b16 v[134:135], v228 offset:26624
	v_exp_f32_e32 v86, v86
	v_exp_f32_e32 v87, v87
	s_waitcnt lgkmcnt(12)
	v_mfma_f32_32x32x16_bf16 v[52:67], v[188:191], v[140:143], v[52:67]
	ds_read_b64_tr_b16 v[136:137], v229 offset:24576
	ds_read_b64_tr_b16 v[138:139], v229 offset:26624
	v_exp_f32_e32 v88, v88
	v_pk_add_f32 v[252:253], v[84:85], v[86:87]
	v_exp_f32_e32 v89, v89
	s_waitcnt lgkmcnt(12)
	s_add_u32 m0, s25, 0x4000
	v_mfma_f32_32x32x16_bf16 v[68:83], v[188:191], v[144:147], v[68:83]
	global_load_lds_dwordx4 v172, s[8:9]
	ds_read_b64_tr_b16 v[140:141], v230 offset:24576
	ds_read_b64_tr_b16 v[142:143], v230 offset:26624
	v_cvt_pk_bf16_f32 v84, v84, v85
	v_cvt_pk_bf16_f32 v85, v86, v87
	v_exp_f32_e32 v90, v90
	s_waitcnt lgkmcnt(12)
	v_mfma_f32_32x32x16_bf16 v[20:35], v[192:195], v[220:223], v[20:35]
	ds_read_b64_tr_b16 v[144:145], v231 offset:24576
	ds_read_b64_tr_b16 v[146:147], v231 offset:26624
	v_exp_f32_e32 v91, v91
	v_pk_add_f32 v[252:253], v[252:253], v[88:89]
	s_waitcnt lgkmcnt(12)
	v_mfma_f32_32x32x16_bf16 v[36:51], v[192:195], v[224:227], v[36:51]
	ds_read_b64_tr_b16 v[220:221], v228 offset:28672
	ds_read_b64_tr_b16 v[222:223], v228 offset:30720
	v_pk_add_f32 v[252:253], v[252:253], v[90:91]
	v_cvt_pk_bf16_f32 v86, v88, v89
	v_cvt_pk_bf16_f32 v87, v90, v91
	v_exp_f32_e32 v92, v92
	s_waitcnt lgkmcnt(12)
	v_mfma_f32_32x32x16_bf16 v[52:67], v[192:195], v[232:235], v[52:67]
	ds_read_b64_tr_b16 v[224:225], v229 offset:28672
	ds_read_b64_tr_b16 v[226:227], v229 offset:30720
	v_exp_f32_e32 v93, v93
	v_exp_f32_e32 v94, v94
	s_waitcnt lgkmcnt(12)
	s_mov_b32 m0, s27
	v_mfma_f32_32x32x16_bf16 v[68:83], v[192:195], v[236:239], v[68:83]
	global_load_lds_dwordx4 v174, s[8:9]
	ds_read_b64_tr_b16 v[232:233], v230 offset:28672
	ds_read_b64_tr_b16 v[234:235], v230 offset:30720
	v_exp_f32_e32 v95, v95
	v_pk_add_f32 v[252:253], v[252:253], v[92:93]
	s_waitcnt lgkmcnt(12)
	v_mfma_f32_32x32x16_bf16 v[20:35], v[204:207], v[132:135], v[20:35]
	ds_read_b64_tr_b16 v[236:237], v231 offset:28672
	ds_read_b64_tr_b16 v[238:239], v231 offset:30720
	v_pk_add_f32 v[252:253], v[252:253], v[94:95]
	v_exp_f32_e32 v96, v96
	s_waitcnt lgkmcnt(12)
	v_mfma_f32_32x32x16_bf16 v[36:51], v[204:207], v[136:139], v[36:51]
	ds_read_b128 v[132:135], v164
	v_exp_f32_e32 v97, v97
	v_cvt_pk_bf16_f32 v88, v92, v93
	v_cvt_pk_bf16_f32 v89, v94, v95
	v_exp_f32_e32 v98, v98
	s_waitcnt lgkmcnt(11)
	v_mfma_f32_32x32x16_bf16 v[52:67], v[204:207], v[140:143], v[52:67]
	ds_read_b128 v[136:139], v164 offset:8192
	v_exp_f32_e32 v99, v99
	v_pk_add_f32 v[252:253], v[252:253], v[96:97]
	s_waitcnt lgkmcnt(10)
	s_add_u32 m0, s25, 0x6000
	v_mfma_f32_32x32x16_bf16 v[68:83], v[204:207], v[144:147], v[68:83]
	global_load_lds_dwordx4 v173, s[8:9]
	ds_read_b128 v[140:143], v165
	v_pk_add_f32 v[252:253], v[252:253], v[98:99]
	v_cvt_pk_bf16_f32 v90, v96, v97
	v_cvt_pk_bf16_f32 v91, v98, v99
	s_waitcnt lgkmcnt(9)
	v_mfma_f32_32x32x16_bf16 v[20:35], v[208:211], v[220:223], v[20:35]
	ds_read_b128 v[144:147], v165 offset:8192
	v_exp_f32_e32 v100, v100
	v_exp_f32_e32 v101, v101
	v_exp_f32_e32 v102, v102
	s_waitcnt lgkmcnt(8)
	v_mfma_f32_32x32x16_bf16 v[36:51], v[208:211], v[224:227], v[36:51]
	ds_read_b128 v[220:223], v166
	v_exp_f32_e32 v103, v103
	v_pk_add_f32 v[252:253], v[252:253], v[100:101]
	s_waitcnt lgkmcnt(7)
	v_mfma_f32_32x32x16_bf16 v[52:67], v[208:211], v[232:235], v[52:67]
	ds_read_b128 v[224:227], v166 offset:8192
	v_pk_add_f32 v[252:253], v[252:253], v[102:103]
	v_exp_f32_e32 v104, v104
	s_waitcnt lgkmcnt(6)
	s_add_u32 m0, s27, 0x2000
	v_mfma_f32_32x32x16_bf16 v[68:83], v[208:211], v[236:239], v[68:83]
	global_load_lds_dwordx4 v175, s[8:9]
	ds_read_b128 v[232:235], v167
	v_exp_f32_e32 v105, v105
	v_cvt_pk_bf16_f32 v100, v100, v101
	v_cvt_pk_bf16_f32 v101, v102, v103
	s_waitcnt lgkmcnt(6)
	v_mfma_f32_32x32x16_bf16 v[188:203], v[132:135], v[116:119], v[2:17]
	ds_read_b128 v[236:239], v167 offset:8192
	v_exp_f32_e32 v106, v106
	v_exp_f32_e32 v107, v107
	v_pk_add_f32 v[252:253], v[252:253], v[104:105]
	s_waitcnt lgkmcnt(6)
	v_mfma_f32_32x32x16_bf16 v[204:219], v[136:139], v[116:119], v[2:17]
	ds_read_b64_tr_b16 v[132:133], v228 offset:32768
	ds_read_b64_tr_b16 v[134:135], v228 offset:34816
	v_pk_add_f32 v[252:253], v[252:253], v[106:107]
	v_cvt_pk_bf16_f32 v102, v104, v105
	v_cvt_pk_bf16_f32 v103, v106, v107
	s_waitcnt lgkmcnt(7)
	v_mfma_f32_32x32x16_bf16 v[188:203], v[140:143], v[120:123], v[188:203]
	ds_read_b64_tr_b16 v[136:137], v229 offset:32768
	ds_read_b64_tr_b16 v[138:139], v229 offset:34816
	v_exp_f32_e32 v108, v108
	v_exp_f32_e32 v109, v109
	s_waitcnt lgkmcnt(8)
	v_mfma_f32_32x32x16_bf16 v[204:219], v[144:147], v[120:123], v[204:219]
	ds_read_b64_tr_b16 v[140:141], v230 offset:32768
	ds_read_b64_tr_b16 v[142:143], v230 offset:34816
	v_exp_f32_e32 v110, v110
	v_exp_f32_e32 v111, v111
	v_pk_add_f32 v[252:253], v[252:253], v[108:109]
	s_waitcnt lgkmcnt(9)
	v_mfma_f32_32x32x16_bf16 v[188:203], v[220:223], v[124:127], v[188:203]
	ds_read_b64_tr_b16 v[144:145], v231 offset:32768
	ds_read_b64_tr_b16 v[146:147], v231 offset:34816
	v_pk_add_f32 v[252:253], v[252:253], v[110:111]
	v_exp_f32_e32 v112, v112
	s_waitcnt lgkmcnt(10)
	v_mfma_f32_32x32x16_bf16 v[204:219], v[224:227], v[124:127], v[204:219]
	ds_read_b64_tr_b16 v[220:221], v228 offset:36864
	ds_read_b64_tr_b16 v[222:223], v228 offset:38912
	v_exp_f32_e32 v113, v113
	v_cvt_pk_bf16_f32 v104, v108, v109
	v_cvt_pk_bf16_f32 v105, v110, v111
	s_waitcnt lgkmcnt(11)
	v_mfma_f32_32x32x16_bf16 v[188:203], v[232:235], v[128:131], v[188:203]
	ds_read_b64_tr_b16 v[224:225], v229 offset:36864
	ds_read_b64_tr_b16 v[226:227], v229 offset:38912
	v_exp_f32_e32 v114, v114
	v_exp_f32_e32 v115, v115
	s_waitcnt lgkmcnt(12)
	v_mfma_f32_32x32x16_bf16 v[204:219], v[236:239], v[128:131], v[204:219]
	ds_read_b64_tr_b16 v[232:233], v230 offset:36864
	ds_read_b64_tr_b16 v[234:235], v230 offset:38912
	v_pk_add_f32 v[252:253], v[252:253], v[112:113]
	v_pk_add_f32 v[252:253], v[252:253], v[114:115]
	v_cvt_pk_bf16_f32 v106, v112, v113
	v_cvt_pk_bf16_f32 v107, v114, v115
	v_max_f32_e32 v251, v252, v253
	v_cmp_nge_f32_e32 vcc, 0x45800000, v251
	s_cbranch_vccnz .LatB_recs_h2

; __device__ __forceinline__ void attn_unit(LAS unsigned char* lds, const bf16_t* Z, bf16_t* A2, const float* tabg, int seq_base, int S, int h, int qb, float lam) {
;     ...
;             bf16x8 kf[8];
; #pragma unroll
;             for (int ds = 0; ds < 4; ++ds) { kf[2 * ds] = *(const LAS bf16x8*)(Kt + (kfo ^ (unsigned)(ds << 5))); kf[2 * ds + 1] = *(const LAS bf16x8*)(Kt + 32 * 256 + (kfo ^ (unsigned)(ds << 5))); }
;             __builtin_amdgcn_sched_barrier(0);
;             p0 = __builtin_amdgcn_mfma_f32_32x32x16_bf16(kf[0], qf[0], cblk, 0, 0, 0);
;             p1 = __builtin_amdgcn_mfma_f32_32x32x16_bf16(kf[1], qf[0], cblk, 0, 0, 0);
; #pragma unroll
;             for (int ds = 1; ds < 4; ++ds) {
;                 p0 = __builtin_amdgcn_mfma_f32_32x32x16_bf16(kf[2 * ds], qf[ds], p0, 0, 0, 0);
;                 p1 = __builtin_amdgcn_mfma_f32_32x32x16_bf16(kf[2 * ds + 1], qf[ds], p1, 0, 0, 0);
;             }
;         }
;     ...
;         const unsigned vbase = (unsigned)(size_t)Vt + vfo;
;         s16x4 va[8], vb[8];
;         VREADS1(va, 0);
;         if (near) {
;             const LAS float* tp = tab + (kv0 + 4 * hi - (qlo + r32) + 224);
; #pragma unroll
;             for (int r = 0; r < 16; ++r) { p0[r] += tp[(r & 3) + 8 * (r >> 2)]; p1[r] += tp[32 + (r & 3) + 8 * (r >> 2)]; }
;         }
;         float mx = max2f(max16f(p0), max16f(p1));
;         const bool first = (t == 0);
;         if (first || __any(mx > THR)) {
;             { auto rr = __builtin_amdgcn_permlane32_swap(__float_as_uint(mx), __float_as_uint(mx), false, false); mx = max2f(__uint_as_float(rr[0]), __uint_as_float(rr[1])); }
;             const float delta = first ? mx : fmaxf(mx, 0.f);
;             const float alpha = first ? 1.0f : __builtin_amdgcn_exp2f(-delta);
;             mu += delta; ls2 *= alpha;
;             if (!first) {
;                 asm volatile("" ::: "memory");
;                 scr[r32] = alpha;
;                 asm volatile("s_waitcnt lgkmcnt(0)" ::: "memory");
; #pragma unroll
;                 for (int g = 0; g < 4; ++g) { const f32x4 a4 = *(const LAS f32x4*)(scr + 8 * g + 4 * hi);
; #pragma unroll
;                     for (int d = 0; d < 4; ++d) { O[d][4 * g + 0] *= a4[0]; O[d][4 * g + 1] *= a4[1]; O[d][4 * g + 2] *= a4[2]; O[d][4 * g + 3] *= a4[3]; } }
;                 asm volatile("s_waitcnt lgkmcnt(0)" ::: "memory");
;             }
; #pragma unroll
.LatB_evret_h3:
	s_waitcnt lgkmcnt(12)
	v_mfma_f32_32x32x16_bf16 v[20:35], v[84:87], v[132:135], v[20:35]
	ds_read_b64_tr_b16 v[236:237], v231 offset:36864
	ds_read_b64_tr_b16 v[238:239], v231 offset:38912
	v_exp_f32_e32 v188, v188
	v_exp_f32_e32 v189, v189
	s_waitcnt lgkmcnt(12)
	v_mfma_f32_32x32x16_bf16 v[36:51], v[84:87], v[136:139], v[36:51]
	ds_read_b64_tr_b16 v[132:133], v228 offset:40960
	ds_read_b64_tr_b16 v[134:135], v228 offset:43008
	v_exp_f32_e32 v190, v190
	v_exp_f32_e32 v191, v191
	s_waitcnt lgkmcnt(12)
	v_mfma_f32_32x32x16_bf16 v[52:67], v[84:87], v[140:143], v[52:67]
	ds_read_b64_tr_b16 v[136:137], v229 offset:40960
	ds_read_b64_tr_b16 v[138:139], v229 offset:43008
	v_exp_f32_e32 v192, v192
	v_pk_add_f32 v[252:253], v[188:189], v[190:191]
	v_exp_f32_e32 v193, v193
	s_waitcnt lgkmcnt(12)
	s_add_u32 m0, s25, 0x8000
	v_mfma_f32_32x32x16_bf16 v[68:83], v[84:87], v[144:147], v[68:83]
	global_load_lds_dwordx4 v172, s[8:9]
	ds_read_b64_tr_b16 v[140:141], v230 offset:40960
	ds_read_b64_tr_b16 v[142:143], v230 offset:43008
	v_cvt_pk_bf16_f32 v188, v188, v189
	v_cvt_pk_bf16_f32 v189, v190, v191
	v_exp_f32_e32 v194, v194
	s_waitcnt lgkmcnt(12)
	v_mfma_f32_32x32x16_bf16 v[20:35], v[88:91], v[220:223], v[20:35]
	ds_read_b64_tr_b16 v[144:145], v231 offset:40960
	ds_read_b64_tr_b16 v[146:147], v231 offset:43008
	v_exp_f32_e32 v195, v195
	v_pk_add_f32 v[252:253], v[252:253], v[192:193]
	s_waitcnt lgkmcnt(12)
	v_mfma_f32_32x32x16_bf16 v[36:51], v[88:91], v[224:227], v[36:51]
	ds_read_b64_tr_b16 v[220:221], v228 offset:45056
	ds_read_b64_tr_b16 v[222:223], v228 offset:47104
	v_pk_add_f32 v[252:253], v[252:253], v[194:195]
	v_cvt_pk_bf16_f32 v190, v192, v193
	v_cvt_pk_bf16_f32 v191, v194, v195
	v_exp_f32_e32 v196, v196
	s_waitcnt lgkmcnt(12)
	v_mfma_f32_32x32x16_bf16 v[52:67], v[88:91], v[232:235], v[52:67]
	ds_read_b64_tr_b16 v[224:225], v229 offset:45056
	ds_read_b64_tr_b16 v[226:227], v229 offset:47104
	v_exp_f32_e32 v197, v197
	v_exp_f32_e32 v198, v198
	s_waitcnt lgkmcnt(12)
	s_add_u32 m0, s27, 0x4000
	v_mfma_f32_32x32x16_bf16 v[68:83], v[88:91], v[236:239], v[68:83]
	global_load_lds_dwordx4 v174, s[8:9]
	ds_read_b64_tr_b16 v[232:233], v230 offset:45056
	ds_read_b64_tr_b16 v[234:235], v230 offset:47104
	v_exp_f32_e32 v199, v199
	v_pk_add_f32 v[252:253], v[252:253], v[196:197]
	s_waitcnt lgkmcnt(12)
	v_mfma_f32_32x32x16_bf16 v[20:35], v[100:103], v[132:135], v[20:35]
	ds_read_b64_tr_b16 v[236:237], v231 offset:45056
	ds_read_b64_tr_b16 v[238:239], v231 offset:47104
	v_pk_add_f32 v[252:253], v[252:253], v[198:199]
	v_exp_f32_e32 v200, v200
	s_waitcnt lgkmcnt(12)
	v_mfma_f32_32x32x16_bf16 v[36:51], v[100:103], v[136:139], v[36:51]
	ds_read_b128 v[132:135], v19
	v_exp_f32_e32 v201, v201
	v_cvt_pk_bf16_f32 v192, v196, v197
	v_cvt_pk_bf16_f32 v193, v198, v199
	v_exp_f32_e32 v202, v202
	s_waitcnt lgkmcnt(11)
	v_mfma_f32_32x32x16_bf16 v[52:67], v[100:103], v[140:143], v[52:67]
	ds_read_b128 v[136:139], v19 offset:8192
	v_exp_f32_e32 v203, v203
	v_pk_add_f32 v[252:253], v[252:253], v[200:201]
	s_waitcnt lgkmcnt(10)
	s_add_u32 m0, s25, 0xa000
	v_mfma_f32_32x32x16_bf16 v[68:83], v[100:103], v[144:147], v[68:83]
	global_load_lds_dwordx4 v173, s[8:9]
	ds_read_b128 v[140:143], v180
	v_pk_add_f32 v[252:253], v[252:253], v[202:203]
	v_cvt_pk_bf16_f32 v194, v200, v201
	v_cvt_pk_bf16_f32 v195, v202, v203
	s_waitcnt lgkmcnt(9)
	v_mfma_f32_32x32x16_bf16 v[20:35], v[104:107], v[220:223], v[20:35]
	ds_read_b128 v[144:147], v180 offset:8192
	v_exp_f32_e32 v204, v204
	v_exp_f32_e32 v205, v205
	v_exp_f32_e32 v206, v206
	s_waitcnt lgkmcnt(8)
	v_mfma_f32_32x32x16_bf16 v[36:51], v[104:107], v[224:227], v[36:51]
	ds_read_b128 v[220:223], v181
	v_exp_f32_e32 v207, v207
	v_pk_add_f32 v[252:253], v[252:253], v[204:205]
	s_waitcnt lgkmcnt(7)
	v_mfma_f32_32x32x16_bf16 v[52:67], v[104:107], v[232:235], v[52:67]
	ds_read_b128 v[224:227], v181 offset:8192
	v_pk_add_f32 v[252:253], v[252:253], v[206:207]
	v_exp_f32_e32 v208, v208
	s_waitcnt lgkmcnt(6)
	s_add_u32 m0, s27, 0x6000
	v_mfma_f32_32x32x16_bf16 v[68:83], v[104:107], v[236:239], v[68:83]
	global_load_lds_dwordx4 v175, s[8:9]
	ds_read_b128 v[232:235], v182
	v_exp_f32_e32 v209, v209
	v_cvt_pk_bf16_f32 v204, v204, v205
	v_cvt_pk_bf16_f32 v205, v206, v207
	s_waitcnt lgkmcnt(6)
	v_mfma_f32_32x32x16_bf16 v[84:99], v[132:135], v[116:119], v[2:17]
	ds_read_b128 v[236:239], v182 offset:8192
	v_exp_f32_e32 v210, v210
	v_exp_f32_e32 v211, v211
	v_pk_add_f32 v[252:253], v[252:253], v[208:209]
	s_waitcnt lgkmcnt(6)
	v_mfma_f32_32x32x16_bf16 v[100:115], v[136:139], v[116:119], v[2:17]
	ds_read_b64_tr_b16 v[132:133], v168 offset:0
	ds_read_b64_tr_b16 v[134:135], v168 offset:2048
	v_pk_add_f32 v[252:253], v[252:253], v[210:211]
	v_cvt_pk_bf16_f32 v206, v208, v209
	v_cvt_pk_bf16_f32 v207, v210, v211
	s_waitcnt lgkmcnt(7)
	v_mfma_f32_32x32x16_bf16 v[84:99], v[140:143], v[120:123], v[84:99]
	ds_read_b64_tr_b16 v[136:137], v169 offset:0
	ds_read_b64_tr_b16 v[138:139], v169 offset:2048
	v_exp_f32_e32 v212, v212
	v_exp_f32_e32 v213, v213
	s_waitcnt lgkmcnt(8)
	v_mfma_f32_32x32x16_bf16 v[100:115], v[144:147], v[120:123], v[100:115]
	ds_read_b64_tr_b16 v[140:141], v170 offset:0
	ds_read_b64_tr_b16 v[142:143], v170 offset:2048
	v_exp_f32_e32 v214, v214
	v_exp_f32_e32 v215, v215
	v_pk_add_f32 v[252:253], v[252:253], v[212:213]
	s_waitcnt lgkmcnt(9)
	v_mfma_f32_32x32x16_bf16 v[84:99], v[220:223], v[124:127], v[84:99]
	ds_read_b64_tr_b16 v[144:145], v171 offset:0
	ds_read_b64_tr_b16 v[146:147], v171 offset:2048
	v_pk_add_f32 v[252:253], v[252:253], v[214:215]
	v_exp_f32_e32 v216, v216
	s_waitcnt lgkmcnt(10)
	v_mfma_f32_32x32x16_bf16 v[100:115], v[224:227], v[124:127], v[100:115]
	ds_read_b64_tr_b16 v[220:221], v168 offset:4096
	ds_read_b64_tr_b16 v[222:223], v168 offset:6144
	v_exp_f32_e32 v217, v217
	v_cvt_pk_bf16_f32 v208, v212, v213
	v_cvt_pk_bf16_f32 v209, v214, v215
	s_waitcnt lgkmcnt(11)
	v_mfma_f32_32x32x16_bf16 v[84:99], v[232:235], v[128:131], v[84:99]
	ds_read_b64_tr_b16 v[224:225], v169 offset:4096
	ds_read_b64_tr_b16 v[226:227], v169 offset:6144
	v_exp_f32_e32 v218, v218
	v_exp_f32_e32 v219, v219
	s_waitcnt lgkmcnt(12)
	v_mfma_f32_32x32x16_bf16 v[100:115], v[236:239], v[128:131], v[100:115]
	ds_read_b64_tr_b16 v[232:233], v170 offset:4096
	ds_read_b64_tr_b16 v[234:235], v170 offset:6144
	v_pk_add_f32 v[252:253], v[252:253], v[216:217]
	v_pk_add_f32 v[252:253], v[252:253], v[218:219]
	v_cvt_pk_bf16_f32 v210, v216, v217
	v_cvt_pk_bf16_f32 v211, v218, v219
	v_max_f32_e32 v251, v252, v253
	v_cmp_nge_f32_e32 vcc, 0x45800000, v251
	s_cbranch_vccnz .LatB_recs_h3
.LatB_recret_h3:
	v_pk_add_f32 v[150:151], v[150:151], v[252:253]
	s_add_u32 s8, s8, 0x40000
	s_addc_u32 s9, s9, 0
	s_waitcnt vmcnt(4)
	s_barrier
	s_movk_i32 s36, 62

; __device__ __forceinline__ void attn_unit(LAS unsigned char* lds, const bf16_t* Z, bf16_t* A2, const float* tabg, int seq_base, int S, int h, int qb, float lam) {
;     ...
;             bf16x8 kf[8];
; #pragma unroll
;             for (int ds = 0; ds < 4; ++ds) { kf[2 * ds] = *(const LAS bf16x8*)(Kt + (kfo ^ (unsigned)(ds << 5))); kf[2 * ds + 1] = *(const LAS bf16x8*)(Kt + 32 * 256 + (kfo ^ (unsigned)(ds << 5))); }
;             __builtin_amdgcn_sched_barrier(0);
;             p0 = __builtin_amdgcn_mfma_f32_32x32x16_bf16(kf[0], qf[0], cblk, 0, 0, 0);
;             p1 = __builtin_amdgcn_mfma_f32_32x32x16_bf16(kf[1], qf[0], cblk, 0, 0, 0);
; #pragma unroll
;             for (int ds = 1; ds < 4; ++ds) {
;                 p0 = __builtin_amdgcn_mfma_f32_32x32x16_bf16(kf[2 * ds], qf[ds], p0, 0, 0, 0);
;                 p1 = __builtin_amdgcn_mfma_f32_32x32x16_bf16(kf[2 * ds + 1], qf[ds], p1, 0, 0, 0);
;             }
;         }
;     ...
;         const unsigned vbase = (unsigned)(size_t)Vt + vfo;
;         s16x4 va[8], vb[8];
;         VREADS1(va, 0);
;         if (near) {
;             const LAS float* tp = tab + (kv0 + 4 * hi - (qlo + r32) + 224);
; #pragma unroll
;             for (int r = 0; r < 16; ++r) { p0[r] += tp[(r & 3) + 8 * (r >> 2)]; p1[r] += tp[32 + (r & 3) + 8 * (r >> 2)]; }
;         }
;         float mx = max2f(max16f(p0), max16f(p1));
;         const bool first = (t == 0);
;         if (first || __any(mx > THR)) {
;             { auto rr = __builtin_amdgcn_permlane32_swap(__float_as_uint(mx), __float_as_uint(mx), false, false); mx = max2f(__uint_as_float(rr[0]), __uint_as_float(rr[1])); }
;             const float delta = first ? mx : fmaxf(mx, 0.f);
;             const float alpha = first ? 1.0f : __builtin_amdgcn_exp2f(-delta);
;             mu += delta; ls2 *= alpha;
;             if (!first) {
;                 asm volatile("" ::: "memory");
;                 scr[r32] = alpha;
;                 asm volatile("s_waitcnt lgkmcnt(0)" ::: "memory");
; #pragma unroll
;                 for (int g = 0; g < 4; ++g) { const f32x4 a4 = *(const LAS f32x4*)(scr + 8 * g + 4 * hi);
; #pragma unroll
;                     for (int d = 0; d < 4; ++d) { O[d][4 * g + 0] *= a4[0]; O[d][4 * g + 1] *= a4[1]; O[d][4 * g + 2] *= a4[2]; O[d][4 * g + 3] *= a4[3]; } }
;                 asm volatile("s_waitcnt lgkmcnt(0)" ::: "memory");
;             }
; #pragma unroll
.LatB_evret_m0:
	s_waitcnt lgkmcnt(12)
	v_mfma_f32_32x32x16_bf16 v[20:35], v[188:191], v[132:135], v[20:35]
	ds_read_b64_tr_b16 v[236:237], v171 offset:4096
	ds_read_b64_tr_b16 v[238:239], v171 offset:6144
	v_exp_f32_e32 v84, v84
	v_exp_f32_e32 v85, v85
	s_waitcnt lgkmcnt(12)
	v_mfma_f32_32x32x16_bf16 v[36:51], v[188:191], v[136:139], v[36:51]
	ds_read_b64_tr_b16 v[132:133], v168 offset:8192
	ds_read_b64_tr_b16 v[134:135], v168 offset:10240
	v_exp_f32_e32 v86, v86
	v_exp_f32_e32 v87, v87
	s_waitcnt lgkmcnt(12)
	v_mfma_f32_32x32x16_bf16 v[52:67], v[188:191], v[140:143], v[52:67]
	ds_read_b64_tr_b16 v[136:137], v169 offset:8192
	ds_read_b64_tr_b16 v[138:139], v169 offset:10240
	v_exp_f32_e32 v88, v88
	v_pk_add_f32 v[252:253], v[84:85], v[86:87]
	v_exp_f32_e32 v89, v89
	s_waitcnt lgkmcnt(12)
	s_add_u32 m0, s25, 0x1d000
	v_mfma_f32_32x32x16_bf16 v[68:83], v[188:191], v[144:147], v[68:83]
	global_load_lds_dwordx4 v172, s[8:9]
	ds_read_b64_tr_b16 v[140:141], v170 offset:8192
	ds_read_b64_tr_b16 v[142:143], v170 offset:10240
	v_cvt_pk_bf16_f32 v84, v84, v85
	v_cvt_pk_bf16_f32 v85, v86, v87
	v_exp_f32_e32 v90, v90
	s_waitcnt lgkmcnt(12)
	v_mfma_f32_32x32x16_bf16 v[20:35], v[192:195], v[220:223], v[20:35]
	ds_read_b64_tr_b16 v[144:145], v171 offset:8192
	ds_read_b64_tr_b16 v[146:147], v171 offset:10240
	v_exp_f32_e32 v91, v91
	v_pk_add_f32 v[252:253], v[252:253], v[88:89]
	s_waitcnt lgkmcnt(12)
	v_mfma_f32_32x32x16_bf16 v[36:51], v[192:195], v[224:227], v[36:51]
	ds_read_b64_tr_b16 v[220:221], v168 offset:12288
	ds_read_b64_tr_b16 v[222:223], v168 offset:14336
	v_pk_add_f32 v[252:253], v[252:253], v[90:91]
	v_cvt_pk_bf16_f32 v86, v88, v89
	v_cvt_pk_bf16_f32 v87, v90, v91
	v_exp_f32_e32 v92, v92
	s_waitcnt lgkmcnt(12)
	v_mfma_f32_32x32x16_bf16 v[52:67], v[192:195], v[232:235], v[52:67]
	ds_read_b64_tr_b16 v[224:225], v169 offset:12288
	ds_read_b64_tr_b16 v[226:227], v169 offset:14336
	v_exp_f32_e32 v93, v93
	v_exp_f32_e32 v94, v94
	s_waitcnt lgkmcnt(12)
	s_add_u32 m0, s27, 0x8000
	v_mfma_f32_32x32x16_bf16 v[68:83], v[192:195], v[236:239], v[68:83]
	global_load_lds_dwordx4 v174, s[8:9]
	ds_read_b64_tr_b16 v[232:233], v170 offset:12288
	ds_read_b64_tr_b16 v[234:235], v170 offset:14336
	v_exp_f32_e32 v95, v95
	v_pk_add_f32 v[252:253], v[252:253], v[92:93]
	s_waitcnt lgkmcnt(12)
	v_mfma_f32_32x32x16_bf16 v[20:35], v[204:207], v[132:135], v[20:35]
	ds_read_b64_tr_b16 v[236:237], v171 offset:12288
	ds_read_b64_tr_b16 v[238:239], v171 offset:14336
	v_pk_add_f32 v[252:253], v[252:253], v[94:95]
	v_exp_f32_e32 v96, v96
	s_waitcnt lgkmcnt(12)
	v_mfma_f32_32x32x16_bf16 v[36:51], v[204:207], v[136:139], v[36:51]
	ds_read_b128 v[132:135], v19 offset:16384
	v_exp_f32_e32 v97, v97
	v_cvt_pk_bf16_f32 v88, v92, v93
	v_cvt_pk_bf16_f32 v89, v94, v95
	v_exp_f32_e32 v98, v98
	s_waitcnt lgkmcnt(11)
	v_mfma_f32_32x32x16_bf16 v[52:67], v[204:207], v[140:143], v[52:67]
	ds_read_b128 v[136:139], v19 offset:24576
	v_exp_f32_e32 v99, v99
	v_pk_add_f32 v[252:253], v[252:253], v[96:97]
	s_waitcnt lgkmcnt(10)
	s_add_u32 m0, s25, 0x1f000
	v_mfma_f32_32x32x16_bf16 v[68:83], v[204:207], v[144:147], v[68:83]
	global_load_lds_dwordx4 v173, s[8:9]
	ds_read_b128 v[140:143], v180 offset:16384
	v_pk_add_f32 v[252:253], v[252:253], v[98:99]
	v_cvt_pk_bf16_f32 v90, v96, v97
	v_cvt_pk_bf16_f32 v91, v98, v99
	s_waitcnt lgkmcnt(9)
	v_mfma_f32_32x32x16_bf16 v[20:35], v[208:211], v[220:223], v[20:35]
	ds_read_b128 v[144:147], v180 offset:24576
	v_exp_f32_e32 v100, v100
	v_exp_f32_e32 v101, v101
	v_exp_f32_e32 v102, v102
	s_waitcnt lgkmcnt(8)
	v_mfma_f32_32x32x16_bf16 v[36:51], v[208:211], v[224:227], v[36:51]
	ds_read_b128 v[220:223], v181 offset:16384
	v_exp_f32_e32 v103, v103
	v_pk_add_f32 v[252:253], v[252:253], v[100:101]
	s_waitcnt lgkmcnt(7)
	v_mfma_f32_32x32x16_bf16 v[52:67], v[208:211], v[232:235], v[52:67]
	ds_read_b128 v[224:227], v181 offset:24576
	v_pk_add_f32 v[252:253], v[252:253], v[102:103]
	v_exp_f32_e32 v104, v104
	s_waitcnt lgkmcnt(6)
	s_add_u32 m0, s27, 0xa000
	v_mfma_f32_32x32x16_bf16 v[68:83], v[208:211], v[236:239], v[68:83]
	global_load_lds_dwordx4 v175, s[8:9]
	ds_read_b128 v[232:235], v182 offset:16384
	v_exp_f32_e32 v105, v105
	v_cvt_pk_bf16_f32 v100, v100, v101
	v_cvt_pk_bf16_f32 v101, v102, v103
	s_waitcnt lgkmcnt(6)
	v_mfma_f32_32x32x16_bf16 v[188:203], v[132:135], v[116:119], v[2:17]
	ds_read_b128 v[236:239], v182 offset:24576
	v_exp_f32_e32 v106, v106
	v_exp_f32_e32 v107, v107
	v_pk_add_f32 v[252:253], v[252:253], v[104:105]
	s_waitcnt lgkmcnt(6)
	v_mfma_f32_32x32x16_bf16 v[204:219], v[136:139], v[116:119], v[2:17]
	ds_read_b64_tr_b16 v[132:133], v228 offset:0
	ds_read_b64_tr_b16 v[134:135], v228 offset:2048
	v_pk_add_f32 v[252:253], v[252:253], v[106:107]
	v_cvt_pk_bf16_f32 v102, v104, v105
	v_cvt_pk_bf16_f32 v103, v106, v107
	s_waitcnt lgkmcnt(7)
	v_mfma_f32_32x32x16_bf16 v[188:203], v[140:143], v[120:123], v[188:203]
	ds_read_b64_tr_b16 v[136:137], v229 offset:0
	ds_read_b64_tr_b16 v[138:139], v229 offset:2048
	v_exp_f32_e32 v108, v108
	v_exp_f32_e32 v109, v109
	s_waitcnt lgkmcnt(8)
	v_mfma_f32_32x32x16_bf16 v[204:219], v[144:147], v[120:123], v[204:219]
	ds_read_b64_tr_b16 v[140:141], v230 offset:0
	ds_read_b64_tr_b16 v[142:143], v230 offset:2048
	v_exp_f32_e32 v110, v110
	v_exp_f32_e32 v111, v111
	v_pk_add_f32 v[252:253], v[252:253], v[108:109]
	s_waitcnt lgkmcnt(9)
	v_mfma_f32_32x32x16_bf16 v[188:203], v[220:223], v[124:127], v[188:203]
	ds_read_b64_tr_b16 v[144:145], v231 offset:0
	ds_read_b64_tr_b16 v[146:147], v231 offset:2048
	v_pk_add_f32 v[252:253], v[252:253], v[110:111]
	v_exp_f32_e32 v112, v112
	s_waitcnt lgkmcnt(10)
	v_mfma_f32_32x32x16_bf16 v[204:219], v[224:227], v[124:127], v[204:219]
	ds_read_b64_tr_b16 v[220:221], v228 offset:4096
	ds_read_b64_tr_b16 v[222:223], v228 offset:6144
	v_exp_f32_e32 v113, v113
	v_cvt_pk_bf16_f32 v104, v108, v109
	v_cvt_pk_bf16_f32 v105, v110, v111
	s_waitcnt lgkmcnt(11)
	v_mfma_f32_32x32x16_bf16 v[188:203], v[232:235], v[128:131], v[188:203]
	ds_read_b64_tr_b16 v[224:225], v229 offset:4096
	ds_read_b64_tr_b16 v[226:227], v229 offset:6144
	v_exp_f32_e32 v114, v114
	v_exp_f32_e32 v115, v115
	s_waitcnt lgkmcnt(12)
	v_mfma_f32_32x32x16_bf16 v[204:219], v[236:239], v[128:131], v[204:219]
	ds_read_b64_tr_b16 v[232:233], v230 offset:4096
	ds_read_b64_tr_b16 v[234:235], v230 offset:6144
	v_pk_add_f32 v[252:253], v[252:253], v[112:113]
	v_pk_add_f32 v[252:253], v[252:253], v[114:115]
	v_cvt_pk_bf16_f32 v106, v112, v113
	v_cvt_pk_bf16_f32 v107, v114, v115
	v_max_f32_e32 v251, v252, v253
	v_cmp_nge_f32_e32 vcc, 0x45800000, v251
	s_cbranch_vccnz .LatB_recs_m0

; __device__ __forceinline__ void attn_unit(LAS unsigned char* lds, const bf16_t* Z, bf16_t* A2, const float* tabg, int seq_base, int S, int h, int qb, float lam) {
;     ...
;             bf16x8 kf[8];
; #pragma unroll
;             for (int ds = 0; ds < 4; ++ds) { kf[2 * ds] = *(const LAS bf16x8*)(Kt + (kfo ^ (unsigned)(ds << 5))); kf[2 * ds + 1] = *(const LAS bf16x8*)(Kt + 32 * 256 + (kfo ^ (unsigned)(ds << 5))); }
;             __builtin_amdgcn_sched_barrier(0);
;             p0 = __builtin_amdgcn_mfma_f32_32x32x16_bf16(kf[0], qf[0], cblk, 0, 0, 0);
;             p1 = __builtin_amdgcn_mfma_f32_32x32x16_bf16(kf[1], qf[0], cblk, 0, 0, 0);
; #pragma unroll
;             for (int ds = 1; ds < 4; ++ds) {
;                 p0 = __builtin_amdgcn_mfma_f32_32x32x16_bf16(kf[2 * ds], qf[ds], p0, 0, 0, 0);
;                 p1 = __builtin_amdgcn_mfma_f32_32x32x16_bf16(kf[2 * ds + 1], qf[ds], p1, 0, 0, 0);
;             }
;         }
;     ...
;         const unsigned vbase = (unsigned)(size_t)Vt + vfo;
;         s16x4 va[8], vb[8];
;         VREADS1(va, 0);
;         if (near) {
;             const LAS float* tp = tab + (kv0 + 4 * hi - (qlo + r32) + 224);
; #pragma unroll
;             for (int r = 0; r < 16; ++r) { p0[r] += tp[(r & 3) + 8 * (r >> 2)]; p1[r] += tp[32 + (r & 3) + 8 * (r >> 2)]; }
;         }
;         float mx = max2f(max16f(p0), max16f(p1));
;         const bool first = (t == 0);
;         if (first || __any(mx > THR)) {
;             { auto rr = __builtin_amdgcn_permlane32_swap(__float_as_uint(mx), __float_as_uint(mx), false, false); mx = max2f(__uint_as_float(rr[0]), __uint_as_float(rr[1])); }
;             const float delta = first ? mx : fmaxf(mx, 0.f);
;             const float alpha = first ? 1.0f : __builtin_amdgcn_exp2f(-delta);
;             mu += delta; ls2 *= alpha;
;             if (!first) {
;                 asm volatile("" ::: "memory");
;                 scr[r32] = alpha;
;                 asm volatile("s_waitcnt lgkmcnt(0)" ::: "memory");
; #pragma unroll
;                 for (int g = 0; g < 4; ++g) { const f32x4 a4 = *(const LAS f32x4*)(scr + 8 * g + 4 * hi);
; #pragma unroll
;                     for (int d = 0; d < 4; ++d) { O[d][4 * g + 0] *= a4[0]; O[d][4 * g + 1] *= a4[1]; O[d][4 * g + 2] *= a4[2]; O[d][4 * g + 3] *= a4[3]; } }
;                 asm volatile("s_waitcnt lgkmcnt(0)" ::: "memory");
;             }
; #pragma unroll
.LatB_evret_x3:
	s_waitcnt lgkmcnt(12)
	v_mfma_f32_32x32x16_bf16 v[20:35], v[84:87], v[132:135], v[20:35]
	ds_read_b64_tr_b16 v[236:237], v231 offset:4096
	ds_read_b64_tr_b16 v[238:239], v231 offset:6144
	v_exp_f32_e32 v188, v188
	v_exp_f32_e32 v189, v189
	s_waitcnt lgkmcnt(12)
	v_mfma_f32_32x32x16_bf16 v[36:51], v[84:87], v[136:139], v[36:51]
	ds_read_b64_tr_b16 v[132:133], v228 offset:8192
	ds_read_b64_tr_b16 v[134:135], v228 offset:10240
	v_exp_f32_e32 v190, v190
	v_exp_f32_e32 v191, v191
	s_waitcnt lgkmcnt(12)
	v_mfma_f32_32x32x16_bf16 v[52:67], v[84:87], v[140:143], v[52:67]
	ds_read_b64_tr_b16 v[136:137], v229 offset:8192
	ds_read_b64_tr_b16 v[138:139], v229 offset:10240
	v_exp_f32_e32 v192, v192
	v_pk_add_f32 v[252:253], v[188:189], v[190:191]
	v_exp_f32_e32 v193, v193
	s_waitcnt lgkmcnt(12)
	v_mfma_f32_32x32x16_bf16 v[68:83], v[84:87], v[144:147], v[68:83]
	ds_read_b64_tr_b16 v[140:141], v230 offset:8192
	ds_read_b64_tr_b16 v[142:143], v230 offset:10240
	v_cvt_pk_bf16_f32 v188, v188, v189
	v_cvt_pk_bf16_f32 v189, v190, v191
	v_exp_f32_e32 v194, v194
	s_waitcnt lgkmcnt(12)
	v_mfma_f32_32x32x16_bf16 v[20:35], v[88:91], v[220:223], v[20:35]
	ds_read_b64_tr_b16 v[144:145], v231 offset:8192
	ds_read_b64_tr_b16 v[146:147], v231 offset:10240
	v_exp_f32_e32 v195, v195
	v_pk_add_f32 v[252:253], v[252:253], v[192:193]
	s_waitcnt lgkmcnt(12)
	v_mfma_f32_32x32x16_bf16 v[36:51], v[88:91], v[224:227], v[36:51]
	ds_read_b64_tr_b16 v[220:221], v228 offset:12288
	ds_read_b64_tr_b16 v[222:223], v228 offset:14336
	v_pk_add_f32 v[252:253], v[252:253], v[194:195]
	v_cvt_pk_bf16_f32 v190, v192, v193
	v_cvt_pk_bf16_f32 v191, v194, v195
	v_exp_f32_e32 v196, v196
	s_waitcnt lgkmcnt(12)
	v_mfma_f32_32x32x16_bf16 v[52:67], v[88:91], v[232:235], v[52:67]
	ds_read_b64_tr_b16 v[224:225], v229 offset:12288
	ds_read_b64_tr_b16 v[226:227], v229 offset:14336
	v_exp_f32_e32 v197, v197
	v_exp_f32_e32 v198, v198
	s_waitcnt lgkmcnt(12)
	s_add_u32 m0, s27, 0xd000
	v_mfma_f32_32x32x16_bf16 v[68:83], v[88:91], v[236:239], v[68:83]
	global_load_lds_dwordx4 v174, s[8:9]
	ds_read_b64_tr_b16 v[232:233], v230 offset:12288
	ds_read_b64_tr_b16 v[234:235], v230 offset:14336
	v_exp_f32_e32 v199, v199
	v_pk_add_f32 v[252:253], v[252:253], v[196:197]
	s_waitcnt lgkmcnt(12)
	v_mfma_f32_32x32x16_bf16 v[20:35], v[100:103], v[132:135], v[20:35]
	ds_read_b64_tr_b16 v[236:237], v231 offset:12288
	ds_read_b64_tr_b16 v[238:239], v231 offset:14336
	v_pk_add_f32 v[252:253], v[252:253], v[198:199]
	v_exp_f32_e32 v200, v200
	s_waitcnt lgkmcnt(12)
	v_mfma_f32_32x32x16_bf16 v[36:51], v[100:103], v[136:139], v[36:51]
	ds_read_b128 v[132:135], v19 offset:32768
	v_exp_f32_e32 v201, v201
	v_cvt_pk_bf16_f32 v192, v196, v197
	v_cvt_pk_bf16_f32 v193, v198, v199
	v_exp_f32_e32 v202, v202
	s_waitcnt lgkmcnt(11)
	v_mfma_f32_32x32x16_bf16 v[52:67], v[100:103], v[140:143], v[52:67]
	ds_read_b128 v[136:139], v19 offset:40960
	v_exp_f32_e32 v203, v203
	v_pk_add_f32 v[252:253], v[252:253], v[200:201]
	s_waitcnt lgkmcnt(10)
	v_mfma_f32_32x32x16_bf16 v[68:83], v[100:103], v[144:147], v[68:83]
	ds_read_b128 v[140:143], v180 offset:32768
	v_pk_add_f32 v[252:253], v[252:253], v[202:203]
	v_cvt_pk_bf16_f32 v194, v200, v201
	v_cvt_pk_bf16_f32 v195, v202, v203
	s_waitcnt lgkmcnt(9)
	v_mfma_f32_32x32x16_bf16 v[20:35], v[104:107], v[220:223], v[20:35]
	ds_read_b128 v[144:147], v180 offset:40960
	v_exp_f32_e32 v204, v204
	v_exp_f32_e32 v205, v205
	v_exp_f32_e32 v206, v206
	s_waitcnt lgkmcnt(8)
	v_mfma_f32_32x32x16_bf16 v[36:51], v[104:107], v[224:227], v[36:51]
	ds_read_b128 v[220:223], v181 offset:32768
	v_exp_f32_e32 v207, v207
	v_pk_add_f32 v[252:253], v[252:253], v[204:205]
	s_waitcnt lgkmcnt(7)
	v_mfma_f32_32x32x16_bf16 v[52:67], v[104:107], v[232:235], v[52:67]
	ds_read_b128 v[224:227], v181 offset:40960
	v_pk_add_f32 v[252:253], v[252:253], v[206:207]
	v_exp_f32_e32 v208, v208
	s_waitcnt lgkmcnt(6)
	s_add_u32 m0, s27, 0xf000
	v_mfma_f32_32x32x16_bf16 v[68:83], v[104:107], v[236:239], v[68:83]
	global_load_lds_dwordx4 v175, s[8:9]
	ds_read_b128 v[232:235], v182 offset:32768
	v_exp_f32_e32 v209, v209
	v_cvt_pk_bf16_f32 v204, v204, v205
	v_cvt_pk_bf16_f32 v205, v206, v207
	s_waitcnt lgkmcnt(6)
	v_mfma_f32_32x32x16_bf16 v[84:99], v[132:135], v[116:119], v[2:17]
	ds_read_b128 v[236:239], v182 offset:40960
	v_exp_f32_e32 v210, v210
	v_exp_f32_e32 v211, v211
	v_pk_add_f32 v[252:253], v[252:253], v[208:209]
	s_waitcnt lgkmcnt(6)
	v_mfma_f32_32x32x16_bf16 v[100:115], v[136:139], v[116:119], v[2:17]
	ds_read_b64_tr_b16 v[132:133], v228 offset:16384
	ds_read_b64_tr_b16 v[134:135], v228 offset:18432
	v_pk_add_f32 v[252:253], v[252:253], v[210:211]
	v_cvt_pk_bf16_f32 v206, v208, v209
	v_cvt_pk_bf16_f32 v207, v210, v211
	s_waitcnt lgkmcnt(7)
	v_mfma_f32_32x32x16_bf16 v[84:99], v[140:143], v[120:123], v[84:99]
	ds_read_b64_tr_b16 v[136:137], v229 offset:16384
	ds_read_b64_tr_b16 v[138:139], v229 offset:18432
	v_exp_f32_e32 v212, v212
	v_exp_f32_e32 v213, v213
	s_waitcnt lgkmcnt(8)
	v_mfma_f32_32x32x16_bf16 v[100:115], v[144:147], v[120:123], v[100:115]
	ds_read_b64_tr_b16 v[140:141], v230 offset:16384
	ds_read_b64_tr_b16 v[142:143], v230 offset:18432
	v_exp_f32_e32 v214, v214
	v_exp_f32_e32 v215, v215
	v_pk_add_f32 v[252:253], v[252:253], v[212:213]
	s_waitcnt lgkmcnt(9)
	v_mfma_f32_32x32x16_bf16 v[84:99], v[220:223], v[124:127], v[84:99]
	ds_read_b64_tr_b16 v[144:145], v231 offset:16384
	ds_read_b64_tr_b16 v[146:147], v231 offset:18432
	v_pk_add_f32 v[252:253], v[252:253], v[214:215]
	v_exp_f32_e32 v216, v216
	s_waitcnt lgkmcnt(10)
	v_mfma_f32_32x32x16_bf16 v[100:115], v[224:227], v[124:127], v[100:115]
	ds_read_b64_tr_b16 v[220:221], v228 offset:20480
	ds_read_b64_tr_b16 v[222:223], v228 offset:22528
	v_exp_f32_e32 v217, v217
	v_cvt_pk_bf16_f32 v208, v212, v213
	v_cvt_pk_bf16_f32 v209, v214, v215
	s_waitcnt lgkmcnt(11)
	v_mfma_f32_32x32x16_bf16 v[84:99], v[232:235], v[128:131], v[84:99]
	ds_read_b64_tr_b16 v[224:225], v229 offset:20480
	ds_read_b64_tr_b16 v[226:227], v229 offset:22528
	v_exp_f32_e32 v218, v218
	v_exp_f32_e32 v219, v219
	s_waitcnt lgkmcnt(12)
	v_mfma_f32_32x32x16_bf16 v[100:115], v[236:239], v[128:131], v[100:115]
	ds_read_b64_tr_b16 v[232:233], v230 offset:20480
	ds_read_b64_tr_b16 v[234:235], v230 offset:22528
	v_pk_add_f32 v[252:253], v[252:253], v[216:217]
	v_pk_add_f32 v[252:253], v[252:253], v[218:219]
	v_cvt_pk_bf16_f32 v210, v216, v217
	v_cvt_pk_bf16_f32 v211, v218, v219
	v_max_f32_e32 v251, v252, v253
	v_cmp_nge_f32_e32 vcc, 0x45800000, v251
	s_cbranch_vccnz .LatB_recs_x3

; __device__ __forceinline__ float max2f(float a, float b) { float r; asm("v_max_f32_e32 %0, %1, %2" : "=v"(r) : "v"(a), "v"(b)); return r; }
; __device__ __forceinline__ void attn_unit(LAS unsigned char* lds, const bf16_t* Z, bf16_t* A2, const float* tabg, int seq_base, int S, int h, int qb, float lam) {
;     ...
;         if (first || __any(mx > THR)) {
;             { auto rr = __builtin_amdgcn_permlane32_swap(__float_as_uint(mx), __float_as_uint(mx), false, false); mx = max2f(__uint_as_float(rr[0]), __uint_as_float(rr[1])); }
;             const float delta = first ? mx : fmaxf(mx, 0.f);
;             const float alpha = first ? 1.0f : __builtin_amdgcn_exp2f(-delta);
;             mu += delta; ls2 *= alpha;
;             if (!first) {
.LatB_evs_m0:
	s_mov_b32 s22, 1
	s_branch .LatB_ev_01
.LatB_recs_m0:
	s_mov_b32 s22, 1
	s_branch .LatB_rec_0

; __device__ __forceinline__ float max2f(float a, float b) { float r; asm("v_max_f32_e32 %0, %1, %2" : "=v"(r) : "v"(a), "v"(b)); return r; }
; __device__ __forceinline__ void attn_unit(LAS unsigned char* lds, const bf16_t* Z, bf16_t* A2, const float* tabg, int seq_base, int S, int h, int qb, float lam) {
;     ...
;         if (first || __any(mx > THR)) {
;             { auto rr = __builtin_amdgcn_permlane32_swap(__float_as_uint(mx), __float_as_uint(mx), false, false); mx = max2f(__uint_as_float(rr[0]), __uint_as_float(rr[1])); }
;             const float delta = first ? mx : fmaxf(mx, 0.f);
;             const float alpha = first ? 1.0f : __builtin_amdgcn_exp2f(-delta);
;             mu += delta; ls2 *= alpha;
;             if (!first) {
.LatB_evs_x4:
	s_mov_b32 s22, 3
	s_branch .LatB_ev_01
.LatB_recs_x4:
	s_mov_b32 s22, 2
	s_branch .LatB_rec_0

; #define LAS __attribute__((address_space(3)))
; #define VREADS1(arr, d_) do { const unsigned ad_ = vbase ^ (unsigned)((d_) << 6); __builtin_amdgcn_sched_barrier(0); \
;         _Pragma("unroll") for (int ks_ = 0; ks_ < 4; ++ks_) { VTR(arr[ks_ * 2], ad_, ks_ * 4096); VTR(arr[ks_ * 2 + 1], ad_, ks_ * 4096 + 2048); } __builtin_amdgcn_sched_barrier(0); } while (0)
; __device__ __forceinline__ void attn_unit(LAS unsigned char* lds, const bf16_t* Z, bf16_t* A2, const float* tabg, int seq_base, int S, int h, int qb, float lam) {
;     ...
;         bool near = true; float cc = 0.f;
;         if (kv0 - (qlo + 31) >= 128) { near = false; cc = tabR; } else if (qlo - (kv0 + 63) >= 128) { near = false; cc = tabL; }
;         { const float coff = cc - mu;
;           if (__any(!(coff == coff_cur))) { coff_cur = coff;
; #pragma unroll
;               for (int r = 0; r < 16; ++r) cblk[r] = coff;
;               asm volatile("" : "+v"(cblk)); } }
;         f32x16 p0, p1;
;         {
;             bf16x8 kf[8];
; #pragma unroll
;             for (int ds = 0; ds < 4; ++ds) { kf[2 * ds] = *(const LAS bf16x8*)(Kt + (kfo ^ (unsigned)(ds << 5))); kf[2 * ds + 1] = *(const LAS bf16x8*)(Kt + 32 * 256 + (kfo ^ (unsigned)(ds << 5))); }
;             __builtin_amdgcn_sched_barrier(0);
;             p0 = __builtin_amdgcn_mfma_f32_32x32x16_bf16(kf[0], qf[0], cblk, 0, 0, 0);
;             p1 = __builtin_amdgcn_mfma_f32_32x32x16_bf16(kf[1], qf[0], cblk, 0, 0, 0);
; #pragma unroll
;             for (int ds = 1; ds < 4; ++ds) {
;                 p0 = __builtin_amdgcn_mfma_f32_32x32x16_bf16(kf[2 * ds], qf[ds], p0, 0, 0, 0);
;                 p1 = __builtin_amdgcn_mfma_f32_32x32x16_bf16(kf[2 * ds + 1], qf[ds], p1, 0, 0, 0);
;             }
;         }
;     ...
;         const unsigned vbase = (unsigned)(size_t)Vt + vfo;
;         s16x4 va[8], vb[8];
;         VREADS1(va, 0);
;         if (near) {
;             const LAS float* tp = tab + (kv0 + 4 * hi - (qlo + r32) + 224);
; #pragma unroll
;             for (int r = 0; r < 16; ++r) { p0[r] += tp[(r & 3) + 8 * (r >> 2)]; p1[r] += tp[32 + (r & 3) + 8 * (r >> 2)]; }
;         }
.LatB_recs_x1:
	s_mov_b32 s22, 2
	s_branch .LatB_rec_3
.LatB_ev_11:
	s_sub_u32 s5, s8, s4
	s_lshr_b32 s5, s5, 12
	s_sub_u32 s5, s5, 64
	s_cmp_ge_u32 s5, s11
	s_cselect_b32 s24, 1, 0
	s_cmp_le_u32 s5, s31
	s_cselect_b32 s29, 1, 0
	s_and_b32 s24, s24, s29
	s_add_u32 s29, s5, 64
	s_cmp_le_u32 s29, s31
	s_cselect_b32 s10, 0, 0x7fffffff
	s_cmp_eq_u32 s24, 0
	s_cbranch_scc1 .LatB_evnn_11
	s_lshl_b32 s29, s5, 2
	s_add_i32 s29, s29, 0x18b80
	v_add_u32_e32 v187, s29, v162
	ds_read2_b32 v[92:93], v187 offset0:0 offset1:1
	ds_read2_b32 v[94:95], v187 offset0:2 offset1:3
	ds_read2_b32 v[96:97], v187 offset0:8 offset1:9
	ds_read2_b32 v[98:99], v187 offset0:10 offset1:11
	ds_read2_b32 v[108:109], v187 offset0:16 offset1:17
	ds_read2_b32 v[110:111], v187 offset0:18 offset1:19
	ds_read2_b32 v[112:113], v187 offset0:24 offset1:25
	ds_read2_b32 v[114:115], v187 offset0:26 offset1:27
	s_waitcnt lgkmcnt(0)
	v_pk_add_f32 v[188:189], v[188:189], v[92:93]
	v_pk_add_f32 v[190:191], v[190:191], v[94:95]
	v_pk_add_f32 v[192:193], v[192:193], v[96:97]
	v_pk_add_f32 v[194:195], v[194:195], v[98:99]
	v_pk_add_f32 v[196:197], v[196:197], v[108:109]
	v_pk_add_f32 v[198:199], v[198:199], v[110:111]
	v_pk_add_f32 v[200:201], v[200:201], v[112:113]
	v_pk_add_f32 v[202:203], v[202:203], v[114:115]
	ds_read2_b32 v[92:93], v187 offset0:32 offset1:33
	ds_read2_b32 v[94:95], v187 offset0:34 offset1:35
	ds_read2_b32 v[96:97], v187 offset0:40 offset1:41
	ds_read2_b32 v[98:99], v187 offset0:42 offset1:43
	ds_read2_b32 v[108:109], v187 offset0:48 offset1:49
	ds_read2_b32 v[110:111], v187 offset0:50 offset1:51
	ds_read2_b32 v[112:113], v187 offset0:56 offset1:57
	ds_read2_b32 v[114:115], v187 offset0:58 offset1:59
	s_waitcnt lgkmcnt(0)
	v_pk_add_f32 v[204:205], v[204:205], v[92:93]
	v_pk_add_f32 v[206:207], v[206:207], v[94:95]
	v_pk_add_f32 v[208:209], v[208:209], v[96:97]
	v_pk_add_f32 v[210:211], v[210:211], v[98:99]
	v_pk_add_f32 v[212:213], v[212:213], v[108:109]
	v_pk_add_f32 v[214:215], v[214:215], v[110:111]
	v_pk_add_f32 v[216:217], v[216:217], v[112:113]
	v_pk_add_f32 v[218:219], v[218:219], v[114:115]

; __device__ __forceinline__ void attn_unit(LAS unsigned char* lds, const bf16_t* Z, bf16_t* A2, const float* tabg, int seq_base, int S, int h, int qb, float lam) {
;     ...
;         bool near = true; float cc = 0.f;
;         if (kv0 - (qlo + 31) >= 128) { near = false; cc = tabR; } else if (qlo - (kv0 + 63) >= 128) { near = false; cc = tabL; }
;         { const float coff = cc - mu;
;           if (__any(!(coff == coff_cur))) { coff_cur = coff;
; #pragma unroll
;               for (int r = 0; r < 16; ++r) cblk[r] = coff;
;               asm volatile("" : "+v"(cblk)); } }
;         f32x16 p0, p1;
;         {
;             bf16x8 kf[8];
; #pragma unroll
;             for (int ds = 0; ds < 4; ++ds) { kf[2 * ds] = *(const LAS bf16x8*)(Kt + (kfo ^ (unsigned)(ds << 5))); kf[2 * ds + 1] = *(const LAS bf16x8*)(Kt + 32 * 256 + (kfo ^ (unsigned)(ds << 5))); }
;             __builtin_amdgcn_sched_barrier(0);
;             p0 = __builtin_amdgcn_mfma_f32_32x32x16_bf16(kf[0], qf[0], cblk, 0, 0, 0);
;             p1 = __builtin_amdgcn_mfma_f32_32x32x16_bf16(kf[1], qf[0], cblk, 0, 0, 0);
; #pragma unroll
;             for (int ds = 1; ds < 4; ++ds) {
;                 p0 = __builtin_amdgcn_mfma_f32_32x32x16_bf16(kf[2 * ds], qf[ds], p0, 0, 0, 0);
;                 p1 = __builtin_amdgcn_mfma_f32_32x32x16_bf16(kf[2 * ds + 1], qf[ds], p1, 0, 0, 0);
;             }
;         }
;     ...
;         const unsigned vbase = (unsigned)(size_t)Vt + vfo;
;         s16x4 va[8], vb[8];
;         VREADS1(va, 0);
;         if (near) {
;             const LAS float* tp = tab + (kv0 + 4 * hi - (qlo + r32) + 224);
; #pragma unroll
;             for (int r = 0; r < 16; ++r) { p0[r] += tp[(r & 3) + 8 * (r >> 2)]; p1[r] += tp[32 + (r & 3) + 8 * (r >> 2)]; }
;         }
;         float mx = max2f(max16f(p0), max16f(p1));
;         const bool first = (t == 0);
;         if (first || __any(mx > THR)) {
;             { auto rr = __builtin_amdgcn_permlane32_swap(__float_as_uint(mx), __float_as_uint(mx), false, false); mx = max2f(__uint_as_float(rr[0]), __uint_as_float(rr[1])); }
;             const float delta = first ? mx : fmaxf(mx, 0.f);
;             const float alpha = first ? 1.0f : __builtin_amdgcn_exp2f(-delta);
;             mu += delta; ls2 *= alpha;
;             if (!first) {
;                 asm volatile("" ::: "memory");
;                 scr[r32] = alpha;
.LatB_rec_0:
	s_waitcnt lgkmcnt(0)
	s_nop 15
	s_sub_u32 s5, s8, s4
	s_lshr_b32 s5, s5, 12
	s_sub_u32 s5, s5, 64
	s_cmp_lt_u32 s5, s11
	s_cselect_b32 s24, 1, 0
	s_cmp_gt_u32 s5, s31
	s_cselect_b32 s30, 2, 0
	s_or_b32 s24, s24, s30
	s_mov_b32 s23, s35
	s_mov_b32 s35, s24
	v_mov_b32_e32 v251, 0
	s_cmp_eq_u32 s24, 1
	s_cselect_b64 vcc, -1, 0
	v_cndmask_b32_e32 v251, v251, v177, vcc
	s_cmp_eq_u32 s24, 2
	s_cselect_b64 vcc, -1, 0
	v_cndmask_b32_e32 v251, v251, v178, vcc
	v_sub_f32_e32 v2, v251, v186
	v_mov_b32_e32 v3, v2
	v_mov_b64_e32 v[4:5], v[2:3]
	v_mov_b64_e32 v[6:7], v[2:3]
	v_mov_b64_e32 v[8:9], v[2:3]
	v_mov_b64_e32 v[10:11], v[2:3]
	v_mov_b64_e32 v[12:13], v[2:3]
	v_mov_b64_e32 v[14:15], v[2:3]
	v_mov_b64_e32 v[16:17], v[2:3]
	s_nop 1
	ds_read_b128 v[132:135], v19
	ds_read_b128 v[136:139], v19 offset:8192
	ds_read_b128 v[140:143], v180
	ds_read_b128 v[144:147], v180 offset:8192
	ds_read_b128 v[220:223], v181
	ds_read_b128 v[224:227], v181 offset:8192
	ds_read_b128 v[232:235], v182
	ds_read_b128 v[236:239], v182 offset:8192
	s_waitcnt lgkmcnt(7)
	v_mfma_f32_32x32x16_bf16 v[84:99], v[132:135], v[116:119], v[2:17]
	s_waitcnt lgkmcnt(6)
	v_mfma_f32_32x32x16_bf16 v[100:115], v[136:139], v[116:119], v[2:17]
	s_waitcnt lgkmcnt(5)
	v_mfma_f32_32x32x16_bf16 v[84:99], v[140:143], v[120:123], v[84:99]
	s_waitcnt lgkmcnt(4)
	v_mfma_f32_32x32x16_bf16 v[100:115], v[144:147], v[120:123], v[100:115]
	s_waitcnt lgkmcnt(3)
	v_mfma_f32_32x32x16_bf16 v[84:99], v[220:223], v[124:127], v[84:99]
	s_waitcnt lgkmcnt(2)
	v_mfma_f32_32x32x16_bf16 v[100:115], v[224:227], v[124:127], v[100:115]
	s_waitcnt lgkmcnt(1)
	v_mfma_f32_32x32x16_bf16 v[84:99], v[232:235], v[128:131], v[84:99]
	s_waitcnt lgkmcnt(0)
	v_mfma_f32_32x32x16_bf16 v[100:115], v[236:239], v[128:131], v[100:115]
	s_nop 15
	s_nop 15
	s_cmp_lg_u32 s35, 0
	s_cbranch_scc1 .LatB_recnn_0
	s_lshl_b32 s29, s5, 2
	s_add_i32 s29, s29, 0x18b80
	v_add_u32_e32 v187, s29, v162
	ds_read2_b32 v[132:133], v187 offset0:0 offset1:1
	ds_read2_b32 v[134:135], v187 offset0:2 offset1:3
	ds_read2_b32 v[136:137], v187 offset0:8 offset1:9
	ds_read2_b32 v[138:139], v187 offset0:10 offset1:11
	ds_read2_b32 v[140:141], v187 offset0:16 offset1:17
	ds_read2_b32 v[142:143], v187 offset0:18 offset1:19
	ds_read2_b32 v[144:145], v187 offset0:24 offset1:25
	ds_read2_b32 v[146:147], v187 offset0:26 offset1:27
	s_waitcnt lgkmcnt(0)
	v_pk_add_f32 v[84:85], v[84:85], v[132:133]
	v_pk_add_f32 v[86:87], v[86:87], v[134:135]
	v_pk_add_f32 v[88:89], v[88:89], v[136:137]
	v_pk_add_f32 v[90:91], v[90:91], v[138:139]
	v_pk_add_f32 v[92:93], v[92:93], v[140:141]
	v_pk_add_f32 v[94:95], v[94:95], v[142:143]
	v_pk_add_f32 v[96:97], v[96:97], v[144:145]
	v_pk_add_f32 v[98:99], v[98:99], v[146:147]
	ds_read2_b32 v[132:133], v187 offset0:32 offset1:33
	ds_read2_b32 v[134:135], v187 offset0:34 offset1:35
	ds_read2_b32 v[136:137], v187 offset0:40 offset1:41
	ds_read2_b32 v[138:139], v187 offset0:42 offset1:43
	ds_read2_b32 v[140:141], v187 offset0:48 offset1:49
	ds_read2_b32 v[142:143], v187 offset0:50 offset1:51
	ds_read2_b32 v[144:145], v187 offset0:56 offset1:57
	ds_read2_b32 v[146:147], v187 offset0:58 offset1:59
	s_waitcnt lgkmcnt(0)
	v_pk_add_f32 v[100:101], v[100:101], v[132:133]
	v_pk_add_f32 v[102:103], v[102:103], v[134:135]
	v_pk_add_f32 v[104:105], v[104:105], v[136:137]
	v_pk_add_f32 v[106:107], v[106:107], v[138:139]
	v_pk_add_f32 v[108:109], v[108:109], v[140:141]
	v_pk_add_f32 v[110:111], v[110:111], v[142:143]
	v_pk_add_f32 v[112:113], v[112:113], v[144:145]
	v_pk_add_f32 v[114:115], v[114:115], v[146:147]
.LatB_recnn_0:
	v_max3_f32 v251, v84, v85, v86
	v_max3_f32 v252, v87, v88, v89
	v_max3_f32 v251, v251, v90, v91
	v_max3_f32 v252, v252, v92, v93
	v_max3_f32 v251, v251, v94, v95
	v_max3_f32 v252, v252, v96, v97
	v_max3_f32 v251, v251, v98, v99
	v_max3_f32 v252, v252, v100, v101
	v_max3_f32 v251, v251, v102, v103
	v_max3_f32 v252, v252, v104, v105
	v_max3_f32 v251, v251, v106, v107
	v_max3_f32 v252, v252, v108, v109
	v_max3_f32 v251, v251, v110, v111
	v_max3_f32 v252, v252, v112, v113
	v_max3_f32 v251, v251, v114, v115
	v_max_f32_e32 v251, v251, v252
	v_mov_b32_e32 v252, v251
	s_nop 1
	v_permlane32_swap_b32_e32 v251, v252
	v_max_f32_e32 v251, v251, v252
	v_max_f32_e32 v253, 0, v251
	v_exp_f32_e64 v254, -v253
	v_add_f32_e32 v186, v186, v253
	s_nop 0
	v_mul_f32_e32 v150, v150, v254
	v_mul_f32_e32 v151, v151, v254
	ds_write_b32 v184, v254
	s_waitcnt lgkmcnt(0)
	ds_read_b128 v[132:135], v185
	ds_read_b128 v[136:139], v185 offset:32
	ds_read_b128 v[140:143], v185 offset:64
	ds_read_b128 v[144:147], v185 offset:96
	s_waitcnt lgkmcnt(0)
; #define LAS __attribute__((address_space(3)))
; __device__ __forceinline__ void attn_unit(LAS unsigned char* lds, const bf16_t* Z, bf16_t* A2, const float* tabg, int seq_base, int S, int h, int qb, float lam) {
;     ...
;                 scr[r32] = alpha;
;                 asm volatile("s_waitcnt lgkmcnt(0)" ::: "memory");
; #pragma unroll
;                 for (int g = 0; g < 4; ++g) { const f32x4 a4 = *(const LAS f32x4*)(scr + 8 * g + 4 * hi);
; #pragma unroll
;                     for (int d = 0; d < 4; ++d) { O[d][4 * g + 0] *= a4[0]; O[d][4 * g + 1] *= a4[1]; O[d][4 * g + 2] *= a4[2]; O[d][4 * g + 3] *= a4[3]; } }
;                 asm volatile("s_waitcnt lgkmcnt(0)" ::: "memory");
;             }
; #pragma unroll
;             for (int r = 0; r < 16; ++r) { p0[r] -= delta; p1[r] -= delta; }
;             asm volatile("" : "+v"(p0), "+v"(p1));
;         }
; #pragma unroll
;         for (int r = 0; r < 16; ++r) { p0[r] = __builtin_amdgcn_exp2f(p0[r]); p1[r] = __builtin_amdgcn_exp2f(p1[r]); }
; #pragma unroll
;         for (int r = 0; r < 16; r += 2) { ls2 += (f32x2){p0[r], p0[r + 1]}; ls2 += (f32x2){p1[r], p1[r + 1]}; }
;         bf16x8 pa[4]; pa[0] = pack8(p0, 0); pa[1] = pack8(p0, 8); pa[2] = pack8(p1, 0); pa[3] = pack8(p1, 8);
	v_pk_mul_f32 v[20:21], v[20:21], v[132:133]
	v_pk_mul_f32 v[22:23], v[22:23], v[134:135]
	v_pk_mul_f32 v[24:25], v[24:25], v[136:137]
	v_pk_mul_f32 v[26:27], v[26:27], v[138:139]
	v_pk_mul_f32 v[28:29], v[28:29], v[140:141]
	v_pk_mul_f32 v[30:31], v[30:31], v[142:143]
	v_pk_mul_f32 v[32:33], v[32:33], v[144:145]
	v_pk_mul_f32 v[34:35], v[34:35], v[146:147]
	v_pk_mul_f32 v[36:37], v[36:37], v[132:133]
	v_pk_mul_f32 v[38:39], v[38:39], v[134:135]
	v_pk_mul_f32 v[40:41], v[40:41], v[136:137]
	v_pk_mul_f32 v[42:43], v[42:43], v[138:139]
	v_pk_mul_f32 v[44:45], v[44:45], v[140:141]
	v_pk_mul_f32 v[46:47], v[46:47], v[142:143]
	v_pk_mul_f32 v[48:49], v[48:49], v[144:145]
	v_pk_mul_f32 v[50:51], v[50:51], v[146:147]
	v_pk_mul_f32 v[52:53], v[52:53], v[132:133]
	v_pk_mul_f32 v[54:55], v[54:55], v[134:135]
	v_pk_mul_f32 v[56:57], v[56:57], v[136:137]
	v_pk_mul_f32 v[58:59], v[58:59], v[138:139]
	v_pk_mul_f32 v[60:61], v[60:61], v[140:141]
	v_pk_mul_f32 v[62:63], v[62:63], v[142:143]
	v_pk_mul_f32 v[64:65], v[64:65], v[144:145]
	v_pk_mul_f32 v[66:67], v[66:67], v[146:147]
	v_pk_mul_f32 v[68:69], v[68:69], v[132:133]
	v_pk_mul_f32 v[70:71], v[70:71], v[134:135]
	v_pk_mul_f32 v[72:73], v[72:73], v[136:137]
	v_pk_mul_f32 v[74:75], v[74:75], v[138:139]
	v_pk_mul_f32 v[76:77], v[76:77], v[140:141]
	v_pk_mul_f32 v[78:79], v[78:79], v[142:143]
	v_pk_mul_f32 v[80:81], v[80:81], v[144:145]
	v_pk_mul_f32 v[82:83], v[82:83], v[146:147]
	v_mov_b32_e32 v252, v253
	v_pk_add_f32 v[84:85], v[84:85], v[252:253] neg_lo:[0,1] neg_hi:[0,1]
	v_pk_add_f32 v[86:87], v[86:87], v[252:253] neg_lo:[0,1] neg_hi:[0,1]
	v_pk_add_f32 v[88:89], v[88:89], v[252:253] neg_lo:[0,1] neg_hi:[0,1]
	v_pk_add_f32 v[90:91], v[90:91], v[252:253] neg_lo:[0,1] neg_hi:[0,1]
	v_pk_add_f32 v[92:93], v[92:93], v[252:253] neg_lo:[0,1] neg_hi:[0,1]
	v_pk_add_f32 v[94:95], v[94:95], v[252:253] neg_lo:[0,1] neg_hi:[0,1]
	v_pk_add_f32 v[96:97], v[96:97], v[252:253] neg_lo:[0,1] neg_hi:[0,1]
	v_pk_add_f32 v[98:99], v[98:99], v[252:253] neg_lo:[0,1] neg_hi:[0,1]
	v_pk_add_f32 v[100:101], v[100:101], v[252:253] neg_lo:[0,1] neg_hi:[0,1]
	v_pk_add_f32 v[102:103], v[102:103], v[252:253] neg_lo:[0,1] neg_hi:[0,1]
	v_pk_add_f32 v[104:105], v[104:105], v[252:253] neg_lo:[0,1] neg_hi:[0,1]
	v_pk_add_f32 v[106:107], v[106:107], v[252:253] neg_lo:[0,1] neg_hi:[0,1]
	v_pk_add_f32 v[108:109], v[108:109], v[252:253] neg_lo:[0,1] neg_hi:[0,1]
	v_pk_add_f32 v[110:111], v[110:111], v[252:253] neg_lo:[0,1] neg_hi:[0,1]
	v_pk_add_f32 v[112:113], v[112:113], v[252:253] neg_lo:[0,1] neg_hi:[0,1]
	v_pk_add_f32 v[114:115], v[114:115], v[252:253] neg_lo:[0,1] neg_hi:[0,1]
	v_pk_add_f32 v[188:189], v[188:189], v[252:253] neg_lo:[0,1] neg_hi:[0,1]
	v_pk_add_f32 v[190:191], v[190:191], v[252:253] neg_lo:[0,1] neg_hi:[0,1]
	v_pk_add_f32 v[192:193], v[192:193], v[252:253] neg_lo:[0,1] neg_hi:[0,1]
	v_pk_add_f32 v[194:195], v[194:195], v[252:253] neg_lo:[0,1] neg_hi:[0,1]
	v_pk_add_f32 v[196:197], v[196:197], v[252:253] neg_lo:[0,1] neg_hi:[0,1]
	v_pk_add_f32 v[198:199], v[198:199], v[252:253] neg_lo:[0,1] neg_hi:[0,1]
	v_pk_add_f32 v[200:201], v[200:201], v[252:253] neg_lo:[0,1] neg_hi:[0,1]
	v_pk_add_f32 v[202:203], v[202:203], v[252:253] neg_lo:[0,1] neg_hi:[0,1]
	v_pk_add_f32 v[204:205], v[204:205], v[252:253] neg_lo:[0,1] neg_hi:[0,1]
	v_pk_add_f32 v[206:207], v[206:207], v[252:253] neg_lo:[0,1] neg_hi:[0,1]
	v_pk_add_f32 v[208:209], v[208:209], v[252:253] neg_lo:[0,1] neg_hi:[0,1]
	v_pk_add_f32 v[210:211], v[210:211], v[252:253] neg_lo:[0,1] neg_hi:[0,1]
	v_pk_add_f32 v[212:213], v[212:213], v[252:253] neg_lo:[0,1] neg_hi:[0,1]
	v_pk_add_f32 v[214:215], v[214:215], v[252:253] neg_lo:[0,1] neg_hi:[0,1]
	v_pk_add_f32 v[216:217], v[216:217], v[252:253] neg_lo:[0,1] neg_hi:[0,1]
	v_pk_add_f32 v[218:219], v[218:219], v[252:253] neg_lo:[0,1] neg_hi:[0,1]
	v_exp_f32_e32 v84, v84
	v_exp_f32_e32 v85, v85
	v_exp_f32_e32 v86, v86
	v_exp_f32_e32 v87, v87
	v_exp_f32_e32 v88, v88
	v_pk_add_f32 v[252:253], v[84:85], v[86:87]
	v_exp_f32_e32 v89, v89
	v_cvt_pk_bf16_f32 v84, v84, v85
	v_cvt_pk_bf16_f32 v85, v86, v87
	v_exp_f32_e32 v90, v90
	v_exp_f32_e32 v91, v91
	v_pk_add_f32 v[252:253], v[252:253], v[88:89]
	v_pk_add_f32 v[252:253], v[252:253], v[90:91]
	v_cvt_pk_bf16_f32 v86, v88, v89
	v_cvt_pk_bf16_f32 v87, v90, v91
	v_exp_f32_e32 v92, v92
	v_exp_f32_e32 v93, v93
	v_exp_f32_e32 v94, v94
	v_exp_f32_e32 v95, v95
	v_pk_add_f32 v[252:253], v[252:253], v[92:93]
	v_pk_add_f32 v[252:253], v[252:253], v[94:95]
	v_exp_f32_e32 v96, v96
	v_exp_f32_e32 v97, v97
	v_cvt_pk_bf16_f32 v88, v92, v93
	v_cvt_pk_bf16_f32 v89, v94, v95
	v_exp_f32_e32 v98, v98
	v_exp_f32_e32 v99, v99
	v_pk_add_f32 v[252:253], v[252:253], v[96:97]
	v_pk_add_f32 v[252:253], v[252:253], v[98:99]
	v_cvt_pk_bf16_f32 v90, v96, v97
	v_cvt_pk_bf16_f32 v91, v98, v99
	v_exp_f32_e32 v100, v100
	v_exp_f32_e32 v101, v101
	v_exp_f32_e32 v102, v102
	v_exp_f32_e32 v103, v103
	v_pk_add_f32 v[252:253], v[252:253], v[100:101]
	v_pk_add_f32 v[252:253], v[252:253], v[102:103]
	v_exp_f32_e32 v104, v104
	v_exp_f32_e32 v105, v105
	v_cvt_pk_bf16_f32 v100, v100, v101
	v_cvt_pk_bf16_f32 v101, v102, v103
	v_exp_f32_e32 v106, v106
	v_exp_f32_e32 v107, v107
	v_pk_add_f32 v[252:253], v[252:253], v[104:105]
	v_pk_add_f32 v[252:253], v[252:253], v[106:107]
	v_cvt_pk_bf16_f32 v102, v104, v105
	v_cvt_pk_bf16_f32 v103, v106, v107
	v_exp_f32_e32 v108, v108
	v_exp_f32_e32 v109, v109
	v_exp_f32_e32 v110, v110
	v_exp_f32_e32 v111, v111
	v_pk_add_f32 v[252:253], v[252:253], v[108:109]
	v_pk_add_f32 v[252:253], v[252:253], v[110:111]
	v_exp_f32_e32 v112, v112
	v_exp_f32_e32 v113, v113
	v_cvt_pk_bf16_f32 v104, v108, v109
; #define LAS __attribute__((address_space(3)))
; #define VREADS1(arr, d_) do { const unsigned ad_ = vbase ^ (unsigned)((d_) << 6); __builtin_amdgcn_sched_barrier(0); \
;         _Pragma("unroll") for (int ks_ = 0; ks_ < 4; ++ks_) { VTR(arr[ks_ * 2], ad_, ks_ * 4096); VTR(arr[ks_ * 2 + 1], ad_, ks_ * 4096 + 2048); } __builtin_amdgcn_sched_barrier(0); } while (0)
; #define LGKM0() do { __builtin_amdgcn_sched_barrier(0); asm volatile("s_waitcnt lgkmcnt(0)" ::: "memory"); __builtin_amdgcn_sched_barrier(0); } while (0)
; __device__ __forceinline__ void attn_unit(LAS unsigned char* lds, const bf16_t* Z, bf16_t* A2, const float* tabg, int seq_base, int S, int h, int qb, float lam) {
;     ...
;         bool near = true; float cc = 0.f;
;         if (kv0 - (qlo + 31) >= 128) { near = false; cc = tabR; } else if (qlo - (kv0 + 63) >= 128) { near = false; cc = tabL; }
;         { const float coff = cc - mu;
;           if (__any(!(coff == coff_cur))) { coff_cur = coff;
; #pragma unroll
;               for (int r = 0; r < 16; ++r) cblk[r] = coff;
;               asm volatile("" : "+v"(cblk)); } }
;         f32x16 p0, p1;
;         {
;             bf16x8 kf[8];
; #pragma unroll
;             for (int ds = 0; ds < 4; ++ds) { kf[2 * ds] = *(const LAS bf16x8*)(Kt + (kfo ^ (unsigned)(ds << 5))); kf[2 * ds + 1] = *(const LAS bf16x8*)(Kt + 32 * 256 + (kfo ^ (unsigned)(ds << 5))); }
;             __builtin_amdgcn_sched_barrier(0);
;             p0 = __builtin_amdgcn_mfma_f32_32x32x16_bf16(kf[0], qf[0], cblk, 0, 0, 0);
;             p1 = __builtin_amdgcn_mfma_f32_32x32x16_bf16(kf[1], qf[0], cblk, 0, 0, 0);
; #pragma unroll
;             for (int ds = 1; ds < 4; ++ds) {
;                 p0 = __builtin_amdgcn_mfma_f32_32x32x16_bf16(kf[2 * ds], qf[ds], p0, 0, 0, 0);
;                 p1 = __builtin_amdgcn_mfma_f32_32x32x16_bf16(kf[2 * ds + 1], qf[ds], p1, 0, 0, 0);
;             }
;         }
;     ...
;         for (int r = 0; r < 16; ++r) { p0[r] = __builtin_amdgcn_exp2f(p0[r]); p1[r] = __builtin_amdgcn_exp2f(p1[r]); }
; #pragma unroll
;         for (int r = 0; r < 16; r += 2) { ls2 += (f32x2){p0[r], p0[r + 1]}; ls2 += (f32x2){p1[r], p1[r + 1]}; }
;         bf16x8 pa[4]; pa[0] = pack8(p0, 0); pa[1] = pack8(p0, 8); pa[2] = pack8(p1, 0); pa[3] = pack8(p1, 8);
;         LGKM0(); VREADS1(vb, 1); PV1(va, 0); LGKM0(); VREADS1(va, 2); PV1(vb, 1); LGKM0(); VREADS1(vb, 3); PV1(va, 2); LGKM0(); PV1(vb, 3);
	v_cvt_pk_bf16_f32 v105, v110, v111
	v_exp_f32_e32 v114, v114
	v_exp_f32_e32 v115, v115
	v_pk_add_f32 v[252:253], v[252:253], v[112:113]
	v_pk_add_f32 v[252:253], v[252:253], v[114:115]
	v_cvt_pk_bf16_f32 v106, v112, v113
	v_cvt_pk_bf16_f32 v107, v114, v115
	s_mov_b32 s24, s23
	s_mov_b32 s35, s24
	v_mov_b32_e32 v251, 0
	s_cmp_eq_u32 s24, 1
	s_cselect_b64 vcc, -1, 0
	v_cndmask_b32_e32 v251, v251, v177, vcc
	s_cmp_eq_u32 s24, 2
	s_cselect_b64 vcc, -1, 0
	v_cndmask_b32_e32 v251, v251, v178, vcc
	v_sub_f32_e32 v2, v251, v186
	v_mov_b32_e32 v3, v2
	v_mov_b64_e32 v[4:5], v[2:3]
	v_mov_b64_e32 v[6:7], v[2:3]
	v_mov_b64_e32 v[8:9], v[2:3]
	v_mov_b64_e32 v[10:11], v[2:3]
	v_mov_b64_e32 v[12:13], v[2:3]
	v_mov_b64_e32 v[14:15], v[2:3]
	v_mov_b64_e32 v[16:17], v[2:3]
	ds_read_b64_tr_b16 v[132:133], v228 offset:0
	ds_read_b64_tr_b16 v[134:135], v228 offset:2048
	ds_read_b64_tr_b16 v[136:137], v229 offset:0
	ds_read_b64_tr_b16 v[138:139], v229 offset:2048
	ds_read_b64_tr_b16 v[140:141], v230 offset:0
	ds_read_b64_tr_b16 v[142:143], v230 offset:2048
	ds_read_b64_tr_b16 v[144:145], v231 offset:0
	ds_read_b64_tr_b16 v[146:147], v231 offset:2048
	ds_read_b64_tr_b16 v[220:221], v228 offset:4096
	ds_read_b64_tr_b16 v[222:223], v228 offset:6144
	ds_read_b64_tr_b16 v[224:225], v229 offset:4096
	ds_read_b64_tr_b16 v[226:227], v229 offset:6144
	ds_read_b64_tr_b16 v[232:233], v230 offset:4096
	ds_read_b64_tr_b16 v[234:235], v230 offset:6144
	s_nop 1
	s_cmp_eq_u32 s22, 0
	s_cbranch_scc1 .LatB_recret_h0
	s_cmp_eq_u32 s22, 1
	s_cbranch_scc1 .LatB_recret_m0
	s_branch .LatB_recret_x4
.LatB_rec_1:
	s_waitcnt lgkmcnt(0)
	s_nop 15
	s_sub_u32 s5, s8, s4
	s_lshr_b32 s5, s5, 12
	s_sub_u32 s5, s5, 64
	s_cmp_lt_u32 s5, s11
	s_cselect_b32 s24, 1, 0
	s_cmp_gt_u32 s5, s31
	s_cselect_b32 s30, 2, 0
	s_or_b32 s24, s24, s30
	s_mov_b32 s23, s35
	s_mov_b32 s35, s24
	v_mov_b32_e32 v251, 0
	s_cmp_eq_u32 s24, 1
	s_cselect_b64 vcc, -1, 0
	v_cndmask_b32_e32 v251, v251, v177, vcc
	s_cmp_eq_u32 s24, 2
	s_cselect_b64 vcc, -1, 0
	v_cndmask_b32_e32 v251, v251, v178, vcc
	v_sub_f32_e32 v2, v251, v186
	v_mov_b32_e32 v3, v2
	v_mov_b64_e32 v[4:5], v[2:3]
	v_mov_b64_e32 v[6:7], v[2:3]
	v_mov_b64_e32 v[8:9], v[2:3]
	v_mov_b64_e32 v[10:11], v[2:3]
	v_mov_b64_e32 v[12:13], v[2:3]
	v_mov_b64_e32 v[14:15], v[2:3]
	v_mov_b64_e32 v[16:17], v[2:3]
	s_nop 1
	ds_read_b128 v[132:135], v19 offset:16384
	ds_read_b128 v[136:139], v19 offset:24576
	ds_read_b128 v[140:143], v180 offset:16384
	ds_read_b128 v[144:147], v180 offset:24576
	ds_read_b128 v[220:223], v181 offset:16384
	ds_read_b128 v[224:227], v181 offset:24576
	ds_read_b128 v[232:235], v182 offset:16384
	ds_read_b128 v[236:239], v182 offset:24576
	s_waitcnt lgkmcnt(7)
	v_mfma_f32_32x32x16_bf16 v[188:203], v[132:135], v[116:119], v[2:17]
	s_waitcnt lgkmcnt(6)
	v_mfma_f32_32x32x16_bf16 v[204:219], v[136:139], v[116:119], v[2:17]
	s_waitcnt lgkmcnt(5)
	v_mfma_f32_32x32x16_bf16 v[188:203], v[140:143], v[120:123], v[188:203]
	s_waitcnt lgkmcnt(4)
	v_mfma_f32_32x32x16_bf16 v[204:219], v[144:147], v[120:123], v[204:219]
	s_waitcnt lgkmcnt(3)
	v_mfma_f32_32x32x16_bf16 v[188:203], v[220:223], v[124:127], v[188:203]
	s_waitcnt lgkmcnt(2)
	v_mfma_f32_32x32x16_bf16 v[204:219], v[224:227], v[124:127], v[204:219]
	s_waitcnt lgkmcnt(1)
	v_mfma_f32_32x32x16_bf16 v[188:203], v[232:235], v[128:131], v[188:203]
	s_waitcnt lgkmcnt(0)
	v_mfma_f32_32x32x16_bf16 v[204:219], v[236:239], v[128:131], v[204:219]
	s_nop 15
	s_nop 15
	s_cmp_lg_u32 s35, 0
	s_cbranch_scc1 .LatB_recnn_1
	s_lshl_b32 s29, s5, 2
	s_add_i32 s29, s29, 0x18b80
	v_add_u32_e32 v187, s29, v162
	ds_read2_b32 v[132:133], v187 offset0:0 offset1:1
	ds_read2_b32 v[134:135], v187 offset0:2 offset1:3
	ds_read2_b32 v[136:137], v187 offset0:8 offset1:9
	ds_read2_b32 v[138:139], v187 offset0:10 offset1:11
	ds_read2_b32 v[140:141], v187 offset0:16 offset1:17
	ds_read2_b32 v[142:143], v187 offset0:18 offset1:19
	ds_read2_b32 v[144:145], v187 offset0:24 offset1:25
	ds_read2_b32 v[146:147], v187 offset0:26 offset1:27
	s_waitcnt lgkmcnt(0)
	v_pk_add_f32 v[188:189], v[188:189], v[132:133]
	v_pk_add_f32 v[190:191], v[190:191], v[134:135]
	v_pk_add_f32 v[192:193], v[192:193], v[136:137]
	v_pk_add_f32 v[194:195], v[194:195], v[138:139]
	v_pk_add_f32 v[196:197], v[196:197], v[140:141]
	v_pk_add_f32 v[198:199], v[198:199], v[142:143]
	v_pk_add_f32 v[200:201], v[200:201], v[144:145]
	v_pk_add_f32 v[202:203], v[202:203], v[146:147]
	ds_read2_b32 v[132:133], v187 offset0:32 offset1:33
	ds_read2_b32 v[134:135], v187 offset0:34 offset1:35
	ds_read2_b32 v[136:137], v187 offset0:40 offset1:41
	ds_read2_b32 v[138:139], v187 offset0:42 offset1:43
	ds_read2_b32 v[140:141], v187 offset0:48 offset1:49
	ds_read2_b32 v[142:143], v187 offset0:50 offset1:51
	ds_read2_b32 v[144:145], v187 offset0:56 offset1:57
	ds_read2_b32 v[146:147], v187 offset0:58 offset1:59
	s_waitcnt lgkmcnt(0)
	v_pk_add_f32 v[204:205], v[204:205], v[132:133]
	v_pk_add_f32 v[206:207], v[206:207], v[134:135]
	v_pk_add_f32 v[208:209], v[208:209], v[136:137]
	v_pk_add_f32 v[210:211], v[210:211], v[138:139]
	v_pk_add_f32 v[212:213], v[212:213], v[140:141]
	v_pk_add_f32 v[214:215], v[214:215], v[142:143]
	v_pk_add_f32 v[216:217], v[216:217], v[144:145]
	v_pk_add_f32 v[218:219], v[218:219], v[146:147]
; #define LAS __attribute__((address_space(3)))
; __device__ __forceinline__ float max2f(float a, float b) { float r; asm("v_max_f32_e32 %0, %1, %2" : "=v"(r) : "v"(a), "v"(b)); return r; }
; __device__ __forceinline__ void attn_unit(LAS unsigned char* lds, const bf16_t* Z, bf16_t* A2, const float* tabg, int seq_base, int S, int h, int qb, float lam) {
;     ...
;         float mx = max2f(max16f(p0), max16f(p1));
;         const bool first = (t == 0);
;         if (first || __any(mx > THR)) {
;             { auto rr = __builtin_amdgcn_permlane32_swap(__float_as_uint(mx), __float_as_uint(mx), false, false); mx = max2f(__uint_as_float(rr[0]), __uint_as_float(rr[1])); }
;             const float delta = first ? mx : fmaxf(mx, 0.f);
;             const float alpha = first ? 1.0f : __builtin_amdgcn_exp2f(-delta);
;             mu += delta; ls2 *= alpha;
;             if (!first) {
;                 asm volatile("" ::: "memory");
;                 scr[r32] = alpha;
;                 asm volatile("s_waitcnt lgkmcnt(0)" ::: "memory");
; #pragma unroll
;                 for (int g = 0; g < 4; ++g) { const f32x4 a4 = *(const LAS f32x4*)(scr + 8 * g + 4 * hi);
; #pragma unroll
;                     for (int d = 0; d < 4; ++d) { O[d][4 * g + 0] *= a4[0]; O[d][4 * g + 1] *= a4[1]; O[d][4 * g + 2] *= a4[2]; O[d][4 * g + 3] *= a4[3]; } }
;                 asm volatile("s_waitcnt lgkmcnt(0)" ::: "memory");
;             }
; #pragma unroll
;             for (int r = 0; r < 16; ++r) { p0[r] -= delta; p1[r] -= delta; }
;             asm volatile("" : "+v"(p0), "+v"(p1));
;         }
; #pragma unroll
;         for (int r = 0; r < 16; ++r) { p0[r] = __builtin_amdgcn_exp2f(p0[r]); p1[r] = __builtin_amdgcn_exp2f(p1[r]); }
; #pragma unroll
;         for (int r = 0; r < 16; r += 2) { ls2 += (f32x2){p0[r], p0[r + 1]}; ls2 += (f32x2){p1[r], p1[r + 1]}; }
;         bf16x8 pa[4]; pa[0] = pack8(p0, 0); pa[1] = pack8(p0, 8); pa[2] = pack8(p1, 0); pa[3] = pack8(p1, 8);
.LatB_recnn_1:
	v_max3_f32 v251, v188, v189, v190
	v_max3_f32 v252, v191, v192, v193
	v_max3_f32 v251, v251, v194, v195
	v_max3_f32 v252, v252, v196, v197
	v_max3_f32 v251, v251, v198, v199
	v_max3_f32 v252, v252, v200, v201
	v_max3_f32 v251, v251, v202, v203
	v_max3_f32 v252, v252, v204, v205
	v_max3_f32 v251, v251, v206, v207
	v_max3_f32 v252, v252, v208, v209
	v_max3_f32 v251, v251, v210, v211
	v_max3_f32 v252, v252, v212, v213
	v_max3_f32 v251, v251, v214, v215
	v_max3_f32 v252, v252, v216, v217
	v_max3_f32 v251, v251, v218, v219
	v_max_f32_e32 v251, v251, v252
	v_mov_b32_e32 v252, v251
	s_nop 1
	v_permlane32_swap_b32_e32 v251, v252
	v_max_f32_e32 v251, v251, v252
	v_max_f32_e32 v253, 0, v251
	v_exp_f32_e64 v254, -v253
	v_add_f32_e32 v186, v186, v253
	s_nop 0
	v_mul_f32_e32 v150, v150, v254
	v_mul_f32_e32 v151, v151, v254
	ds_write_b32 v184, v254
	s_waitcnt lgkmcnt(0)
	ds_read_b128 v[132:135], v185
	ds_read_b128 v[136:139], v185 offset:32
	ds_read_b128 v[140:143], v185 offset:64
	ds_read_b128 v[144:147], v185 offset:96
	s_waitcnt lgkmcnt(0)
	v_pk_mul_f32 v[20:21], v[20:21], v[132:133]
	v_pk_mul_f32 v[22:23], v[22:23], v[134:135]
	v_pk_mul_f32 v[24:25], v[24:25], v[136:137]
	v_pk_mul_f32 v[26:27], v[26:27], v[138:139]
	v_pk_mul_f32 v[28:29], v[28:29], v[140:141]
	v_pk_mul_f32 v[30:31], v[30:31], v[142:143]
	v_pk_mul_f32 v[32:33], v[32:33], v[144:145]
	v_pk_mul_f32 v[34:35], v[34:35], v[146:147]
	v_pk_mul_f32 v[36:37], v[36:37], v[132:133]
	v_pk_mul_f32 v[38:39], v[38:39], v[134:135]
	v_pk_mul_f32 v[40:41], v[40:41], v[136:137]
	v_pk_mul_f32 v[42:43], v[42:43], v[138:139]
	v_pk_mul_f32 v[44:45], v[44:45], v[140:141]
	v_pk_mul_f32 v[46:47], v[46:47], v[142:143]
	v_pk_mul_f32 v[48:49], v[48:49], v[144:145]
	v_pk_mul_f32 v[50:51], v[50:51], v[146:147]
	v_pk_mul_f32 v[52:53], v[52:53], v[132:133]
	v_pk_mul_f32 v[54:55], v[54:55], v[134:135]
	v_pk_mul_f32 v[56:57], v[56:57], v[136:137]
	v_pk_mul_f32 v[58:59], v[58:59], v[138:139]
	v_pk_mul_f32 v[60:61], v[60:61], v[140:141]
	v_pk_mul_f32 v[62:63], v[62:63], v[142:143]
	v_pk_mul_f32 v[64:65], v[64:65], v[144:145]
	v_pk_mul_f32 v[66:67], v[66:67], v[146:147]
	v_pk_mul_f32 v[68:69], v[68:69], v[132:133]
	v_pk_mul_f32 v[70:71], v[70:71], v[134:135]
	v_pk_mul_f32 v[72:73], v[72:73], v[136:137]
	v_pk_mul_f32 v[74:75], v[74:75], v[138:139]
	v_pk_mul_f32 v[76:77], v[76:77], v[140:141]
	v_pk_mul_f32 v[78:79], v[78:79], v[142:143]
	v_pk_mul_f32 v[80:81], v[80:81], v[144:145]
	v_pk_mul_f32 v[82:83], v[82:83], v[146:147]
	v_mov_b32_e32 v252, v253
	v_pk_add_f32 v[188:189], v[188:189], v[252:253] neg_lo:[0,1] neg_hi:[0,1]
	v_pk_add_f32 v[190:191], v[190:191], v[252:253] neg_lo:[0,1] neg_hi:[0,1]
	v_pk_add_f32 v[192:193], v[192:193], v[252:253] neg_lo:[0,1] neg_hi:[0,1]
	v_pk_add_f32 v[194:195], v[194:195], v[252:253] neg_lo:[0,1] neg_hi:[0,1]
	v_pk_add_f32 v[196:197], v[196:197], v[252:253] neg_lo:[0,1] neg_hi:[0,1]
	v_pk_add_f32 v[198:199], v[198:199], v[252:253] neg_lo:[0,1] neg_hi:[0,1]
	v_pk_add_f32 v[200:201], v[200:201], v[252:253] neg_lo:[0,1] neg_hi:[0,1]
	v_pk_add_f32 v[202:203], v[202:203], v[252:253] neg_lo:[0,1] neg_hi:[0,1]
	v_pk_add_f32 v[204:205], v[204:205], v[252:253] neg_lo:[0,1] neg_hi:[0,1]
	v_pk_add_f32 v[206:207], v[206:207], v[252:253] neg_lo:[0,1] neg_hi:[0,1]
	v_pk_add_f32 v[208:209], v[208:209], v[252:253] neg_lo:[0,1] neg_hi:[0,1]
	v_pk_add_f32 v[210:211], v[210:211], v[252:253] neg_lo:[0,1] neg_hi:[0,1]
	v_pk_add_f32 v[212:213], v[212:213], v[252:253] neg_lo:[0,1] neg_hi:[0,1]
	v_pk_add_f32 v[214:215], v[214:215], v[252:253] neg_lo:[0,1] neg_hi:[0,1]
	v_pk_add_f32 v[216:217], v[216:217], v[252:253] neg_lo:[0,1] neg_hi:[0,1]
	v_pk_add_f32 v[218:219], v[218:219], v[252:253] neg_lo:[0,1] neg_hi:[0,1]
	v_pk_add_f32 v[84:85], v[84:85], v[252:253] neg_lo:[0,1] neg_hi:[0,1]
	v_pk_add_f32 v[86:87], v[86:87], v[252:253] neg_lo:[0,1] neg_hi:[0,1]
	v_pk_add_f32 v[88:89], v[88:89], v[252:253] neg_lo:[0,1] neg_hi:[0,1]
	v_pk_add_f32 v[90:91], v[90:91], v[252:253] neg_lo:[0,1] neg_hi:[0,1]
	v_pk_add_f32 v[92:93], v[92:93], v[252:253] neg_lo:[0,1] neg_hi:[0,1]
	v_pk_add_f32 v[94:95], v[94:95], v[252:253] neg_lo:[0,1] neg_hi:[0,1]
	v_pk_add_f32 v[96:97], v[96:97], v[252:253] neg_lo:[0,1] neg_hi:[0,1]
	v_pk_add_f32 v[98:99], v[98:99], v[252:253] neg_lo:[0,1] neg_hi:[0,1]
	v_pk_add_f32 v[100:101], v[100:101], v[252:253] neg_lo:[0,1] neg_hi:[0,1]
	v_pk_add_f32 v[102:103], v[102:103], v[252:253] neg_lo:[0,1] neg_hi:[0,1]
	v_pk_add_f32 v[104:105], v[104:105], v[252:253] neg_lo:[0,1] neg_hi:[0,1]
	v_pk_add_f32 v[106:107], v[106:107], v[252:253] neg_lo:[0,1] neg_hi:[0,1]
	v_pk_add_f32 v[108:109], v[108:109], v[252:253] neg_lo:[0,1] neg_hi:[0,1]
	v_pk_add_f32 v[110:111], v[110:111], v[252:253] neg_lo:[0,1] neg_hi:[0,1]
	v_pk_add_f32 v[112:113], v[112:113], v[252:253] neg_lo:[0,1] neg_hi:[0,1]
	v_pk_add_f32 v[114:115], v[114:115], v[252:253] neg_lo:[0,1] neg_hi:[0,1]
	v_exp_f32_e32 v188, v188
	v_exp_f32_e32 v189, v189
	v_exp_f32_e32 v190, v190
	v_exp_f32_e32 v191, v191
	v_exp_f32_e32 v192, v192
	v_pk_add_f32 v[252:253], v[188:189], v[190:191]
	v_exp_f32_e32 v193, v193
	v_cvt_pk_bf16_f32 v188, v188, v189
	v_cvt_pk_bf16_f32 v189, v190, v191
	v_exp_f32_e32 v194, v194
	v_exp_f32_e32 v195, v195
	v_pk_add_f32 v[252:253], v[252:253], v[192:193]
	v_pk_add_f32 v[252:253], v[252:253], v[194:195]
	v_cvt_pk_bf16_f32 v190, v192, v193
	v_cvt_pk_bf16_f32 v191, v194, v195
	v_exp_f32_e32 v196, v196
	v_exp_f32_e32 v197, v197
	v_exp_f32_e32 v198, v198
	v_exp_f32_e32 v199, v199
	v_pk_add_f32 v[252:253], v[252:253], v[196:197]
	v_pk_add_f32 v[252:253], v[252:253], v[198:199]
	v_exp_f32_e32 v200, v200
	v_exp_f32_e32 v201, v201
; #define LAS __attribute__((address_space(3)))
; #define VREADS1(arr, d_) do { const unsigned ad_ = vbase ^ (unsigned)((d_) << 6); __builtin_amdgcn_sched_barrier(0); \
;         _Pragma("unroll") for (int ks_ = 0; ks_ < 4; ++ks_) { VTR(arr[ks_ * 2], ad_, ks_ * 4096); VTR(arr[ks_ * 2 + 1], ad_, ks_ * 4096 + 2048); } __builtin_amdgcn_sched_barrier(0); } while (0)
; #define LGKM0() do { __builtin_amdgcn_sched_barrier(0); asm volatile("s_waitcnt lgkmcnt(0)" ::: "memory"); __builtin_amdgcn_sched_barrier(0); } while (0)
; __device__ __forceinline__ void attn_unit(LAS unsigned char* lds, const bf16_t* Z, bf16_t* A2, const float* tabg, int seq_base, int S, int h, int qb, float lam) {
;     ...
;         bool near = true; float cc = 0.f;
;         if (kv0 - (qlo + 31) >= 128) { near = false; cc = tabR; } else if (qlo - (kv0 + 63) >= 128) { near = false; cc = tabL; }
;         { const float coff = cc - mu;
;           if (__any(!(coff == coff_cur))) { coff_cur = coff;
; #pragma unroll
;               for (int r = 0; r < 16; ++r) cblk[r] = coff;
;               asm volatile("" : "+v"(cblk)); } }
;         f32x16 p0, p1;
;         {
;             bf16x8 kf[8];
; #pragma unroll
;             for (int ds = 0; ds < 4; ++ds) { kf[2 * ds] = *(const LAS bf16x8*)(Kt + (kfo ^ (unsigned)(ds << 5))); kf[2 * ds + 1] = *(const LAS bf16x8*)(Kt + 32 * 256 + (kfo ^ (unsigned)(ds << 5))); }
;             __builtin_amdgcn_sched_barrier(0);
;             p0 = __builtin_amdgcn_mfma_f32_32x32x16_bf16(kf[0], qf[0], cblk, 0, 0, 0);
;             p1 = __builtin_amdgcn_mfma_f32_32x32x16_bf16(kf[1], qf[0], cblk, 0, 0, 0);
; #pragma unroll
;             for (int ds = 1; ds < 4; ++ds) {
;                 p0 = __builtin_amdgcn_mfma_f32_32x32x16_bf16(kf[2 * ds], qf[ds], p0, 0, 0, 0);
;                 p1 = __builtin_amdgcn_mfma_f32_32x32x16_bf16(kf[2 * ds + 1], qf[ds], p1, 0, 0, 0);
;             }
;         }
;     ...
;         for (int r = 0; r < 16; ++r) { p0[r] = __builtin_amdgcn_exp2f(p0[r]); p1[r] = __builtin_amdgcn_exp2f(p1[r]); }
; #pragma unroll
;         for (int r = 0; r < 16; r += 2) { ls2 += (f32x2){p0[r], p0[r + 1]}; ls2 += (f32x2){p1[r], p1[r + 1]}; }
;         bf16x8 pa[4]; pa[0] = pack8(p0, 0); pa[1] = pack8(p0, 8); pa[2] = pack8(p1, 0); pa[3] = pack8(p1, 8);
;         LGKM0(); VREADS1(vb, 1); PV1(va, 0); LGKM0(); VREADS1(va, 2); PV1(vb, 1); LGKM0(); VREADS1(vb, 3); PV1(va, 2); LGKM0(); PV1(vb, 3);
	v_cvt_pk_bf16_f32 v192, v196, v197
	v_cvt_pk_bf16_f32 v193, v198, v199
	v_exp_f32_e32 v202, v202
	v_exp_f32_e32 v203, v203
	v_pk_add_f32 v[252:253], v[252:253], v[200:201]
	v_pk_add_f32 v[252:253], v[252:253], v[202:203]
	v_cvt_pk_bf16_f32 v194, v200, v201
	v_cvt_pk_bf16_f32 v195, v202, v203
	v_exp_f32_e32 v204, v204
	v_exp_f32_e32 v205, v205
	v_exp_f32_e32 v206, v206
	v_exp_f32_e32 v207, v207
	v_pk_add_f32 v[252:253], v[252:253], v[204:205]
	v_pk_add_f32 v[252:253], v[252:253], v[206:207]
	v_exp_f32_e32 v208, v208
	v_exp_f32_e32 v209, v209
	v_cvt_pk_bf16_f32 v204, v204, v205
	v_cvt_pk_bf16_f32 v205, v206, v207
	v_exp_f32_e32 v210, v210
	v_exp_f32_e32 v211, v211
	v_pk_add_f32 v[252:253], v[252:253], v[208:209]
	v_pk_add_f32 v[252:253], v[252:253], v[210:211]
	v_cvt_pk_bf16_f32 v206, v208, v209
	v_cvt_pk_bf16_f32 v207, v210, v211
	v_exp_f32_e32 v212, v212
	v_exp_f32_e32 v213, v213
	v_exp_f32_e32 v214, v214
	v_exp_f32_e32 v215, v215
	v_pk_add_f32 v[252:253], v[252:253], v[212:213]
	v_pk_add_f32 v[252:253], v[252:253], v[214:215]
	v_exp_f32_e32 v216, v216
	v_exp_f32_e32 v217, v217
	v_cvt_pk_bf16_f32 v208, v212, v213
	v_cvt_pk_bf16_f32 v209, v214, v215
	v_exp_f32_e32 v218, v218
	v_exp_f32_e32 v219, v219
	v_pk_add_f32 v[252:253], v[252:253], v[216:217]
	v_pk_add_f32 v[252:253], v[252:253], v[218:219]
	v_cvt_pk_bf16_f32 v210, v216, v217
	v_cvt_pk_bf16_f32 v211, v218, v219
	s_mov_b32 s24, s23
	s_mov_b32 s35, s24
	v_mov_b32_e32 v251, 0
	s_cmp_eq_u32 s24, 1
	s_cselect_b64 vcc, -1, 0
	v_cndmask_b32_e32 v251, v251, v177, vcc
	s_cmp_eq_u32 s24, 2
	s_cselect_b64 vcc, -1, 0
	v_cndmask_b32_e32 v251, v251, v178, vcc
	v_sub_f32_e32 v2, v251, v186
	v_mov_b32_e32 v3, v2
	v_mov_b64_e32 v[4:5], v[2:3]
	v_mov_b64_e32 v[6:7], v[2:3]
	v_mov_b64_e32 v[8:9], v[2:3]
	v_mov_b64_e32 v[10:11], v[2:3]
	v_mov_b64_e32 v[12:13], v[2:3]
	v_mov_b64_e32 v[14:15], v[2:3]
	v_mov_b64_e32 v[16:17], v[2:3]
	ds_read_b64_tr_b16 v[132:133], v228 offset:16384
	ds_read_b64_tr_b16 v[134:135], v228 offset:18432
	ds_read_b64_tr_b16 v[136:137], v229 offset:16384
	ds_read_b64_tr_b16 v[138:139], v229 offset:18432
	ds_read_b64_tr_b16 v[140:141], v230 offset:16384
	ds_read_b64_tr_b16 v[142:143], v230 offset:18432
	ds_read_b64_tr_b16 v[144:145], v231 offset:16384
	ds_read_b64_tr_b16 v[146:147], v231 offset:18432
	ds_read_b64_tr_b16 v[220:221], v228 offset:20480
	ds_read_b64_tr_b16 v[222:223], v228 offset:22528
	ds_read_b64_tr_b16 v[224:225], v229 offset:20480
	ds_read_b64_tr_b16 v[226:227], v229 offset:22528
	ds_read_b64_tr_b16 v[232:233], v230 offset:20480
	ds_read_b64_tr_b16 v[234:235], v230 offset:22528
	s_nop 1
	s_cmp_eq_u32 s22, 0
	s_cbranch_scc1 .LatB_recret_h1
	s_cmp_eq_u32 s22, 1
	s_cbranch_scc1 .LatB_recret_m1
	s_branch .LatB_recret_x3
.LatB_rec_2:
	s_waitcnt lgkmcnt(0)
	s_nop 15
	s_sub_u32 s5, s8, s4
	s_lshr_b32 s5, s5, 12
	s_sub_u32 s5, s5, 64
	s_cmp_lt_u32 s5, s11
	s_cselect_b32 s24, 1, 0
	s_cmp_gt_u32 s5, s31
	s_cselect_b32 s30, 2, 0
	s_or_b32 s24, s24, s30
	s_mov_b32 s23, s35
	s_mov_b32 s35, s24
	v_mov_b32_e32 v251, 0
	s_cmp_eq_u32 s24, 1
	s_cselect_b64 vcc, -1, 0
	v_cndmask_b32_e32 v251, v251, v177, vcc
	s_cmp_eq_u32 s24, 2
	s_cselect_b64 vcc, -1, 0
	v_cndmask_b32_e32 v251, v251, v178, vcc
	v_sub_f32_e32 v2, v251, v186
	v_mov_b32_e32 v3, v2
	v_mov_b64_e32 v[4:5], v[2:3]
	v_mov_b64_e32 v[6:7], v[2:3]
	v_mov_b64_e32 v[8:9], v[2:3]
	v_mov_b64_e32 v[10:11], v[2:3]
	v_mov_b64_e32 v[12:13], v[2:3]
	v_mov_b64_e32 v[14:15], v[2:3]
	v_mov_b64_e32 v[16:17], v[2:3]
	s_nop 1
	ds_read_b128 v[132:135], v19 offset:32768
	ds_read_b128 v[136:139], v19 offset:40960
	ds_read_b128 v[140:143], v180 offset:32768
	ds_read_b128 v[144:147], v180 offset:40960
	ds_read_b128 v[220:223], v181 offset:32768
	ds_read_b128 v[224:227], v181 offset:40960
	ds_read_b128 v[232:235], v182 offset:32768
	ds_read_b128 v[236:239], v182 offset:40960
	s_waitcnt lgkmcnt(7)
	v_mfma_f32_32x32x16_bf16 v[84:99], v[132:135], v[116:119], v[2:17]
	s_waitcnt lgkmcnt(6)
	v_mfma_f32_32x32x16_bf16 v[100:115], v[136:139], v[116:119], v[2:17]
	s_waitcnt lgkmcnt(5)
	v_mfma_f32_32x32x16_bf16 v[84:99], v[140:143], v[120:123], v[84:99]
	s_waitcnt lgkmcnt(4)
	v_mfma_f32_32x32x16_bf16 v[100:115], v[144:147], v[120:123], v[100:115]
	s_waitcnt lgkmcnt(3)
	v_mfma_f32_32x32x16_bf16 v[84:99], v[220:223], v[124:127], v[84:99]
	s_waitcnt lgkmcnt(2)
	v_mfma_f32_32x32x16_bf16 v[100:115], v[224:227], v[124:127], v[100:115]
	s_waitcnt lgkmcnt(1)
	v_mfma_f32_32x32x16_bf16 v[84:99], v[232:235], v[128:131], v[84:99]
	s_waitcnt lgkmcnt(0)
	v_mfma_f32_32x32x16_bf16 v[100:115], v[236:239], v[128:131], v[100:115]
	s_nop 15
	s_nop 15
	s_cmp_lg_u32 s35, 0
	s_cbranch_scc1 .LatB_recnn_2
	s_lshl_b32 s29, s5, 2
	s_add_i32 s29, s29, 0x18b80
	v_add_u32_e32 v187, s29, v162
	ds_read2_b32 v[132:133], v187 offset0:0 offset1:1
	ds_read2_b32 v[134:135], v187 offset0:2 offset1:3
	ds_read2_b32 v[136:137], v187 offset0:8 offset1:9
	ds_read2_b32 v[138:139], v187 offset0:10 offset1:11
	ds_read2_b32 v[140:141], v187 offset0:16 offset1:17
	ds_read2_b32 v[142:143], v187 offset0:18 offset1:19
	ds_read2_b32 v[144:145], v187 offset0:24 offset1:25
	ds_read2_b32 v[146:147], v187 offset0:26 offset1:27
	s_waitcnt lgkmcnt(0)
	v_pk_add_f32 v[84:85], v[84:85], v[132:133]
	v_pk_add_f32 v[86:87], v[86:87], v[134:135]
	v_pk_add_f32 v[88:89], v[88:89], v[136:137]
	v_pk_add_f32 v[90:91], v[90:91], v[138:139]
	v_pk_add_f32 v[92:93], v[92:93], v[140:141]
	v_pk_add_f32 v[94:95], v[94:95], v[142:143]
	v_pk_add_f32 v[96:97], v[96:97], v[144:145]
	v_pk_add_f32 v[98:99], v[98:99], v[146:147]
	ds_read2_b32 v[132:133], v187 offset0:32 offset1:33
	ds_read2_b32 v[134:135], v187 offset0:34 offset1:35
	ds_read2_b32 v[136:137], v187 offset0:40 offset1:41
	ds_read2_b32 v[138:139], v187 offset0:42 offset1:43
	ds_read2_b32 v[140:141], v187 offset0:48 offset1:49
	ds_read2_b32 v[142:143], v187 offset0:50 offset1:51
	ds_read2_b32 v[144:145], v187 offset0:56 offset1:57
	ds_read2_b32 v[146:147], v187 offset0:58 offset1:59
	s_waitcnt lgkmcnt(0)
	v_pk_add_f32 v[100:101], v[100:101], v[132:133]
	v_pk_add_f32 v[102:103], v[102:103], v[134:135]
	v_pk_add_f32 v[104:105], v[104:105], v[136:137]
	v_pk_add_f32 v[106:107], v[106:107], v[138:139]
	v_pk_add_f32 v[108:109], v[108:109], v[140:141]
	v_pk_add_f32 v[110:111], v[110:111], v[142:143]
	v_pk_add_f32 v[112:113], v[112:113], v[144:145]
	v_pk_add_f32 v[114:115], v[114:115], v[146:147]
; #define LAS __attribute__((address_space(3)))
; __device__ __forceinline__ float max2f(float a, float b) { float r; asm("v_max_f32_e32 %0, %1, %2" : "=v"(r) : "v"(a), "v"(b)); return r; }
; __device__ __forceinline__ void attn_unit(LAS unsigned char* lds, const bf16_t* Z, bf16_t* A2, const float* tabg, int seq_base, int S, int h, int qb, float lam) {
;     ...
;         float mx = max2f(max16f(p0), max16f(p1));
;         const bool first = (t == 0);
;         if (first || __any(mx > THR)) {
;             { auto rr = __builtin_amdgcn_permlane32_swap(__float_as_uint(mx), __float_as_uint(mx), false, false); mx = max2f(__uint_as_float(rr[0]), __uint_as_float(rr[1])); }
;             const float delta = first ? mx : fmaxf(mx, 0.f);
;             const float alpha = first ? 1.0f : __builtin_amdgcn_exp2f(-delta);
;             mu += delta; ls2 *= alpha;
;             if (!first) {
;                 asm volatile("" ::: "memory");
;                 scr[r32] = alpha;
;                 asm volatile("s_waitcnt lgkmcnt(0)" ::: "memory");
; #pragma unroll
;                 for (int g = 0; g < 4; ++g) { const f32x4 a4 = *(const LAS f32x4*)(scr + 8 * g + 4 * hi);
; #pragma unroll
;                     for (int d = 0; d < 4; ++d) { O[d][4 * g + 0] *= a4[0]; O[d][4 * g + 1] *= a4[1]; O[d][4 * g + 2] *= a4[2]; O[d][4 * g + 3] *= a4[3]; } }
;                 asm volatile("s_waitcnt lgkmcnt(0)" ::: "memory");
;             }
; #pragma unroll
;             for (int r = 0; r < 16; ++r) { p0[r] -= delta; p1[r] -= delta; }
;             asm volatile("" : "+v"(p0), "+v"(p1));
;         }
; #pragma unroll
;         for (int r = 0; r < 16; ++r) { p0[r] = __builtin_amdgcn_exp2f(p0[r]); p1[r] = __builtin_amdgcn_exp2f(p1[r]); }
; #pragma unroll
;         for (int r = 0; r < 16; r += 2) { ls2 += (f32x2){p0[r], p0[r + 1]}; ls2 += (f32x2){p1[r], p1[r + 1]}; }
;         bf16x8 pa[4]; pa[0] = pack8(p0, 0); pa[1] = pack8(p0, 8); pa[2] = pack8(p1, 0); pa[3] = pack8(p1, 8);
.LatB_recnn_2:
	v_max3_f32 v251, v84, v85, v86
	v_max3_f32 v252, v87, v88, v89
	v_max3_f32 v251, v251, v90, v91
	v_max3_f32 v252, v252, v92, v93
	v_max3_f32 v251, v251, v94, v95
	v_max3_f32 v252, v252, v96, v97
	v_max3_f32 v251, v251, v98, v99
	v_max3_f32 v252, v252, v100, v101
	v_max3_f32 v251, v251, v102, v103
	v_max3_f32 v252, v252, v104, v105
	v_max3_f32 v251, v251, v106, v107
	v_max3_f32 v252, v252, v108, v109
	v_max3_f32 v251, v251, v110, v111
	v_max3_f32 v252, v252, v112, v113
	v_max3_f32 v251, v251, v114, v115
	v_max_f32_e32 v251, v251, v252
	v_mov_b32_e32 v252, v251
	s_nop 1
	v_permlane32_swap_b32_e32 v251, v252
	v_max_f32_e32 v251, v251, v252
	v_max_f32_e32 v253, 0, v251
	v_exp_f32_e64 v254, -v253
	v_add_f32_e32 v186, v186, v253
	s_nop 0
	v_mul_f32_e32 v150, v150, v254
	v_mul_f32_e32 v151, v151, v254
	ds_write_b32 v184, v254
	s_waitcnt lgkmcnt(0)
	ds_read_b128 v[132:135], v185
	ds_read_b128 v[136:139], v185 offset:32
	ds_read_b128 v[140:143], v185 offset:64
	ds_read_b128 v[144:147], v185 offset:96
	s_waitcnt lgkmcnt(0)
	v_pk_mul_f32 v[20:21], v[20:21], v[132:133]
	v_pk_mul_f32 v[22:23], v[22:23], v[134:135]
	v_pk_mul_f32 v[24:25], v[24:25], v[136:137]
	v_pk_mul_f32 v[26:27], v[26:27], v[138:139]
	v_pk_mul_f32 v[28:29], v[28:29], v[140:141]
	v_pk_mul_f32 v[30:31], v[30:31], v[142:143]
	v_pk_mul_f32 v[32:33], v[32:33], v[144:145]
	v_pk_mul_f32 v[34:35], v[34:35], v[146:147]
	v_pk_mul_f32 v[36:37], v[36:37], v[132:133]
	v_pk_mul_f32 v[38:39], v[38:39], v[134:135]
	v_pk_mul_f32 v[40:41], v[40:41], v[136:137]
	v_pk_mul_f32 v[42:43], v[42:43], v[138:139]
	v_pk_mul_f32 v[44:45], v[44:45], v[140:141]
	v_pk_mul_f32 v[46:47], v[46:47], v[142:143]
	v_pk_mul_f32 v[48:49], v[48:49], v[144:145]
	v_pk_mul_f32 v[50:51], v[50:51], v[146:147]
	v_pk_mul_f32 v[52:53], v[52:53], v[132:133]
	v_pk_mul_f32 v[54:55], v[54:55], v[134:135]
	v_pk_mul_f32 v[56:57], v[56:57], v[136:137]
	v_pk_mul_f32 v[58:59], v[58:59], v[138:139]
	v_pk_mul_f32 v[60:61], v[60:61], v[140:141]
	v_pk_mul_f32 v[62:63], v[62:63], v[142:143]
	v_pk_mul_f32 v[64:65], v[64:65], v[144:145]
	v_pk_mul_f32 v[66:67], v[66:67], v[146:147]
	v_pk_mul_f32 v[68:69], v[68:69], v[132:133]
	v_pk_mul_f32 v[70:71], v[70:71], v[134:135]
	v_pk_mul_f32 v[72:73], v[72:73], v[136:137]
	v_pk_mul_f32 v[74:75], v[74:75], v[138:139]
	v_pk_mul_f32 v[76:77], v[76:77], v[140:141]
	v_pk_mul_f32 v[78:79], v[78:79], v[142:143]
	v_pk_mul_f32 v[80:81], v[80:81], v[144:145]
	v_pk_mul_f32 v[82:83], v[82:83], v[146:147]
	v_mov_b32_e32 v252, v253
	v_pk_add_f32 v[84:85], v[84:85], v[252:253] neg_lo:[0,1] neg_hi:[0,1]
	v_pk_add_f32 v[86:87], v[86:87], v[252:253] neg_lo:[0,1] neg_hi:[0,1]
	v_pk_add_f32 v[88:89], v[88:89], v[252:253] neg_lo:[0,1] neg_hi:[0,1]
	v_pk_add_f32 v[90:91], v[90:91], v[252:253] neg_lo:[0,1] neg_hi:[0,1]
	v_pk_add_f32 v[92:93], v[92:93], v[252:253] neg_lo:[0,1] neg_hi:[0,1]
	v_pk_add_f32 v[94:95], v[94:95], v[252:253] neg_lo:[0,1] neg_hi:[0,1]
	v_pk_add_f32 v[96:97], v[96:97], v[252:253] neg_lo:[0,1] neg_hi:[0,1]
	v_pk_add_f32 v[98:99], v[98:99], v[252:253] neg_lo:[0,1] neg_hi:[0,1]
	v_pk_add_f32 v[100:101], v[100:101], v[252:253] neg_lo:[0,1] neg_hi:[0,1]
	v_pk_add_f32 v[102:103], v[102:103], v[252:253] neg_lo:[0,1] neg_hi:[0,1]
	v_pk_add_f32 v[104:105], v[104:105], v[252:253] neg_lo:[0,1] neg_hi:[0,1]
	v_pk_add_f32 v[106:107], v[106:107], v[252:253] neg_lo:[0,1] neg_hi:[0,1]
	v_pk_add_f32 v[108:109], v[108:109], v[252:253] neg_lo:[0,1] neg_hi:[0,1]
	v_pk_add_f32 v[110:111], v[110:111], v[252:253] neg_lo:[0,1] neg_hi:[0,1]
	v_pk_add_f32 v[112:113], v[112:113], v[252:253] neg_lo:[0,1] neg_hi:[0,1]
	v_pk_add_f32 v[114:115], v[114:115], v[252:253] neg_lo:[0,1] neg_hi:[0,1]
	v_pk_add_f32 v[188:189], v[188:189], v[252:253] neg_lo:[0,1] neg_hi:[0,1]
	v_pk_add_f32 v[190:191], v[190:191], v[252:253] neg_lo:[0,1] neg_hi:[0,1]
	v_pk_add_f32 v[192:193], v[192:193], v[252:253] neg_lo:[0,1] neg_hi:[0,1]
	v_pk_add_f32 v[194:195], v[194:195], v[252:253] neg_lo:[0,1] neg_hi:[0,1]
	v_pk_add_f32 v[196:197], v[196:197], v[252:253] neg_lo:[0,1] neg_hi:[0,1]
	v_pk_add_f32 v[198:199], v[198:199], v[252:253] neg_lo:[0,1] neg_hi:[0,1]
	v_pk_add_f32 v[200:201], v[200:201], v[252:253] neg_lo:[0,1] neg_hi:[0,1]
	v_pk_add_f32 v[202:203], v[202:203], v[252:253] neg_lo:[0,1] neg_hi:[0,1]
	v_pk_add_f32 v[204:205], v[204:205], v[252:253] neg_lo:[0,1] neg_hi:[0,1]
	v_pk_add_f32 v[206:207], v[206:207], v[252:253] neg_lo:[0,1] neg_hi:[0,1]
	v_pk_add_f32 v[208:209], v[208:209], v[252:253] neg_lo:[0,1] neg_hi:[0,1]
	v_pk_add_f32 v[210:211], v[210:211], v[252:253] neg_lo:[0,1] neg_hi:[0,1]
	v_pk_add_f32 v[212:213], v[212:213], v[252:253] neg_lo:[0,1] neg_hi:[0,1]
	v_pk_add_f32 v[214:215], v[214:215], v[252:253] neg_lo:[0,1] neg_hi:[0,1]
	v_pk_add_f32 v[216:217], v[216:217], v[252:253] neg_lo:[0,1] neg_hi:[0,1]
	v_pk_add_f32 v[218:219], v[218:219], v[252:253] neg_lo:[0,1] neg_hi:[0,1]
	v_exp_f32_e32 v84, v84
	v_exp_f32_e32 v85, v85
	v_exp_f32_e32 v86, v86
	v_exp_f32_e32 v87, v87
	v_exp_f32_e32 v88, v88
	v_pk_add_f32 v[252:253], v[84:85], v[86:87]
	v_exp_f32_e32 v89, v89
	v_cvt_pk_bf16_f32 v84, v84, v85
	v_cvt_pk_bf16_f32 v85, v86, v87
	v_exp_f32_e32 v90, v90
	v_exp_f32_e32 v91, v91
	v_pk_add_f32 v[252:253], v[252:253], v[88:89]
	v_pk_add_f32 v[252:253], v[252:253], v[90:91]
	v_cvt_pk_bf16_f32 v86, v88, v89
	v_cvt_pk_bf16_f32 v87, v90, v91
	v_exp_f32_e32 v92, v92
	v_exp_f32_e32 v93, v93
	v_exp_f32_e32 v94, v94
	v_exp_f32_e32 v95, v95
	v_pk_add_f32 v[252:253], v[252:253], v[92:93]
	v_pk_add_f32 v[252:253], v[252:253], v[94:95]
	v_exp_f32_e32 v96, v96
	v_exp_f32_e32 v97, v97
	v_cvt_pk_bf16_f32 v88, v92, v93
	v_cvt_pk_bf16_f32 v89, v94, v95
; #define LAS __attribute__((address_space(3)))
; __device__ __forceinline__ void attn_unit(LAS unsigned char* lds, const bf16_t* Z, bf16_t* A2, const float* tabg, int seq_base, int S, int h, int qb, float lam) {
;     ...
;         bool near = true; float cc = 0.f;
;         if (kv0 - (qlo + 31) >= 128) { near = false; cc = tabR; } else if (qlo - (kv0 + 63) >= 128) { near = false; cc = tabL; }
;         { const float coff = cc - mu;
;           if (__any(!(coff == coff_cur))) { coff_cur = coff;
; #pragma unroll
;               for (int r = 0; r < 16; ++r) cblk[r] = coff;
;               asm volatile("" : "+v"(cblk)); } }
;         f32x16 p0, p1;
;         {
;             bf16x8 kf[8];
; #pragma unroll
;             for (int ds = 0; ds < 4; ++ds) { kf[2 * ds] = *(const LAS bf16x8*)(Kt + (kfo ^ (unsigned)(ds << 5))); kf[2 * ds + 1] = *(const LAS bf16x8*)(Kt + 32 * 256 + (kfo ^ (unsigned)(ds << 5))); }
;             __builtin_amdgcn_sched_barrier(0);
;             p0 = __builtin_amdgcn_mfma_f32_32x32x16_bf16(kf[0], qf[0], cblk, 0, 0, 0);
;             p1 = __builtin_amdgcn_mfma_f32_32x32x16_bf16(kf[1], qf[0], cblk, 0, 0, 0);
; #pragma unroll
;             for (int ds = 1; ds < 4; ++ds) {
;                 p0 = __builtin_amdgcn_mfma_f32_32x32x16_bf16(kf[2 * ds], qf[ds], p0, 0, 0, 0);
;                 p1 = __builtin_amdgcn_mfma_f32_32x32x16_bf16(kf[2 * ds + 1], qf[ds], p1, 0, 0, 0);
;             }
;         }
;     ...
;         const unsigned vbase = (unsigned)(size_t)Vt + vfo;
;         s16x4 va[8], vb[8];
;         VREADS1(va, 0);
;         if (near) {
;             const LAS float* tp = tab + (kv0 + 4 * hi - (qlo + r32) + 224);
; #pragma unroll
;             for (int r = 0; r < 16; ++r) { p0[r] += tp[(r & 3) + 8 * (r >> 2)]; p1[r] += tp[32 + (r & 3) + 8 * (r >> 2)]; }
;         }
;     ...
; #pragma unroll
;         for (int r = 0; r < 16; ++r) { p0[r] = __builtin_amdgcn_exp2f(p0[r]); p1[r] = __builtin_amdgcn_exp2f(p1[r]); }
; #pragma unroll
;         for (int r = 0; r < 16; r += 2) { ls2 += (f32x2){p0[r], p0[r + 1]}; ls2 += (f32x2){p1[r], p1[r + 1]}; }
;         bf16x8 pa[4]; pa[0] = pack8(p0, 0); pa[1] = pack8(p0, 8); pa[2] = pack8(p1, 0); pa[3] = pack8(p1, 8);
	v_exp_f32_e32 v98, v98
	v_exp_f32_e32 v99, v99
	v_pk_add_f32 v[252:253], v[252:253], v[96:97]
	v_pk_add_f32 v[252:253], v[252:253], v[98:99]
	v_cvt_pk_bf16_f32 v90, v96, v97
	v_cvt_pk_bf16_f32 v91, v98, v99
	v_exp_f32_e32 v100, v100
	v_exp_f32_e32 v101, v101
	v_exp_f32_e32 v102, v102
	v_exp_f32_e32 v103, v103
	v_pk_add_f32 v[252:253], v[252:253], v[100:101]
	v_pk_add_f32 v[252:253], v[252:253], v[102:103]
	v_exp_f32_e32 v104, v104
	v_exp_f32_e32 v105, v105
	v_cvt_pk_bf16_f32 v100, v100, v101
	v_cvt_pk_bf16_f32 v101, v102, v103
	v_exp_f32_e32 v106, v106
	v_exp_f32_e32 v107, v107
	v_pk_add_f32 v[252:253], v[252:253], v[104:105]
	v_pk_add_f32 v[252:253], v[252:253], v[106:107]
	v_cvt_pk_bf16_f32 v102, v104, v105
	v_cvt_pk_bf16_f32 v103, v106, v107
	v_exp_f32_e32 v108, v108
	v_exp_f32_e32 v109, v109
	v_exp_f32_e32 v110, v110
	v_exp_f32_e32 v111, v111
	v_pk_add_f32 v[252:253], v[252:253], v[108:109]
	v_pk_add_f32 v[252:253], v[252:253], v[110:111]
	v_exp_f32_e32 v112, v112
	v_exp_f32_e32 v113, v113
	v_cvt_pk_bf16_f32 v104, v108, v109
	v_cvt_pk_bf16_f32 v105, v110, v111
	v_exp_f32_e32 v114, v114
	v_exp_f32_e32 v115, v115
	v_pk_add_f32 v[252:253], v[252:253], v[112:113]
	v_pk_add_f32 v[252:253], v[252:253], v[114:115]
	v_cvt_pk_bf16_f32 v106, v112, v113
	v_cvt_pk_bf16_f32 v107, v114, v115
	s_mov_b32 s24, s23
	s_mov_b32 s35, s24
	v_mov_b32_e32 v251, 0
	s_cmp_eq_u32 s24, 1
	s_cselect_b64 vcc, -1, 0
	v_cndmask_b32_e32 v251, v251, v177, vcc
	s_cmp_eq_u32 s24, 2
	s_cselect_b64 vcc, -1, 0
	v_cndmask_b32_e32 v251, v251, v178, vcc
	v_sub_f32_e32 v2, v251, v186
	v_mov_b32_e32 v3, v2
	v_mov_b64_e32 v[4:5], v[2:3]
	v_mov_b64_e32 v[6:7], v[2:3]
	v_mov_b64_e32 v[8:9], v[2:3]
	v_mov_b64_e32 v[10:11], v[2:3]
	v_mov_b64_e32 v[12:13], v[2:3]
	v_mov_b64_e32 v[14:15], v[2:3]
	v_mov_b64_e32 v[16:17], v[2:3]
	ds_read_b64_tr_b16 v[132:133], v228 offset:32768
	ds_read_b64_tr_b16 v[134:135], v228 offset:34816
	ds_read_b64_tr_b16 v[136:137], v229 offset:32768
	ds_read_b64_tr_b16 v[138:139], v229 offset:34816
	ds_read_b64_tr_b16 v[140:141], v230 offset:32768
	ds_read_b64_tr_b16 v[142:143], v230 offset:34816
	ds_read_b64_tr_b16 v[144:145], v231 offset:32768
	ds_read_b64_tr_b16 v[146:147], v231 offset:34816
	ds_read_b64_tr_b16 v[220:221], v228 offset:36864
	ds_read_b64_tr_b16 v[222:223], v228 offset:38912
	ds_read_b64_tr_b16 v[224:225], v229 offset:36864
	ds_read_b64_tr_b16 v[226:227], v229 offset:38912
	ds_read_b64_tr_b16 v[232:233], v230 offset:36864
	ds_read_b64_tr_b16 v[234:235], v230 offset:38912
	s_nop 1
	s_cmp_eq_u32 s22, 0
	s_cbranch_scc1 .LatB_recret_h2
	s_cmp_eq_u32 s22, 1
	s_cbranch_scc1 .LatB_recret_m2
	s_branch .LatB_recret_x2
.LatB_rec_3:
	s_waitcnt lgkmcnt(0)
	s_nop 15
	s_sub_u32 s5, s8, s4
	s_lshr_b32 s5, s5, 12
	s_sub_u32 s5, s5, 64
	s_cmp_lt_u32 s5, s11
	s_cselect_b32 s24, 1, 0
	s_cmp_gt_u32 s5, s31
	s_cselect_b32 s30, 2, 0
	s_or_b32 s24, s24, s30
	s_mov_b32 s23, s35
	s_mov_b32 s35, s24
	v_mov_b32_e32 v251, 0
	s_cmp_eq_u32 s24, 1
	s_cselect_b64 vcc, -1, 0
	v_cndmask_b32_e32 v251, v251, v177, vcc
	s_cmp_eq_u32 s24, 2
	s_cselect_b64 vcc, -1, 0
	v_cndmask_b32_e32 v251, v251, v178, vcc
	v_sub_f32_e32 v2, v251, v186
	v_mov_b32_e32 v3, v2
	v_mov_b64_e32 v[4:5], v[2:3]
	v_mov_b64_e32 v[6:7], v[2:3]
	v_mov_b64_e32 v[8:9], v[2:3]
	v_mov_b64_e32 v[10:11], v[2:3]
	v_mov_b64_e32 v[12:13], v[2:3]
	v_mov_b64_e32 v[14:15], v[2:3]
	v_mov_b64_e32 v[16:17], v[2:3]
	s_nop 1
	ds_read_b128 v[132:135], v164
	ds_read_b128 v[136:139], v164 offset:8192
	ds_read_b128 v[140:143], v165
	ds_read_b128 v[144:147], v165 offset:8192
	ds_read_b128 v[220:223], v166
	ds_read_b128 v[224:227], v166 offset:8192
	ds_read_b128 v[232:235], v167
	ds_read_b128 v[236:239], v167 offset:8192
	s_waitcnt lgkmcnt(7)
	v_mfma_f32_32x32x16_bf16 v[188:203], v[132:135], v[116:119], v[2:17]
	s_waitcnt lgkmcnt(6)
	v_mfma_f32_32x32x16_bf16 v[204:219], v[136:139], v[116:119], v[2:17]
	s_waitcnt lgkmcnt(5)
	v_mfma_f32_32x32x16_bf16 v[188:203], v[140:143], v[120:123], v[188:203]
	s_waitcnt lgkmcnt(4)
	v_mfma_f32_32x32x16_bf16 v[204:219], v[144:147], v[120:123], v[204:219]
	s_waitcnt lgkmcnt(3)
	v_mfma_f32_32x32x16_bf16 v[188:203], v[220:223], v[124:127], v[188:203]
	s_waitcnt lgkmcnt(2)
	v_mfma_f32_32x32x16_bf16 v[204:219], v[224:227], v[124:127], v[204:219]
	s_waitcnt lgkmcnt(1)
	v_mfma_f32_32x32x16_bf16 v[188:203], v[232:235], v[128:131], v[188:203]
	s_waitcnt lgkmcnt(0)
	v_mfma_f32_32x32x16_bf16 v[204:219], v[236:239], v[128:131], v[204:219]
	s_nop 15
	s_nop 15
	s_cmp_lg_u32 s35, 0
	s_cbranch_scc1 .LatB_recnn_3
	s_lshl_b32 s29, s5, 2
	s_add_i32 s29, s29, 0x18b80
	v_add_u32_e32 v187, s29, v162
	ds_read2_b32 v[132:133], v187 offset0:0 offset1:1
	ds_read2_b32 v[134:135], v187 offset0:2 offset1:3
	ds_read2_b32 v[136:137], v187 offset0:8 offset1:9
	ds_read2_b32 v[138:139], v187 offset0:10 offset1:11
	ds_read2_b32 v[140:141], v187 offset0:16 offset1:17
	ds_read2_b32 v[142:143], v187 offset0:18 offset1:19
	ds_read2_b32 v[144:145], v187 offset0:24 offset1:25
	ds_read2_b32 v[146:147], v187 offset0:26 offset1:27
	s_waitcnt lgkmcnt(0)
	v_pk_add_f32 v[188:189], v[188:189], v[132:133]
	v_pk_add_f32 v[190:191], v[190:191], v[134:135]
	v_pk_add_f32 v[192:193], v[192:193], v[136:137]
	v_pk_add_f32 v[194:195], v[194:195], v[138:139]
	v_pk_add_f32 v[196:197], v[196:197], v[140:141]
	v_pk_add_f32 v[198:199], v[198:199], v[142:143]
	v_pk_add_f32 v[200:201], v[200:201], v[144:145]
	v_pk_add_f32 v[202:203], v[202:203], v[146:147]
	ds_read2_b32 v[132:133], v187 offset0:32 offset1:33
	ds_read2_b32 v[134:135], v187 offset0:34 offset1:35
	ds_read2_b32 v[136:137], v187 offset0:40 offset1:41
	ds_read2_b32 v[138:139], v187 offset0:42 offset1:43
	ds_read2_b32 v[140:141], v187 offset0:48 offset1:49
	ds_read2_b32 v[142:143], v187 offset0:50 offset1:51
	ds_read2_b32 v[144:145], v187 offset0:56 offset1:57
	ds_read2_b32 v[146:147], v187 offset0:58 offset1:59
	s_waitcnt lgkmcnt(0)
	v_pk_add_f32 v[204:205], v[204:205], v[132:133]
	v_pk_add_f32 v[206:207], v[206:207], v[134:135]
	v_pk_add_f32 v[208:209], v[208:209], v[136:137]
	v_pk_add_f32 v[210:211], v[210:211], v[138:139]
	v_pk_add_f32 v[212:213], v[212:213], v[140:141]
	v_pk_add_f32 v[214:215], v[214:215], v[142:143]
	v_pk_add_f32 v[216:217], v[216:217], v[144:145]
	v_pk_add_f32 v[218:219], v[218:219], v[146:147]
; #define LAS __attribute__((address_space(3)))
; __device__ __forceinline__ float max2f(float a, float b) { float r; asm("v_max_f32_e32 %0, %1, %2" : "=v"(r) : "v"(a), "v"(b)); return r; }
; __device__ __forceinline__ void attn_unit(LAS unsigned char* lds, const bf16_t* Z, bf16_t* A2, const float* tabg, int seq_base, int S, int h, int qb, float lam) {
;     ...
;         float mx = max2f(max16f(p0), max16f(p1));
;         const bool first = (t == 0);
;         if (first || __any(mx > THR)) {
;             { auto rr = __builtin_amdgcn_permlane32_swap(__float_as_uint(mx), __float_as_uint(mx), false, false); mx = max2f(__uint_as_float(rr[0]), __uint_as_float(rr[1])); }
;             const float delta = first ? mx : fmaxf(mx, 0.f);
;             const float alpha = first ? 1.0f : __builtin_amdgcn_exp2f(-delta);
;             mu += delta; ls2 *= alpha;
;             if (!first) {
;                 asm volatile("" ::: "memory");
;                 scr[r32] = alpha;
;                 asm volatile("s_waitcnt lgkmcnt(0)" ::: "memory");
; #pragma unroll
;                 for (int g = 0; g < 4; ++g) { const f32x4 a4 = *(const LAS f32x4*)(scr + 8 * g + 4 * hi);
; #pragma unroll
;                     for (int d = 0; d < 4; ++d) { O[d][4 * g + 0] *= a4[0]; O[d][4 * g + 1] *= a4[1]; O[d][4 * g + 2] *= a4[2]; O[d][4 * g + 3] *= a4[3]; } }
;                 asm volatile("s_waitcnt lgkmcnt(0)" ::: "memory");
;             }
; #pragma unroll
;             for (int r = 0; r < 16; ++r) { p0[r] -= delta; p1[r] -= delta; }
;             asm volatile("" : "+v"(p0), "+v"(p1));
;         }
.LatB_recnn_3:
	v_max3_f32 v251, v188, v189, v190
	v_max3_f32 v252, v191, v192, v193
	v_max3_f32 v251, v251, v194, v195
	v_max3_f32 v252, v252, v196, v197
	v_max3_f32 v251, v251, v198, v199
	v_max3_f32 v252, v252, v200, v201
	v_max3_f32 v251, v251, v202, v203
	v_max3_f32 v252, v252, v204, v205
	v_max3_f32 v251, v251, v206, v207
	v_max3_f32 v252, v252, v208, v209
	v_max3_f32 v251, v251, v210, v211
	v_max3_f32 v252, v252, v212, v213
	v_max3_f32 v251, v251, v214, v215
	v_max3_f32 v252, v252, v216, v217
	v_max3_f32 v251, v251, v218, v219
	v_max_f32_e32 v251, v251, v252
	v_mov_b32_e32 v252, v251
	s_nop 1
	v_permlane32_swap_b32_e32 v251, v252
	v_max_f32_e32 v251, v251, v252
	v_max_f32_e32 v253, 0, v251
	v_exp_f32_e64 v254, -v253
	v_add_f32_e32 v186, v186, v253
	s_nop 0
	v_mul_f32_e32 v150, v150, v254
	v_mul_f32_e32 v151, v151, v254
	ds_write_b32 v184, v254
	s_waitcnt lgkmcnt(0)
	ds_read_b128 v[132:135], v185
	ds_read_b128 v[136:139], v185 offset:32
	ds_read_b128 v[140:143], v185 offset:64
	ds_read_b128 v[144:147], v185 offset:96
	s_waitcnt lgkmcnt(0)
	v_pk_mul_f32 v[20:21], v[20:21], v[132:133]
	v_pk_mul_f32 v[22:23], v[22:23], v[134:135]
	v_pk_mul_f32 v[24:25], v[24:25], v[136:137]
	v_pk_mul_f32 v[26:27], v[26:27], v[138:139]
	v_pk_mul_f32 v[28:29], v[28:29], v[140:141]
	v_pk_mul_f32 v[30:31], v[30:31], v[142:143]
	v_pk_mul_f32 v[32:33], v[32:33], v[144:145]
	v_pk_mul_f32 v[34:35], v[34:35], v[146:147]
	v_pk_mul_f32 v[36:37], v[36:37], v[132:133]
	v_pk_mul_f32 v[38:39], v[38:39], v[134:135]
	v_pk_mul_f32 v[40:41], v[40:41], v[136:137]
	v_pk_mul_f32 v[42:43], v[42:43], v[138:139]
	v_pk_mul_f32 v[44:45], v[44:45], v[140:141]
	v_pk_mul_f32 v[46:47], v[46:47], v[142:143]
	v_pk_mul_f32 v[48:49], v[48:49], v[144:145]
	v_pk_mul_f32 v[50:51], v[50:51], v[146:147]
	v_pk_mul_f32 v[52:53], v[52:53], v[132:133]
	v_pk_mul_f32 v[54:55], v[54:55], v[134:135]
	v_pk_mul_f32 v[56:57], v[56:57], v[136:137]
	v_pk_mul_f32 v[58:59], v[58:59], v[138:139]
	v_pk_mul_f32 v[60:61], v[60:61], v[140:141]
	v_pk_mul_f32 v[62:63], v[62:63], v[142:143]
	v_pk_mul_f32 v[64:65], v[64:65], v[144:145]
	v_pk_mul_f32 v[66:67], v[66:67], v[146:147]
	v_pk_mul_f32 v[68:69], v[68:69], v[132:133]
	v_pk_mul_f32 v[70:71], v[70:71], v[134:135]
	v_pk_mul_f32 v[72:73], v[72:73], v[136:137]
	v_pk_mul_f32 v[74:75], v[74:75], v[138:139]
	v_pk_mul_f32 v[76:77], v[76:77], v[140:141]
	v_pk_mul_f32 v[78:79], v[78:79], v[142:143]
	v_pk_mul_f32 v[80:81], v[80:81], v[144:145]
	v_pk_mul_f32 v[82:83], v[82:83], v[146:147]
	v_mov_b32_e32 v252, v253
	v_pk_add_f32 v[188:189], v[188:189], v[252:253] neg_lo:[0,1] neg_hi:[0,1]
	v_pk_add_f32 v[190:191], v[190:191], v[252:253] neg_lo:[0,1] neg_hi:[0,1]
	v_pk_add_f32 v[192:193], v[192:193], v[252:253] neg_lo:[0,1] neg_hi:[0,1]
	v_pk_add_f32 v[194:195], v[194:195], v[252:253] neg_lo:[0,1] neg_hi:[0,1]
	v_pk_add_f32 v[196:197], v[196:197], v[252:253] neg_lo:[0,1] neg_hi:[0,1]
	v_pk_add_f32 v[198:199], v[198:199], v[252:253] neg_lo:[0,1] neg_hi:[0,1]
	v_pk_add_f32 v[200:201], v[200:201], v[252:253] neg_lo:[0,1] neg_hi:[0,1]
	v_pk_add_f32 v[202:203], v[202:203], v[252:253] neg_lo:[0,1] neg_hi:[0,1]
	v_pk_add_f32 v[204:205], v[204:205], v[252:253] neg_lo:[0,1] neg_hi:[0,1]
	v_pk_add_f32 v[206:207], v[206:207], v[252:253] neg_lo:[0,1] neg_hi:[0,1]
	v_pk_add_f32 v[208:209], v[208:209], v[252:253] neg_lo:[0,1] neg_hi:[0,1]
	v_pk_add_f32 v[210:211], v[210:211], v[252:253] neg_lo:[0,1] neg_hi:[0,1]
	v_pk_add_f32 v[212:213], v[212:213], v[252:253] neg_lo:[0,1] neg_hi:[0,1]
	v_pk_add_f32 v[214:215], v[214:215], v[252:253] neg_lo:[0,1] neg_hi:[0,1]
	v_pk_add_f32 v[216:217], v[216:217], v[252:253] neg_lo:[0,1] neg_hi:[0,1]
	v_pk_add_f32 v[218:219], v[218:219], v[252:253] neg_lo:[0,1] neg_hi:[0,1]
	v_pk_add_f32 v[84:85], v[84:85], v[252:253] neg_lo:[0,1] neg_hi:[0,1]
	v_pk_add_f32 v[86:87], v[86:87], v[252:253] neg_lo:[0,1] neg_hi:[0,1]
	v_pk_add_f32 v[88:89], v[88:89], v[252:253] neg_lo:[0,1] neg_hi:[0,1]
	v_pk_add_f32 v[90:91], v[90:91], v[252:253] neg_lo:[0,1] neg_hi:[0,1]
	v_pk_add_f32 v[92:93], v[92:93], v[252:253] neg_lo:[0,1] neg_hi:[0,1]
	v_pk_add_f32 v[94:95], v[94:95], v[252:253] neg_lo:[0,1] neg_hi:[0,1]
; #define VREADS1(arr, d_) do { const unsigned ad_ = vbase ^ (unsigned)((d_) << 6); __builtin_amdgcn_sched_barrier(0); \
;         _Pragma("unroll") for (int ks_ = 0; ks_ < 4; ++ks_) { VTR(arr[ks_ * 2], ad_, ks_ * 4096); VTR(arr[ks_ * 2 + 1], ad_, ks_ * 4096 + 2048); } __builtin_amdgcn_sched_barrier(0); } while (0)
; #define PV1(arr, d_) do { _Pragma("unroll") for (int ks_ = 0; ks_ < 4; ++ks_) { const s16x4 lo_ = arr[ks_ * 2], hh_ = arr[ks_ * 2 + 1]; \
;         const bf16x8 bv_ = (bf16x8){lo_[0], lo_[1], lo_[2], lo_[3], hh_[0], hh_[1], hh_[2], hh_[3]}; \
;         O[d_] = __builtin_amdgcn_mfma_f32_32x32x16_bf16(pa[ks_], bv_, O[d_], 0, 0, 0); } __builtin_amdgcn_sched_barrier(0); } while (0)
; #define LGKM0() do { __builtin_amdgcn_sched_barrier(0); asm volatile("s_waitcnt lgkmcnt(0)" ::: "memory"); __builtin_amdgcn_sched_barrier(0); } while (0)
; __device__ __forceinline__ void attn_unit(LAS unsigned char* lds, const bf16_t* Z, bf16_t* A2, const float* tabg, int seq_base, int S, int h, int qb, float lam) {
;     ...
;         bool near = true; float cc = 0.f;
;         if (kv0 - (qlo + 31) >= 128) { near = false; cc = tabR; } else if (qlo - (kv0 + 63) >= 128) { near = false; cc = tabL; }
;         { const float coff = cc - mu;
;           if (__any(!(coff == coff_cur))) { coff_cur = coff;
; #pragma unroll
;               for (int r = 0; r < 16; ++r) cblk[r] = coff;
;               asm volatile("" : "+v"(cblk)); } }
;     ...
; #pragma unroll
;             for (int r = 0; r < 16; ++r) { p0[r] -= delta; p1[r] -= delta; }
;             asm volatile("" : "+v"(p0), "+v"(p1));
;         }
; #pragma unroll
;         for (int r = 0; r < 16; ++r) { p0[r] = __builtin_amdgcn_exp2f(p0[r]); p1[r] = __builtin_amdgcn_exp2f(p1[r]); }
; #pragma unroll
;         for (int r = 0; r < 16; r += 2) { ls2 += (f32x2){p0[r], p0[r + 1]}; ls2 += (f32x2){p1[r], p1[r + 1]}; }
;         bf16x8 pa[4]; pa[0] = pack8(p0, 0); pa[1] = pack8(p0, 8); pa[2] = pack8(p1, 0); pa[3] = pack8(p1, 8);
;         LGKM0(); VREADS1(vb, 1); PV1(va, 0); LGKM0(); VREADS1(va, 2); PV1(vb, 1); LGKM0(); VREADS1(vb, 3); PV1(va, 2); LGKM0(); PV1(vb, 3);
	v_pk_add_f32 v[96:97], v[96:97], v[252:253] neg_lo:[0,1] neg_hi:[0,1]
	v_pk_add_f32 v[98:99], v[98:99], v[252:253] neg_lo:[0,1] neg_hi:[0,1]
	v_pk_add_f32 v[100:101], v[100:101], v[252:253] neg_lo:[0,1] neg_hi:[0,1]
	v_pk_add_f32 v[102:103], v[102:103], v[252:253] neg_lo:[0,1] neg_hi:[0,1]
	v_pk_add_f32 v[104:105], v[104:105], v[252:253] neg_lo:[0,1] neg_hi:[0,1]
	v_pk_add_f32 v[106:107], v[106:107], v[252:253] neg_lo:[0,1] neg_hi:[0,1]
	v_pk_add_f32 v[108:109], v[108:109], v[252:253] neg_lo:[0,1] neg_hi:[0,1]
	v_pk_add_f32 v[110:111], v[110:111], v[252:253] neg_lo:[0,1] neg_hi:[0,1]
	v_pk_add_f32 v[112:113], v[112:113], v[252:253] neg_lo:[0,1] neg_hi:[0,1]
	v_pk_add_f32 v[114:115], v[114:115], v[252:253] neg_lo:[0,1] neg_hi:[0,1]
	v_exp_f32_e32 v188, v188
	v_exp_f32_e32 v189, v189
	v_exp_f32_e32 v190, v190
	v_exp_f32_e32 v191, v191
	v_exp_f32_e32 v192, v192
	v_pk_add_f32 v[252:253], v[188:189], v[190:191]
	v_exp_f32_e32 v193, v193
	v_cvt_pk_bf16_f32 v188, v188, v189
	v_cvt_pk_bf16_f32 v189, v190, v191
	v_exp_f32_e32 v194, v194
	v_exp_f32_e32 v195, v195
	v_pk_add_f32 v[252:253], v[252:253], v[192:193]
	v_pk_add_f32 v[252:253], v[252:253], v[194:195]
	v_cvt_pk_bf16_f32 v190, v192, v193
	v_cvt_pk_bf16_f32 v191, v194, v195
	v_exp_f32_e32 v196, v196
	v_exp_f32_e32 v197, v197
	v_exp_f32_e32 v198, v198
	v_exp_f32_e32 v199, v199
	v_pk_add_f32 v[252:253], v[252:253], v[196:197]
	v_pk_add_f32 v[252:253], v[252:253], v[198:199]
	v_exp_f32_e32 v200, v200
	v_exp_f32_e32 v201, v201
	v_cvt_pk_bf16_f32 v192, v196, v197
	v_cvt_pk_bf16_f32 v193, v198, v199
	v_exp_f32_e32 v202, v202
	v_exp_f32_e32 v203, v203
	v_pk_add_f32 v[252:253], v[252:253], v[200:201]
	v_pk_add_f32 v[252:253], v[252:253], v[202:203]
	v_cvt_pk_bf16_f32 v194, v200, v201
	v_cvt_pk_bf16_f32 v195, v202, v203
	v_exp_f32_e32 v204, v204
	v_exp_f32_e32 v205, v205
	v_exp_f32_e32 v206, v206
	v_exp_f32_e32 v207, v207
	v_pk_add_f32 v[252:253], v[252:253], v[204:205]
	v_pk_add_f32 v[252:253], v[252:253], v[206:207]
	v_exp_f32_e32 v208, v208
	v_exp_f32_e32 v209, v209
	v_cvt_pk_bf16_f32 v204, v204, v205
	v_cvt_pk_bf16_f32 v205, v206, v207
	v_exp_f32_e32 v210, v210
	v_exp_f32_e32 v211, v211
	v_pk_add_f32 v[252:253], v[252:253], v[208:209]
	v_pk_add_f32 v[252:253], v[252:253], v[210:211]
	v_cvt_pk_bf16_f32 v206, v208, v209
	v_cvt_pk_bf16_f32 v207, v210, v211
	v_exp_f32_e32 v212, v212
	v_exp_f32_e32 v213, v213
	v_exp_f32_e32 v214, v214
	v_exp_f32_e32 v215, v215
	v_pk_add_f32 v[252:253], v[252:253], v[212:213]
	v_pk_add_f32 v[252:253], v[252:253], v[214:215]
	v_exp_f32_e32 v216, v216
	v_exp_f32_e32 v217, v217
	v_cvt_pk_bf16_f32 v208, v212, v213
	v_cvt_pk_bf16_f32 v209, v214, v215
	v_exp_f32_e32 v218, v218
	v_exp_f32_e32 v219, v219
	v_pk_add_f32 v[252:253], v[252:253], v[216:217]
	v_pk_add_f32 v[252:253], v[252:253], v[218:219]
	v_cvt_pk_bf16_f32 v210, v216, v217
	v_cvt_pk_bf16_f32 v211, v218, v219
	s_mov_b32 s24, s23
	s_mov_b32 s35, s24
	v_mov_b32_e32 v251, 0
	s_cmp_eq_u32 s24, 1
	s_cselect_b64 vcc, -1, 0
	v_cndmask_b32_e32 v251, v251, v177, vcc
	s_cmp_eq_u32 s24, 2
	s_cselect_b64 vcc, -1, 0
	v_cndmask_b32_e32 v251, v251, v178, vcc
	v_sub_f32_e32 v2, v251, v186
	v_mov_b32_e32 v3, v2
	v_mov_b64_e32 v[4:5], v[2:3]
	v_mov_b64_e32 v[6:7], v[2:3]
	v_mov_b64_e32 v[8:9], v[2:3]
	v_mov_b64_e32 v[10:11], v[2:3]
	v_mov_b64_e32 v[12:13], v[2:3]
	v_mov_b64_e32 v[14:15], v[2:3]
	v_mov_b64_e32 v[16:17], v[2:3]
	ds_read_b64_tr_b16 v[132:133], v168 offset:0
	ds_read_b64_tr_b16 v[134:135], v168 offset:2048
	ds_read_b64_tr_b16 v[136:137], v169 offset:0
	ds_read_b64_tr_b16 v[138:139], v169 offset:2048
	ds_read_b64_tr_b16 v[140:141], v170 offset:0
	ds_read_b64_tr_b16 v[142:143], v170 offset:2048
	ds_read_b64_tr_b16 v[144:145], v171 offset:0
	ds_read_b64_tr_b16 v[146:147], v171 offset:2048
	ds_read_b64_tr_b16 v[220:221], v168 offset:4096
	ds_read_b64_tr_b16 v[222:223], v168 offset:6144
	ds_read_b64_tr_b16 v[224:225], v169 offset:4096
	ds_read_b64_tr_b16 v[226:227], v169 offset:6144
	ds_read_b64_tr_b16 v[232:233], v170 offset:4096
	ds_read_b64_tr_b16 v[234:235], v170 offset:6144
	s_nop 1
	s_cmp_eq_u32 s22, 0
	s_cbranch_scc1 .LatB_recret_h3
	s_cmp_eq_u32 s22, 1
	s_cbranch_scc1 .LatB_recret_m3
	s_branch .LatB_recret_x1
